# c22: c16 without the mid-segment s_setprio 0/1 yield pair: the MFMA wave keeps priority 1 through its whole segment
# speedup vs baseline: 1.0063x; 1.0063x over previous
.LBB0_343:
	s_ashr_i32 s11, s10, 31
	s_lshl_b64 s[12:13], s[10:11], 20
	s_add_u32 s12, s26, s12
	s_addc_u32 s13, s27, s13
	s_and_b64 s[14:15], s[2:3], exec
	s_cselect_b32 s11, s13, s21
	s_cselect_b32 s75, s12, s20
	s_ashr_i32 s9, s8, 31
	s_lshl_b64 s[14:15], s[8:9], 20
	s_add_u32 s14, s28, s14
	s_addc_u32 s15, s29, s15
	s_and_b64 s[22:23], s[2:3], exec
	s_cselect_b32 s9, s15, s19
	s_cselect_b32 s76, s14, s18
	s_add_u32 s77, s18, 0x100
	s_addc_u32 s78, s19, 0
	s_add_u32 s18, s20, 0x80080
	s_addc_u32 s19, s21, 0
	s_add_u32 s79, s20, 0x100
	s_addc_u32 s80, s21, 0
	s_mov_b32 s81, -2
	ds_read_b128 v[148:151], v143
	ds_read_b128 v[152:155], v143 offset:1024
	ds_read_b128 v[156:159], v143 offset:2048
	ds_read_b128 v[160:163], v143 offset:3072
	ds_read_b128 v[164:167], v144
	ds_read_b128 v[168:171], v144 offset:1024
	ds_read_b128 v[172:175], v144 offset:2048
	ds_read_b128 v[176:179], v144 offset:3072
	s_cmp_eq_u32 s81, 28
	s_cselect_b32 s21, s9, s78
	s_cselect_b32 s20, s76, s77
	s_cselect_b32 s23, s11, s80
	s_cselect_b32 s22, s75, s79
	ds_read_b128 v[180:183], v145
	ds_read_b128 v[184:187], v145 offset:1024
	ds_read_b128 v[188:191], v145 offset:2048
	ds_read_b128 v[192:195], v145 offset:3072
	ds_read_b128 v[196:199], v145 offset:4096
	ds_read_b128 v[200:203], v145 offset:5120
	ds_read_b128 v[204:207], v145 offset:6144
	ds_read_b128 v[208:211], v145 offset:7168
	s_add_u32 s82, s18, 0xfff80000
	s_addc_u32 s83, s19, -1
	s_mov_b32 s86, m0
	s_mov_b32 m0, s64
	s_nop 0
	global_load_lds_dwordx4 v138, s[82:83]
	s_mov_b32 m0, s86
	s_nop 0
	s_mov_b32 s86, m0
	s_mov_b32 m0, s67
	s_nop 0
	global_load_lds_dwordx4 v140, s[82:83]
	s_mov_b32 m0, s86
	s_mov_b32 s82, m0
	s_mov_b32 m0, s65
	s_nop 0
	global_load_lds_dwordx4 v138, s[18:19]
	s_mov_b32 m0, s82
	s_nop 0
	s_mov_b32 s82, m0
	s_mov_b32 m0, s73
	s_nop 0
	global_load_lds_dwordx4 v140, s[18:19]
	s_mov_b32 m0, s82
	s_waitcnt vmcnt(8)
	s_waitcnt lgkmcnt(0)
	s_barrier
	s_setprio 1
	s_waitcnt lgkmcnt(7)
	v_mfma_f32_16x16x32_bf16 v[126:129], v[148:151], v[180:183], 0
	v_mfma_f32_16x16x32_bf16 v[126:129], v[152:155], v[184:187], v[126:129]
	s_waitcnt lgkmcnt(5)
	v_mfma_f32_16x16x32_bf16 v[122:125], v[156:159], v[180:183], 0
	v_mfma_f32_16x16x32_bf16 v[122:125], v[160:163], v[184:187], v[122:125]
	s_waitcnt lgkmcnt(3)
	v_mfma_f32_16x16x32_bf16 v[106:109], v[156:159], v[188:191], 0
	v_mfma_f32_16x16x32_bf16 v[106:109], v[160:163], v[192:195], v[106:109]
	s_waitcnt lgkmcnt(1)
	v_mfma_f32_16x16x32_bf16 v[110:113], v[148:151], v[188:191], 0
	v_mfma_f32_16x16x32_bf16 v[110:113], v[152:155], v[192:195], v[110:113]
	v_mfma_f32_16x16x32_bf16 v[94:97], v[148:151], v[196:199], 0
	v_mfma_f32_16x16x32_bf16 v[94:97], v[152:155], v[200:203], v[94:97]
	v_mfma_f32_16x16x32_bf16 v[90:93], v[156:159], v[196:199], 0
	v_mfma_f32_16x16x32_bf16 v[90:93], v[160:163], v[200:203], v[90:93]
	v_mfma_f32_16x16x32_bf16 v[74:77], v[156:159], v[204:207], 0
	v_mfma_f32_16x16x32_bf16 v[74:77], v[160:163], v[208:211], v[74:77]
	s_waitcnt lgkmcnt(0)
	v_mfma_f32_16x16x32_bf16 v[78:81], v[148:151], v[204:207], 0
	v_mfma_f32_16x16x32_bf16 v[78:81], v[152:155], v[208:211], v[78:81]
	v_mfma_f32_16x16x32_bf16 v[118:121], v[164:167], v[180:183], 0
	v_mfma_f32_16x16x32_bf16 v[118:121], v[168:171], v[184:187], v[118:121]
	v_mfma_f32_16x16x32_bf16 v[114:117], v[172:175], v[180:183], 0
	v_mfma_f32_16x16x32_bf16 v[114:117], v[176:179], v[184:187], v[114:117]
	v_mfma_f32_16x16x32_bf16 v[98:101], v[172:175], v[188:191], 0
	v_mfma_f32_16x16x32_bf16 v[98:101], v[176:179], v[192:195], v[98:101]
	v_mfma_f32_16x16x32_bf16 v[102:105], v[164:167], v[188:191], 0
	v_mfma_f32_16x16x32_bf16 v[102:105], v[168:171], v[192:195], v[102:105]
	v_mfma_f32_16x16x32_bf16 v[86:89], v[164:167], v[196:199], 0
	v_mfma_f32_16x16x32_bf16 v[86:89], v[168:171], v[200:203], v[86:89]
	v_mfma_f32_16x16x32_bf16 v[82:85], v[172:175], v[196:199], 0
	v_mfma_f32_16x16x32_bf16 v[82:85], v[176:179], v[200:203], v[82:85]
	v_mfma_f32_16x16x32_bf16 v[66:69], v[172:175], v[204:207], 0
	v_mfma_f32_16x16x32_bf16 v[66:69], v[176:179], v[208:211], v[66:69]
	s_setprio 2
	s_barrier
	v_mfma_f32_16x16x32_bf16 v[70:73], v[164:167], v[204:207], 0
	v_mfma_f32_16x16x32_bf16 v[70:73], v[168:171], v[208:211], v[70:73]
	s_setprio 0
	ds_read_b128 v[180:183], v145 offset:16384
	ds_read_b128 v[184:187], v145 offset:17408
	ds_read_b128 v[188:191], v145 offset:18432
	ds_read_b128 v[192:195], v145 offset:19456
	ds_read_b128 v[196:199], v145 offset:20480
	ds_read_b128 v[200:203], v145 offset:21504
	ds_read_b128 v[204:207], v145 offset:22528
	ds_read_b128 v[208:211], v145 offset:23552
	s_mov_b32 s82, m0
	s_mov_b32 m0, s35
	s_nop 0
	global_load_lds_dwordx4 v139, s[20:21]
	s_mov_b32 m0, s82
	s_nop 0
	s_mov_b32 s82, m0
	s_mov_b32 m0, s36
	s_nop 0
	global_load_lds_dwordx4 v141, s[20:21]
	s_mov_b32 m0, s82
	s_add_u32 s82, s20, 0x80000
	s_addc_u32 s83, s21, 0
	s_mov_b32 s86, m0
	s_mov_b32 m0, s37
	s_nop 0
	global_load_lds_dwordx4 v139, s[82:83]
	s_mov_b32 m0, s86
	s_nop 0
	s_mov_b32 s86, m0
	s_mov_b32 m0, s42
	s_nop 0
	global_load_lds_dwordx4 v141, s[82:83]
	s_mov_b32 m0, s86
	s_waitcnt vmcnt(4)
	s_waitcnt lgkmcnt(0)
	s_barrier
	s_setprio 1
	s_waitcnt lgkmcnt(7)
	v_mfma_f32_16x16x32_bf16 v[62:65], v[148:151], v[180:183], 0
	v_mfma_f32_16x16x32_bf16 v[62:65], v[152:155], v[184:187], v[62:65]
	s_waitcnt lgkmcnt(5)
	v_mfma_f32_16x16x32_bf16 v[58:61], v[156:159], v[180:183], 0
	v_mfma_f32_16x16x32_bf16 v[58:61], v[160:163], v[184:187], v[58:61]
	s_waitcnt lgkmcnt(3)
	v_mfma_f32_16x16x32_bf16 v[42:45], v[156:159], v[188:191], 0
	v_mfma_f32_16x16x32_bf16 v[42:45], v[160:163], v[192:195], v[42:45]
	s_waitcnt lgkmcnt(1)
	v_mfma_f32_16x16x32_bf16 v[46:49], v[148:151], v[188:191], 0
	v_mfma_f32_16x16x32_bf16 v[46:49], v[152:155], v[192:195], v[46:49]
	v_mfma_f32_16x16x32_bf16 v[30:33], v[148:151], v[196:199], 0
	v_mfma_f32_16x16x32_bf16 v[30:33], v[152:155], v[200:203], v[30:33]
	v_mfma_f32_16x16x32_bf16 v[26:29], v[156:159], v[196:199], 0
	v_mfma_f32_16x16x32_bf16 v[26:29], v[160:163], v[200:203], v[26:29]
	v_mfma_f32_16x16x32_bf16 v[10:13], v[156:159], v[204:207], 0
	v_mfma_f32_16x16x32_bf16 v[10:13], v[160:163], v[208:211], v[10:13]
	s_waitcnt lgkmcnt(0)
	v_mfma_f32_16x16x32_bf16 v[14:17], v[148:151], v[204:207], 0
	v_mfma_f32_16x16x32_bf16 v[14:17], v[152:155], v[208:211], v[14:17]
	v_mfma_f32_16x16x32_bf16 v[54:57], v[164:167], v[180:183], 0
	v_mfma_f32_16x16x32_bf16 v[54:57], v[168:171], v[184:187], v[54:57]
	v_mfma_f32_16x16x32_bf16 v[50:53], v[172:175], v[180:183], 0
	v_mfma_f32_16x16x32_bf16 v[50:53], v[176:179], v[184:187], v[50:53]
	v_mfma_f32_16x16x32_bf16 v[34:37], v[172:175], v[188:191], 0
	v_mfma_f32_16x16x32_bf16 v[34:37], v[176:179], v[192:195], v[34:37]
	v_mfma_f32_16x16x32_bf16 v[38:41], v[164:167], v[188:191], 0
	v_mfma_f32_16x16x32_bf16 v[38:41], v[168:171], v[192:195], v[38:41]
	v_mfma_f32_16x16x32_bf16 v[22:25], v[164:167], v[196:199], 0
	v_mfma_f32_16x16x32_bf16 v[22:25], v[168:171], v[200:203], v[22:25]
	v_mfma_f32_16x16x32_bf16 v[18:21], v[172:175], v[196:199], 0
	v_mfma_f32_16x16x32_bf16 v[18:21], v[176:179], v[200:203], v[18:21]
	v_mfma_f32_16x16x32_bf16 v[2:5], v[172:175], v[204:207], 0
	v_mfma_f32_16x16x32_bf16 v[2:5], v[176:179], v[208:211], v[2:5]
	s_setprio 2
	s_barrier
	v_mfma_f32_16x16x32_bf16 v[6:9], v[164:167], v[204:207], 0
	v_mfma_f32_16x16x32_bf16 v[6:9], v[168:171], v[208:211], v[6:9]
	s_setprio 0
	ds_read_b128 v[148:151], v146
	ds_read_b128 v[152:155], v146 offset:1024
	ds_read_b128 v[156:159], v146 offset:2048
	ds_read_b128 v[160:163], v146 offset:3072
	ds_read_b128 v[164:167], v147
	ds_read_b128 v[168:171], v147 offset:1024
	ds_read_b128 v[172:175], v147 offset:2048
	ds_read_b128 v[176:179], v147 offset:3072
	ds_read_b128 v[180:183], v145 offset:32768
	ds_read_b128 v[184:187], v145 offset:33792
	ds_read_b128 v[188:191], v145 offset:34816
	ds_read_b128 v[192:195], v145 offset:35840
	ds_read_b128 v[196:199], v145 offset:36864
	ds_read_b128 v[200:203], v145 offset:37888
	ds_read_b128 v[204:207], v145 offset:38912
	ds_read_b128 v[208:211], v145 offset:39936
	s_mov_b32 s82, m0
	s_mov_b32 m0, s31
	s_nop 0
	global_load_lds_dwordx4 v138, s[22:23]
	s_mov_b32 m0, s82
	s_nop 0
	s_mov_b32 s82, m0
	s_mov_b32 m0, s43
	s_nop 0
	global_load_lds_dwordx4 v140, s[22:23]
	s_mov_b32 m0, s82
	s_add_u32 s22, s22, 0x80000
	s_addc_u32 s23, s23, 0
	s_mov_b32 s82, m0
	s_mov_b32 m0, s46
	s_nop 0
	global_load_lds_dwordx4 v138, s[22:23]
	s_mov_b32 m0, s82
	s_nop 0
	s_mov_b32 s82, m0
	s_mov_b32 m0, s47
	s_nop 0
	global_load_lds_dwordx4 v140, s[22:23]
	s_mov_b32 m0, s82
	s_waitcnt vmcnt(8)
	s_waitcnt lgkmcnt(0)
	s_barrier
	s_setprio 1
	s_waitcnt lgkmcnt(7)
	v_mfma_f32_16x16x32_bf16 v[126:129], v[148:151], v[180:183], v[126:129]
	v_mfma_f32_16x16x32_bf16 v[126:129], v[152:155], v[184:187], v[126:129]
	s_waitcnt lgkmcnt(5)
	v_mfma_f32_16x16x32_bf16 v[122:125], v[156:159], v[180:183], v[122:125]
	v_mfma_f32_16x16x32_bf16 v[122:125], v[160:163], v[184:187], v[122:125]
	s_waitcnt lgkmcnt(3)
	v_mfma_f32_16x16x32_bf16 v[106:109], v[156:159], v[188:191], v[106:109]
	v_mfma_f32_16x16x32_bf16 v[106:109], v[160:163], v[192:195], v[106:109]
	s_waitcnt lgkmcnt(1)
	v_mfma_f32_16x16x32_bf16 v[110:113], v[148:151], v[188:191], v[110:113]
	v_mfma_f32_16x16x32_bf16 v[110:113], v[152:155], v[192:195], v[110:113]
	v_mfma_f32_16x16x32_bf16 v[94:97], v[148:151], v[196:199], v[94:97]
	v_mfma_f32_16x16x32_bf16 v[94:97], v[152:155], v[200:203], v[94:97]
	v_mfma_f32_16x16x32_bf16 v[90:93], v[156:159], v[196:199], v[90:93]
	v_mfma_f32_16x16x32_bf16 v[90:93], v[160:163], v[200:203], v[90:93]
	v_mfma_f32_16x16x32_bf16 v[74:77], v[156:159], v[204:207], v[74:77]
	v_mfma_f32_16x16x32_bf16 v[74:77], v[160:163], v[208:211], v[74:77]
	s_waitcnt lgkmcnt(0)
	v_mfma_f32_16x16x32_bf16 v[78:81], v[148:151], v[204:207], v[78:81]
	v_mfma_f32_16x16x32_bf16 v[78:81], v[152:155], v[208:211], v[78:81]
	v_mfma_f32_16x16x32_bf16 v[118:121], v[164:167], v[180:183], v[118:121]
	v_mfma_f32_16x16x32_bf16 v[118:121], v[168:171], v[184:187], v[118:121]
	v_mfma_f32_16x16x32_bf16 v[114:117], v[172:175], v[180:183], v[114:117]
	v_mfma_f32_16x16x32_bf16 v[114:117], v[176:179], v[184:187], v[114:117]
	v_mfma_f32_16x16x32_bf16 v[98:101], v[172:175], v[188:191], v[98:101]
	v_mfma_f32_16x16x32_bf16 v[98:101], v[176:179], v[192:195], v[98:101]
	v_mfma_f32_16x16x32_bf16 v[102:105], v[164:167], v[188:191], v[102:105]
	v_mfma_f32_16x16x32_bf16 v[102:105], v[168:171], v[192:195], v[102:105]
	v_mfma_f32_16x16x32_bf16 v[86:89], v[164:167], v[196:199], v[86:89]
	v_mfma_f32_16x16x32_bf16 v[86:89], v[168:171], v[200:203], v[86:89]
	v_mfma_f32_16x16x32_bf16 v[82:85], v[172:175], v[196:199], v[82:85]
	v_mfma_f32_16x16x32_bf16 v[82:85], v[176:179], v[200:203], v[82:85]
	v_mfma_f32_16x16x32_bf16 v[66:69], v[172:175], v[204:207], v[66:69]
	v_mfma_f32_16x16x32_bf16 v[66:69], v[176:179], v[208:211], v[66:69]
	s_setprio 2
	s_barrier
	v_mfma_f32_16x16x32_bf16 v[70:73], v[164:167], v[204:207], v[70:73]
	v_mfma_f32_16x16x32_bf16 v[70:73], v[168:171], v[208:211], v[70:73]
	s_setprio 0
	ds_read_b128 v[180:183], v145 offset:49152
	ds_read_b128 v[184:187], v145 offset:50176
	ds_read_b128 v[188:191], v145 offset:51200
	ds_read_b128 v[192:195], v145 offset:52224
	ds_read_b128 v[196:199], v145 offset:53248
	ds_read_b128 v[200:203], v145 offset:54272
	ds_read_b128 v[204:207], v145 offset:55296
	ds_read_b128 v[208:211], v145 offset:56320
	s_add_u32 s22, s20, 0x80
	s_addc_u32 s23, s21, 0
	s_mov_b32 s82, m0
	s_mov_b32 m0, s48
	s_nop 0
	global_load_lds_dwordx4 v139, s[22:23]
	s_mov_b32 m0, s82
	s_add_u32 s20, s20, 0x80080
	s_mov_b32 s82, m0
	s_mov_b32 m0, s49
	s_nop 0
	global_load_lds_dwordx4 v141, s[22:23]
	s_mov_b32 m0, s82
	s_addc_u32 s21, s21, 0
	s_mov_b32 s22, m0
	s_mov_b32 m0, s56
	s_nop 0
	global_load_lds_dwordx4 v139, s[20:21]
	s_mov_b32 m0, s22
	s_nop 0
	s_mov_b32 s22, m0
	s_mov_b32 m0, s57
	s_nop 0
	global_load_lds_dwordx4 v141, s[20:21]
	s_mov_b32 m0, s22
	s_waitcnt vmcnt(4)
	s_waitcnt lgkmcnt(0)
	s_barrier
	s_setprio 1
	s_waitcnt lgkmcnt(7)
	v_mfma_f32_16x16x32_bf16 v[62:65], v[148:151], v[180:183], v[62:65]
	v_mfma_f32_16x16x32_bf16 v[62:65], v[152:155], v[184:187], v[62:65]
	s_waitcnt lgkmcnt(5)
	v_mfma_f32_16x16x32_bf16 v[58:61], v[156:159], v[180:183], v[58:61]
	v_mfma_f32_16x16x32_bf16 v[58:61], v[160:163], v[184:187], v[58:61]
	s_waitcnt lgkmcnt(3)
	v_mfma_f32_16x16x32_bf16 v[42:45], v[156:159], v[188:191], v[42:45]
	v_mfma_f32_16x16x32_bf16 v[42:45], v[160:163], v[192:195], v[42:45]
	s_waitcnt lgkmcnt(1)
	v_mfma_f32_16x16x32_bf16 v[46:49], v[148:151], v[188:191], v[46:49]
	v_mfma_f32_16x16x32_bf16 v[46:49], v[152:155], v[192:195], v[46:49]
	v_mfma_f32_16x16x32_bf16 v[30:33], v[148:151], v[196:199], v[30:33]
	v_mfma_f32_16x16x32_bf16 v[30:33], v[152:155], v[200:203], v[30:33]
	v_mfma_f32_16x16x32_bf16 v[26:29], v[156:159], v[196:199], v[26:29]
	v_mfma_f32_16x16x32_bf16 v[26:29], v[160:163], v[200:203], v[26:29]
	v_mfma_f32_16x16x32_bf16 v[10:13], v[156:159], v[204:207], v[10:13]
	v_mfma_f32_16x16x32_bf16 v[10:13], v[160:163], v[208:211], v[10:13]
	s_waitcnt lgkmcnt(0)
	v_mfma_f32_16x16x32_bf16 v[14:17], v[148:151], v[204:207], v[14:17]
	v_mfma_f32_16x16x32_bf16 v[14:17], v[152:155], v[208:211], v[14:17]
	v_mfma_f32_16x16x32_bf16 v[54:57], v[164:167], v[180:183], v[54:57]
	v_mfma_f32_16x16x32_bf16 v[54:57], v[168:171], v[184:187], v[54:57]
	v_mfma_f32_16x16x32_bf16 v[50:53], v[172:175], v[180:183], v[50:53]
	v_mfma_f32_16x16x32_bf16 v[50:53], v[176:179], v[184:187], v[50:53]
	v_mfma_f32_16x16x32_bf16 v[34:37], v[172:175], v[188:191], v[34:37]
	v_mfma_f32_16x16x32_bf16 v[34:37], v[176:179], v[192:195], v[34:37]
	v_mfma_f32_16x16x32_bf16 v[38:41], v[164:167], v[188:191], v[38:41]
	v_mfma_f32_16x16x32_bf16 v[38:41], v[168:171], v[192:195], v[38:41]
	v_mfma_f32_16x16x32_bf16 v[22:25], v[164:167], v[196:199], v[22:25]
	v_mfma_f32_16x16x32_bf16 v[22:25], v[168:171], v[200:203], v[22:25]
	v_mfma_f32_16x16x32_bf16 v[18:21], v[172:175], v[196:199], v[18:21]
	v_mfma_f32_16x16x32_bf16 v[18:21], v[176:179], v[200:203], v[18:21]
	v_mfma_f32_16x16x32_bf16 v[2:5], v[172:175], v[204:207], v[2:5]
	v_mfma_f32_16x16x32_bf16 v[2:5], v[176:179], v[208:211], v[2:5]
	s_setprio 2
	s_barrier
	v_mfma_f32_16x16x32_bf16 v[6:9], v[164:167], v[204:207], v[6:9]
	v_mfma_f32_16x16x32_bf16 v[6:9], v[168:171], v[208:211], v[6:9]
	s_setprio 0
	s_add_i32 s81, s81, 2
	s_add_u32 s77, s77, 0x100
	s_addc_u32 s78, s78, 0
	s_add_u32 s18, s18, 0x100
	s_addc_u32 s19, s19, 0
	s_add_u32 s79, s79, 0x100
	s_addc_u32 s80, s80, 0
	s_cmp_gt_u32 s81, 29
	.p2align 6
.LBB0_344:
	ds_read_b128 v[148:151], v143
	ds_read_b128 v[152:155], v143 offset:1024
	ds_read_b128 v[156:159], v143 offset:2048
	ds_read_b128 v[160:163], v143 offset:3072
	ds_read_b128 v[164:167], v144
	ds_read_b128 v[168:171], v144 offset:1024
	ds_read_b128 v[172:175], v144 offset:2048
	ds_read_b128 v[176:179], v144 offset:3072
	s_cmp_eq_u32 s81, 28
	s_cselect_b32 s21, s9, s78
	s_cselect_b32 s20, s76, s77
	s_cselect_b32 s23, s11, s80
	s_cselect_b32 s22, s75, s79
	ds_read_b128 v[180:183], v145
	ds_read_b128 v[184:187], v145 offset:1024
	ds_read_b128 v[188:191], v145 offset:2048
	ds_read_b128 v[192:195], v145 offset:3072
	ds_read_b128 v[196:199], v145 offset:4096
	ds_read_b128 v[200:203], v145 offset:5120
	ds_read_b128 v[204:207], v145 offset:6144
	ds_read_b128 v[208:211], v145 offset:7168
	s_add_u32 s82, s18, 0xfff80000
	s_addc_u32 s83, s19, -1
	s_mov_b32 s86, m0
	s_mov_b32 m0, s64
	s_nop 0
	global_load_lds_dwordx4 v138, s[82:83]
	s_mov_b32 m0, s86
	s_nop 0
	s_mov_b32 s86, m0
	s_mov_b32 m0, s67
	s_nop 0
	global_load_lds_dwordx4 v140, s[82:83]
	s_mov_b32 m0, s86
	s_mov_b32 s82, m0
	s_mov_b32 m0, s65
	s_nop 0
	global_load_lds_dwordx4 v138, s[18:19]
	s_mov_b32 m0, s82
	s_nop 0
	s_mov_b32 s82, m0
	s_mov_b32 m0, s73
	s_nop 0
	global_load_lds_dwordx4 v140, s[18:19]
	s_mov_b32 m0, s82
	s_waitcnt vmcnt(8)
	s_waitcnt lgkmcnt(0)
	s_barrier
	s_setprio 1
	s_waitcnt lgkmcnt(7)
	v_mfma_f32_16x16x32_bf16 v[126:129], v[148:151], v[180:183], v[126:129]
	v_mfma_f32_16x16x32_bf16 v[126:129], v[152:155], v[184:187], v[126:129]
	s_waitcnt lgkmcnt(5)
	v_mfma_f32_16x16x32_bf16 v[122:125], v[156:159], v[180:183], v[122:125]
	v_mfma_f32_16x16x32_bf16 v[122:125], v[160:163], v[184:187], v[122:125]
	s_waitcnt lgkmcnt(3)
	v_mfma_f32_16x16x32_bf16 v[106:109], v[156:159], v[188:191], v[106:109]
	v_mfma_f32_16x16x32_bf16 v[106:109], v[160:163], v[192:195], v[106:109]
	s_waitcnt lgkmcnt(1)
	v_mfma_f32_16x16x32_bf16 v[110:113], v[148:151], v[188:191], v[110:113]
	v_mfma_f32_16x16x32_bf16 v[110:113], v[152:155], v[192:195], v[110:113]
	v_mfma_f32_16x16x32_bf16 v[94:97], v[148:151], v[196:199], v[94:97]
	v_mfma_f32_16x16x32_bf16 v[94:97], v[152:155], v[200:203], v[94:97]
	v_mfma_f32_16x16x32_bf16 v[90:93], v[156:159], v[196:199], v[90:93]
	v_mfma_f32_16x16x32_bf16 v[90:93], v[160:163], v[200:203], v[90:93]
	v_mfma_f32_16x16x32_bf16 v[74:77], v[156:159], v[204:207], v[74:77]
	v_mfma_f32_16x16x32_bf16 v[74:77], v[160:163], v[208:211], v[74:77]
	s_waitcnt lgkmcnt(0)
	v_mfma_f32_16x16x32_bf16 v[78:81], v[148:151], v[204:207], v[78:81]
	v_mfma_f32_16x16x32_bf16 v[78:81], v[152:155], v[208:211], v[78:81]
	v_mfma_f32_16x16x32_bf16 v[118:121], v[164:167], v[180:183], v[118:121]
	v_mfma_f32_16x16x32_bf16 v[118:121], v[168:171], v[184:187], v[118:121]
	v_mfma_f32_16x16x32_bf16 v[114:117], v[172:175], v[180:183], v[114:117]
	v_mfma_f32_16x16x32_bf16 v[114:117], v[176:179], v[184:187], v[114:117]
	v_mfma_f32_16x16x32_bf16 v[98:101], v[172:175], v[188:191], v[98:101]
	v_mfma_f32_16x16x32_bf16 v[98:101], v[176:179], v[192:195], v[98:101]
	v_mfma_f32_16x16x32_bf16 v[102:105], v[164:167], v[188:191], v[102:105]
	v_mfma_f32_16x16x32_bf16 v[102:105], v[168:171], v[192:195], v[102:105]
	v_mfma_f32_16x16x32_bf16 v[86:89], v[164:167], v[196:199], v[86:89]
	v_mfma_f32_16x16x32_bf16 v[86:89], v[168:171], v[200:203], v[86:89]
	v_mfma_f32_16x16x32_bf16 v[82:85], v[172:175], v[196:199], v[82:85]
	v_mfma_f32_16x16x32_bf16 v[82:85], v[176:179], v[200:203], v[82:85]
	v_mfma_f32_16x16x32_bf16 v[66:69], v[172:175], v[204:207], v[66:69]
	v_mfma_f32_16x16x32_bf16 v[66:69], v[176:179], v[208:211], v[66:69]
	s_setprio 2
	s_barrier
	v_mfma_f32_16x16x32_bf16 v[70:73], v[164:167], v[204:207], v[70:73]
	v_mfma_f32_16x16x32_bf16 v[70:73], v[168:171], v[208:211], v[70:73]
	s_setprio 0
	ds_read_b128 v[180:183], v145 offset:16384
	ds_read_b128 v[184:187], v145 offset:17408
	ds_read_b128 v[188:191], v145 offset:18432
	ds_read_b128 v[192:195], v145 offset:19456
	ds_read_b128 v[196:199], v145 offset:20480
	ds_read_b128 v[200:203], v145 offset:21504
	ds_read_b128 v[204:207], v145 offset:22528
	ds_read_b128 v[208:211], v145 offset:23552
	s_mov_b32 s82, m0
	s_mov_b32 m0, s35
	s_nop 0
	global_load_lds_dwordx4 v139, s[20:21]
	s_mov_b32 m0, s82
	s_nop 0
	s_mov_b32 s82, m0
	s_mov_b32 m0, s36
	s_nop 0
	global_load_lds_dwordx4 v141, s[20:21]
	s_mov_b32 m0, s82
	s_add_u32 s82, s20, 0x80000
	s_addc_u32 s83, s21, 0
	s_mov_b32 s86, m0
	s_mov_b32 m0, s37
	s_nop 0
	global_load_lds_dwordx4 v139, s[82:83]
	s_mov_b32 m0, s86
	s_nop 0
	s_mov_b32 s86, m0
	s_mov_b32 m0, s42
	s_nop 0
	global_load_lds_dwordx4 v141, s[82:83]
	s_mov_b32 m0, s86
	s_waitcnt vmcnt(4)
	s_waitcnt lgkmcnt(0)
	s_barrier
	s_setprio 1
	s_waitcnt lgkmcnt(7)
	v_mfma_f32_16x16x32_bf16 v[62:65], v[148:151], v[180:183], v[62:65]
	v_mfma_f32_16x16x32_bf16 v[62:65], v[152:155], v[184:187], v[62:65]
	s_waitcnt lgkmcnt(5)
	v_mfma_f32_16x16x32_bf16 v[58:61], v[156:159], v[180:183], v[58:61]
	v_mfma_f32_16x16x32_bf16 v[58:61], v[160:163], v[184:187], v[58:61]
	s_waitcnt lgkmcnt(3)
	v_mfma_f32_16x16x32_bf16 v[42:45], v[156:159], v[188:191], v[42:45]
	v_mfma_f32_16x16x32_bf16 v[42:45], v[160:163], v[192:195], v[42:45]
	s_waitcnt lgkmcnt(1)
	v_mfma_f32_16x16x32_bf16 v[46:49], v[148:151], v[188:191], v[46:49]
	v_mfma_f32_16x16x32_bf16 v[46:49], v[152:155], v[192:195], v[46:49]
	v_mfma_f32_16x16x32_bf16 v[30:33], v[148:151], v[196:199], v[30:33]
	v_mfma_f32_16x16x32_bf16 v[30:33], v[152:155], v[200:203], v[30:33]
	v_mfma_f32_16x16x32_bf16 v[26:29], v[156:159], v[196:199], v[26:29]
	v_mfma_f32_16x16x32_bf16 v[26:29], v[160:163], v[200:203], v[26:29]
	v_mfma_f32_16x16x32_bf16 v[10:13], v[156:159], v[204:207], v[10:13]
	v_mfma_f32_16x16x32_bf16 v[10:13], v[160:163], v[208:211], v[10:13]
	s_waitcnt lgkmcnt(0)
	v_mfma_f32_16x16x32_bf16 v[14:17], v[148:151], v[204:207], v[14:17]
	v_mfma_f32_16x16x32_bf16 v[14:17], v[152:155], v[208:211], v[14:17]
	v_mfma_f32_16x16x32_bf16 v[54:57], v[164:167], v[180:183], v[54:57]
	v_mfma_f32_16x16x32_bf16 v[54:57], v[168:171], v[184:187], v[54:57]
	v_mfma_f32_16x16x32_bf16 v[50:53], v[172:175], v[180:183], v[50:53]
	v_mfma_f32_16x16x32_bf16 v[50:53], v[176:179], v[184:187], v[50:53]
	v_mfma_f32_16x16x32_bf16 v[34:37], v[172:175], v[188:191], v[34:37]
	v_mfma_f32_16x16x32_bf16 v[34:37], v[176:179], v[192:195], v[34:37]
	v_mfma_f32_16x16x32_bf16 v[38:41], v[164:167], v[188:191], v[38:41]
	v_mfma_f32_16x16x32_bf16 v[38:41], v[168:171], v[192:195], v[38:41]
	v_mfma_f32_16x16x32_bf16 v[22:25], v[164:167], v[196:199], v[22:25]
	v_mfma_f32_16x16x32_bf16 v[22:25], v[168:171], v[200:203], v[22:25]
	v_mfma_f32_16x16x32_bf16 v[18:21], v[172:175], v[196:199], v[18:21]
	v_mfma_f32_16x16x32_bf16 v[18:21], v[176:179], v[200:203], v[18:21]
	v_mfma_f32_16x16x32_bf16 v[2:5], v[172:175], v[204:207], v[2:5]
	v_mfma_f32_16x16x32_bf16 v[2:5], v[176:179], v[208:211], v[2:5]
	s_setprio 2
	s_barrier
	v_mfma_f32_16x16x32_bf16 v[6:9], v[164:167], v[204:207], v[6:9]
	v_mfma_f32_16x16x32_bf16 v[6:9], v[168:171], v[208:211], v[6:9]
	s_setprio 0
	ds_read_b128 v[148:151], v146
	ds_read_b128 v[152:155], v146 offset:1024
	ds_read_b128 v[156:159], v146 offset:2048
	ds_read_b128 v[160:163], v146 offset:3072
	ds_read_b128 v[164:167], v147
	ds_read_b128 v[168:171], v147 offset:1024
	ds_read_b128 v[172:175], v147 offset:2048
	ds_read_b128 v[176:179], v147 offset:3072
	ds_read_b128 v[180:183], v145 offset:32768
	ds_read_b128 v[184:187], v145 offset:33792
	ds_read_b128 v[188:191], v145 offset:34816
	ds_read_b128 v[192:195], v145 offset:35840
	ds_read_b128 v[196:199], v145 offset:36864
	ds_read_b128 v[200:203], v145 offset:37888
	ds_read_b128 v[204:207], v145 offset:38912
	ds_read_b128 v[208:211], v145 offset:39936
	s_mov_b32 s82, m0
	s_mov_b32 m0, s31
	s_nop 0
	global_load_lds_dwordx4 v138, s[22:23]
	s_mov_b32 m0, s82
	s_nop 0
	s_mov_b32 s82, m0
	s_mov_b32 m0, s43
	s_nop 0
	global_load_lds_dwordx4 v140, s[22:23]
	s_mov_b32 m0, s82
	s_add_u32 s22, s22, 0x80000
	s_addc_u32 s23, s23, 0
	s_mov_b32 s82, m0
	s_mov_b32 m0, s46
	s_nop 0
	global_load_lds_dwordx4 v138, s[22:23]
	s_mov_b32 m0, s82
	s_nop 0
	s_mov_b32 s82, m0
	s_mov_b32 m0, s47
	s_nop 0
	global_load_lds_dwordx4 v140, s[22:23]
	s_mov_b32 m0, s82
	s_waitcnt vmcnt(8)
	s_waitcnt lgkmcnt(0)
	s_barrier
	s_setprio 1
	s_waitcnt lgkmcnt(7)
	v_mfma_f32_16x16x32_bf16 v[126:129], v[148:151], v[180:183], v[126:129]
	v_mfma_f32_16x16x32_bf16 v[126:129], v[152:155], v[184:187], v[126:129]
	s_waitcnt lgkmcnt(5)
	v_mfma_f32_16x16x32_bf16 v[122:125], v[156:159], v[180:183], v[122:125]
	v_mfma_f32_16x16x32_bf16 v[122:125], v[160:163], v[184:187], v[122:125]
	s_waitcnt lgkmcnt(3)
	v_mfma_f32_16x16x32_bf16 v[106:109], v[156:159], v[188:191], v[106:109]
	v_mfma_f32_16x16x32_bf16 v[106:109], v[160:163], v[192:195], v[106:109]
	s_waitcnt lgkmcnt(1)
	v_mfma_f32_16x16x32_bf16 v[110:113], v[148:151], v[188:191], v[110:113]
	v_mfma_f32_16x16x32_bf16 v[110:113], v[152:155], v[192:195], v[110:113]
	v_mfma_f32_16x16x32_bf16 v[94:97], v[148:151], v[196:199], v[94:97]
	v_mfma_f32_16x16x32_bf16 v[94:97], v[152:155], v[200:203], v[94:97]
	v_mfma_f32_16x16x32_bf16 v[90:93], v[156:159], v[196:199], v[90:93]
	v_mfma_f32_16x16x32_bf16 v[90:93], v[160:163], v[200:203], v[90:93]
	v_mfma_f32_16x16x32_bf16 v[74:77], v[156:159], v[204:207], v[74:77]
	v_mfma_f32_16x16x32_bf16 v[74:77], v[160:163], v[208:211], v[74:77]
	s_waitcnt lgkmcnt(0)
	v_mfma_f32_16x16x32_bf16 v[78:81], v[148:151], v[204:207], v[78:81]
	v_mfma_f32_16x16x32_bf16 v[78:81], v[152:155], v[208:211], v[78:81]
	v_mfma_f32_16x16x32_bf16 v[118:121], v[164:167], v[180:183], v[118:121]
	v_mfma_f32_16x16x32_bf16 v[118:121], v[168:171], v[184:187], v[118:121]
	v_mfma_f32_16x16x32_bf16 v[114:117], v[172:175], v[180:183], v[114:117]
	v_mfma_f32_16x16x32_bf16 v[114:117], v[176:179], v[184:187], v[114:117]
	v_mfma_f32_16x16x32_bf16 v[98:101], v[172:175], v[188:191], v[98:101]
	v_mfma_f32_16x16x32_bf16 v[98:101], v[176:179], v[192:195], v[98:101]
	v_mfma_f32_16x16x32_bf16 v[102:105], v[164:167], v[188:191], v[102:105]
	v_mfma_f32_16x16x32_bf16 v[102:105], v[168:171], v[192:195], v[102:105]
	v_mfma_f32_16x16x32_bf16 v[86:89], v[164:167], v[196:199], v[86:89]
	v_mfma_f32_16x16x32_bf16 v[86:89], v[168:171], v[200:203], v[86:89]
	v_mfma_f32_16x16x32_bf16 v[82:85], v[172:175], v[196:199], v[82:85]
	v_mfma_f32_16x16x32_bf16 v[82:85], v[176:179], v[200:203], v[82:85]
	v_mfma_f32_16x16x32_bf16 v[66:69], v[172:175], v[204:207], v[66:69]
	v_mfma_f32_16x16x32_bf16 v[66:69], v[176:179], v[208:211], v[66:69]
	s_setprio 2
	s_barrier
	v_mfma_f32_16x16x32_bf16 v[70:73], v[164:167], v[204:207], v[70:73]
	v_mfma_f32_16x16x32_bf16 v[70:73], v[168:171], v[208:211], v[70:73]
	s_setprio 0
	ds_read_b128 v[180:183], v145 offset:49152
	ds_read_b128 v[184:187], v145 offset:50176
	ds_read_b128 v[188:191], v145 offset:51200
	ds_read_b128 v[192:195], v145 offset:52224
	ds_read_b128 v[196:199], v145 offset:53248
	ds_read_b128 v[200:203], v145 offset:54272
	ds_read_b128 v[204:207], v145 offset:55296
	ds_read_b128 v[208:211], v145 offset:56320
	s_add_u32 s22, s20, 0x80
	s_addc_u32 s23, s21, 0
	s_mov_b32 s82, m0
	s_mov_b32 m0, s48
	s_nop 0
	global_load_lds_dwordx4 v139, s[22:23]
	s_mov_b32 m0, s82
	s_add_u32 s20, s20, 0x80080
	s_mov_b32 s82, m0
	s_mov_b32 m0, s49
	s_nop 0
	global_load_lds_dwordx4 v141, s[22:23]
	s_mov_b32 m0, s82
	s_addc_u32 s21, s21, 0
	s_mov_b32 s22, m0
	s_mov_b32 m0, s56
	s_nop 0
	global_load_lds_dwordx4 v139, s[20:21]
	s_mov_b32 m0, s22
	s_nop 0
	s_mov_b32 s22, m0
	s_mov_b32 m0, s57
	s_nop 0
	global_load_lds_dwordx4 v141, s[20:21]
	s_mov_b32 m0, s22
	s_waitcnt vmcnt(4)
	s_waitcnt lgkmcnt(0)
	s_barrier
	s_setprio 1
	s_waitcnt lgkmcnt(7)
	v_mfma_f32_16x16x32_bf16 v[62:65], v[148:151], v[180:183], v[62:65]
	v_mfma_f32_16x16x32_bf16 v[62:65], v[152:155], v[184:187], v[62:65]
	s_waitcnt lgkmcnt(5)
	v_mfma_f32_16x16x32_bf16 v[58:61], v[156:159], v[180:183], v[58:61]
	v_mfma_f32_16x16x32_bf16 v[58:61], v[160:163], v[184:187], v[58:61]
	s_waitcnt lgkmcnt(3)
	v_mfma_f32_16x16x32_bf16 v[42:45], v[156:159], v[188:191], v[42:45]
	v_mfma_f32_16x16x32_bf16 v[42:45], v[160:163], v[192:195], v[42:45]
	s_waitcnt lgkmcnt(1)
	v_mfma_f32_16x16x32_bf16 v[46:49], v[148:151], v[188:191], v[46:49]
	v_mfma_f32_16x16x32_bf16 v[46:49], v[152:155], v[192:195], v[46:49]
	v_mfma_f32_16x16x32_bf16 v[30:33], v[148:151], v[196:199], v[30:33]
	v_mfma_f32_16x16x32_bf16 v[30:33], v[152:155], v[200:203], v[30:33]
	v_mfma_f32_16x16x32_bf16 v[26:29], v[156:159], v[196:199], v[26:29]
	v_mfma_f32_16x16x32_bf16 v[26:29], v[160:163], v[200:203], v[26:29]
	v_mfma_f32_16x16x32_bf16 v[10:13], v[156:159], v[204:207], v[10:13]
	v_mfma_f32_16x16x32_bf16 v[10:13], v[160:163], v[208:211], v[10:13]
	s_waitcnt lgkmcnt(0)
	v_mfma_f32_16x16x32_bf16 v[14:17], v[148:151], v[204:207], v[14:17]
	v_mfma_f32_16x16x32_bf16 v[14:17], v[152:155], v[208:211], v[14:17]
	v_mfma_f32_16x16x32_bf16 v[54:57], v[164:167], v[180:183], v[54:57]
	v_mfma_f32_16x16x32_bf16 v[54:57], v[168:171], v[184:187], v[54:57]
	v_mfma_f32_16x16x32_bf16 v[50:53], v[172:175], v[180:183], v[50:53]
	v_mfma_f32_16x16x32_bf16 v[50:53], v[176:179], v[184:187], v[50:53]
	v_mfma_f32_16x16x32_bf16 v[34:37], v[172:175], v[188:191], v[34:37]
	v_mfma_f32_16x16x32_bf16 v[34:37], v[176:179], v[192:195], v[34:37]
	v_mfma_f32_16x16x32_bf16 v[38:41], v[164:167], v[188:191], v[38:41]
	v_mfma_f32_16x16x32_bf16 v[38:41], v[168:171], v[192:195], v[38:41]
	v_mfma_f32_16x16x32_bf16 v[22:25], v[164:167], v[196:199], v[22:25]
	v_mfma_f32_16x16x32_bf16 v[22:25], v[168:171], v[200:203], v[22:25]
	v_mfma_f32_16x16x32_bf16 v[18:21], v[172:175], v[196:199], v[18:21]
	v_mfma_f32_16x16x32_bf16 v[18:21], v[176:179], v[200:203], v[18:21]
	v_mfma_f32_16x16x32_bf16 v[2:5], v[172:175], v[204:207], v[2:5]
	v_mfma_f32_16x16x32_bf16 v[2:5], v[176:179], v[208:211], v[2:5]
	s_setprio 2
	s_barrier
	v_mfma_f32_16x16x32_bf16 v[6:9], v[164:167], v[204:207], v[6:9]
	v_mfma_f32_16x16x32_bf16 v[6:9], v[168:171], v[208:211], v[6:9]
	s_setprio 0
	s_add_i32 s81, s81, 2
	s_add_u32 s77, s77, 0x100
	s_addc_u32 s78, s78, 0
	s_add_u32 s18, s18, 0x100
	s_addc_u32 s19, s19, 0
	s_add_u32 s79, s79, 0x100
	s_addc_u32 s80, s80, 0
	s_cmp_gt_u32 s81, 29
	s_cbranch_scc0 .LBB0_344
	s_and_b64 vcc, exec, s[6:7]
	s_cbranch_vccz .LBB0_347
	s_barrier

.LBB0_472:
	s_ashr_i32 s13, s12, 31
	s_lshl_b64 s[14:15], s[12:13], 15
	s_add_u32 s14, s28, s14
	s_addc_u32 s15, s29, s15
	s_and_b64 s[16:17], s[2:3], exec
	s_cselect_b32 s13, s15, s23
	s_cselect_b32 s76, s14, s22
	s_ashr_i32 s11, s10, 31
	s_lshl_b64 s[16:17], s[10:11], 15
	s_add_u32 s16, s30, s16
	s_addc_u32 s17, s31, s17
	s_and_b64 s[24:25], s[2:3], exec
	s_cselect_b32 s11, s17, s21
	s_cselect_b32 s77, s16, s20
	s_add_u32 s78, s20, 0x80000
	s_addc_u32 s79, s21, 0
	s_add_u32 s20, s22, 0x204000
	s_addc_u32 s21, s23, 0
	s_add_u32 s80, s22, 0x400000
	s_addc_u32 s81, s23, 0
	s_mov_b32 s82, -2
	s_waitcnt vmcnt(25)
	s_waitcnt vmcnt(24)
	s_waitcnt vmcnt(23)
	s_waitcnt vmcnt(22)
	s_waitcnt vmcnt(21)
	s_waitcnt vmcnt(20)
	s_waitcnt vmcnt(15)
	s_waitcnt vmcnt(14)
	s_waitcnt vmcnt(13)
	s_waitcnt vmcnt(12)
	s_waitcnt vmcnt(7)
	s_waitcnt vmcnt(6)
	s_waitcnt vmcnt(5)
	s_waitcnt vmcnt(4)
	s_waitcnt vmcnt(3)
	s_waitcnt vmcnt(2)
	s_waitcnt vmcnt(1)
	s_waitcnt vmcnt(0)
	ds_read_b128 v[134:137], v161
	ds_read_b128 v[138:141], v161 offset:1024
	ds_read_b128 v[142:145], v161 offset:2048
	ds_read_b128 v[146:149], v161 offset:3072
	ds_read_b128 v[150:153], v162
	ds_read_b128 v[166:169], v162 offset:1024
	ds_read_b128 v[170:173], v162 offset:2048
	ds_read_b128 v[174:177], v162 offset:3072
	s_cmpk_eq_i32 s82, 0x52
	s_cselect_b32 s23, s11, s79
	s_cselect_b32 s22, s77, s78
	s_cselect_b32 s25, s13, s81
	s_cselect_b32 s24, s76, s80
	ds_read_b128 v[178:181], v163
	ds_read_b128 v[182:185], v163 offset:1024
	ds_read_b128 v[186:189], v163 offset:2048
	ds_read_b128 v[190:193], v163 offset:3072
	ds_read_b128 v[194:197], v163 offset:4096
	ds_read_b128 v[198:201], v163 offset:5120
	ds_read_b128 v[202:205], v163 offset:6144
	ds_read_b128 v[206:209], v163 offset:7168
	s_add_u32 s86, s20, 0xffffc000
	s_addc_u32 s87, s21, -1
	s_mov_b32 s83, m0
	s_mov_b32 m0, s65
	s_nop 0
	global_load_lds_dwordx4 v1, s[86:87]
	s_mov_b32 m0, s83
	s_nop 0
	s_mov_b32 s83, m0
	s_mov_b32 m0, s67
	s_nop 0
	global_load_lds_dwordx4 v157, s[86:87]
	s_mov_b32 m0, s83
	s_nop 0
	s_mov_b32 s83, m0
	s_mov_b32 m0, s66
	s_nop 0
	global_load_lds_dwordx4 v1, s[20:21]
	s_mov_b32 m0, s83
	s_nop 0
	s_mov_b32 s83, m0
	s_mov_b32 m0, s73
	s_nop 0
	global_load_lds_dwordx4 v157, s[20:21]
	s_mov_b32 m0, s83
	s_waitcnt vmcnt(8)
	s_waitcnt lgkmcnt(0)
	s_barrier
	s_setprio 1
	s_waitcnt lgkmcnt(7)
	v_mfma_f32_16x16x32_bf16 v[126:129], v[134:137], v[178:181], 0
	v_mfma_f32_16x16x32_bf16 v[126:129], v[138:141], v[182:185], v[126:129]
	s_waitcnt lgkmcnt(5)
	v_mfma_f32_16x16x32_bf16 v[122:125], v[142:145], v[178:181], 0
	v_mfma_f32_16x16x32_bf16 v[122:125], v[146:149], v[182:185], v[122:125]
	s_waitcnt lgkmcnt(3)
	v_mfma_f32_16x16x32_bf16 v[114:117], v[142:145], v[186:189], 0
	v_mfma_f32_16x16x32_bf16 v[114:117], v[146:149], v[190:193], v[114:117]
	s_waitcnt lgkmcnt(1)
	v_mfma_f32_16x16x32_bf16 v[118:121], v[134:137], v[186:189], 0
	v_mfma_f32_16x16x32_bf16 v[118:121], v[138:141], v[190:193], v[118:121]
	v_mfma_f32_16x16x32_bf16 v[102:105], v[134:137], v[194:197], 0
	v_mfma_f32_16x16x32_bf16 v[102:105], v[138:141], v[198:201], v[102:105]
	v_mfma_f32_16x16x32_bf16 v[94:97], v[142:145], v[194:197], 0
	v_mfma_f32_16x16x32_bf16 v[94:97], v[146:149], v[198:201], v[94:97]
	v_mfma_f32_16x16x32_bf16 v[78:81], v[142:145], v[202:205], 0
	v_mfma_f32_16x16x32_bf16 v[78:81], v[146:149], v[206:209], v[78:81]
	s_waitcnt lgkmcnt(0)
	v_mfma_f32_16x16x32_bf16 v[86:89], v[134:137], v[202:205], 0
	v_mfma_f32_16x16x32_bf16 v[86:89], v[138:141], v[206:209], v[86:89]
	v_mfma_f32_16x16x32_bf16 v[110:113], v[150:153], v[178:181], 0
	v_mfma_f32_16x16x32_bf16 v[110:113], v[166:169], v[182:185], v[110:113]
	v_mfma_f32_16x16x32_bf16 v[106:109], v[170:173], v[178:181], 0
	v_mfma_f32_16x16x32_bf16 v[106:109], v[174:177], v[182:185], v[106:109]
	v_mfma_f32_16x16x32_bf16 v[90:93], v[170:173], v[186:189], 0
	v_mfma_f32_16x16x32_bf16 v[90:93], v[174:177], v[190:193], v[90:93]
	v_mfma_f32_16x16x32_bf16 v[98:101], v[150:153], v[186:189], 0
	v_mfma_f32_16x16x32_bf16 v[98:101], v[166:169], v[190:193], v[98:101]
	v_mfma_f32_16x16x32_bf16 v[82:85], v[150:153], v[194:197], 0
	v_mfma_f32_16x16x32_bf16 v[82:85], v[166:169], v[198:201], v[82:85]
	v_mfma_f32_16x16x32_bf16 v[74:77], v[170:173], v[194:197], 0
	v_mfma_f32_16x16x32_bf16 v[74:77], v[174:177], v[198:201], v[74:77]
	v_mfma_f32_16x16x32_bf16 v[66:69], v[170:173], v[202:205], 0
	v_mfma_f32_16x16x32_bf16 v[66:69], v[174:177], v[206:209], v[66:69]
	s_setprio 2
	s_barrier
	v_mfma_f32_16x16x32_bf16 v[70:73], v[150:153], v[202:205], 0
	v_mfma_f32_16x16x32_bf16 v[70:73], v[166:169], v[206:209], v[70:73]
	s_setprio 0
	ds_read_b128 v[178:181], v163 offset:16384
	ds_read_b128 v[182:185], v163 offset:17408
	ds_read_b128 v[186:189], v163 offset:18432
	ds_read_b128 v[190:193], v163 offset:19456
	ds_read_b128 v[194:197], v163 offset:20480
	ds_read_b128 v[198:201], v163 offset:21504
	ds_read_b128 v[202:205], v163 offset:22528
	ds_read_b128 v[206:209], v163 offset:23552
	s_mov_b32 s83, m0
	s_mov_b32 m0, s19
	s_nop 0
	global_load_lds_dwordx4 v156, s[22:23]
	s_mov_b32 m0, s83
	s_add_u32 s86, s22, 0x4000
	s_mov_b32 s83, m0
	s_mov_b32 m0, s35
	s_nop 0
	global_load_lds_dwordx4 v158, s[22:23]
	s_mov_b32 m0, s83
	s_addc_u32 s87, s23, 0
	s_mov_b32 s83, m0
	s_mov_b32 m0, s36
	s_nop 0
	global_load_lds_dwordx4 v156, s[86:87]
	s_mov_b32 m0, s83
	s_nop 0
	s_mov_b32 s83, m0
	s_mov_b32 m0, s37
	s_nop 0
	global_load_lds_dwordx4 v158, s[86:87]
	s_mov_b32 m0, s83
	s_waitcnt vmcnt(4)
	s_waitcnt lgkmcnt(0)
	s_barrier
	s_setprio 1
	s_waitcnt lgkmcnt(7)
	v_mfma_f32_16x16x32_bf16 v[62:65], v[134:137], v[178:181], 0
	v_mfma_f32_16x16x32_bf16 v[62:65], v[138:141], v[182:185], v[62:65]
	s_waitcnt lgkmcnt(5)
	v_mfma_f32_16x16x32_bf16 v[58:61], v[142:145], v[178:181], 0
	v_mfma_f32_16x16x32_bf16 v[58:61], v[146:149], v[182:185], v[58:61]
	s_waitcnt lgkmcnt(3)
	v_mfma_f32_16x16x32_bf16 v[46:49], v[142:145], v[186:189], 0
	v_mfma_f32_16x16x32_bf16 v[46:49], v[146:149], v[190:193], v[46:49]
	s_waitcnt lgkmcnt(1)
	v_mfma_f32_16x16x32_bf16 v[54:57], v[134:137], v[186:189], 0
	v_mfma_f32_16x16x32_bf16 v[54:57], v[138:141], v[190:193], v[54:57]
	v_mfma_f32_16x16x32_bf16 v[38:41], v[134:137], v[194:197], 0
	v_mfma_f32_16x16x32_bf16 v[38:41], v[138:141], v[198:201], v[38:41]
	v_mfma_f32_16x16x32_bf16 v[30:33], v[142:145], v[194:197], 0
	v_mfma_f32_16x16x32_bf16 v[30:33], v[146:149], v[198:201], v[30:33]
	v_mfma_f32_16x16x32_bf16 v[14:17], v[142:145], v[202:205], 0
	v_mfma_f32_16x16x32_bf16 v[14:17], v[146:149], v[206:209], v[14:17]
	s_waitcnt lgkmcnt(0)
	v_mfma_f32_16x16x32_bf16 v[22:25], v[134:137], v[202:205], 0
	v_mfma_f32_16x16x32_bf16 v[22:25], v[138:141], v[206:209], v[22:25]
	v_mfma_f32_16x16x32_bf16 v[50:53], v[150:153], v[178:181], 0
	v_mfma_f32_16x16x32_bf16 v[50:53], v[166:169], v[182:185], v[50:53]
	v_mfma_f32_16x16x32_bf16 v[42:45], v[170:173], v[178:181], 0
	v_mfma_f32_16x16x32_bf16 v[42:45], v[174:177], v[182:185], v[42:45]
	v_mfma_f32_16x16x32_bf16 v[26:29], v[170:173], v[186:189], 0
	v_mfma_f32_16x16x32_bf16 v[26:29], v[174:177], v[190:193], v[26:29]
	v_mfma_f32_16x16x32_bf16 v[34:37], v[150:153], v[186:189], 0
	v_mfma_f32_16x16x32_bf16 v[34:37], v[166:169], v[190:193], v[34:37]
	v_mfma_f32_16x16x32_bf16 v[18:21], v[150:153], v[194:197], 0
	v_mfma_f32_16x16x32_bf16 v[18:21], v[166:169], v[198:201], v[18:21]
	v_mfma_f32_16x16x32_bf16 v[10:13], v[170:173], v[194:197], 0
	v_mfma_f32_16x16x32_bf16 v[10:13], v[174:177], v[198:201], v[10:13]
	v_mfma_f32_16x16x32_bf16 v[2:5], v[170:173], v[202:205], 0
	v_mfma_f32_16x16x32_bf16 v[2:5], v[174:177], v[206:209], v[2:5]
	s_setprio 2
	s_barrier
	v_mfma_f32_16x16x32_bf16 v[6:9], v[150:153], v[202:205], 0
	v_mfma_f32_16x16x32_bf16 v[6:9], v[166:169], v[206:209], v[6:9]
	s_setprio 0
	ds_read_b128 v[134:137], v164
	ds_read_b128 v[138:141], v164 offset:1024
	ds_read_b128 v[142:145], v164 offset:2048
	ds_read_b128 v[146:149], v164 offset:3072
	ds_read_b128 v[150:153], v165
	ds_read_b128 v[166:169], v165 offset:1024
	ds_read_b128 v[170:173], v165 offset:2048
	ds_read_b128 v[174:177], v165 offset:3072
	ds_read_b128 v[178:181], v163 offset:32768
	ds_read_b128 v[182:185], v163 offset:33792
	ds_read_b128 v[186:189], v163 offset:34816
	ds_read_b128 v[190:193], v163 offset:35840
	ds_read_b128 v[194:197], v163 offset:36864
	ds_read_b128 v[198:201], v163 offset:37888
	ds_read_b128 v[202:205], v163 offset:38912
	ds_read_b128 v[206:209], v163 offset:39936
	s_mov_b32 s83, m0
	s_mov_b32 m0, s34
	s_nop 0
	global_load_lds_dwordx4 v1, s[24:25]
	s_mov_b32 m0, s83
	s_nop 0
	s_mov_b32 s83, m0
	s_mov_b32 m0, s42
	s_nop 0
	global_load_lds_dwordx4 v157, s[24:25]
	s_mov_b32 m0, s83
	s_add_u32 s24, s24, 0x4000
	s_addc_u32 s25, s25, 0
	s_mov_b32 s83, m0
	s_mov_b32 m0, s43
	s_nop 0
	global_load_lds_dwordx4 v1, s[24:25]
	s_mov_b32 m0, s83
	s_nop 0
	s_mov_b32 s83, m0
	s_mov_b32 m0, s46
	s_nop 0
	global_load_lds_dwordx4 v157, s[24:25]
	s_mov_b32 m0, s83
	s_waitcnt vmcnt(8)
	s_waitcnt lgkmcnt(0)
	s_barrier
	s_setprio 1
	s_waitcnt lgkmcnt(7)
	v_mfma_f32_16x16x32_bf16 v[126:129], v[134:137], v[178:181], v[126:129]
	v_mfma_f32_16x16x32_bf16 v[126:129], v[138:141], v[182:185], v[126:129]
	s_waitcnt lgkmcnt(5)
	v_mfma_f32_16x16x32_bf16 v[122:125], v[142:145], v[178:181], v[122:125]
	v_mfma_f32_16x16x32_bf16 v[122:125], v[146:149], v[182:185], v[122:125]
	s_waitcnt lgkmcnt(3)
	v_mfma_f32_16x16x32_bf16 v[114:117], v[142:145], v[186:189], v[114:117]
	v_mfma_f32_16x16x32_bf16 v[114:117], v[146:149], v[190:193], v[114:117]
	s_waitcnt lgkmcnt(1)
	v_mfma_f32_16x16x32_bf16 v[118:121], v[134:137], v[186:189], v[118:121]
	v_mfma_f32_16x16x32_bf16 v[118:121], v[138:141], v[190:193], v[118:121]
	v_mfma_f32_16x16x32_bf16 v[102:105], v[134:137], v[194:197], v[102:105]
	v_mfma_f32_16x16x32_bf16 v[102:105], v[138:141], v[198:201], v[102:105]
	v_mfma_f32_16x16x32_bf16 v[94:97], v[142:145], v[194:197], v[94:97]
	v_mfma_f32_16x16x32_bf16 v[94:97], v[146:149], v[198:201], v[94:97]
	v_mfma_f32_16x16x32_bf16 v[78:81], v[142:145], v[202:205], v[78:81]
	v_mfma_f32_16x16x32_bf16 v[78:81], v[146:149], v[206:209], v[78:81]
	s_waitcnt lgkmcnt(0)
	v_mfma_f32_16x16x32_bf16 v[86:89], v[134:137], v[202:205], v[86:89]
	v_mfma_f32_16x16x32_bf16 v[86:89], v[138:141], v[206:209], v[86:89]
	v_mfma_f32_16x16x32_bf16 v[110:113], v[150:153], v[178:181], v[110:113]
	v_mfma_f32_16x16x32_bf16 v[110:113], v[166:169], v[182:185], v[110:113]
	v_mfma_f32_16x16x32_bf16 v[106:109], v[170:173], v[178:181], v[106:109]
	v_mfma_f32_16x16x32_bf16 v[106:109], v[174:177], v[182:185], v[106:109]
	v_mfma_f32_16x16x32_bf16 v[90:93], v[170:173], v[186:189], v[90:93]
	v_mfma_f32_16x16x32_bf16 v[90:93], v[174:177], v[190:193], v[90:93]
	v_mfma_f32_16x16x32_bf16 v[98:101], v[150:153], v[186:189], v[98:101]
	v_mfma_f32_16x16x32_bf16 v[98:101], v[166:169], v[190:193], v[98:101]
	v_mfma_f32_16x16x32_bf16 v[82:85], v[150:153], v[194:197], v[82:85]
	v_mfma_f32_16x16x32_bf16 v[82:85], v[166:169], v[198:201], v[82:85]
	v_mfma_f32_16x16x32_bf16 v[74:77], v[170:173], v[194:197], v[74:77]
	v_mfma_f32_16x16x32_bf16 v[74:77], v[174:177], v[198:201], v[74:77]
	v_mfma_f32_16x16x32_bf16 v[66:69], v[170:173], v[202:205], v[66:69]
	v_mfma_f32_16x16x32_bf16 v[66:69], v[174:177], v[206:209], v[66:69]
	s_setprio 2
	s_barrier
	v_mfma_f32_16x16x32_bf16 v[70:73], v[150:153], v[202:205], v[70:73]
	v_mfma_f32_16x16x32_bf16 v[70:73], v[166:169], v[206:209], v[70:73]
	s_setprio 0
	ds_read_b128 v[178:181], v163 offset:49152
	ds_read_b128 v[182:185], v163 offset:50176
	ds_read_b128 v[186:189], v163 offset:51200
	ds_read_b128 v[190:193], v163 offset:52224
	ds_read_b128 v[194:197], v163 offset:53248
	ds_read_b128 v[198:201], v163 offset:54272
	ds_read_b128 v[202:205], v163 offset:55296
	ds_read_b128 v[206:209], v163 offset:56320
	s_add_u32 s24, s22, 0x40000
	s_addc_u32 s25, s23, 0
	s_mov_b32 s83, m0
	s_mov_b32 m0, s47
	s_nop 0
	global_load_lds_dwordx4 v156, s[24:25]
	s_mov_b32 m0, s83
	s_add_u32 s22, s22, 0x44000
	s_mov_b32 s83, m0
	s_mov_b32 m0, s48
	s_nop 0
	global_load_lds_dwordx4 v158, s[24:25]
	s_mov_b32 m0, s83
	s_addc_u32 s23, s23, 0
	s_mov_b32 s24, m0
	s_mov_b32 m0, s49
	s_nop 0
	global_load_lds_dwordx4 v156, s[22:23]
	s_mov_b32 m0, s24
	s_nop 0
	s_mov_b32 s24, m0
	s_mov_b32 m0, s56
	s_nop 0
	global_load_lds_dwordx4 v158, s[22:23]
	s_mov_b32 m0, s24
	s_waitcnt vmcnt(4)
	s_waitcnt lgkmcnt(0)
	s_barrier
	s_setprio 1
	s_waitcnt lgkmcnt(7)
	v_mfma_f32_16x16x32_bf16 v[62:65], v[134:137], v[178:181], v[62:65]
	v_mfma_f32_16x16x32_bf16 v[62:65], v[138:141], v[182:185], v[62:65]
	s_waitcnt lgkmcnt(5)
	v_mfma_f32_16x16x32_bf16 v[58:61], v[142:145], v[178:181], v[58:61]
	v_mfma_f32_16x16x32_bf16 v[58:61], v[146:149], v[182:185], v[58:61]
	s_waitcnt lgkmcnt(3)
	v_mfma_f32_16x16x32_bf16 v[46:49], v[142:145], v[186:189], v[46:49]
	v_mfma_f32_16x16x32_bf16 v[46:49], v[146:149], v[190:193], v[46:49]
	s_waitcnt lgkmcnt(1)
	v_mfma_f32_16x16x32_bf16 v[54:57], v[134:137], v[186:189], v[54:57]
	v_mfma_f32_16x16x32_bf16 v[54:57], v[138:141], v[190:193], v[54:57]
	v_mfma_f32_16x16x32_bf16 v[38:41], v[134:137], v[194:197], v[38:41]
	v_mfma_f32_16x16x32_bf16 v[38:41], v[138:141], v[198:201], v[38:41]
	v_mfma_f32_16x16x32_bf16 v[30:33], v[142:145], v[194:197], v[30:33]
	v_mfma_f32_16x16x32_bf16 v[30:33], v[146:149], v[198:201], v[30:33]
	v_mfma_f32_16x16x32_bf16 v[14:17], v[142:145], v[202:205], v[14:17]
	v_mfma_f32_16x16x32_bf16 v[14:17], v[146:149], v[206:209], v[14:17]
	s_waitcnt lgkmcnt(0)
	v_mfma_f32_16x16x32_bf16 v[22:25], v[134:137], v[202:205], v[22:25]
	v_mfma_f32_16x16x32_bf16 v[22:25], v[138:141], v[206:209], v[22:25]
	v_mfma_f32_16x16x32_bf16 v[50:53], v[150:153], v[178:181], v[50:53]
	v_mfma_f32_16x16x32_bf16 v[50:53], v[166:169], v[182:185], v[50:53]
	v_mfma_f32_16x16x32_bf16 v[42:45], v[170:173], v[178:181], v[42:45]
	v_mfma_f32_16x16x32_bf16 v[42:45], v[174:177], v[182:185], v[42:45]
	v_mfma_f32_16x16x32_bf16 v[26:29], v[170:173], v[186:189], v[26:29]
	v_mfma_f32_16x16x32_bf16 v[26:29], v[174:177], v[190:193], v[26:29]
	v_mfma_f32_16x16x32_bf16 v[34:37], v[150:153], v[186:189], v[34:37]
	v_mfma_f32_16x16x32_bf16 v[34:37], v[166:169], v[190:193], v[34:37]
	v_mfma_f32_16x16x32_bf16 v[18:21], v[150:153], v[194:197], v[18:21]
	v_mfma_f32_16x16x32_bf16 v[18:21], v[166:169], v[198:201], v[18:21]
	v_mfma_f32_16x16x32_bf16 v[10:13], v[170:173], v[194:197], v[10:13]
	v_mfma_f32_16x16x32_bf16 v[10:13], v[174:177], v[198:201], v[10:13]
	v_mfma_f32_16x16x32_bf16 v[2:5], v[170:173], v[202:205], v[2:5]
	v_mfma_f32_16x16x32_bf16 v[2:5], v[174:177], v[206:209], v[2:5]
	s_setprio 2
	s_barrier
	v_mfma_f32_16x16x32_bf16 v[6:9], v[150:153], v[202:205], v[6:9]
	v_mfma_f32_16x16x32_bf16 v[6:9], v[166:169], v[206:209], v[6:9]
	s_setprio 0
	s_add_i32 s82, s82, 2
	s_add_u32 s78, s78, 0x80000
	s_addc_u32 s79, s79, 0
	s_add_u32 s20, s20, 0x400000
	s_addc_u32 s21, s21, 0
	s_add_u32 s80, s80, 0x400000
	s_addc_u32 s81, s81, 0
	s_cmpk_gt_u32 s82, 0x53
	.p2align 6
.LBB0_473:
	ds_read_b128 v[134:137], v161
	ds_read_b128 v[138:141], v161 offset:1024
	ds_read_b128 v[142:145], v161 offset:2048
	ds_read_b128 v[146:149], v161 offset:3072
	ds_read_b128 v[150:153], v162
	ds_read_b128 v[166:169], v162 offset:1024
	ds_read_b128 v[170:173], v162 offset:2048
	ds_read_b128 v[174:177], v162 offset:3072
	s_cmpk_eq_i32 s82, 0x52
	s_cselect_b32 s23, s11, s79
	s_cselect_b32 s22, s77, s78
	s_cselect_b32 s25, s13, s81
	s_cselect_b32 s24, s76, s80
	ds_read_b128 v[178:181], v163
	ds_read_b128 v[182:185], v163 offset:1024
	ds_read_b128 v[186:189], v163 offset:2048
	ds_read_b128 v[190:193], v163 offset:3072
	ds_read_b128 v[194:197], v163 offset:4096
	ds_read_b128 v[198:201], v163 offset:5120
	ds_read_b128 v[202:205], v163 offset:6144
	ds_read_b128 v[206:209], v163 offset:7168
	s_add_u32 s86, s20, 0xffffc000
	s_addc_u32 s87, s21, -1
	s_mov_b32 s83, m0
	s_mov_b32 m0, s65
	s_nop 0
	global_load_lds_dwordx4 v1, s[86:87]
	s_mov_b32 m0, s83
	s_nop 0
	s_mov_b32 s83, m0
	s_mov_b32 m0, s67
	s_nop 0
	global_load_lds_dwordx4 v157, s[86:87]
	s_mov_b32 m0, s83
	s_nop 0
	s_mov_b32 s83, m0
	s_mov_b32 m0, s66
	s_nop 0
	global_load_lds_dwordx4 v1, s[20:21]
	s_mov_b32 m0, s83
	s_nop 0
	s_mov_b32 s83, m0
	s_mov_b32 m0, s73
	s_nop 0
	global_load_lds_dwordx4 v157, s[20:21]
	s_mov_b32 m0, s83
	s_waitcnt vmcnt(8)
	s_waitcnt lgkmcnt(0)
	s_barrier
	s_setprio 1
	s_waitcnt lgkmcnt(7)
	v_mfma_f32_16x16x32_bf16 v[126:129], v[134:137], v[178:181], v[126:129]
	v_mfma_f32_16x16x32_bf16 v[126:129], v[138:141], v[182:185], v[126:129]
	s_waitcnt lgkmcnt(5)
	v_mfma_f32_16x16x32_bf16 v[122:125], v[142:145], v[178:181], v[122:125]
	v_mfma_f32_16x16x32_bf16 v[122:125], v[146:149], v[182:185], v[122:125]
	s_waitcnt lgkmcnt(3)
	v_mfma_f32_16x16x32_bf16 v[114:117], v[142:145], v[186:189], v[114:117]
	v_mfma_f32_16x16x32_bf16 v[114:117], v[146:149], v[190:193], v[114:117]
	s_waitcnt lgkmcnt(1)
	v_mfma_f32_16x16x32_bf16 v[118:121], v[134:137], v[186:189], v[118:121]
	v_mfma_f32_16x16x32_bf16 v[118:121], v[138:141], v[190:193], v[118:121]
	v_mfma_f32_16x16x32_bf16 v[102:105], v[134:137], v[194:197], v[102:105]
	v_mfma_f32_16x16x32_bf16 v[102:105], v[138:141], v[198:201], v[102:105]
	v_mfma_f32_16x16x32_bf16 v[94:97], v[142:145], v[194:197], v[94:97]
	v_mfma_f32_16x16x32_bf16 v[94:97], v[146:149], v[198:201], v[94:97]
	v_mfma_f32_16x16x32_bf16 v[78:81], v[142:145], v[202:205], v[78:81]
	v_mfma_f32_16x16x32_bf16 v[78:81], v[146:149], v[206:209], v[78:81]
	s_waitcnt lgkmcnt(0)
	v_mfma_f32_16x16x32_bf16 v[86:89], v[134:137], v[202:205], v[86:89]
	v_mfma_f32_16x16x32_bf16 v[86:89], v[138:141], v[206:209], v[86:89]
	v_mfma_f32_16x16x32_bf16 v[110:113], v[150:153], v[178:181], v[110:113]
	v_mfma_f32_16x16x32_bf16 v[110:113], v[166:169], v[182:185], v[110:113]
	v_mfma_f32_16x16x32_bf16 v[106:109], v[170:173], v[178:181], v[106:109]
	v_mfma_f32_16x16x32_bf16 v[106:109], v[174:177], v[182:185], v[106:109]
	v_mfma_f32_16x16x32_bf16 v[90:93], v[170:173], v[186:189], v[90:93]
	v_mfma_f32_16x16x32_bf16 v[90:93], v[174:177], v[190:193], v[90:93]
	v_mfma_f32_16x16x32_bf16 v[98:101], v[150:153], v[186:189], v[98:101]
	v_mfma_f32_16x16x32_bf16 v[98:101], v[166:169], v[190:193], v[98:101]
	v_mfma_f32_16x16x32_bf16 v[82:85], v[150:153], v[194:197], v[82:85]
	v_mfma_f32_16x16x32_bf16 v[82:85], v[166:169], v[198:201], v[82:85]
	v_mfma_f32_16x16x32_bf16 v[74:77], v[170:173], v[194:197], v[74:77]
	v_mfma_f32_16x16x32_bf16 v[74:77], v[174:177], v[198:201], v[74:77]
	v_mfma_f32_16x16x32_bf16 v[66:69], v[170:173], v[202:205], v[66:69]
	v_mfma_f32_16x16x32_bf16 v[66:69], v[174:177], v[206:209], v[66:69]
	s_setprio 2
	s_barrier
	v_mfma_f32_16x16x32_bf16 v[70:73], v[150:153], v[202:205], v[70:73]
	v_mfma_f32_16x16x32_bf16 v[70:73], v[166:169], v[206:209], v[70:73]
	s_setprio 0
	ds_read_b128 v[178:181], v163 offset:16384
	ds_read_b128 v[182:185], v163 offset:17408
	ds_read_b128 v[186:189], v163 offset:18432
	ds_read_b128 v[190:193], v163 offset:19456
	ds_read_b128 v[194:197], v163 offset:20480
	ds_read_b128 v[198:201], v163 offset:21504
	ds_read_b128 v[202:205], v163 offset:22528
	ds_read_b128 v[206:209], v163 offset:23552
	s_mov_b32 s83, m0
	s_mov_b32 m0, s19
	s_nop 0
	global_load_lds_dwordx4 v156, s[22:23]
	s_mov_b32 m0, s83
	s_add_u32 s86, s22, 0x4000
	s_mov_b32 s83, m0
	s_mov_b32 m0, s35
	s_nop 0
	global_load_lds_dwordx4 v158, s[22:23]
	s_mov_b32 m0, s83
	s_addc_u32 s87, s23, 0
	s_mov_b32 s83, m0
	s_mov_b32 m0, s36
	s_nop 0
	global_load_lds_dwordx4 v156, s[86:87]
	s_mov_b32 m0, s83
	s_nop 0
	s_mov_b32 s83, m0
	s_mov_b32 m0, s37
	s_nop 0
	global_load_lds_dwordx4 v158, s[86:87]
	s_mov_b32 m0, s83
	s_waitcnt vmcnt(4)
	s_waitcnt lgkmcnt(0)
	s_barrier
	s_setprio 1
	s_waitcnt lgkmcnt(7)
	v_mfma_f32_16x16x32_bf16 v[62:65], v[134:137], v[178:181], v[62:65]
	v_mfma_f32_16x16x32_bf16 v[62:65], v[138:141], v[182:185], v[62:65]
	s_waitcnt lgkmcnt(5)
	v_mfma_f32_16x16x32_bf16 v[58:61], v[142:145], v[178:181], v[58:61]
	v_mfma_f32_16x16x32_bf16 v[58:61], v[146:149], v[182:185], v[58:61]
	s_waitcnt lgkmcnt(3)
	v_mfma_f32_16x16x32_bf16 v[46:49], v[142:145], v[186:189], v[46:49]
	v_mfma_f32_16x16x32_bf16 v[46:49], v[146:149], v[190:193], v[46:49]
	s_waitcnt lgkmcnt(1)
	v_mfma_f32_16x16x32_bf16 v[54:57], v[134:137], v[186:189], v[54:57]
	v_mfma_f32_16x16x32_bf16 v[54:57], v[138:141], v[190:193], v[54:57]
	v_mfma_f32_16x16x32_bf16 v[38:41], v[134:137], v[194:197], v[38:41]
	v_mfma_f32_16x16x32_bf16 v[38:41], v[138:141], v[198:201], v[38:41]
	v_mfma_f32_16x16x32_bf16 v[30:33], v[142:145], v[194:197], v[30:33]
	v_mfma_f32_16x16x32_bf16 v[30:33], v[146:149], v[198:201], v[30:33]
	v_mfma_f32_16x16x32_bf16 v[14:17], v[142:145], v[202:205], v[14:17]
	v_mfma_f32_16x16x32_bf16 v[14:17], v[146:149], v[206:209], v[14:17]
	s_waitcnt lgkmcnt(0)
	v_mfma_f32_16x16x32_bf16 v[22:25], v[134:137], v[202:205], v[22:25]
	v_mfma_f32_16x16x32_bf16 v[22:25], v[138:141], v[206:209], v[22:25]
	v_mfma_f32_16x16x32_bf16 v[50:53], v[150:153], v[178:181], v[50:53]
	v_mfma_f32_16x16x32_bf16 v[50:53], v[166:169], v[182:185], v[50:53]
	v_mfma_f32_16x16x32_bf16 v[42:45], v[170:173], v[178:181], v[42:45]
	v_mfma_f32_16x16x32_bf16 v[42:45], v[174:177], v[182:185], v[42:45]
	v_mfma_f32_16x16x32_bf16 v[26:29], v[170:173], v[186:189], v[26:29]
	v_mfma_f32_16x16x32_bf16 v[26:29], v[174:177], v[190:193], v[26:29]
	v_mfma_f32_16x16x32_bf16 v[34:37], v[150:153], v[186:189], v[34:37]
	v_mfma_f32_16x16x32_bf16 v[34:37], v[166:169], v[190:193], v[34:37]
	v_mfma_f32_16x16x32_bf16 v[18:21], v[150:153], v[194:197], v[18:21]
	v_mfma_f32_16x16x32_bf16 v[18:21], v[166:169], v[198:201], v[18:21]
	v_mfma_f32_16x16x32_bf16 v[10:13], v[170:173], v[194:197], v[10:13]
	v_mfma_f32_16x16x32_bf16 v[10:13], v[174:177], v[198:201], v[10:13]
	v_mfma_f32_16x16x32_bf16 v[2:5], v[170:173], v[202:205], v[2:5]
	v_mfma_f32_16x16x32_bf16 v[2:5], v[174:177], v[206:209], v[2:5]
	s_setprio 2
	s_barrier
	v_mfma_f32_16x16x32_bf16 v[6:9], v[150:153], v[202:205], v[6:9]
	v_mfma_f32_16x16x32_bf16 v[6:9], v[166:169], v[206:209], v[6:9]
	s_setprio 0
	ds_read_b128 v[134:137], v164
	ds_read_b128 v[138:141], v164 offset:1024
	ds_read_b128 v[142:145], v164 offset:2048
	ds_read_b128 v[146:149], v164 offset:3072
	ds_read_b128 v[150:153], v165
	ds_read_b128 v[166:169], v165 offset:1024
	ds_read_b128 v[170:173], v165 offset:2048
	ds_read_b128 v[174:177], v165 offset:3072
	ds_read_b128 v[178:181], v163 offset:32768
	ds_read_b128 v[182:185], v163 offset:33792
	ds_read_b128 v[186:189], v163 offset:34816
	ds_read_b128 v[190:193], v163 offset:35840
	ds_read_b128 v[194:197], v163 offset:36864
	ds_read_b128 v[198:201], v163 offset:37888
	ds_read_b128 v[202:205], v163 offset:38912
	ds_read_b128 v[206:209], v163 offset:39936
	s_mov_b32 s83, m0
	s_mov_b32 m0, s34
	s_nop 0
	global_load_lds_dwordx4 v1, s[24:25]
	s_mov_b32 m0, s83
	s_nop 0
	s_mov_b32 s83, m0
	s_mov_b32 m0, s42
	s_nop 0
	global_load_lds_dwordx4 v157, s[24:25]
	s_mov_b32 m0, s83
	s_add_u32 s24, s24, 0x4000
	s_addc_u32 s25, s25, 0
	s_mov_b32 s83, m0
	s_mov_b32 m0, s43
	s_nop 0
	global_load_lds_dwordx4 v1, s[24:25]
	s_mov_b32 m0, s83
	s_nop 0
	s_mov_b32 s83, m0
	s_mov_b32 m0, s46
	s_nop 0
	global_load_lds_dwordx4 v157, s[24:25]
	s_mov_b32 m0, s83
	s_waitcnt vmcnt(8)
	s_waitcnt lgkmcnt(0)
	s_barrier
	s_setprio 1
	s_waitcnt lgkmcnt(7)
	v_mfma_f32_16x16x32_bf16 v[126:129], v[134:137], v[178:181], v[126:129]
	v_mfma_f32_16x16x32_bf16 v[126:129], v[138:141], v[182:185], v[126:129]
	s_waitcnt lgkmcnt(5)
	v_mfma_f32_16x16x32_bf16 v[122:125], v[142:145], v[178:181], v[122:125]
	v_mfma_f32_16x16x32_bf16 v[122:125], v[146:149], v[182:185], v[122:125]
	s_waitcnt lgkmcnt(3)
	v_mfma_f32_16x16x32_bf16 v[114:117], v[142:145], v[186:189], v[114:117]
	v_mfma_f32_16x16x32_bf16 v[114:117], v[146:149], v[190:193], v[114:117]
	s_waitcnt lgkmcnt(1)
	v_mfma_f32_16x16x32_bf16 v[118:121], v[134:137], v[186:189], v[118:121]
	v_mfma_f32_16x16x32_bf16 v[118:121], v[138:141], v[190:193], v[118:121]
	v_mfma_f32_16x16x32_bf16 v[102:105], v[134:137], v[194:197], v[102:105]
	v_mfma_f32_16x16x32_bf16 v[102:105], v[138:141], v[198:201], v[102:105]
	v_mfma_f32_16x16x32_bf16 v[94:97], v[142:145], v[194:197], v[94:97]
	v_mfma_f32_16x16x32_bf16 v[94:97], v[146:149], v[198:201], v[94:97]
	v_mfma_f32_16x16x32_bf16 v[78:81], v[142:145], v[202:205], v[78:81]
	v_mfma_f32_16x16x32_bf16 v[78:81], v[146:149], v[206:209], v[78:81]
	s_waitcnt lgkmcnt(0)
	v_mfma_f32_16x16x32_bf16 v[86:89], v[134:137], v[202:205], v[86:89]
	v_mfma_f32_16x16x32_bf16 v[86:89], v[138:141], v[206:209], v[86:89]
	v_mfma_f32_16x16x32_bf16 v[110:113], v[150:153], v[178:181], v[110:113]
	v_mfma_f32_16x16x32_bf16 v[110:113], v[166:169], v[182:185], v[110:113]
	v_mfma_f32_16x16x32_bf16 v[106:109], v[170:173], v[178:181], v[106:109]
	v_mfma_f32_16x16x32_bf16 v[106:109], v[174:177], v[182:185], v[106:109]
	v_mfma_f32_16x16x32_bf16 v[90:93], v[170:173], v[186:189], v[90:93]
	v_mfma_f32_16x16x32_bf16 v[90:93], v[174:177], v[190:193], v[90:93]
	v_mfma_f32_16x16x32_bf16 v[98:101], v[150:153], v[186:189], v[98:101]
	v_mfma_f32_16x16x32_bf16 v[98:101], v[166:169], v[190:193], v[98:101]
	v_mfma_f32_16x16x32_bf16 v[82:85], v[150:153], v[194:197], v[82:85]
	v_mfma_f32_16x16x32_bf16 v[82:85], v[166:169], v[198:201], v[82:85]
	v_mfma_f32_16x16x32_bf16 v[74:77], v[170:173], v[194:197], v[74:77]
	v_mfma_f32_16x16x32_bf16 v[74:77], v[174:177], v[198:201], v[74:77]
	v_mfma_f32_16x16x32_bf16 v[66:69], v[170:173], v[202:205], v[66:69]
	v_mfma_f32_16x16x32_bf16 v[66:69], v[174:177], v[206:209], v[66:69]
	s_setprio 2
	s_barrier
	v_mfma_f32_16x16x32_bf16 v[70:73], v[150:153], v[202:205], v[70:73]
	v_mfma_f32_16x16x32_bf16 v[70:73], v[166:169], v[206:209], v[70:73]
	s_setprio 0
	ds_read_b128 v[178:181], v163 offset:49152
	ds_read_b128 v[182:185], v163 offset:50176
	ds_read_b128 v[186:189], v163 offset:51200
	ds_read_b128 v[190:193], v163 offset:52224
	ds_read_b128 v[194:197], v163 offset:53248
	ds_read_b128 v[198:201], v163 offset:54272
	ds_read_b128 v[202:205], v163 offset:55296
	ds_read_b128 v[206:209], v163 offset:56320
	s_add_u32 s24, s22, 0x40000
	s_addc_u32 s25, s23, 0
	s_mov_b32 s83, m0
	s_mov_b32 m0, s47
	s_nop 0
	global_load_lds_dwordx4 v156, s[24:25]
	s_mov_b32 m0, s83
	s_add_u32 s22, s22, 0x44000
	s_mov_b32 s83, m0
	s_mov_b32 m0, s48
	s_nop 0
	global_load_lds_dwordx4 v158, s[24:25]
	s_mov_b32 m0, s83
	s_addc_u32 s23, s23, 0
	s_mov_b32 s24, m0
	s_mov_b32 m0, s49
	s_nop 0
	global_load_lds_dwordx4 v156, s[22:23]
	s_mov_b32 m0, s24
	s_nop 0
	s_mov_b32 s24, m0
	s_mov_b32 m0, s56
	s_nop 0
	global_load_lds_dwordx4 v158, s[22:23]
	s_mov_b32 m0, s24
	s_waitcnt vmcnt(4)
	s_waitcnt lgkmcnt(0)
	s_barrier
	s_setprio 1
	s_waitcnt lgkmcnt(7)
	v_mfma_f32_16x16x32_bf16 v[62:65], v[134:137], v[178:181], v[62:65]
	v_mfma_f32_16x16x32_bf16 v[62:65], v[138:141], v[182:185], v[62:65]
	s_waitcnt lgkmcnt(5)
	v_mfma_f32_16x16x32_bf16 v[58:61], v[142:145], v[178:181], v[58:61]
	v_mfma_f32_16x16x32_bf16 v[58:61], v[146:149], v[182:185], v[58:61]
	s_waitcnt lgkmcnt(3)
	v_mfma_f32_16x16x32_bf16 v[46:49], v[142:145], v[186:189], v[46:49]
	v_mfma_f32_16x16x32_bf16 v[46:49], v[146:149], v[190:193], v[46:49]
	s_waitcnt lgkmcnt(1)
	v_mfma_f32_16x16x32_bf16 v[54:57], v[134:137], v[186:189], v[54:57]
	v_mfma_f32_16x16x32_bf16 v[54:57], v[138:141], v[190:193], v[54:57]
	v_mfma_f32_16x16x32_bf16 v[38:41], v[134:137], v[194:197], v[38:41]
	v_mfma_f32_16x16x32_bf16 v[38:41], v[138:141], v[198:201], v[38:41]
	v_mfma_f32_16x16x32_bf16 v[30:33], v[142:145], v[194:197], v[30:33]
	v_mfma_f32_16x16x32_bf16 v[30:33], v[146:149], v[198:201], v[30:33]
	v_mfma_f32_16x16x32_bf16 v[14:17], v[142:145], v[202:205], v[14:17]
	v_mfma_f32_16x16x32_bf16 v[14:17], v[146:149], v[206:209], v[14:17]
	s_waitcnt lgkmcnt(0)
	v_mfma_f32_16x16x32_bf16 v[22:25], v[134:137], v[202:205], v[22:25]
	v_mfma_f32_16x16x32_bf16 v[22:25], v[138:141], v[206:209], v[22:25]
	v_mfma_f32_16x16x32_bf16 v[50:53], v[150:153], v[178:181], v[50:53]
	v_mfma_f32_16x16x32_bf16 v[50:53], v[166:169], v[182:185], v[50:53]
	v_mfma_f32_16x16x32_bf16 v[42:45], v[170:173], v[178:181], v[42:45]
	v_mfma_f32_16x16x32_bf16 v[42:45], v[174:177], v[182:185], v[42:45]
	v_mfma_f32_16x16x32_bf16 v[26:29], v[170:173], v[186:189], v[26:29]
	v_mfma_f32_16x16x32_bf16 v[26:29], v[174:177], v[190:193], v[26:29]
	v_mfma_f32_16x16x32_bf16 v[34:37], v[150:153], v[186:189], v[34:37]
	v_mfma_f32_16x16x32_bf16 v[34:37], v[166:169], v[190:193], v[34:37]
	v_mfma_f32_16x16x32_bf16 v[18:21], v[150:153], v[194:197], v[18:21]
	v_mfma_f32_16x16x32_bf16 v[18:21], v[166:169], v[198:201], v[18:21]
	v_mfma_f32_16x16x32_bf16 v[10:13], v[170:173], v[194:197], v[10:13]
	v_mfma_f32_16x16x32_bf16 v[10:13], v[174:177], v[198:201], v[10:13]
	v_mfma_f32_16x16x32_bf16 v[2:5], v[170:173], v[202:205], v[2:5]
	v_mfma_f32_16x16x32_bf16 v[2:5], v[174:177], v[206:209], v[2:5]
	s_setprio 2
	s_barrier
	v_mfma_f32_16x16x32_bf16 v[6:9], v[150:153], v[202:205], v[6:9]
	v_mfma_f32_16x16x32_bf16 v[6:9], v[166:169], v[206:209], v[6:9]
	s_setprio 0
	s_add_i32 s82, s82, 2
	s_add_u32 s78, s78, 0x80000
	s_addc_u32 s79, s79, 0
	s_add_u32 s20, s20, 0x400000
	s_addc_u32 s21, s21, 0
	s_add_u32 s80, s80, 0x400000
	s_addc_u32 s81, s81, 0
	s_cmpk_gt_u32 s82, 0x53
	s_cbranch_scc0 .LBB0_473
	s_and_b64 vcc, exec, s[8:9]
	s_cbranch_vccz .LBB0_476
	s_barrier

.LBB0_653:
	s_ashr_i32 s23, s22, 31
	s_lshl_b64 s[24:25], s[22:23], 20
	s_add_u32 s24, s35, s24
	s_addc_u32 s25, s36, s25
	s_and_b64 s[26:27], s[2:3], exec
	s_cselect_b32 s7, s25, s11
	s_cselect_b32 s9, s24, s10
	s_ashr_i32 s21, s20, 31
	s_lshl_b64 s[26:27], s[20:21], 20
	s_add_u32 s26, s37, s26
	s_addc_u32 s27, s40, s27
	s_and_b64 s[28:29], s[2:3], exec
	s_cselect_b32 s21, s27, s5
	s_cselect_b32 s23, s26, s4
	s_add_u32 s30, s4, 0x100
	s_addc_u32 s31, s5, 0
	s_add_u32 s4, s10, 0x80080
	s_addc_u32 s5, s11, 0
	s_add_u32 s33, s10, 0x100
	s_addc_u32 s73, s11, 0
	s_mov_b32 s74, -2
	s_waitcnt vmcnt(25)
	s_waitcnt vmcnt(24)
	s_waitcnt vmcnt(15)
	s_waitcnt vmcnt(14)
	s_waitcnt vmcnt(13)
	s_waitcnt vmcnt(12)
	s_waitcnt vmcnt(11)
	s_waitcnt vmcnt(10)
	s_waitcnt vmcnt(9)
	s_waitcnt vmcnt(8)
	s_waitcnt vmcnt(7)
	s_waitcnt vmcnt(6)
	s_waitcnt vmcnt(5)
	s_waitcnt vmcnt(4)
	s_waitcnt vmcnt(3)
	s_waitcnt vmcnt(2)
	s_waitcnt vmcnt(1)
	s_waitcnt vmcnt(0)
	ds_read_b128 v[130:133], v161
	ds_read_b128 v[138:141], v161 offset:1024
	ds_read_b128 v[142:145], v161 offset:2048
	ds_read_b128 v[146:149], v161 offset:3072
	ds_read_b128 v[150:153], v162
	ds_read_b128 v[168:171], v162 offset:1024
	ds_read_b128 v[172:175], v162 offset:2048
	ds_read_b128 v[176:179], v162 offset:3072
	s_cmp_eq_u32 s74, 28
	s_cselect_b32 s11, s21, s31
	s_cselect_b32 s10, s23, s30
	s_cselect_b32 s29, s7, s73
	s_cselect_b32 s28, s9, s33
	ds_read_b128 v[180:183], v163
	ds_read_b128 v[184:187], v163 offset:1024
	ds_read_b128 v[188:191], v163 offset:2048
	ds_read_b128 v[192:195], v163 offset:3072
	ds_read_b128 v[196:199], v163 offset:4096
	ds_read_b128 v[200:203], v163 offset:5120
	ds_read_b128 v[204:207], v163 offset:6144
	ds_read_b128 v[208:211], v163 offset:7168
	s_add_u32 s76, s4, 0xfff80000
	s_addc_u32 s77, s5, -1
	s_mov_b32 s75, m0
	s_mov_b32 m0, s80
	s_nop 0
	global_load_lds_dwordx4 v1, s[76:77]
	s_mov_b32 m0, s75
	s_nop 0
	s_mov_b32 s75, m0
	s_mov_b32 m0, s82
	s_nop 0
	global_load_lds_dwordx4 v157, s[76:77]
	s_mov_b32 m0, s75
	s_nop 0
	s_mov_b32 s75, m0
	s_mov_b32 m0, s81
	s_nop 0
	global_load_lds_dwordx4 v1, s[4:5]
	s_mov_b32 m0, s75
	s_nop 0
	s_mov_b32 s75, m0
	s_mov_b32 m0, s83
	s_nop 0
	global_load_lds_dwordx4 v157, s[4:5]
	s_mov_b32 m0, s75
	s_waitcnt vmcnt(8)
	s_waitcnt lgkmcnt(0)
	s_barrier
	s_setprio 1
	s_waitcnt lgkmcnt(7)
	v_mfma_f32_16x16x32_bf16 v[126:129], v[130:133], v[180:183], 0
	v_mfma_f32_16x16x32_bf16 v[126:129], v[138:141], v[184:187], v[126:129]
	s_waitcnt lgkmcnt(5)
	v_mfma_f32_16x16x32_bf16 v[122:125], v[142:145], v[180:183], 0
	v_mfma_f32_16x16x32_bf16 v[122:125], v[146:149], v[184:187], v[122:125]
	s_waitcnt lgkmcnt(3)
	v_mfma_f32_16x16x32_bf16 v[106:109], v[142:145], v[188:191], 0
	v_mfma_f32_16x16x32_bf16 v[106:109], v[146:149], v[192:195], v[106:109]
	s_waitcnt lgkmcnt(1)
	v_mfma_f32_16x16x32_bf16 v[110:113], v[130:133], v[188:191], 0
	v_mfma_f32_16x16x32_bf16 v[110:113], v[138:141], v[192:195], v[110:113]
	v_mfma_f32_16x16x32_bf16 v[94:97], v[130:133], v[196:199], 0
	v_mfma_f32_16x16x32_bf16 v[94:97], v[138:141], v[200:203], v[94:97]
	v_mfma_f32_16x16x32_bf16 v[90:93], v[142:145], v[196:199], 0
	v_mfma_f32_16x16x32_bf16 v[90:93], v[146:149], v[200:203], v[90:93]
	v_mfma_f32_16x16x32_bf16 v[74:77], v[142:145], v[204:207], 0
	v_mfma_f32_16x16x32_bf16 v[74:77], v[146:149], v[208:211], v[74:77]
	s_waitcnt lgkmcnt(0)
	v_mfma_f32_16x16x32_bf16 v[78:81], v[130:133], v[204:207], 0
	v_mfma_f32_16x16x32_bf16 v[78:81], v[138:141], v[208:211], v[78:81]
	v_mfma_f32_16x16x32_bf16 v[118:121], v[150:153], v[180:183], 0
	v_mfma_f32_16x16x32_bf16 v[118:121], v[168:171], v[184:187], v[118:121]
	v_mfma_f32_16x16x32_bf16 v[114:117], v[172:175], v[180:183], 0
	v_mfma_f32_16x16x32_bf16 v[114:117], v[176:179], v[184:187], v[114:117]
	v_mfma_f32_16x16x32_bf16 v[98:101], v[172:175], v[188:191], 0
	v_mfma_f32_16x16x32_bf16 v[98:101], v[176:179], v[192:195], v[98:101]
	v_mfma_f32_16x16x32_bf16 v[102:105], v[150:153], v[188:191], 0
	v_mfma_f32_16x16x32_bf16 v[102:105], v[168:171], v[192:195], v[102:105]
	v_mfma_f32_16x16x32_bf16 v[86:89], v[150:153], v[196:199], 0
	v_mfma_f32_16x16x32_bf16 v[86:89], v[168:171], v[200:203], v[86:89]
	v_mfma_f32_16x16x32_bf16 v[82:85], v[172:175], v[196:199], 0
	v_mfma_f32_16x16x32_bf16 v[82:85], v[176:179], v[200:203], v[82:85]
	v_mfma_f32_16x16x32_bf16 v[66:69], v[172:175], v[204:207], 0
	v_mfma_f32_16x16x32_bf16 v[66:69], v[176:179], v[208:211], v[66:69]
	s_setprio 2
	s_barrier
	v_mfma_f32_16x16x32_bf16 v[70:73], v[150:153], v[204:207], 0
	v_mfma_f32_16x16x32_bf16 v[70:73], v[168:171], v[208:211], v[70:73]
	s_setprio 0
	ds_read_b128 v[180:183], v163 offset:16384
	ds_read_b128 v[184:187], v163 offset:17408
	ds_read_b128 v[188:191], v163 offset:18432
	ds_read_b128 v[192:195], v163 offset:19456
	ds_read_b128 v[196:199], v163 offset:20480
	ds_read_b128 v[200:203], v163 offset:21504
	ds_read_b128 v[204:207], v163 offset:22528
	ds_read_b128 v[208:211], v163 offset:23552
	s_mov_b32 s75, m0
	s_mov_b32 m0, s43
	s_nop 0
	global_load_lds_dwordx4 v156, s[10:11]
	s_mov_b32 m0, s75
	s_add_u32 s76, s10, 0x80000
	s_mov_b32 s75, m0
	s_mov_b32 m0, s46
	s_nop 0
	global_load_lds_dwordx4 v158, s[10:11]
	s_mov_b32 m0, s75
	s_addc_u32 s77, s11, 0
	s_mov_b32 s75, m0
	s_mov_b32 m0, s47
	s_nop 0
	global_load_lds_dwordx4 v156, s[76:77]
	s_mov_b32 m0, s75
	s_nop 0
	s_mov_b32 s75, m0
	s_mov_b32 m0, s48
	s_nop 0
	global_load_lds_dwordx4 v158, s[76:77]
	s_mov_b32 m0, s75
	s_waitcnt vmcnt(4)
	s_waitcnt lgkmcnt(0)
	s_barrier
	s_setprio 1
	s_waitcnt lgkmcnt(7)
	v_mfma_f32_16x16x32_bf16 v[62:65], v[130:133], v[180:183], 0
	v_mfma_f32_16x16x32_bf16 v[62:65], v[138:141], v[184:187], v[62:65]
	s_waitcnt lgkmcnt(5)
	v_mfma_f32_16x16x32_bf16 v[58:61], v[142:145], v[180:183], 0
	v_mfma_f32_16x16x32_bf16 v[58:61], v[146:149], v[184:187], v[58:61]
	s_waitcnt lgkmcnt(3)
	v_mfma_f32_16x16x32_bf16 v[42:45], v[142:145], v[188:191], 0
	v_mfma_f32_16x16x32_bf16 v[42:45], v[146:149], v[192:195], v[42:45]
	s_waitcnt lgkmcnt(1)
	v_mfma_f32_16x16x32_bf16 v[46:49], v[130:133], v[188:191], 0
	v_mfma_f32_16x16x32_bf16 v[46:49], v[138:141], v[192:195], v[46:49]
	v_mfma_f32_16x16x32_bf16 v[30:33], v[130:133], v[196:199], 0
	v_mfma_f32_16x16x32_bf16 v[30:33], v[138:141], v[200:203], v[30:33]
	v_mfma_f32_16x16x32_bf16 v[26:29], v[142:145], v[196:199], 0
	v_mfma_f32_16x16x32_bf16 v[26:29], v[146:149], v[200:203], v[26:29]
	v_mfma_f32_16x16x32_bf16 v[10:13], v[142:145], v[204:207], 0
	v_mfma_f32_16x16x32_bf16 v[10:13], v[146:149], v[208:211], v[10:13]
	s_waitcnt lgkmcnt(0)
	v_mfma_f32_16x16x32_bf16 v[14:17], v[130:133], v[204:207], 0
	v_mfma_f32_16x16x32_bf16 v[14:17], v[138:141], v[208:211], v[14:17]
	v_mfma_f32_16x16x32_bf16 v[54:57], v[150:153], v[180:183], 0
	v_mfma_f32_16x16x32_bf16 v[54:57], v[168:171], v[184:187], v[54:57]
	v_mfma_f32_16x16x32_bf16 v[50:53], v[172:175], v[180:183], 0
	v_mfma_f32_16x16x32_bf16 v[50:53], v[176:179], v[184:187], v[50:53]
	v_mfma_f32_16x16x32_bf16 v[34:37], v[172:175], v[188:191], 0
	v_mfma_f32_16x16x32_bf16 v[34:37], v[176:179], v[192:195], v[34:37]
	v_mfma_f32_16x16x32_bf16 v[38:41], v[150:153], v[188:191], 0
	v_mfma_f32_16x16x32_bf16 v[38:41], v[168:171], v[192:195], v[38:41]
	v_mfma_f32_16x16x32_bf16 v[22:25], v[150:153], v[196:199], 0
	v_mfma_f32_16x16x32_bf16 v[22:25], v[168:171], v[200:203], v[22:25]
	v_mfma_f32_16x16x32_bf16 v[18:21], v[172:175], v[196:199], 0
	v_mfma_f32_16x16x32_bf16 v[18:21], v[176:179], v[200:203], v[18:21]
	v_mfma_f32_16x16x32_bf16 v[2:5], v[172:175], v[204:207], 0
	v_mfma_f32_16x16x32_bf16 v[2:5], v[176:179], v[208:211], v[2:5]
	s_setprio 2
	s_barrier
	v_mfma_f32_16x16x32_bf16 v[6:9], v[150:153], v[204:207], 0
	v_mfma_f32_16x16x32_bf16 v[6:9], v[168:171], v[208:211], v[6:9]
	s_setprio 0
	ds_read_b128 v[130:133], v164
	ds_read_b128 v[138:141], v164 offset:1024
	ds_read_b128 v[142:145], v164 offset:2048
	ds_read_b128 v[146:149], v164 offset:3072
	ds_read_b128 v[150:153], v165
	ds_read_b128 v[168:171], v165 offset:1024
	ds_read_b128 v[172:175], v165 offset:2048
	ds_read_b128 v[176:179], v165 offset:3072
	ds_read_b128 v[180:183], v163 offset:32768
	ds_read_b128 v[184:187], v163 offset:33792
	ds_read_b128 v[188:191], v163 offset:34816
	ds_read_b128 v[192:195], v163 offset:35840
	ds_read_b128 v[196:199], v163 offset:36864
	ds_read_b128 v[200:203], v163 offset:37888
	ds_read_b128 v[204:207], v163 offset:38912
	ds_read_b128 v[208:211], v163 offset:39936
	s_mov_b32 s75, m0
	s_mov_b32 m0, s42
	s_nop 0
	global_load_lds_dwordx4 v1, s[28:29]
	s_mov_b32 m0, s75
	s_nop 0
	s_mov_b32 s75, m0
	s_mov_b32 m0, s49
	s_nop 0
	global_load_lds_dwordx4 v157, s[28:29]
	s_mov_b32 m0, s75
	s_add_u32 s28, s28, 0x80000
	s_addc_u32 s29, s29, 0
	s_mov_b32 s75, m0
	s_mov_b32 m0, s56
	s_nop 0
	global_load_lds_dwordx4 v1, s[28:29]
	s_mov_b32 m0, s75
	s_nop 0
	s_mov_b32 s75, m0
	s_mov_b32 m0, s57
	s_nop 0
	global_load_lds_dwordx4 v157, s[28:29]
	s_mov_b32 m0, s75
	s_waitcnt vmcnt(8)
	s_waitcnt lgkmcnt(0)
	s_barrier
	s_setprio 1
	s_waitcnt lgkmcnt(7)
	v_mfma_f32_16x16x32_bf16 v[126:129], v[130:133], v[180:183], v[126:129]
	v_mfma_f32_16x16x32_bf16 v[126:129], v[138:141], v[184:187], v[126:129]
	s_waitcnt lgkmcnt(5)
	v_mfma_f32_16x16x32_bf16 v[122:125], v[142:145], v[180:183], v[122:125]
	v_mfma_f32_16x16x32_bf16 v[122:125], v[146:149], v[184:187], v[122:125]
	s_waitcnt lgkmcnt(3)
	v_mfma_f32_16x16x32_bf16 v[106:109], v[142:145], v[188:191], v[106:109]
	v_mfma_f32_16x16x32_bf16 v[106:109], v[146:149], v[192:195], v[106:109]
	s_waitcnt lgkmcnt(1)
	v_mfma_f32_16x16x32_bf16 v[110:113], v[130:133], v[188:191], v[110:113]
	v_mfma_f32_16x16x32_bf16 v[110:113], v[138:141], v[192:195], v[110:113]
	v_mfma_f32_16x16x32_bf16 v[94:97], v[130:133], v[196:199], v[94:97]
	v_mfma_f32_16x16x32_bf16 v[94:97], v[138:141], v[200:203], v[94:97]
	v_mfma_f32_16x16x32_bf16 v[90:93], v[142:145], v[196:199], v[90:93]
	v_mfma_f32_16x16x32_bf16 v[90:93], v[146:149], v[200:203], v[90:93]
	v_mfma_f32_16x16x32_bf16 v[74:77], v[142:145], v[204:207], v[74:77]
	v_mfma_f32_16x16x32_bf16 v[74:77], v[146:149], v[208:211], v[74:77]
	s_waitcnt lgkmcnt(0)
	v_mfma_f32_16x16x32_bf16 v[78:81], v[130:133], v[204:207], v[78:81]
	v_mfma_f32_16x16x32_bf16 v[78:81], v[138:141], v[208:211], v[78:81]
	v_mfma_f32_16x16x32_bf16 v[118:121], v[150:153], v[180:183], v[118:121]
	v_mfma_f32_16x16x32_bf16 v[118:121], v[168:171], v[184:187], v[118:121]
	v_mfma_f32_16x16x32_bf16 v[114:117], v[172:175], v[180:183], v[114:117]
	v_mfma_f32_16x16x32_bf16 v[114:117], v[176:179], v[184:187], v[114:117]
	v_mfma_f32_16x16x32_bf16 v[98:101], v[172:175], v[188:191], v[98:101]
	v_mfma_f32_16x16x32_bf16 v[98:101], v[176:179], v[192:195], v[98:101]
	v_mfma_f32_16x16x32_bf16 v[102:105], v[150:153], v[188:191], v[102:105]
	v_mfma_f32_16x16x32_bf16 v[102:105], v[168:171], v[192:195], v[102:105]
	v_mfma_f32_16x16x32_bf16 v[86:89], v[150:153], v[196:199], v[86:89]
	v_mfma_f32_16x16x32_bf16 v[86:89], v[168:171], v[200:203], v[86:89]
	v_mfma_f32_16x16x32_bf16 v[82:85], v[172:175], v[196:199], v[82:85]
	v_mfma_f32_16x16x32_bf16 v[82:85], v[176:179], v[200:203], v[82:85]
	v_mfma_f32_16x16x32_bf16 v[66:69], v[172:175], v[204:207], v[66:69]
	v_mfma_f32_16x16x32_bf16 v[66:69], v[176:179], v[208:211], v[66:69]
	s_setprio 2
	s_barrier
	v_mfma_f32_16x16x32_bf16 v[70:73], v[150:153], v[204:207], v[70:73]
	v_mfma_f32_16x16x32_bf16 v[70:73], v[168:171], v[208:211], v[70:73]
	s_setprio 0
	ds_read_b128 v[180:183], v163 offset:49152
	ds_read_b128 v[184:187], v163 offset:50176
	ds_read_b128 v[188:191], v163 offset:51200
	ds_read_b128 v[192:195], v163 offset:52224
	ds_read_b128 v[196:199], v163 offset:53248
	ds_read_b128 v[200:203], v163 offset:54272
	ds_read_b128 v[204:207], v163 offset:55296
	ds_read_b128 v[208:211], v163 offset:56320
	s_add_u32 s28, s10, 0x80
	s_addc_u32 s29, s11, 0
	s_mov_b32 s75, m0
	s_mov_b32 m0, s64
	s_nop 0
	global_load_lds_dwordx4 v156, s[28:29]
	s_mov_b32 m0, s75
	s_add_u32 s10, s10, 0x80080
	s_mov_b32 s75, m0
	s_mov_b32 m0, s65
	s_nop 0
	global_load_lds_dwordx4 v158, s[28:29]
	s_mov_b32 m0, s75
	s_addc_u32 s11, s11, 0
	s_mov_b32 s28, m0
	s_mov_b32 m0, s66
	s_nop 0
	global_load_lds_dwordx4 v156, s[10:11]
	s_mov_b32 m0, s28
	s_nop 0
	s_mov_b32 s28, m0
	s_mov_b32 m0, s67
	s_nop 0
	global_load_lds_dwordx4 v158, s[10:11]
	s_mov_b32 m0, s28
	s_waitcnt vmcnt(4)
	s_waitcnt lgkmcnt(0)
	s_barrier
	s_setprio 1
	s_waitcnt lgkmcnt(7)
	v_mfma_f32_16x16x32_bf16 v[62:65], v[130:133], v[180:183], v[62:65]
	v_mfma_f32_16x16x32_bf16 v[62:65], v[138:141], v[184:187], v[62:65]
	s_waitcnt lgkmcnt(5)
	v_mfma_f32_16x16x32_bf16 v[58:61], v[142:145], v[180:183], v[58:61]
	v_mfma_f32_16x16x32_bf16 v[58:61], v[146:149], v[184:187], v[58:61]
	s_waitcnt lgkmcnt(3)
	v_mfma_f32_16x16x32_bf16 v[42:45], v[142:145], v[188:191], v[42:45]
	v_mfma_f32_16x16x32_bf16 v[42:45], v[146:149], v[192:195], v[42:45]
	s_waitcnt lgkmcnt(1)
	v_mfma_f32_16x16x32_bf16 v[46:49], v[130:133], v[188:191], v[46:49]
	v_mfma_f32_16x16x32_bf16 v[46:49], v[138:141], v[192:195], v[46:49]
	v_mfma_f32_16x16x32_bf16 v[30:33], v[130:133], v[196:199], v[30:33]
	v_mfma_f32_16x16x32_bf16 v[30:33], v[138:141], v[200:203], v[30:33]
	v_mfma_f32_16x16x32_bf16 v[26:29], v[142:145], v[196:199], v[26:29]
	v_mfma_f32_16x16x32_bf16 v[26:29], v[146:149], v[200:203], v[26:29]
	v_mfma_f32_16x16x32_bf16 v[10:13], v[142:145], v[204:207], v[10:13]
	v_mfma_f32_16x16x32_bf16 v[10:13], v[146:149], v[208:211], v[10:13]
	s_waitcnt lgkmcnt(0)
	v_mfma_f32_16x16x32_bf16 v[14:17], v[130:133], v[204:207], v[14:17]
	v_mfma_f32_16x16x32_bf16 v[14:17], v[138:141], v[208:211], v[14:17]
	v_mfma_f32_16x16x32_bf16 v[54:57], v[150:153], v[180:183], v[54:57]
	v_mfma_f32_16x16x32_bf16 v[54:57], v[168:171], v[184:187], v[54:57]
	v_mfma_f32_16x16x32_bf16 v[50:53], v[172:175], v[180:183], v[50:53]
	v_mfma_f32_16x16x32_bf16 v[50:53], v[176:179], v[184:187], v[50:53]
	v_mfma_f32_16x16x32_bf16 v[34:37], v[172:175], v[188:191], v[34:37]
	v_mfma_f32_16x16x32_bf16 v[34:37], v[176:179], v[192:195], v[34:37]
	v_mfma_f32_16x16x32_bf16 v[38:41], v[150:153], v[188:191], v[38:41]
	v_mfma_f32_16x16x32_bf16 v[38:41], v[168:171], v[192:195], v[38:41]
	v_mfma_f32_16x16x32_bf16 v[22:25], v[150:153], v[196:199], v[22:25]
	v_mfma_f32_16x16x32_bf16 v[22:25], v[168:171], v[200:203], v[22:25]
	v_mfma_f32_16x16x32_bf16 v[18:21], v[172:175], v[196:199], v[18:21]
	v_mfma_f32_16x16x32_bf16 v[18:21], v[176:179], v[200:203], v[18:21]
	v_mfma_f32_16x16x32_bf16 v[2:5], v[172:175], v[204:207], v[2:5]
	v_mfma_f32_16x16x32_bf16 v[2:5], v[176:179], v[208:211], v[2:5]
	s_setprio 2
	s_barrier
	v_mfma_f32_16x16x32_bf16 v[6:9], v[150:153], v[204:207], v[6:9]
	v_mfma_f32_16x16x32_bf16 v[6:9], v[168:171], v[208:211], v[6:9]
	s_setprio 0
	s_add_i32 s74, s74, 2
	s_add_u32 s30, s30, 0x100
	s_addc_u32 s31, s31, 0
	s_add_u32 s4, s4, 0x100
	s_addc_u32 s5, s5, 0
	s_add_u32 s33, s33, 0x100
	s_addc_u32 s73, s73, 0
	s_cmp_gt_u32 s74, 29
	.p2align 6
.LBB0_654:
	ds_read_b128 v[130:133], v161
	ds_read_b128 v[138:141], v161 offset:1024
	ds_read_b128 v[142:145], v161 offset:2048
	ds_read_b128 v[146:149], v161 offset:3072
	ds_read_b128 v[150:153], v162
	ds_read_b128 v[168:171], v162 offset:1024
	ds_read_b128 v[172:175], v162 offset:2048
	ds_read_b128 v[176:179], v162 offset:3072
	s_cmp_eq_u32 s74, 28
	s_cselect_b32 s11, s21, s31
	s_cselect_b32 s10, s23, s30
	s_cselect_b32 s29, s7, s73
	s_cselect_b32 s28, s9, s33
	ds_read_b128 v[180:183], v163
	ds_read_b128 v[184:187], v163 offset:1024
	ds_read_b128 v[188:191], v163 offset:2048
	ds_read_b128 v[192:195], v163 offset:3072
	ds_read_b128 v[196:199], v163 offset:4096
	ds_read_b128 v[200:203], v163 offset:5120
	ds_read_b128 v[204:207], v163 offset:6144
	ds_read_b128 v[208:211], v163 offset:7168
	s_add_u32 s76, s4, 0xfff80000
	s_addc_u32 s77, s5, -1
	s_mov_b32 s75, m0
	s_mov_b32 m0, s80
	s_nop 0
	global_load_lds_dwordx4 v1, s[76:77]
	s_mov_b32 m0, s75
	s_nop 0
	s_mov_b32 s75, m0
	s_mov_b32 m0, s82
	s_nop 0
	global_load_lds_dwordx4 v157, s[76:77]
	s_mov_b32 m0, s75
	s_nop 0
	s_mov_b32 s75, m0
	s_mov_b32 m0, s81
	s_nop 0
	global_load_lds_dwordx4 v1, s[4:5]
	s_mov_b32 m0, s75
	s_nop 0
	s_mov_b32 s75, m0
	s_mov_b32 m0, s83
	s_nop 0
	global_load_lds_dwordx4 v157, s[4:5]
	s_mov_b32 m0, s75
	s_waitcnt vmcnt(8)
	s_waitcnt lgkmcnt(0)
	s_barrier
	s_setprio 1
	s_waitcnt lgkmcnt(7)
	v_mfma_f32_16x16x32_bf16 v[126:129], v[130:133], v[180:183], v[126:129]
	v_mfma_f32_16x16x32_bf16 v[126:129], v[138:141], v[184:187], v[126:129]
	s_waitcnt lgkmcnt(5)
	v_mfma_f32_16x16x32_bf16 v[122:125], v[142:145], v[180:183], v[122:125]
	v_mfma_f32_16x16x32_bf16 v[122:125], v[146:149], v[184:187], v[122:125]
	s_waitcnt lgkmcnt(3)
	v_mfma_f32_16x16x32_bf16 v[106:109], v[142:145], v[188:191], v[106:109]
	v_mfma_f32_16x16x32_bf16 v[106:109], v[146:149], v[192:195], v[106:109]
	s_waitcnt lgkmcnt(1)
	v_mfma_f32_16x16x32_bf16 v[110:113], v[130:133], v[188:191], v[110:113]
	v_mfma_f32_16x16x32_bf16 v[110:113], v[138:141], v[192:195], v[110:113]
	v_mfma_f32_16x16x32_bf16 v[94:97], v[130:133], v[196:199], v[94:97]
	v_mfma_f32_16x16x32_bf16 v[94:97], v[138:141], v[200:203], v[94:97]
	v_mfma_f32_16x16x32_bf16 v[90:93], v[142:145], v[196:199], v[90:93]
	v_mfma_f32_16x16x32_bf16 v[90:93], v[146:149], v[200:203], v[90:93]
	v_mfma_f32_16x16x32_bf16 v[74:77], v[142:145], v[204:207], v[74:77]
	v_mfma_f32_16x16x32_bf16 v[74:77], v[146:149], v[208:211], v[74:77]
	s_waitcnt lgkmcnt(0)
	v_mfma_f32_16x16x32_bf16 v[78:81], v[130:133], v[204:207], v[78:81]
	v_mfma_f32_16x16x32_bf16 v[78:81], v[138:141], v[208:211], v[78:81]
	v_mfma_f32_16x16x32_bf16 v[118:121], v[150:153], v[180:183], v[118:121]
	v_mfma_f32_16x16x32_bf16 v[118:121], v[168:171], v[184:187], v[118:121]
	v_mfma_f32_16x16x32_bf16 v[114:117], v[172:175], v[180:183], v[114:117]
	v_mfma_f32_16x16x32_bf16 v[114:117], v[176:179], v[184:187], v[114:117]
	v_mfma_f32_16x16x32_bf16 v[98:101], v[172:175], v[188:191], v[98:101]
	v_mfma_f32_16x16x32_bf16 v[98:101], v[176:179], v[192:195], v[98:101]
	v_mfma_f32_16x16x32_bf16 v[102:105], v[150:153], v[188:191], v[102:105]
	v_mfma_f32_16x16x32_bf16 v[102:105], v[168:171], v[192:195], v[102:105]
	v_mfma_f32_16x16x32_bf16 v[86:89], v[150:153], v[196:199], v[86:89]
	v_mfma_f32_16x16x32_bf16 v[86:89], v[168:171], v[200:203], v[86:89]
	v_mfma_f32_16x16x32_bf16 v[82:85], v[172:175], v[196:199], v[82:85]
	v_mfma_f32_16x16x32_bf16 v[82:85], v[176:179], v[200:203], v[82:85]
	v_mfma_f32_16x16x32_bf16 v[66:69], v[172:175], v[204:207], v[66:69]
	v_mfma_f32_16x16x32_bf16 v[66:69], v[176:179], v[208:211], v[66:69]
	s_setprio 2
	s_barrier
	v_mfma_f32_16x16x32_bf16 v[70:73], v[150:153], v[204:207], v[70:73]
	v_mfma_f32_16x16x32_bf16 v[70:73], v[168:171], v[208:211], v[70:73]
	s_setprio 0
	ds_read_b128 v[180:183], v163 offset:16384
	ds_read_b128 v[184:187], v163 offset:17408
	ds_read_b128 v[188:191], v163 offset:18432
	ds_read_b128 v[192:195], v163 offset:19456
	ds_read_b128 v[196:199], v163 offset:20480
	ds_read_b128 v[200:203], v163 offset:21504
	ds_read_b128 v[204:207], v163 offset:22528
	ds_read_b128 v[208:211], v163 offset:23552
	s_mov_b32 s75, m0
	s_mov_b32 m0, s43
	s_nop 0
	global_load_lds_dwordx4 v156, s[10:11]
	s_mov_b32 m0, s75
	s_add_u32 s76, s10, 0x80000
	s_mov_b32 s75, m0
	s_mov_b32 m0, s46
	s_nop 0
	global_load_lds_dwordx4 v158, s[10:11]
	s_mov_b32 m0, s75
	s_addc_u32 s77, s11, 0
	s_mov_b32 s75, m0
	s_mov_b32 m0, s47
	s_nop 0
	global_load_lds_dwordx4 v156, s[76:77]
	s_mov_b32 m0, s75
	s_nop 0
	s_mov_b32 s75, m0
	s_mov_b32 m0, s48
	s_nop 0
	global_load_lds_dwordx4 v158, s[76:77]
	s_mov_b32 m0, s75
	s_waitcnt vmcnt(4)
	s_waitcnt lgkmcnt(0)
	s_barrier
	s_setprio 1
	s_waitcnt lgkmcnt(7)
	v_mfma_f32_16x16x32_bf16 v[62:65], v[130:133], v[180:183], v[62:65]
	v_mfma_f32_16x16x32_bf16 v[62:65], v[138:141], v[184:187], v[62:65]
	s_waitcnt lgkmcnt(5)
	v_mfma_f32_16x16x32_bf16 v[58:61], v[142:145], v[180:183], v[58:61]
	v_mfma_f32_16x16x32_bf16 v[58:61], v[146:149], v[184:187], v[58:61]
	s_waitcnt lgkmcnt(3)
	v_mfma_f32_16x16x32_bf16 v[42:45], v[142:145], v[188:191], v[42:45]
	v_mfma_f32_16x16x32_bf16 v[42:45], v[146:149], v[192:195], v[42:45]
	s_waitcnt lgkmcnt(1)
	v_mfma_f32_16x16x32_bf16 v[46:49], v[130:133], v[188:191], v[46:49]
	v_mfma_f32_16x16x32_bf16 v[46:49], v[138:141], v[192:195], v[46:49]
	v_mfma_f32_16x16x32_bf16 v[30:33], v[130:133], v[196:199], v[30:33]
	v_mfma_f32_16x16x32_bf16 v[30:33], v[138:141], v[200:203], v[30:33]
	v_mfma_f32_16x16x32_bf16 v[26:29], v[142:145], v[196:199], v[26:29]
	v_mfma_f32_16x16x32_bf16 v[26:29], v[146:149], v[200:203], v[26:29]
	v_mfma_f32_16x16x32_bf16 v[10:13], v[142:145], v[204:207], v[10:13]
	v_mfma_f32_16x16x32_bf16 v[10:13], v[146:149], v[208:211], v[10:13]
	s_waitcnt lgkmcnt(0)
	v_mfma_f32_16x16x32_bf16 v[14:17], v[130:133], v[204:207], v[14:17]
	v_mfma_f32_16x16x32_bf16 v[14:17], v[138:141], v[208:211], v[14:17]
	v_mfma_f32_16x16x32_bf16 v[54:57], v[150:153], v[180:183], v[54:57]
	v_mfma_f32_16x16x32_bf16 v[54:57], v[168:171], v[184:187], v[54:57]
	v_mfma_f32_16x16x32_bf16 v[50:53], v[172:175], v[180:183], v[50:53]
	v_mfma_f32_16x16x32_bf16 v[50:53], v[176:179], v[184:187], v[50:53]
	v_mfma_f32_16x16x32_bf16 v[34:37], v[172:175], v[188:191], v[34:37]
	v_mfma_f32_16x16x32_bf16 v[34:37], v[176:179], v[192:195], v[34:37]
	v_mfma_f32_16x16x32_bf16 v[38:41], v[150:153], v[188:191], v[38:41]
	v_mfma_f32_16x16x32_bf16 v[38:41], v[168:171], v[192:195], v[38:41]
	v_mfma_f32_16x16x32_bf16 v[22:25], v[150:153], v[196:199], v[22:25]
	v_mfma_f32_16x16x32_bf16 v[22:25], v[168:171], v[200:203], v[22:25]
	v_mfma_f32_16x16x32_bf16 v[18:21], v[172:175], v[196:199], v[18:21]
	v_mfma_f32_16x16x32_bf16 v[18:21], v[176:179], v[200:203], v[18:21]
	v_mfma_f32_16x16x32_bf16 v[2:5], v[172:175], v[204:207], v[2:5]
	v_mfma_f32_16x16x32_bf16 v[2:5], v[176:179], v[208:211], v[2:5]
	s_setprio 2
	s_barrier
	v_mfma_f32_16x16x32_bf16 v[6:9], v[150:153], v[204:207], v[6:9]
	v_mfma_f32_16x16x32_bf16 v[6:9], v[168:171], v[208:211], v[6:9]
	s_setprio 0
	ds_read_b128 v[130:133], v164
	ds_read_b128 v[138:141], v164 offset:1024
	ds_read_b128 v[142:145], v164 offset:2048
	ds_read_b128 v[146:149], v164 offset:3072
	ds_read_b128 v[150:153], v165
	ds_read_b128 v[168:171], v165 offset:1024
	ds_read_b128 v[172:175], v165 offset:2048
	ds_read_b128 v[176:179], v165 offset:3072
	ds_read_b128 v[180:183], v163 offset:32768
	ds_read_b128 v[184:187], v163 offset:33792
	ds_read_b128 v[188:191], v163 offset:34816
	ds_read_b128 v[192:195], v163 offset:35840
	ds_read_b128 v[196:199], v163 offset:36864
	ds_read_b128 v[200:203], v163 offset:37888
	ds_read_b128 v[204:207], v163 offset:38912
	ds_read_b128 v[208:211], v163 offset:39936
	s_mov_b32 s75, m0
	s_mov_b32 m0, s42
	s_nop 0
	global_load_lds_dwordx4 v1, s[28:29]
	s_mov_b32 m0, s75
	s_nop 0
	s_mov_b32 s75, m0
	s_mov_b32 m0, s49
	s_nop 0
	global_load_lds_dwordx4 v157, s[28:29]
	s_mov_b32 m0, s75
	s_add_u32 s28, s28, 0x80000
	s_addc_u32 s29, s29, 0
	s_mov_b32 s75, m0
	s_mov_b32 m0, s56
	s_nop 0
	global_load_lds_dwordx4 v1, s[28:29]
	s_mov_b32 m0, s75
	s_nop 0
	s_mov_b32 s75, m0
	s_mov_b32 m0, s57
	s_nop 0
	global_load_lds_dwordx4 v157, s[28:29]
	s_mov_b32 m0, s75
	s_waitcnt vmcnt(8)
	s_waitcnt lgkmcnt(0)
	s_barrier
	s_setprio 1
	s_waitcnt lgkmcnt(7)
	v_mfma_f32_16x16x32_bf16 v[126:129], v[130:133], v[180:183], v[126:129]
	v_mfma_f32_16x16x32_bf16 v[126:129], v[138:141], v[184:187], v[126:129]
	s_waitcnt lgkmcnt(5)
	v_mfma_f32_16x16x32_bf16 v[122:125], v[142:145], v[180:183], v[122:125]
	v_mfma_f32_16x16x32_bf16 v[122:125], v[146:149], v[184:187], v[122:125]
	s_waitcnt lgkmcnt(3)
	v_mfma_f32_16x16x32_bf16 v[106:109], v[142:145], v[188:191], v[106:109]
	v_mfma_f32_16x16x32_bf16 v[106:109], v[146:149], v[192:195], v[106:109]
	s_waitcnt lgkmcnt(1)
	v_mfma_f32_16x16x32_bf16 v[110:113], v[130:133], v[188:191], v[110:113]
	v_mfma_f32_16x16x32_bf16 v[110:113], v[138:141], v[192:195], v[110:113]
	v_mfma_f32_16x16x32_bf16 v[94:97], v[130:133], v[196:199], v[94:97]
	v_mfma_f32_16x16x32_bf16 v[94:97], v[138:141], v[200:203], v[94:97]
	v_mfma_f32_16x16x32_bf16 v[90:93], v[142:145], v[196:199], v[90:93]
	v_mfma_f32_16x16x32_bf16 v[90:93], v[146:149], v[200:203], v[90:93]
	v_mfma_f32_16x16x32_bf16 v[74:77], v[142:145], v[204:207], v[74:77]
	v_mfma_f32_16x16x32_bf16 v[74:77], v[146:149], v[208:211], v[74:77]
	s_waitcnt lgkmcnt(0)
	v_mfma_f32_16x16x32_bf16 v[78:81], v[130:133], v[204:207], v[78:81]
	v_mfma_f32_16x16x32_bf16 v[78:81], v[138:141], v[208:211], v[78:81]
	v_mfma_f32_16x16x32_bf16 v[118:121], v[150:153], v[180:183], v[118:121]
	v_mfma_f32_16x16x32_bf16 v[118:121], v[168:171], v[184:187], v[118:121]
	v_mfma_f32_16x16x32_bf16 v[114:117], v[172:175], v[180:183], v[114:117]
	v_mfma_f32_16x16x32_bf16 v[114:117], v[176:179], v[184:187], v[114:117]
	v_mfma_f32_16x16x32_bf16 v[98:101], v[172:175], v[188:191], v[98:101]
	v_mfma_f32_16x16x32_bf16 v[98:101], v[176:179], v[192:195], v[98:101]
	v_mfma_f32_16x16x32_bf16 v[102:105], v[150:153], v[188:191], v[102:105]
	v_mfma_f32_16x16x32_bf16 v[102:105], v[168:171], v[192:195], v[102:105]
	v_mfma_f32_16x16x32_bf16 v[86:89], v[150:153], v[196:199], v[86:89]
	v_mfma_f32_16x16x32_bf16 v[86:89], v[168:171], v[200:203], v[86:89]
	v_mfma_f32_16x16x32_bf16 v[82:85], v[172:175], v[196:199], v[82:85]
	v_mfma_f32_16x16x32_bf16 v[82:85], v[176:179], v[200:203], v[82:85]
	v_mfma_f32_16x16x32_bf16 v[66:69], v[172:175], v[204:207], v[66:69]
	v_mfma_f32_16x16x32_bf16 v[66:69], v[176:179], v[208:211], v[66:69]
	s_setprio 2
	s_barrier
	v_mfma_f32_16x16x32_bf16 v[70:73], v[150:153], v[204:207], v[70:73]
	v_mfma_f32_16x16x32_bf16 v[70:73], v[168:171], v[208:211], v[70:73]
	s_setprio 0
	ds_read_b128 v[180:183], v163 offset:49152
	ds_read_b128 v[184:187], v163 offset:50176
	ds_read_b128 v[188:191], v163 offset:51200
	ds_read_b128 v[192:195], v163 offset:52224
	ds_read_b128 v[196:199], v163 offset:53248
	ds_read_b128 v[200:203], v163 offset:54272
	ds_read_b128 v[204:207], v163 offset:55296
	ds_read_b128 v[208:211], v163 offset:56320
	s_add_u32 s28, s10, 0x80
	s_addc_u32 s29, s11, 0
	s_mov_b32 s75, m0
	s_mov_b32 m0, s64
	s_nop 0
	global_load_lds_dwordx4 v156, s[28:29]
	s_mov_b32 m0, s75
	s_add_u32 s10, s10, 0x80080
	s_mov_b32 s75, m0
	s_mov_b32 m0, s65
	s_nop 0
	global_load_lds_dwordx4 v158, s[28:29]
	s_mov_b32 m0, s75
	s_addc_u32 s11, s11, 0
	s_mov_b32 s28, m0
	s_mov_b32 m0, s66
	s_nop 0
	global_load_lds_dwordx4 v156, s[10:11]
	s_mov_b32 m0, s28
	s_nop 0
	s_mov_b32 s28, m0
	s_mov_b32 m0, s67
	s_nop 0
	global_load_lds_dwordx4 v158, s[10:11]
	s_mov_b32 m0, s28
	s_waitcnt vmcnt(4)
	s_waitcnt lgkmcnt(0)
	s_barrier
	s_setprio 1
	s_waitcnt lgkmcnt(7)
	v_mfma_f32_16x16x32_bf16 v[62:65], v[130:133], v[180:183], v[62:65]
	v_mfma_f32_16x16x32_bf16 v[62:65], v[138:141], v[184:187], v[62:65]
	s_waitcnt lgkmcnt(5)
	v_mfma_f32_16x16x32_bf16 v[58:61], v[142:145], v[180:183], v[58:61]
	v_mfma_f32_16x16x32_bf16 v[58:61], v[146:149], v[184:187], v[58:61]
	s_waitcnt lgkmcnt(3)
	v_mfma_f32_16x16x32_bf16 v[42:45], v[142:145], v[188:191], v[42:45]
	v_mfma_f32_16x16x32_bf16 v[42:45], v[146:149], v[192:195], v[42:45]
	s_waitcnt lgkmcnt(1)
	v_mfma_f32_16x16x32_bf16 v[46:49], v[130:133], v[188:191], v[46:49]
	v_mfma_f32_16x16x32_bf16 v[46:49], v[138:141], v[192:195], v[46:49]
	v_mfma_f32_16x16x32_bf16 v[30:33], v[130:133], v[196:199], v[30:33]
	v_mfma_f32_16x16x32_bf16 v[30:33], v[138:141], v[200:203], v[30:33]
	v_mfma_f32_16x16x32_bf16 v[26:29], v[142:145], v[196:199], v[26:29]
	v_mfma_f32_16x16x32_bf16 v[26:29], v[146:149], v[200:203], v[26:29]
	v_mfma_f32_16x16x32_bf16 v[10:13], v[142:145], v[204:207], v[10:13]
	v_mfma_f32_16x16x32_bf16 v[10:13], v[146:149], v[208:211], v[10:13]
	s_waitcnt lgkmcnt(0)
	v_mfma_f32_16x16x32_bf16 v[14:17], v[130:133], v[204:207], v[14:17]
	v_mfma_f32_16x16x32_bf16 v[14:17], v[138:141], v[208:211], v[14:17]
	v_mfma_f32_16x16x32_bf16 v[54:57], v[150:153], v[180:183], v[54:57]
	v_mfma_f32_16x16x32_bf16 v[54:57], v[168:171], v[184:187], v[54:57]
	v_mfma_f32_16x16x32_bf16 v[50:53], v[172:175], v[180:183], v[50:53]
	v_mfma_f32_16x16x32_bf16 v[50:53], v[176:179], v[184:187], v[50:53]
	v_mfma_f32_16x16x32_bf16 v[34:37], v[172:175], v[188:191], v[34:37]
	v_mfma_f32_16x16x32_bf16 v[34:37], v[176:179], v[192:195], v[34:37]
	v_mfma_f32_16x16x32_bf16 v[38:41], v[150:153], v[188:191], v[38:41]
	v_mfma_f32_16x16x32_bf16 v[38:41], v[168:171], v[192:195], v[38:41]
	v_mfma_f32_16x16x32_bf16 v[22:25], v[150:153], v[196:199], v[22:25]
	v_mfma_f32_16x16x32_bf16 v[22:25], v[168:171], v[200:203], v[22:25]
	v_mfma_f32_16x16x32_bf16 v[18:21], v[172:175], v[196:199], v[18:21]
	v_mfma_f32_16x16x32_bf16 v[18:21], v[176:179], v[200:203], v[18:21]
	v_mfma_f32_16x16x32_bf16 v[2:5], v[172:175], v[204:207], v[2:5]
	v_mfma_f32_16x16x32_bf16 v[2:5], v[176:179], v[208:211], v[2:5]
	s_setprio 2
	s_barrier
	v_mfma_f32_16x16x32_bf16 v[6:9], v[150:153], v[204:207], v[6:9]
	v_mfma_f32_16x16x32_bf16 v[6:9], v[168:171], v[208:211], v[6:9]
	s_setprio 0
	s_add_i32 s74, s74, 2
	s_add_u32 s30, s30, 0x100
	s_addc_u32 s31, s31, 0
	s_add_u32 s4, s4, 0x100
	s_addc_u32 s5, s5, 0
	s_add_u32 s33, s33, 0x100
	s_addc_u32 s73, s73, 0
	s_cmp_gt_u32 s74, 29
	s_cbranch_scc0 .LBB0_654
	s_and_b64 vcc, exec, s[18:19]
	s_cbranch_vccz .LBB0_657
	s_barrier

.LBB0_1052:
	s_ashr_i32 s13, s12, 31
	s_lshl_b64 s[14:15], s[12:13], 20
	s_add_u32 s14, s28, s14
	s_addc_u32 s15, s29, s15
	s_and_b64 s[16:17], s[2:3], exec
	s_cselect_b32 s13, s15, s23
	s_cselect_b32 s67, s14, s22
	s_ashr_i32 s11, s10, 31
	s_lshl_b64 s[16:17], s[10:11], 20
	s_add_u32 s16, s30, s16
	s_addc_u32 s17, s31, s17
	s_and_b64 s[24:25], s[2:3], exec
	s_cselect_b32 s11, s17, s21
	s_cselect_b32 s73, s16, s20
	s_add_u32 s74, s20, 0x100
	s_addc_u32 s75, s21, 0
	s_add_u32 s20, s22, 0x80080
	s_addc_u32 s21, s23, 0
	s_add_u32 s76, s22, 0x100
	s_addc_u32 s77, s23, 0
	s_mov_b32 s78, -2
	s_waitcnt vmcnt(25)
	s_waitcnt vmcnt(24)
	s_waitcnt vmcnt(15)
	s_waitcnt vmcnt(14)
	s_waitcnt vmcnt(13)
	s_waitcnt vmcnt(12)
	s_waitcnt vmcnt(11)
	s_waitcnt vmcnt(10)
	s_waitcnt vmcnt(9)
	s_waitcnt vmcnt(8)
	s_waitcnt vmcnt(7)
	s_waitcnt vmcnt(6)
	s_waitcnt vmcnt(5)
	s_waitcnt vmcnt(4)
	s_waitcnt vmcnt(3)
	s_waitcnt vmcnt(2)
	s_waitcnt vmcnt(1)
	s_waitcnt vmcnt(0)
	ds_read_b128 v[130:133], v181
	ds_read_b128 v[134:137], v181 offset:1024
	ds_read_b128 v[138:141], v181 offset:2048
	ds_read_b128 v[142:145], v181 offset:3072
	ds_read_b128 v[146:149], v182
	ds_read_b128 v[150:153], v182 offset:1024
	ds_read_b128 v[154:157], v182 offset:2048
	ds_read_b128 v[158:161], v182 offset:3072
	s_cmp_eq_u32 s78, 28
	s_cselect_b32 s23, s11, s75
	s_cselect_b32 s22, s73, s74
	s_cselect_b32 s25, s13, s77
	s_cselect_b32 s24, s67, s76
	ds_read_b128 v[166:169], v183
	ds_read_b128 v[170:173], v183 offset:1024
	ds_read_b128 v[186:189], v183 offset:2048
	ds_read_b128 v[190:193], v183 offset:3072
	ds_read_b128 v[194:197], v183 offset:4096
	ds_read_b128 v[198:201], v183 offset:5120
	ds_read_b128 v[202:205], v183 offset:6144
	ds_read_b128 v[206:209], v183 offset:7168
	s_add_u32 s80, s20, 0xfff80000
	s_addc_u32 s81, s21, -1
	s_mov_b32 s79, m0
	s_mov_b32 m0, s58
	s_nop 0
	global_load_lds_dwordx4 v1, s[80:81]
	s_mov_b32 m0, s79
	s_nop 0
	s_mov_b32 s79, m0
	s_mov_b32 m0, s64
	s_nop 0
	global_load_lds_dwordx4 v177, s[80:81]
	s_mov_b32 m0, s79
	s_nop 0
	s_mov_b32 s79, m0
	s_mov_b32 m0, s59
	s_nop 0
	global_load_lds_dwordx4 v1, s[20:21]
	s_mov_b32 m0, s79
	s_nop 0
	s_mov_b32 s79, m0
	s_mov_b32 m0, s65
	s_nop 0
	global_load_lds_dwordx4 v177, s[20:21]
	s_mov_b32 m0, s79
	s_waitcnt vmcnt(8)
	s_waitcnt lgkmcnt(0)
	s_barrier
	s_setprio 1
	s_waitcnt lgkmcnt(7)
	v_mfma_f32_16x16x32_bf16 v[126:129], v[130:133], v[166:169], 0
	v_mfma_f32_16x16x32_bf16 v[126:129], v[134:137], v[170:173], v[126:129]
	s_waitcnt lgkmcnt(5)
	v_mfma_f32_16x16x32_bf16 v[122:125], v[138:141], v[166:169], 0
	v_mfma_f32_16x16x32_bf16 v[122:125], v[142:145], v[170:173], v[122:125]
	s_waitcnt lgkmcnt(3)
	v_mfma_f32_16x16x32_bf16 v[114:117], v[138:141], v[186:189], 0
	v_mfma_f32_16x16x32_bf16 v[114:117], v[142:145], v[190:193], v[114:117]
	s_waitcnt lgkmcnt(1)
	v_mfma_f32_16x16x32_bf16 v[118:121], v[130:133], v[186:189], 0
	v_mfma_f32_16x16x32_bf16 v[118:121], v[134:137], v[190:193], v[118:121]
	v_mfma_f32_16x16x32_bf16 v[94:97], v[130:133], v[194:197], 0
	v_mfma_f32_16x16x32_bf16 v[94:97], v[134:137], v[198:201], v[94:97]
	v_mfma_f32_16x16x32_bf16 v[90:93], v[138:141], v[194:197], 0
	v_mfma_f32_16x16x32_bf16 v[90:93], v[142:145], v[198:201], v[90:93]
	v_mfma_f32_16x16x32_bf16 v[78:81], v[138:141], v[202:205], 0
	v_mfma_f32_16x16x32_bf16 v[78:81], v[142:145], v[206:209], v[78:81]
	s_waitcnt lgkmcnt(0)
	v_mfma_f32_16x16x32_bf16 v[86:89], v[130:133], v[202:205], 0
	v_mfma_f32_16x16x32_bf16 v[86:89], v[134:137], v[206:209], v[86:89]
	v_mfma_f32_16x16x32_bf16 v[110:113], v[146:149], v[166:169], 0
	v_mfma_f32_16x16x32_bf16 v[110:113], v[150:153], v[170:173], v[110:113]
	v_mfma_f32_16x16x32_bf16 v[106:109], v[154:157], v[166:169], 0
	v_mfma_f32_16x16x32_bf16 v[106:109], v[158:161], v[170:173], v[106:109]
	v_mfma_f32_16x16x32_bf16 v[98:101], v[154:157], v[186:189], 0
	v_mfma_f32_16x16x32_bf16 v[98:101], v[158:161], v[190:193], v[98:101]
	v_mfma_f32_16x16x32_bf16 v[102:105], v[146:149], v[186:189], 0
	v_mfma_f32_16x16x32_bf16 v[102:105], v[150:153], v[190:193], v[102:105]
	v_mfma_f32_16x16x32_bf16 v[82:85], v[146:149], v[194:197], 0
	v_mfma_f32_16x16x32_bf16 v[82:85], v[150:153], v[198:201], v[82:85]
	v_mfma_f32_16x16x32_bf16 v[74:77], v[154:157], v[194:197], 0
	v_mfma_f32_16x16x32_bf16 v[74:77], v[158:161], v[198:201], v[74:77]
	v_mfma_f32_16x16x32_bf16 v[66:69], v[154:157], v[202:205], 0
	v_mfma_f32_16x16x32_bf16 v[66:69], v[158:161], v[206:209], v[66:69]
	s_setprio 2
	s_barrier
	v_mfma_f32_16x16x32_bf16 v[70:73], v[146:149], v[202:205], 0
	v_mfma_f32_16x16x32_bf16 v[70:73], v[150:153], v[206:209], v[70:73]
	s_setprio 0
	ds_read_b128 v[166:169], v183 offset:16384
	ds_read_b128 v[170:173], v183 offset:17408
	ds_read_b128 v[186:189], v183 offset:18432
	ds_read_b128 v[190:193], v183 offset:19456
	ds_read_b128 v[194:197], v183 offset:20480
	ds_read_b128 v[198:201], v183 offset:21504
	ds_read_b128 v[202:205], v183 offset:22528
	ds_read_b128 v[206:209], v183 offset:23552
	s_mov_b32 s79, m0
	s_mov_b32 m0, s35
	s_nop 0
	global_load_lds_dwordx4 v176, s[22:23]
	s_mov_b32 m0, s79
	s_add_u32 s80, s22, 0x80000
	s_mov_b32 s79, m0
	s_mov_b32 m0, s36
	s_nop 0
	global_load_lds_dwordx4 v178, s[22:23]
	s_mov_b32 m0, s79
	s_addc_u32 s81, s23, 0
	s_mov_b32 s79, m0
	s_mov_b32 m0, s37
	s_nop 0
	global_load_lds_dwordx4 v176, s[80:81]
	s_mov_b32 m0, s79
	s_nop 0
	s_mov_b32 s79, m0
	s_mov_b32 m0, s40
	s_nop 0
	global_load_lds_dwordx4 v178, s[80:81]
	s_mov_b32 m0, s79
	s_waitcnt vmcnt(4)
	s_waitcnt lgkmcnt(0)
	s_barrier
	s_setprio 1
	s_waitcnt lgkmcnt(7)
	v_mfma_f32_16x16x32_bf16 v[62:65], v[130:133], v[166:169], 0
	v_mfma_f32_16x16x32_bf16 v[62:65], v[134:137], v[170:173], v[62:65]
	s_waitcnt lgkmcnt(5)
	v_mfma_f32_16x16x32_bf16 v[58:61], v[138:141], v[166:169], 0
	v_mfma_f32_16x16x32_bf16 v[58:61], v[142:145], v[170:173], v[58:61]
	s_waitcnt lgkmcnt(3)
	v_mfma_f32_16x16x32_bf16 v[42:45], v[138:141], v[186:189], 0
	v_mfma_f32_16x16x32_bf16 v[42:45], v[142:145], v[190:193], v[42:45]
	s_waitcnt lgkmcnt(1)
	v_mfma_f32_16x16x32_bf16 v[46:49], v[130:133], v[186:189], 0
	v_mfma_f32_16x16x32_bf16 v[46:49], v[134:137], v[190:193], v[46:49]
	v_mfma_f32_16x16x32_bf16 v[30:33], v[130:133], v[194:197], 0
	v_mfma_f32_16x16x32_bf16 v[30:33], v[134:137], v[198:201], v[30:33]
	v_mfma_f32_16x16x32_bf16 v[26:29], v[138:141], v[194:197], 0
	v_mfma_f32_16x16x32_bf16 v[26:29], v[142:145], v[198:201], v[26:29]
	v_mfma_f32_16x16x32_bf16 v[10:13], v[138:141], v[202:205], 0
	v_mfma_f32_16x16x32_bf16 v[10:13], v[142:145], v[206:209], v[10:13]
	s_waitcnt lgkmcnt(0)
	v_mfma_f32_16x16x32_bf16 v[14:17], v[130:133], v[202:205], 0
	v_mfma_f32_16x16x32_bf16 v[14:17], v[134:137], v[206:209], v[14:17]
	v_mfma_f32_16x16x32_bf16 v[54:57], v[146:149], v[166:169], 0
	v_mfma_f32_16x16x32_bf16 v[54:57], v[150:153], v[170:173], v[54:57]
	v_mfma_f32_16x16x32_bf16 v[50:53], v[154:157], v[166:169], 0
	v_mfma_f32_16x16x32_bf16 v[50:53], v[158:161], v[170:173], v[50:53]
	v_mfma_f32_16x16x32_bf16 v[34:37], v[154:157], v[186:189], 0
	v_mfma_f32_16x16x32_bf16 v[34:37], v[158:161], v[190:193], v[34:37]
	v_mfma_f32_16x16x32_bf16 v[38:41], v[146:149], v[186:189], 0
	v_mfma_f32_16x16x32_bf16 v[38:41], v[150:153], v[190:193], v[38:41]
	v_mfma_f32_16x16x32_bf16 v[22:25], v[146:149], v[194:197], 0
	v_mfma_f32_16x16x32_bf16 v[22:25], v[150:153], v[198:201], v[22:25]
	v_mfma_f32_16x16x32_bf16 v[18:21], v[154:157], v[194:197], 0
	v_mfma_f32_16x16x32_bf16 v[18:21], v[158:161], v[198:201], v[18:21]
	v_mfma_f32_16x16x32_bf16 v[2:5], v[154:157], v[202:205], 0
	v_mfma_f32_16x16x32_bf16 v[2:5], v[158:161], v[206:209], v[2:5]
	s_setprio 2
	s_barrier
	v_mfma_f32_16x16x32_bf16 v[6:9], v[146:149], v[202:205], 0
	v_mfma_f32_16x16x32_bf16 v[6:9], v[150:153], v[206:209], v[6:9]
	s_setprio 0
	ds_read_b128 v[130:133], v184
	ds_read_b128 v[134:137], v184 offset:1024
	ds_read_b128 v[138:141], v184 offset:2048
	ds_read_b128 v[142:145], v184 offset:3072
	ds_read_b128 v[146:149], v185
	ds_read_b128 v[150:153], v185 offset:1024
	ds_read_b128 v[154:157], v185 offset:2048
	ds_read_b128 v[158:161], v185 offset:3072
	ds_read_b128 v[166:169], v183 offset:32768
	ds_read_b128 v[170:173], v183 offset:33792
	ds_read_b128 v[186:189], v183 offset:34816
	ds_read_b128 v[190:193], v183 offset:35840
	ds_read_b128 v[194:197], v183 offset:36864
	ds_read_b128 v[198:201], v183 offset:37888
	ds_read_b128 v[202:205], v183 offset:38912
	ds_read_b128 v[206:209], v183 offset:39936
	s_mov_b32 s79, m0
	s_mov_b32 m0, s34
	s_nop 0
	global_load_lds_dwordx4 v1, s[24:25]
	s_mov_b32 m0, s79
	s_nop 0
	s_mov_b32 s79, m0
	s_mov_b32 m0, s41
	s_nop 0
	global_load_lds_dwordx4 v177, s[24:25]
	s_mov_b32 m0, s79
	s_add_u32 s24, s24, 0x80000
	s_addc_u32 s25, s25, 0
	s_mov_b32 s79, m0
	s_mov_b32 m0, s42
	s_nop 0
	global_load_lds_dwordx4 v1, s[24:25]
	s_mov_b32 m0, s79
	s_nop 0
	s_mov_b32 s79, m0
	s_mov_b32 m0, s43
	s_nop 0
	global_load_lds_dwordx4 v177, s[24:25]
	s_mov_b32 m0, s79
	s_waitcnt vmcnt(8)
	s_waitcnt lgkmcnt(0)
	s_barrier
	s_setprio 1
	s_waitcnt lgkmcnt(7)
	v_mfma_f32_16x16x32_bf16 v[126:129], v[130:133], v[166:169], v[126:129]
	v_mfma_f32_16x16x32_bf16 v[126:129], v[134:137], v[170:173], v[126:129]
	s_waitcnt lgkmcnt(5)
	v_mfma_f32_16x16x32_bf16 v[122:125], v[138:141], v[166:169], v[122:125]
	v_mfma_f32_16x16x32_bf16 v[122:125], v[142:145], v[170:173], v[122:125]
	s_waitcnt lgkmcnt(3)
	v_mfma_f32_16x16x32_bf16 v[114:117], v[138:141], v[186:189], v[114:117]
	v_mfma_f32_16x16x32_bf16 v[114:117], v[142:145], v[190:193], v[114:117]
	s_waitcnt lgkmcnt(1)
	v_mfma_f32_16x16x32_bf16 v[118:121], v[130:133], v[186:189], v[118:121]
	v_mfma_f32_16x16x32_bf16 v[118:121], v[134:137], v[190:193], v[118:121]
	v_mfma_f32_16x16x32_bf16 v[94:97], v[130:133], v[194:197], v[94:97]
	v_mfma_f32_16x16x32_bf16 v[94:97], v[134:137], v[198:201], v[94:97]
	v_mfma_f32_16x16x32_bf16 v[90:93], v[138:141], v[194:197], v[90:93]
	v_mfma_f32_16x16x32_bf16 v[90:93], v[142:145], v[198:201], v[90:93]
	v_mfma_f32_16x16x32_bf16 v[78:81], v[138:141], v[202:205], v[78:81]
	v_mfma_f32_16x16x32_bf16 v[78:81], v[142:145], v[206:209], v[78:81]
	s_waitcnt lgkmcnt(0)
	v_mfma_f32_16x16x32_bf16 v[86:89], v[130:133], v[202:205], v[86:89]
	v_mfma_f32_16x16x32_bf16 v[86:89], v[134:137], v[206:209], v[86:89]
	v_mfma_f32_16x16x32_bf16 v[110:113], v[146:149], v[166:169], v[110:113]
	v_mfma_f32_16x16x32_bf16 v[110:113], v[150:153], v[170:173], v[110:113]
	v_mfma_f32_16x16x32_bf16 v[106:109], v[154:157], v[166:169], v[106:109]
	v_mfma_f32_16x16x32_bf16 v[106:109], v[158:161], v[170:173], v[106:109]
	v_mfma_f32_16x16x32_bf16 v[98:101], v[154:157], v[186:189], v[98:101]
	v_mfma_f32_16x16x32_bf16 v[98:101], v[158:161], v[190:193], v[98:101]
	v_mfma_f32_16x16x32_bf16 v[102:105], v[146:149], v[186:189], v[102:105]
	v_mfma_f32_16x16x32_bf16 v[102:105], v[150:153], v[190:193], v[102:105]
	v_mfma_f32_16x16x32_bf16 v[82:85], v[146:149], v[194:197], v[82:85]
	v_mfma_f32_16x16x32_bf16 v[82:85], v[150:153], v[198:201], v[82:85]
	v_mfma_f32_16x16x32_bf16 v[74:77], v[154:157], v[194:197], v[74:77]
	v_mfma_f32_16x16x32_bf16 v[74:77], v[158:161], v[198:201], v[74:77]
	v_mfma_f32_16x16x32_bf16 v[66:69], v[154:157], v[202:205], v[66:69]
	v_mfma_f32_16x16x32_bf16 v[66:69], v[158:161], v[206:209], v[66:69]
	s_setprio 2
	s_barrier
	v_mfma_f32_16x16x32_bf16 v[70:73], v[146:149], v[202:205], v[70:73]
	v_mfma_f32_16x16x32_bf16 v[70:73], v[150:153], v[206:209], v[70:73]
	s_setprio 0
	ds_read_b128 v[166:169], v183 offset:49152
	ds_read_b128 v[170:173], v183 offset:50176
	ds_read_b128 v[186:189], v183 offset:51200
	ds_read_b128 v[190:193], v183 offset:52224
	ds_read_b128 v[194:197], v183 offset:53248
	ds_read_b128 v[198:201], v183 offset:54272
	ds_read_b128 v[202:205], v183 offset:55296
	ds_read_b128 v[206:209], v183 offset:56320
	s_add_u32 s24, s22, 0x80
	s_addc_u32 s25, s23, 0
	s_mov_b32 s79, m0
	s_mov_b32 m0, s46
	s_nop 0
	global_load_lds_dwordx4 v176, s[24:25]
	s_mov_b32 m0, s79
	s_add_u32 s22, s22, 0x80080
	s_mov_b32 s79, m0
	s_mov_b32 m0, s47
	s_nop 0
	global_load_lds_dwordx4 v178, s[24:25]
	s_mov_b32 m0, s79
	s_addc_u32 s23, s23, 0
	s_mov_b32 s24, m0
	s_mov_b32 m0, s48
	s_nop 0
	global_load_lds_dwordx4 v176, s[22:23]
	s_mov_b32 m0, s24
	s_nop 0
	s_mov_b32 s24, m0
	s_mov_b32 m0, s49
	s_nop 0
	global_load_lds_dwordx4 v178, s[22:23]
	s_mov_b32 m0, s24
	s_waitcnt vmcnt(4)
	s_waitcnt lgkmcnt(0)
	s_barrier
	s_setprio 1
	s_waitcnt lgkmcnt(7)
	v_mfma_f32_16x16x32_bf16 v[62:65], v[130:133], v[166:169], v[62:65]
	v_mfma_f32_16x16x32_bf16 v[62:65], v[134:137], v[170:173], v[62:65]
	s_waitcnt lgkmcnt(5)
	v_mfma_f32_16x16x32_bf16 v[58:61], v[138:141], v[166:169], v[58:61]
	v_mfma_f32_16x16x32_bf16 v[58:61], v[142:145], v[170:173], v[58:61]
	s_waitcnt lgkmcnt(3)
	v_mfma_f32_16x16x32_bf16 v[42:45], v[138:141], v[186:189], v[42:45]
	v_mfma_f32_16x16x32_bf16 v[42:45], v[142:145], v[190:193], v[42:45]
	s_waitcnt lgkmcnt(1)
	v_mfma_f32_16x16x32_bf16 v[46:49], v[130:133], v[186:189], v[46:49]
	v_mfma_f32_16x16x32_bf16 v[46:49], v[134:137], v[190:193], v[46:49]
	v_mfma_f32_16x16x32_bf16 v[30:33], v[130:133], v[194:197], v[30:33]
	v_mfma_f32_16x16x32_bf16 v[30:33], v[134:137], v[198:201], v[30:33]
	v_mfma_f32_16x16x32_bf16 v[26:29], v[138:141], v[194:197], v[26:29]
	v_mfma_f32_16x16x32_bf16 v[26:29], v[142:145], v[198:201], v[26:29]
	v_mfma_f32_16x16x32_bf16 v[10:13], v[138:141], v[202:205], v[10:13]
	v_mfma_f32_16x16x32_bf16 v[10:13], v[142:145], v[206:209], v[10:13]
	s_waitcnt lgkmcnt(0)
	v_mfma_f32_16x16x32_bf16 v[14:17], v[130:133], v[202:205], v[14:17]
	v_mfma_f32_16x16x32_bf16 v[14:17], v[134:137], v[206:209], v[14:17]
	v_mfma_f32_16x16x32_bf16 v[54:57], v[146:149], v[166:169], v[54:57]
	v_mfma_f32_16x16x32_bf16 v[54:57], v[150:153], v[170:173], v[54:57]
	v_mfma_f32_16x16x32_bf16 v[50:53], v[154:157], v[166:169], v[50:53]
	v_mfma_f32_16x16x32_bf16 v[50:53], v[158:161], v[170:173], v[50:53]
	v_mfma_f32_16x16x32_bf16 v[34:37], v[154:157], v[186:189], v[34:37]
	v_mfma_f32_16x16x32_bf16 v[34:37], v[158:161], v[190:193], v[34:37]
	v_mfma_f32_16x16x32_bf16 v[38:41], v[146:149], v[186:189], v[38:41]
	v_mfma_f32_16x16x32_bf16 v[38:41], v[150:153], v[190:193], v[38:41]
	v_mfma_f32_16x16x32_bf16 v[22:25], v[146:149], v[194:197], v[22:25]
	v_mfma_f32_16x16x32_bf16 v[22:25], v[150:153], v[198:201], v[22:25]
	v_mfma_f32_16x16x32_bf16 v[18:21], v[154:157], v[194:197], v[18:21]
	v_mfma_f32_16x16x32_bf16 v[18:21], v[158:161], v[198:201], v[18:21]
	v_mfma_f32_16x16x32_bf16 v[2:5], v[154:157], v[202:205], v[2:5]
	v_mfma_f32_16x16x32_bf16 v[2:5], v[158:161], v[206:209], v[2:5]
	s_setprio 2
	s_barrier
	v_mfma_f32_16x16x32_bf16 v[6:9], v[146:149], v[202:205], v[6:9]
	v_mfma_f32_16x16x32_bf16 v[6:9], v[150:153], v[206:209], v[6:9]
	s_setprio 0
	s_add_i32 s78, s78, 2
	s_add_u32 s74, s74, 0x100
	s_addc_u32 s75, s75, 0
	s_add_u32 s20, s20, 0x100
	s_addc_u32 s21, s21, 0
	s_add_u32 s76, s76, 0x100
	s_addc_u32 s77, s77, 0
	s_cmp_gt_u32 s78, 29
	.p2align 6
.LBB0_1053:
	ds_read_b128 v[130:133], v181
	ds_read_b128 v[134:137], v181 offset:1024
	ds_read_b128 v[138:141], v181 offset:2048
	ds_read_b128 v[142:145], v181 offset:3072
	ds_read_b128 v[146:149], v182
	ds_read_b128 v[150:153], v182 offset:1024
	ds_read_b128 v[154:157], v182 offset:2048
	ds_read_b128 v[158:161], v182 offset:3072
	s_cmp_eq_u32 s78, 28
	s_cselect_b32 s23, s11, s75
	s_cselect_b32 s22, s73, s74
	s_cselect_b32 s25, s13, s77
	s_cselect_b32 s24, s67, s76
	ds_read_b128 v[166:169], v183
	ds_read_b128 v[170:173], v183 offset:1024
	ds_read_b128 v[186:189], v183 offset:2048
	ds_read_b128 v[190:193], v183 offset:3072
	ds_read_b128 v[194:197], v183 offset:4096
	ds_read_b128 v[198:201], v183 offset:5120
	ds_read_b128 v[202:205], v183 offset:6144
	ds_read_b128 v[206:209], v183 offset:7168
	s_add_u32 s80, s20, 0xfff80000
	s_addc_u32 s81, s21, -1
	s_mov_b32 s79, m0
	s_mov_b32 m0, s58
	s_nop 0
	global_load_lds_dwordx4 v1, s[80:81]
	s_mov_b32 m0, s79
	s_nop 0
	s_mov_b32 s79, m0
	s_mov_b32 m0, s64
	s_nop 0
	global_load_lds_dwordx4 v177, s[80:81]
	s_mov_b32 m0, s79
	s_nop 0
	s_mov_b32 s79, m0
	s_mov_b32 m0, s59
	s_nop 0
	global_load_lds_dwordx4 v1, s[20:21]
	s_mov_b32 m0, s79
	s_nop 0
	s_mov_b32 s79, m0
	s_mov_b32 m0, s65
	s_nop 0
	global_load_lds_dwordx4 v177, s[20:21]
	s_mov_b32 m0, s79
	s_waitcnt vmcnt(8)
	s_waitcnt lgkmcnt(0)
	s_barrier
	s_setprio 1
	s_waitcnt lgkmcnt(7)
	v_mfma_f32_16x16x32_bf16 v[126:129], v[130:133], v[166:169], v[126:129]
	v_mfma_f32_16x16x32_bf16 v[126:129], v[134:137], v[170:173], v[126:129]
	s_waitcnt lgkmcnt(5)
	v_mfma_f32_16x16x32_bf16 v[122:125], v[138:141], v[166:169], v[122:125]
	v_mfma_f32_16x16x32_bf16 v[122:125], v[142:145], v[170:173], v[122:125]
	s_waitcnt lgkmcnt(3)
	v_mfma_f32_16x16x32_bf16 v[114:117], v[138:141], v[186:189], v[114:117]
	v_mfma_f32_16x16x32_bf16 v[114:117], v[142:145], v[190:193], v[114:117]
	s_waitcnt lgkmcnt(1)
	v_mfma_f32_16x16x32_bf16 v[118:121], v[130:133], v[186:189], v[118:121]
	v_mfma_f32_16x16x32_bf16 v[118:121], v[134:137], v[190:193], v[118:121]
	v_mfma_f32_16x16x32_bf16 v[94:97], v[130:133], v[194:197], v[94:97]
	v_mfma_f32_16x16x32_bf16 v[94:97], v[134:137], v[198:201], v[94:97]
	v_mfma_f32_16x16x32_bf16 v[90:93], v[138:141], v[194:197], v[90:93]
	v_mfma_f32_16x16x32_bf16 v[90:93], v[142:145], v[198:201], v[90:93]
	v_mfma_f32_16x16x32_bf16 v[78:81], v[138:141], v[202:205], v[78:81]
	v_mfma_f32_16x16x32_bf16 v[78:81], v[142:145], v[206:209], v[78:81]
	s_waitcnt lgkmcnt(0)
	v_mfma_f32_16x16x32_bf16 v[86:89], v[130:133], v[202:205], v[86:89]
	v_mfma_f32_16x16x32_bf16 v[86:89], v[134:137], v[206:209], v[86:89]
	v_mfma_f32_16x16x32_bf16 v[110:113], v[146:149], v[166:169], v[110:113]
	v_mfma_f32_16x16x32_bf16 v[110:113], v[150:153], v[170:173], v[110:113]
	v_mfma_f32_16x16x32_bf16 v[106:109], v[154:157], v[166:169], v[106:109]
	v_mfma_f32_16x16x32_bf16 v[106:109], v[158:161], v[170:173], v[106:109]
	v_mfma_f32_16x16x32_bf16 v[98:101], v[154:157], v[186:189], v[98:101]
	v_mfma_f32_16x16x32_bf16 v[98:101], v[158:161], v[190:193], v[98:101]
	v_mfma_f32_16x16x32_bf16 v[102:105], v[146:149], v[186:189], v[102:105]
	v_mfma_f32_16x16x32_bf16 v[102:105], v[150:153], v[190:193], v[102:105]
	v_mfma_f32_16x16x32_bf16 v[82:85], v[146:149], v[194:197], v[82:85]
	v_mfma_f32_16x16x32_bf16 v[82:85], v[150:153], v[198:201], v[82:85]
	v_mfma_f32_16x16x32_bf16 v[74:77], v[154:157], v[194:197], v[74:77]
	v_mfma_f32_16x16x32_bf16 v[74:77], v[158:161], v[198:201], v[74:77]
	v_mfma_f32_16x16x32_bf16 v[66:69], v[154:157], v[202:205], v[66:69]
	v_mfma_f32_16x16x32_bf16 v[66:69], v[158:161], v[206:209], v[66:69]
	s_setprio 2
	s_barrier
	v_mfma_f32_16x16x32_bf16 v[70:73], v[146:149], v[202:205], v[70:73]
	v_mfma_f32_16x16x32_bf16 v[70:73], v[150:153], v[206:209], v[70:73]
	s_setprio 0
	ds_read_b128 v[166:169], v183 offset:16384
	ds_read_b128 v[170:173], v183 offset:17408
	ds_read_b128 v[186:189], v183 offset:18432
	ds_read_b128 v[190:193], v183 offset:19456
	ds_read_b128 v[194:197], v183 offset:20480
	ds_read_b128 v[198:201], v183 offset:21504
	ds_read_b128 v[202:205], v183 offset:22528
	ds_read_b128 v[206:209], v183 offset:23552
	s_mov_b32 s79, m0
	s_mov_b32 m0, s35
	s_nop 0
	global_load_lds_dwordx4 v176, s[22:23]
	s_mov_b32 m0, s79
	s_add_u32 s80, s22, 0x80000
	s_mov_b32 s79, m0
	s_mov_b32 m0, s36
	s_nop 0
	global_load_lds_dwordx4 v178, s[22:23]
	s_mov_b32 m0, s79
	s_addc_u32 s81, s23, 0
	s_mov_b32 s79, m0
	s_mov_b32 m0, s37
	s_nop 0
	global_load_lds_dwordx4 v176, s[80:81]
	s_mov_b32 m0, s79
	s_nop 0
	s_mov_b32 s79, m0
	s_mov_b32 m0, s40
	s_nop 0
	global_load_lds_dwordx4 v178, s[80:81]
	s_mov_b32 m0, s79
	s_waitcnt vmcnt(4)
	s_waitcnt lgkmcnt(0)
	s_barrier
	s_setprio 1
	s_waitcnt lgkmcnt(7)
	v_mfma_f32_16x16x32_bf16 v[62:65], v[130:133], v[166:169], v[62:65]
	v_mfma_f32_16x16x32_bf16 v[62:65], v[134:137], v[170:173], v[62:65]
	s_waitcnt lgkmcnt(5)
	v_mfma_f32_16x16x32_bf16 v[58:61], v[138:141], v[166:169], v[58:61]
	v_mfma_f32_16x16x32_bf16 v[58:61], v[142:145], v[170:173], v[58:61]
	s_waitcnt lgkmcnt(3)
	v_mfma_f32_16x16x32_bf16 v[42:45], v[138:141], v[186:189], v[42:45]
	v_mfma_f32_16x16x32_bf16 v[42:45], v[142:145], v[190:193], v[42:45]
	s_waitcnt lgkmcnt(1)
	v_mfma_f32_16x16x32_bf16 v[46:49], v[130:133], v[186:189], v[46:49]
	v_mfma_f32_16x16x32_bf16 v[46:49], v[134:137], v[190:193], v[46:49]
	v_mfma_f32_16x16x32_bf16 v[30:33], v[130:133], v[194:197], v[30:33]
	v_mfma_f32_16x16x32_bf16 v[30:33], v[134:137], v[198:201], v[30:33]
	v_mfma_f32_16x16x32_bf16 v[26:29], v[138:141], v[194:197], v[26:29]
	v_mfma_f32_16x16x32_bf16 v[26:29], v[142:145], v[198:201], v[26:29]
	v_mfma_f32_16x16x32_bf16 v[10:13], v[138:141], v[202:205], v[10:13]
	v_mfma_f32_16x16x32_bf16 v[10:13], v[142:145], v[206:209], v[10:13]
	s_waitcnt lgkmcnt(0)
	v_mfma_f32_16x16x32_bf16 v[14:17], v[130:133], v[202:205], v[14:17]
	v_mfma_f32_16x16x32_bf16 v[14:17], v[134:137], v[206:209], v[14:17]
	v_mfma_f32_16x16x32_bf16 v[54:57], v[146:149], v[166:169], v[54:57]
	v_mfma_f32_16x16x32_bf16 v[54:57], v[150:153], v[170:173], v[54:57]
	v_mfma_f32_16x16x32_bf16 v[50:53], v[154:157], v[166:169], v[50:53]
	v_mfma_f32_16x16x32_bf16 v[50:53], v[158:161], v[170:173], v[50:53]
	v_mfma_f32_16x16x32_bf16 v[34:37], v[154:157], v[186:189], v[34:37]
	v_mfma_f32_16x16x32_bf16 v[34:37], v[158:161], v[190:193], v[34:37]
	v_mfma_f32_16x16x32_bf16 v[38:41], v[146:149], v[186:189], v[38:41]
	v_mfma_f32_16x16x32_bf16 v[38:41], v[150:153], v[190:193], v[38:41]
	v_mfma_f32_16x16x32_bf16 v[22:25], v[146:149], v[194:197], v[22:25]
	v_mfma_f32_16x16x32_bf16 v[22:25], v[150:153], v[198:201], v[22:25]
	v_mfma_f32_16x16x32_bf16 v[18:21], v[154:157], v[194:197], v[18:21]
	v_mfma_f32_16x16x32_bf16 v[18:21], v[158:161], v[198:201], v[18:21]
	v_mfma_f32_16x16x32_bf16 v[2:5], v[154:157], v[202:205], v[2:5]
	v_mfma_f32_16x16x32_bf16 v[2:5], v[158:161], v[206:209], v[2:5]
	s_setprio 2
	s_barrier
	v_mfma_f32_16x16x32_bf16 v[6:9], v[146:149], v[202:205], v[6:9]
	v_mfma_f32_16x16x32_bf16 v[6:9], v[150:153], v[206:209], v[6:9]
	s_setprio 0
	ds_read_b128 v[130:133], v184
	ds_read_b128 v[134:137], v184 offset:1024
	ds_read_b128 v[138:141], v184 offset:2048
	ds_read_b128 v[142:145], v184 offset:3072
	ds_read_b128 v[146:149], v185
	ds_read_b128 v[150:153], v185 offset:1024
	ds_read_b128 v[154:157], v185 offset:2048
	ds_read_b128 v[158:161], v185 offset:3072
	ds_read_b128 v[166:169], v183 offset:32768
	ds_read_b128 v[170:173], v183 offset:33792
	ds_read_b128 v[186:189], v183 offset:34816
	ds_read_b128 v[190:193], v183 offset:35840
	ds_read_b128 v[194:197], v183 offset:36864
	ds_read_b128 v[198:201], v183 offset:37888
	ds_read_b128 v[202:205], v183 offset:38912
	ds_read_b128 v[206:209], v183 offset:39936
	s_mov_b32 s79, m0
	s_mov_b32 m0, s34
	s_nop 0
	global_load_lds_dwordx4 v1, s[24:25]
	s_mov_b32 m0, s79
	s_nop 0
	s_mov_b32 s79, m0
	s_mov_b32 m0, s41
	s_nop 0
	global_load_lds_dwordx4 v177, s[24:25]
	s_mov_b32 m0, s79
	s_add_u32 s24, s24, 0x80000
	s_addc_u32 s25, s25, 0
	s_mov_b32 s79, m0
	s_mov_b32 m0, s42
	s_nop 0
	global_load_lds_dwordx4 v1, s[24:25]
	s_mov_b32 m0, s79
	s_nop 0
	s_mov_b32 s79, m0
	s_mov_b32 m0, s43
	s_nop 0
	global_load_lds_dwordx4 v177, s[24:25]
	s_mov_b32 m0, s79
	s_waitcnt vmcnt(8)
	s_waitcnt lgkmcnt(0)
	s_barrier
	s_setprio 1
	s_waitcnt lgkmcnt(7)
	v_mfma_f32_16x16x32_bf16 v[126:129], v[130:133], v[166:169], v[126:129]
	v_mfma_f32_16x16x32_bf16 v[126:129], v[134:137], v[170:173], v[126:129]
	s_waitcnt lgkmcnt(5)
	v_mfma_f32_16x16x32_bf16 v[122:125], v[138:141], v[166:169], v[122:125]
	v_mfma_f32_16x16x32_bf16 v[122:125], v[142:145], v[170:173], v[122:125]
	s_waitcnt lgkmcnt(3)
	v_mfma_f32_16x16x32_bf16 v[114:117], v[138:141], v[186:189], v[114:117]
	v_mfma_f32_16x16x32_bf16 v[114:117], v[142:145], v[190:193], v[114:117]
	s_waitcnt lgkmcnt(1)
	v_mfma_f32_16x16x32_bf16 v[118:121], v[130:133], v[186:189], v[118:121]
	v_mfma_f32_16x16x32_bf16 v[118:121], v[134:137], v[190:193], v[118:121]
	v_mfma_f32_16x16x32_bf16 v[94:97], v[130:133], v[194:197], v[94:97]
	v_mfma_f32_16x16x32_bf16 v[94:97], v[134:137], v[198:201], v[94:97]
	v_mfma_f32_16x16x32_bf16 v[90:93], v[138:141], v[194:197], v[90:93]
	v_mfma_f32_16x16x32_bf16 v[90:93], v[142:145], v[198:201], v[90:93]
	v_mfma_f32_16x16x32_bf16 v[78:81], v[138:141], v[202:205], v[78:81]
	v_mfma_f32_16x16x32_bf16 v[78:81], v[142:145], v[206:209], v[78:81]
	s_waitcnt lgkmcnt(0)
	v_mfma_f32_16x16x32_bf16 v[86:89], v[130:133], v[202:205], v[86:89]
	v_mfma_f32_16x16x32_bf16 v[86:89], v[134:137], v[206:209], v[86:89]
	v_mfma_f32_16x16x32_bf16 v[110:113], v[146:149], v[166:169], v[110:113]
	v_mfma_f32_16x16x32_bf16 v[110:113], v[150:153], v[170:173], v[110:113]
	v_mfma_f32_16x16x32_bf16 v[106:109], v[154:157], v[166:169], v[106:109]
	v_mfma_f32_16x16x32_bf16 v[106:109], v[158:161], v[170:173], v[106:109]
	v_mfma_f32_16x16x32_bf16 v[98:101], v[154:157], v[186:189], v[98:101]
	v_mfma_f32_16x16x32_bf16 v[98:101], v[158:161], v[190:193], v[98:101]
	v_mfma_f32_16x16x32_bf16 v[102:105], v[146:149], v[186:189], v[102:105]
	v_mfma_f32_16x16x32_bf16 v[102:105], v[150:153], v[190:193], v[102:105]
	v_mfma_f32_16x16x32_bf16 v[82:85], v[146:149], v[194:197], v[82:85]
	v_mfma_f32_16x16x32_bf16 v[82:85], v[150:153], v[198:201], v[82:85]
	v_mfma_f32_16x16x32_bf16 v[74:77], v[154:157], v[194:197], v[74:77]
	v_mfma_f32_16x16x32_bf16 v[74:77], v[158:161], v[198:201], v[74:77]
	v_mfma_f32_16x16x32_bf16 v[66:69], v[154:157], v[202:205], v[66:69]
	v_mfma_f32_16x16x32_bf16 v[66:69], v[158:161], v[206:209], v[66:69]
	s_setprio 2
	s_barrier
	v_mfma_f32_16x16x32_bf16 v[70:73], v[146:149], v[202:205], v[70:73]
	v_mfma_f32_16x16x32_bf16 v[70:73], v[150:153], v[206:209], v[70:73]
	s_setprio 0
	ds_read_b128 v[166:169], v183 offset:49152
	ds_read_b128 v[170:173], v183 offset:50176
	ds_read_b128 v[186:189], v183 offset:51200
	ds_read_b128 v[190:193], v183 offset:52224
	ds_read_b128 v[194:197], v183 offset:53248
	ds_read_b128 v[198:201], v183 offset:54272
	ds_read_b128 v[202:205], v183 offset:55296
	ds_read_b128 v[206:209], v183 offset:56320
	s_add_u32 s24, s22, 0x80
	s_addc_u32 s25, s23, 0
	s_mov_b32 s79, m0
	s_mov_b32 m0, s46
	s_nop 0
	global_load_lds_dwordx4 v176, s[24:25]
	s_mov_b32 m0, s79
	s_add_u32 s22, s22, 0x80080
	s_mov_b32 s79, m0
	s_mov_b32 m0, s47
	s_nop 0
	global_load_lds_dwordx4 v178, s[24:25]
	s_mov_b32 m0, s79
	s_addc_u32 s23, s23, 0
	s_mov_b32 s24, m0
	s_mov_b32 m0, s48
	s_nop 0
	global_load_lds_dwordx4 v176, s[22:23]
	s_mov_b32 m0, s24
	s_nop 0
	s_mov_b32 s24, m0
	s_mov_b32 m0, s49
	s_nop 0
	global_load_lds_dwordx4 v178, s[22:23]
	s_mov_b32 m0, s24
	s_waitcnt vmcnt(4)
	s_waitcnt lgkmcnt(0)
	s_barrier
	s_setprio 1
	s_waitcnt lgkmcnt(7)
	v_mfma_f32_16x16x32_bf16 v[62:65], v[130:133], v[166:169], v[62:65]
	v_mfma_f32_16x16x32_bf16 v[62:65], v[134:137], v[170:173], v[62:65]
	s_waitcnt lgkmcnt(5)
	v_mfma_f32_16x16x32_bf16 v[58:61], v[138:141], v[166:169], v[58:61]
	v_mfma_f32_16x16x32_bf16 v[58:61], v[142:145], v[170:173], v[58:61]
	s_waitcnt lgkmcnt(3)
	v_mfma_f32_16x16x32_bf16 v[42:45], v[138:141], v[186:189], v[42:45]
	v_mfma_f32_16x16x32_bf16 v[42:45], v[142:145], v[190:193], v[42:45]
	s_waitcnt lgkmcnt(1)
	v_mfma_f32_16x16x32_bf16 v[46:49], v[130:133], v[186:189], v[46:49]
	v_mfma_f32_16x16x32_bf16 v[46:49], v[134:137], v[190:193], v[46:49]
	v_mfma_f32_16x16x32_bf16 v[30:33], v[130:133], v[194:197], v[30:33]
	v_mfma_f32_16x16x32_bf16 v[30:33], v[134:137], v[198:201], v[30:33]
	v_mfma_f32_16x16x32_bf16 v[26:29], v[138:141], v[194:197], v[26:29]
	v_mfma_f32_16x16x32_bf16 v[26:29], v[142:145], v[198:201], v[26:29]
	v_mfma_f32_16x16x32_bf16 v[10:13], v[138:141], v[202:205], v[10:13]
	v_mfma_f32_16x16x32_bf16 v[10:13], v[142:145], v[206:209], v[10:13]
	s_waitcnt lgkmcnt(0)
	v_mfma_f32_16x16x32_bf16 v[14:17], v[130:133], v[202:205], v[14:17]
	v_mfma_f32_16x16x32_bf16 v[14:17], v[134:137], v[206:209], v[14:17]
	v_mfma_f32_16x16x32_bf16 v[54:57], v[146:149], v[166:169], v[54:57]
	v_mfma_f32_16x16x32_bf16 v[54:57], v[150:153], v[170:173], v[54:57]
	v_mfma_f32_16x16x32_bf16 v[50:53], v[154:157], v[166:169], v[50:53]
	v_mfma_f32_16x16x32_bf16 v[50:53], v[158:161], v[170:173], v[50:53]
	v_mfma_f32_16x16x32_bf16 v[34:37], v[154:157], v[186:189], v[34:37]
	v_mfma_f32_16x16x32_bf16 v[34:37], v[158:161], v[190:193], v[34:37]
	v_mfma_f32_16x16x32_bf16 v[38:41], v[146:149], v[186:189], v[38:41]
	v_mfma_f32_16x16x32_bf16 v[38:41], v[150:153], v[190:193], v[38:41]
	v_mfma_f32_16x16x32_bf16 v[22:25], v[146:149], v[194:197], v[22:25]
	v_mfma_f32_16x16x32_bf16 v[22:25], v[150:153], v[198:201], v[22:25]
	v_mfma_f32_16x16x32_bf16 v[18:21], v[154:157], v[194:197], v[18:21]
	v_mfma_f32_16x16x32_bf16 v[18:21], v[158:161], v[198:201], v[18:21]
	v_mfma_f32_16x16x32_bf16 v[2:5], v[154:157], v[202:205], v[2:5]
	v_mfma_f32_16x16x32_bf16 v[2:5], v[158:161], v[206:209], v[2:5]
	s_setprio 2
	s_barrier
	v_mfma_f32_16x16x32_bf16 v[6:9], v[146:149], v[202:205], v[6:9]
	v_mfma_f32_16x16x32_bf16 v[6:9], v[150:153], v[206:209], v[6:9]
	s_setprio 0
	s_add_i32 s78, s78, 2
	s_add_u32 s74, s74, 0x100
	s_addc_u32 s75, s75, 0
	s_add_u32 s20, s20, 0x100
	s_addc_u32 s21, s21, 0
	s_add_u32 s76, s76, 0x100
	s_addc_u32 s77, s77, 0
	s_cmp_gt_u32 s78, 29
	s_cbranch_scc0 .LBB0_1053
	s_and_b64 vcc, exec, s[8:9]
	s_cbranch_vccz .LBB0_1056
	s_barrier

.LBB0_1223:
	s_ashr_i32 s11, s10, 31
	s_lshl_b64 s[12:13], s[10:11], 20
	s_add_u32 s12, s26, s12
	s_addc_u32 s13, s27, s13
	s_and_b64 s[14:15], s[2:3], exec
	s_cselect_b32 s11, s13, s21
	s_cselect_b32 s66, s12, s20
	s_ashr_i32 s9, s8, 31
	s_lshl_b64 s[14:15], s[8:9], 20
	s_add_u32 s14, s28, s14
	s_addc_u32 s15, s29, s15
	s_and_b64 s[22:23], s[2:3], exec
	s_cselect_b32 s9, s15, s19
	s_cselect_b32 s67, s14, s18
	s_add_u32 s73, s18, 0x100
	s_addc_u32 s74, s19, 0
	s_add_u32 s18, s20, 0x80080
	s_addc_u32 s19, s21, 0
	s_add_u32 s75, s20, 0x100
	s_addc_u32 s76, s21, 0
	s_mov_b32 s77, -2
	ds_read_b128 v[148:151], v143
	ds_read_b128 v[152:155], v143 offset:1024
	ds_read_b128 v[156:159], v143 offset:2048
	ds_read_b128 v[160:163], v143 offset:3072
	ds_read_b128 v[164:167], v144
	ds_read_b128 v[168:171], v144 offset:1024
	ds_read_b128 v[172:175], v144 offset:2048
	ds_read_b128 v[176:179], v144 offset:3072
	s_cmp_eq_u32 s77, 28
	s_cselect_b32 s21, s9, s74
	s_cselect_b32 s20, s67, s73
	s_cselect_b32 s23, s11, s76
	s_cselect_b32 s22, s66, s75
	ds_read_b128 v[180:183], v145
	ds_read_b128 v[184:187], v145 offset:1024
	ds_read_b128 v[188:191], v145 offset:2048
	ds_read_b128 v[192:195], v145 offset:3072
	ds_read_b128 v[196:199], v145 offset:4096
	ds_read_b128 v[200:203], v145 offset:5120
	ds_read_b128 v[204:207], v145 offset:6144
	ds_read_b128 v[208:211], v145 offset:7168
	s_add_u32 s78, s18, 0xfff80000
	s_addc_u32 s79, s19, -1
	s_mov_b32 s80, m0
	s_mov_b32 m0, s56
	s_nop 0
	global_load_lds_dwordx4 v138, s[78:79]
	s_mov_b32 m0, s80
	s_nop 0
	s_mov_b32 s80, m0
	s_mov_b32 m0, s59
	s_nop 0
	global_load_lds_dwordx4 v140, s[78:79]
	s_mov_b32 m0, s80
	s_mov_b32 s78, m0
	s_mov_b32 m0, s57
	s_nop 0
	global_load_lds_dwordx4 v138, s[18:19]
	s_mov_b32 m0, s78
	s_nop 0
	s_mov_b32 s78, m0
	s_mov_b32 m0, s64
	s_nop 0
	global_load_lds_dwordx4 v140, s[18:19]
	s_mov_b32 m0, s78
	s_waitcnt vmcnt(8)
	s_waitcnt lgkmcnt(0)
	s_barrier
	s_setprio 1
	s_waitcnt lgkmcnt(7)
	v_mfma_f32_16x16x32_bf16 v[126:129], v[148:151], v[180:183], 0
	v_mfma_f32_16x16x32_bf16 v[126:129], v[152:155], v[184:187], v[126:129]
	s_waitcnt lgkmcnt(5)
	v_mfma_f32_16x16x32_bf16 v[122:125], v[156:159], v[180:183], 0
	v_mfma_f32_16x16x32_bf16 v[122:125], v[160:163], v[184:187], v[122:125]
	s_waitcnt lgkmcnt(3)
	v_mfma_f32_16x16x32_bf16 v[106:109], v[156:159], v[188:191], 0
	v_mfma_f32_16x16x32_bf16 v[106:109], v[160:163], v[192:195], v[106:109]
	s_waitcnt lgkmcnt(1)
	v_mfma_f32_16x16x32_bf16 v[110:113], v[148:151], v[188:191], 0
	v_mfma_f32_16x16x32_bf16 v[110:113], v[152:155], v[192:195], v[110:113]
	v_mfma_f32_16x16x32_bf16 v[94:97], v[148:151], v[196:199], 0
	v_mfma_f32_16x16x32_bf16 v[94:97], v[152:155], v[200:203], v[94:97]
	v_mfma_f32_16x16x32_bf16 v[90:93], v[156:159], v[196:199], 0
	v_mfma_f32_16x16x32_bf16 v[90:93], v[160:163], v[200:203], v[90:93]
	v_mfma_f32_16x16x32_bf16 v[74:77], v[156:159], v[204:207], 0
	v_mfma_f32_16x16x32_bf16 v[74:77], v[160:163], v[208:211], v[74:77]
	s_waitcnt lgkmcnt(0)
	v_mfma_f32_16x16x32_bf16 v[78:81], v[148:151], v[204:207], 0
	v_mfma_f32_16x16x32_bf16 v[78:81], v[152:155], v[208:211], v[78:81]
	v_mfma_f32_16x16x32_bf16 v[118:121], v[164:167], v[180:183], 0
	v_mfma_f32_16x16x32_bf16 v[118:121], v[168:171], v[184:187], v[118:121]
	v_mfma_f32_16x16x32_bf16 v[114:117], v[172:175], v[180:183], 0
	v_mfma_f32_16x16x32_bf16 v[114:117], v[176:179], v[184:187], v[114:117]
	v_mfma_f32_16x16x32_bf16 v[98:101], v[172:175], v[188:191], 0
	v_mfma_f32_16x16x32_bf16 v[98:101], v[176:179], v[192:195], v[98:101]
	v_mfma_f32_16x16x32_bf16 v[102:105], v[164:167], v[188:191], 0
	v_mfma_f32_16x16x32_bf16 v[102:105], v[168:171], v[192:195], v[102:105]
	v_mfma_f32_16x16x32_bf16 v[86:89], v[164:167], v[196:199], 0
	v_mfma_f32_16x16x32_bf16 v[86:89], v[168:171], v[200:203], v[86:89]
	v_mfma_f32_16x16x32_bf16 v[82:85], v[172:175], v[196:199], 0
	v_mfma_f32_16x16x32_bf16 v[82:85], v[176:179], v[200:203], v[82:85]
	v_mfma_f32_16x16x32_bf16 v[66:69], v[172:175], v[204:207], 0
	v_mfma_f32_16x16x32_bf16 v[66:69], v[176:179], v[208:211], v[66:69]
	s_setprio 2
	s_barrier
	v_mfma_f32_16x16x32_bf16 v[70:73], v[164:167], v[204:207], 0
	v_mfma_f32_16x16x32_bf16 v[70:73], v[168:171], v[208:211], v[70:73]
	s_setprio 0
	ds_read_b128 v[180:183], v145 offset:16384
	ds_read_b128 v[184:187], v145 offset:17408
	ds_read_b128 v[188:191], v145 offset:18432
	ds_read_b128 v[192:195], v145 offset:19456
	ds_read_b128 v[196:199], v145 offset:20480
	ds_read_b128 v[200:203], v145 offset:21504
	ds_read_b128 v[204:207], v145 offset:22528
	ds_read_b128 v[208:211], v145 offset:23552
	s_mov_b32 s78, m0
	s_mov_b32 m0, s35
	s_nop 0
	global_load_lds_dwordx4 v139, s[20:21]
	s_mov_b32 m0, s78
	s_nop 0
	s_mov_b32 s78, m0
	s_mov_b32 m0, s36
	s_nop 0
	global_load_lds_dwordx4 v141, s[20:21]
	s_mov_b32 m0, s78
	s_add_u32 s78, s20, 0x80000
	s_addc_u32 s79, s21, 0
	s_mov_b32 s80, m0
	s_mov_b32 m0, s37
	s_nop 0
	global_load_lds_dwordx4 v139, s[78:79]
	s_mov_b32 m0, s80
	s_nop 0
	s_mov_b32 s80, m0
	s_mov_b32 m0, s40
	s_nop 0
	global_load_lds_dwordx4 v141, s[78:79]
	s_mov_b32 m0, s80
	s_waitcnt vmcnt(4)
	s_waitcnt lgkmcnt(0)
	s_barrier
	s_setprio 1
	s_waitcnt lgkmcnt(7)
	v_mfma_f32_16x16x32_bf16 v[62:65], v[148:151], v[180:183], 0
	v_mfma_f32_16x16x32_bf16 v[62:65], v[152:155], v[184:187], v[62:65]
	s_waitcnt lgkmcnt(5)
	v_mfma_f32_16x16x32_bf16 v[58:61], v[156:159], v[180:183], 0
	v_mfma_f32_16x16x32_bf16 v[58:61], v[160:163], v[184:187], v[58:61]
	s_waitcnt lgkmcnt(3)
	v_mfma_f32_16x16x32_bf16 v[42:45], v[156:159], v[188:191], 0
	v_mfma_f32_16x16x32_bf16 v[42:45], v[160:163], v[192:195], v[42:45]
	s_waitcnt lgkmcnt(1)
	v_mfma_f32_16x16x32_bf16 v[46:49], v[148:151], v[188:191], 0
	v_mfma_f32_16x16x32_bf16 v[46:49], v[152:155], v[192:195], v[46:49]
	v_mfma_f32_16x16x32_bf16 v[30:33], v[148:151], v[196:199], 0
	v_mfma_f32_16x16x32_bf16 v[30:33], v[152:155], v[200:203], v[30:33]
	v_mfma_f32_16x16x32_bf16 v[26:29], v[156:159], v[196:199], 0
	v_mfma_f32_16x16x32_bf16 v[26:29], v[160:163], v[200:203], v[26:29]
	v_mfma_f32_16x16x32_bf16 v[10:13], v[156:159], v[204:207], 0
	v_mfma_f32_16x16x32_bf16 v[10:13], v[160:163], v[208:211], v[10:13]
	s_waitcnt lgkmcnt(0)
	v_mfma_f32_16x16x32_bf16 v[14:17], v[148:151], v[204:207], 0
	v_mfma_f32_16x16x32_bf16 v[14:17], v[152:155], v[208:211], v[14:17]
	v_mfma_f32_16x16x32_bf16 v[54:57], v[164:167], v[180:183], 0
	v_mfma_f32_16x16x32_bf16 v[54:57], v[168:171], v[184:187], v[54:57]
	v_mfma_f32_16x16x32_bf16 v[50:53], v[172:175], v[180:183], 0
	v_mfma_f32_16x16x32_bf16 v[50:53], v[176:179], v[184:187], v[50:53]
	v_mfma_f32_16x16x32_bf16 v[34:37], v[172:175], v[188:191], 0
	v_mfma_f32_16x16x32_bf16 v[34:37], v[176:179], v[192:195], v[34:37]
	v_mfma_f32_16x16x32_bf16 v[38:41], v[164:167], v[188:191], 0
	v_mfma_f32_16x16x32_bf16 v[38:41], v[168:171], v[192:195], v[38:41]
	v_mfma_f32_16x16x32_bf16 v[22:25], v[164:167], v[196:199], 0
	v_mfma_f32_16x16x32_bf16 v[22:25], v[168:171], v[200:203], v[22:25]
	v_mfma_f32_16x16x32_bf16 v[18:21], v[172:175], v[196:199], 0
	v_mfma_f32_16x16x32_bf16 v[18:21], v[176:179], v[200:203], v[18:21]
	v_mfma_f32_16x16x32_bf16 v[2:5], v[172:175], v[204:207], 0
	v_mfma_f32_16x16x32_bf16 v[2:5], v[176:179], v[208:211], v[2:5]
	s_setprio 2
	s_barrier
	v_mfma_f32_16x16x32_bf16 v[6:9], v[164:167], v[204:207], 0
	v_mfma_f32_16x16x32_bf16 v[6:9], v[168:171], v[208:211], v[6:9]
	s_setprio 0
	ds_read_b128 v[148:151], v146
	ds_read_b128 v[152:155], v146 offset:1024
	ds_read_b128 v[156:159], v146 offset:2048
	ds_read_b128 v[160:163], v146 offset:3072
	ds_read_b128 v[164:167], v147
	ds_read_b128 v[168:171], v147 offset:1024
	ds_read_b128 v[172:175], v147 offset:2048
	ds_read_b128 v[176:179], v147 offset:3072
	ds_read_b128 v[180:183], v145 offset:32768
	ds_read_b128 v[184:187], v145 offset:33792
	ds_read_b128 v[188:191], v145 offset:34816
	ds_read_b128 v[192:195], v145 offset:35840
	ds_read_b128 v[196:199], v145 offset:36864
	ds_read_b128 v[200:203], v145 offset:37888
	ds_read_b128 v[204:207], v145 offset:38912
	ds_read_b128 v[208:211], v145 offset:39936
	s_mov_b32 s78, m0
	s_mov_b32 m0, s31
	s_nop 0
	global_load_lds_dwordx4 v138, s[22:23]
	s_mov_b32 m0, s78
	s_nop 0
	s_mov_b32 s78, m0
	s_mov_b32 m0, s41
	s_nop 0
	global_load_lds_dwordx4 v140, s[22:23]
	s_mov_b32 m0, s78
	s_add_u32 s22, s22, 0x80000
	s_addc_u32 s23, s23, 0
	s_mov_b32 s78, m0
	s_mov_b32 m0, s42
	s_nop 0
	global_load_lds_dwordx4 v138, s[22:23]
	s_mov_b32 m0, s78
	s_nop 0
	s_mov_b32 s78, m0
	s_mov_b32 m0, s43
	s_nop 0
	global_load_lds_dwordx4 v140, s[22:23]
	s_mov_b32 m0, s78
	s_waitcnt vmcnt(8)
	s_waitcnt lgkmcnt(0)
	s_barrier
	s_setprio 1
	s_waitcnt lgkmcnt(7)
	v_mfma_f32_16x16x32_bf16 v[126:129], v[148:151], v[180:183], v[126:129]
	v_mfma_f32_16x16x32_bf16 v[126:129], v[152:155], v[184:187], v[126:129]
	s_waitcnt lgkmcnt(5)
	v_mfma_f32_16x16x32_bf16 v[122:125], v[156:159], v[180:183], v[122:125]
	v_mfma_f32_16x16x32_bf16 v[122:125], v[160:163], v[184:187], v[122:125]
	s_waitcnt lgkmcnt(3)
	v_mfma_f32_16x16x32_bf16 v[106:109], v[156:159], v[188:191], v[106:109]
	v_mfma_f32_16x16x32_bf16 v[106:109], v[160:163], v[192:195], v[106:109]
	s_waitcnt lgkmcnt(1)
	v_mfma_f32_16x16x32_bf16 v[110:113], v[148:151], v[188:191], v[110:113]
	v_mfma_f32_16x16x32_bf16 v[110:113], v[152:155], v[192:195], v[110:113]
	v_mfma_f32_16x16x32_bf16 v[94:97], v[148:151], v[196:199], v[94:97]
	v_mfma_f32_16x16x32_bf16 v[94:97], v[152:155], v[200:203], v[94:97]
	v_mfma_f32_16x16x32_bf16 v[90:93], v[156:159], v[196:199], v[90:93]
	v_mfma_f32_16x16x32_bf16 v[90:93], v[160:163], v[200:203], v[90:93]
	v_mfma_f32_16x16x32_bf16 v[74:77], v[156:159], v[204:207], v[74:77]
	v_mfma_f32_16x16x32_bf16 v[74:77], v[160:163], v[208:211], v[74:77]
	s_waitcnt lgkmcnt(0)
	v_mfma_f32_16x16x32_bf16 v[78:81], v[148:151], v[204:207], v[78:81]
	v_mfma_f32_16x16x32_bf16 v[78:81], v[152:155], v[208:211], v[78:81]
	v_mfma_f32_16x16x32_bf16 v[118:121], v[164:167], v[180:183], v[118:121]
	v_mfma_f32_16x16x32_bf16 v[118:121], v[168:171], v[184:187], v[118:121]
	v_mfma_f32_16x16x32_bf16 v[114:117], v[172:175], v[180:183], v[114:117]
	v_mfma_f32_16x16x32_bf16 v[114:117], v[176:179], v[184:187], v[114:117]
	v_mfma_f32_16x16x32_bf16 v[98:101], v[172:175], v[188:191], v[98:101]
	v_mfma_f32_16x16x32_bf16 v[98:101], v[176:179], v[192:195], v[98:101]
	v_mfma_f32_16x16x32_bf16 v[102:105], v[164:167], v[188:191], v[102:105]
	v_mfma_f32_16x16x32_bf16 v[102:105], v[168:171], v[192:195], v[102:105]
	v_mfma_f32_16x16x32_bf16 v[86:89], v[164:167], v[196:199], v[86:89]
	v_mfma_f32_16x16x32_bf16 v[86:89], v[168:171], v[200:203], v[86:89]
	v_mfma_f32_16x16x32_bf16 v[82:85], v[172:175], v[196:199], v[82:85]
	v_mfma_f32_16x16x32_bf16 v[82:85], v[176:179], v[200:203], v[82:85]
	v_mfma_f32_16x16x32_bf16 v[66:69], v[172:175], v[204:207], v[66:69]
	v_mfma_f32_16x16x32_bf16 v[66:69], v[176:179], v[208:211], v[66:69]
	s_setprio 2
	s_barrier
	v_mfma_f32_16x16x32_bf16 v[70:73], v[164:167], v[204:207], v[70:73]
	v_mfma_f32_16x16x32_bf16 v[70:73], v[168:171], v[208:211], v[70:73]
	s_setprio 0
	ds_read_b128 v[180:183], v145 offset:49152
	ds_read_b128 v[184:187], v145 offset:50176
	ds_read_b128 v[188:191], v145 offset:51200
	ds_read_b128 v[192:195], v145 offset:52224
	ds_read_b128 v[196:199], v145 offset:53248
	ds_read_b128 v[200:203], v145 offset:54272
	ds_read_b128 v[204:207], v145 offset:55296
	ds_read_b128 v[208:211], v145 offset:56320
	s_add_u32 s22, s20, 0x80
	s_addc_u32 s23, s21, 0
	s_mov_b32 s78, m0
	s_mov_b32 m0, s46
	s_nop 0
	global_load_lds_dwordx4 v139, s[22:23]
	s_mov_b32 m0, s78
	s_add_u32 s20, s20, 0x80080
	s_mov_b32 s78, m0
	s_mov_b32 m0, s47
	s_nop 0
	global_load_lds_dwordx4 v141, s[22:23]
	s_mov_b32 m0, s78
	s_addc_u32 s21, s21, 0
	s_mov_b32 s22, m0
	s_mov_b32 m0, s48
	s_nop 0
	global_load_lds_dwordx4 v139, s[20:21]
	s_mov_b32 m0, s22
	s_nop 0
	s_mov_b32 s22, m0
	s_mov_b32 m0, s49
	s_nop 0
	global_load_lds_dwordx4 v141, s[20:21]
	s_mov_b32 m0, s22
	s_waitcnt vmcnt(4)
	s_waitcnt lgkmcnt(0)
	s_barrier
	s_setprio 1
	s_waitcnt lgkmcnt(7)
	v_mfma_f32_16x16x32_bf16 v[62:65], v[148:151], v[180:183], v[62:65]
	v_mfma_f32_16x16x32_bf16 v[62:65], v[152:155], v[184:187], v[62:65]
	s_waitcnt lgkmcnt(5)
	v_mfma_f32_16x16x32_bf16 v[58:61], v[156:159], v[180:183], v[58:61]
	v_mfma_f32_16x16x32_bf16 v[58:61], v[160:163], v[184:187], v[58:61]
	s_waitcnt lgkmcnt(3)
	v_mfma_f32_16x16x32_bf16 v[42:45], v[156:159], v[188:191], v[42:45]
	v_mfma_f32_16x16x32_bf16 v[42:45], v[160:163], v[192:195], v[42:45]
	s_waitcnt lgkmcnt(1)
	v_mfma_f32_16x16x32_bf16 v[46:49], v[148:151], v[188:191], v[46:49]
	v_mfma_f32_16x16x32_bf16 v[46:49], v[152:155], v[192:195], v[46:49]
	v_mfma_f32_16x16x32_bf16 v[30:33], v[148:151], v[196:199], v[30:33]
	v_mfma_f32_16x16x32_bf16 v[30:33], v[152:155], v[200:203], v[30:33]
	v_mfma_f32_16x16x32_bf16 v[26:29], v[156:159], v[196:199], v[26:29]
	v_mfma_f32_16x16x32_bf16 v[26:29], v[160:163], v[200:203], v[26:29]
	v_mfma_f32_16x16x32_bf16 v[10:13], v[156:159], v[204:207], v[10:13]
	v_mfma_f32_16x16x32_bf16 v[10:13], v[160:163], v[208:211], v[10:13]
	s_waitcnt lgkmcnt(0)
	v_mfma_f32_16x16x32_bf16 v[14:17], v[148:151], v[204:207], v[14:17]
	v_mfma_f32_16x16x32_bf16 v[14:17], v[152:155], v[208:211], v[14:17]
	v_mfma_f32_16x16x32_bf16 v[54:57], v[164:167], v[180:183], v[54:57]
	v_mfma_f32_16x16x32_bf16 v[54:57], v[168:171], v[184:187], v[54:57]
	v_mfma_f32_16x16x32_bf16 v[50:53], v[172:175], v[180:183], v[50:53]
	v_mfma_f32_16x16x32_bf16 v[50:53], v[176:179], v[184:187], v[50:53]
	v_mfma_f32_16x16x32_bf16 v[34:37], v[172:175], v[188:191], v[34:37]
	v_mfma_f32_16x16x32_bf16 v[34:37], v[176:179], v[192:195], v[34:37]
	v_mfma_f32_16x16x32_bf16 v[38:41], v[164:167], v[188:191], v[38:41]
	v_mfma_f32_16x16x32_bf16 v[38:41], v[168:171], v[192:195], v[38:41]
	v_mfma_f32_16x16x32_bf16 v[22:25], v[164:167], v[196:199], v[22:25]
	v_mfma_f32_16x16x32_bf16 v[22:25], v[168:171], v[200:203], v[22:25]
	v_mfma_f32_16x16x32_bf16 v[18:21], v[172:175], v[196:199], v[18:21]
	v_mfma_f32_16x16x32_bf16 v[18:21], v[176:179], v[200:203], v[18:21]
	v_mfma_f32_16x16x32_bf16 v[2:5], v[172:175], v[204:207], v[2:5]
	v_mfma_f32_16x16x32_bf16 v[2:5], v[176:179], v[208:211], v[2:5]
	s_setprio 2
	s_barrier
	v_mfma_f32_16x16x32_bf16 v[6:9], v[164:167], v[204:207], v[6:9]
	v_mfma_f32_16x16x32_bf16 v[6:9], v[168:171], v[208:211], v[6:9]
	s_setprio 0
	s_add_i32 s77, s77, 2
	s_add_u32 s73, s73, 0x100
	s_addc_u32 s74, s74, 0
	s_add_u32 s18, s18, 0x100
	s_addc_u32 s19, s19, 0
	s_add_u32 s75, s75, 0x100
	s_addc_u32 s76, s76, 0
	s_cmp_gt_u32 s77, 29
	.p2align 6
.LBB0_1224:
	ds_read_b128 v[148:151], v143
	ds_read_b128 v[152:155], v143 offset:1024
	ds_read_b128 v[156:159], v143 offset:2048
	ds_read_b128 v[160:163], v143 offset:3072
	ds_read_b128 v[164:167], v144
	ds_read_b128 v[168:171], v144 offset:1024
	ds_read_b128 v[172:175], v144 offset:2048
	ds_read_b128 v[176:179], v144 offset:3072
	s_cmp_eq_u32 s77, 28
	s_cselect_b32 s21, s9, s74
	s_cselect_b32 s20, s67, s73
	s_cselect_b32 s23, s11, s76
	s_cselect_b32 s22, s66, s75
	ds_read_b128 v[180:183], v145
	ds_read_b128 v[184:187], v145 offset:1024
	ds_read_b128 v[188:191], v145 offset:2048
	ds_read_b128 v[192:195], v145 offset:3072
	ds_read_b128 v[196:199], v145 offset:4096
	ds_read_b128 v[200:203], v145 offset:5120
	ds_read_b128 v[204:207], v145 offset:6144
	ds_read_b128 v[208:211], v145 offset:7168
	s_add_u32 s78, s18, 0xfff80000
	s_addc_u32 s79, s19, -1
	s_mov_b32 s80, m0
	s_mov_b32 m0, s56
	s_nop 0
	global_load_lds_dwordx4 v138, s[78:79]
	s_mov_b32 m0, s80
	s_nop 0
	s_mov_b32 s80, m0
	s_mov_b32 m0, s59
	s_nop 0
	global_load_lds_dwordx4 v140, s[78:79]
	s_mov_b32 m0, s80
	s_mov_b32 s78, m0
	s_mov_b32 m0, s57
	s_nop 0
	global_load_lds_dwordx4 v138, s[18:19]
	s_mov_b32 m0, s78
	s_nop 0
	s_mov_b32 s78, m0
	s_mov_b32 m0, s64
	s_nop 0
	global_load_lds_dwordx4 v140, s[18:19]
	s_mov_b32 m0, s78
	s_waitcnt vmcnt(8)
	s_waitcnt lgkmcnt(0)
	s_barrier
	s_setprio 1
	s_waitcnt lgkmcnt(7)
	v_mfma_f32_16x16x32_bf16 v[126:129], v[148:151], v[180:183], v[126:129]
	v_mfma_f32_16x16x32_bf16 v[126:129], v[152:155], v[184:187], v[126:129]
	s_waitcnt lgkmcnt(5)
	v_mfma_f32_16x16x32_bf16 v[122:125], v[156:159], v[180:183], v[122:125]
	v_mfma_f32_16x16x32_bf16 v[122:125], v[160:163], v[184:187], v[122:125]
	s_waitcnt lgkmcnt(3)
	v_mfma_f32_16x16x32_bf16 v[106:109], v[156:159], v[188:191], v[106:109]
	v_mfma_f32_16x16x32_bf16 v[106:109], v[160:163], v[192:195], v[106:109]
	s_waitcnt lgkmcnt(1)
	v_mfma_f32_16x16x32_bf16 v[110:113], v[148:151], v[188:191], v[110:113]
	v_mfma_f32_16x16x32_bf16 v[110:113], v[152:155], v[192:195], v[110:113]
	v_mfma_f32_16x16x32_bf16 v[94:97], v[148:151], v[196:199], v[94:97]
	v_mfma_f32_16x16x32_bf16 v[94:97], v[152:155], v[200:203], v[94:97]
	v_mfma_f32_16x16x32_bf16 v[90:93], v[156:159], v[196:199], v[90:93]
	v_mfma_f32_16x16x32_bf16 v[90:93], v[160:163], v[200:203], v[90:93]
	v_mfma_f32_16x16x32_bf16 v[74:77], v[156:159], v[204:207], v[74:77]
	v_mfma_f32_16x16x32_bf16 v[74:77], v[160:163], v[208:211], v[74:77]
	s_waitcnt lgkmcnt(0)
	v_mfma_f32_16x16x32_bf16 v[78:81], v[148:151], v[204:207], v[78:81]
	v_mfma_f32_16x16x32_bf16 v[78:81], v[152:155], v[208:211], v[78:81]
	v_mfma_f32_16x16x32_bf16 v[118:121], v[164:167], v[180:183], v[118:121]
	v_mfma_f32_16x16x32_bf16 v[118:121], v[168:171], v[184:187], v[118:121]
	v_mfma_f32_16x16x32_bf16 v[114:117], v[172:175], v[180:183], v[114:117]
	v_mfma_f32_16x16x32_bf16 v[114:117], v[176:179], v[184:187], v[114:117]
	v_mfma_f32_16x16x32_bf16 v[98:101], v[172:175], v[188:191], v[98:101]
	v_mfma_f32_16x16x32_bf16 v[98:101], v[176:179], v[192:195], v[98:101]
	v_mfma_f32_16x16x32_bf16 v[102:105], v[164:167], v[188:191], v[102:105]
	v_mfma_f32_16x16x32_bf16 v[102:105], v[168:171], v[192:195], v[102:105]
	v_mfma_f32_16x16x32_bf16 v[86:89], v[164:167], v[196:199], v[86:89]
	v_mfma_f32_16x16x32_bf16 v[86:89], v[168:171], v[200:203], v[86:89]
	v_mfma_f32_16x16x32_bf16 v[82:85], v[172:175], v[196:199], v[82:85]
	v_mfma_f32_16x16x32_bf16 v[82:85], v[176:179], v[200:203], v[82:85]
	v_mfma_f32_16x16x32_bf16 v[66:69], v[172:175], v[204:207], v[66:69]
	v_mfma_f32_16x16x32_bf16 v[66:69], v[176:179], v[208:211], v[66:69]
	s_setprio 2
	s_barrier
	v_mfma_f32_16x16x32_bf16 v[70:73], v[164:167], v[204:207], v[70:73]
	v_mfma_f32_16x16x32_bf16 v[70:73], v[168:171], v[208:211], v[70:73]
	s_setprio 0
	ds_read_b128 v[180:183], v145 offset:16384
	ds_read_b128 v[184:187], v145 offset:17408
	ds_read_b128 v[188:191], v145 offset:18432
	ds_read_b128 v[192:195], v145 offset:19456
	ds_read_b128 v[196:199], v145 offset:20480
	ds_read_b128 v[200:203], v145 offset:21504
	ds_read_b128 v[204:207], v145 offset:22528
	ds_read_b128 v[208:211], v145 offset:23552
	s_mov_b32 s78, m0
	s_mov_b32 m0, s35
	s_nop 0
	global_load_lds_dwordx4 v139, s[20:21]
	s_mov_b32 m0, s78
	s_nop 0
	s_mov_b32 s78, m0
	s_mov_b32 m0, s36
	s_nop 0
	global_load_lds_dwordx4 v141, s[20:21]
	s_mov_b32 m0, s78
	s_add_u32 s78, s20, 0x80000
	s_addc_u32 s79, s21, 0
	s_mov_b32 s80, m0
	s_mov_b32 m0, s37
	s_nop 0
	global_load_lds_dwordx4 v139, s[78:79]
	s_mov_b32 m0, s80
	s_nop 0
	s_mov_b32 s80, m0
	s_mov_b32 m0, s40
	s_nop 0
	global_load_lds_dwordx4 v141, s[78:79]
	s_mov_b32 m0, s80
	s_waitcnt vmcnt(4)
	s_waitcnt lgkmcnt(0)
	s_barrier
	s_setprio 1
	s_waitcnt lgkmcnt(7)
	v_mfma_f32_16x16x32_bf16 v[62:65], v[148:151], v[180:183], v[62:65]
	v_mfma_f32_16x16x32_bf16 v[62:65], v[152:155], v[184:187], v[62:65]
	s_waitcnt lgkmcnt(5)
	v_mfma_f32_16x16x32_bf16 v[58:61], v[156:159], v[180:183], v[58:61]
	v_mfma_f32_16x16x32_bf16 v[58:61], v[160:163], v[184:187], v[58:61]
	s_waitcnt lgkmcnt(3)
	v_mfma_f32_16x16x32_bf16 v[42:45], v[156:159], v[188:191], v[42:45]
	v_mfma_f32_16x16x32_bf16 v[42:45], v[160:163], v[192:195], v[42:45]
	s_waitcnt lgkmcnt(1)
	v_mfma_f32_16x16x32_bf16 v[46:49], v[148:151], v[188:191], v[46:49]
	v_mfma_f32_16x16x32_bf16 v[46:49], v[152:155], v[192:195], v[46:49]
	v_mfma_f32_16x16x32_bf16 v[30:33], v[148:151], v[196:199], v[30:33]
	v_mfma_f32_16x16x32_bf16 v[30:33], v[152:155], v[200:203], v[30:33]
	v_mfma_f32_16x16x32_bf16 v[26:29], v[156:159], v[196:199], v[26:29]
	v_mfma_f32_16x16x32_bf16 v[26:29], v[160:163], v[200:203], v[26:29]
	v_mfma_f32_16x16x32_bf16 v[10:13], v[156:159], v[204:207], v[10:13]
	v_mfma_f32_16x16x32_bf16 v[10:13], v[160:163], v[208:211], v[10:13]
	s_waitcnt lgkmcnt(0)
	v_mfma_f32_16x16x32_bf16 v[14:17], v[148:151], v[204:207], v[14:17]
	v_mfma_f32_16x16x32_bf16 v[14:17], v[152:155], v[208:211], v[14:17]
	v_mfma_f32_16x16x32_bf16 v[54:57], v[164:167], v[180:183], v[54:57]
	v_mfma_f32_16x16x32_bf16 v[54:57], v[168:171], v[184:187], v[54:57]
	v_mfma_f32_16x16x32_bf16 v[50:53], v[172:175], v[180:183], v[50:53]
	v_mfma_f32_16x16x32_bf16 v[50:53], v[176:179], v[184:187], v[50:53]
	v_mfma_f32_16x16x32_bf16 v[34:37], v[172:175], v[188:191], v[34:37]
	v_mfma_f32_16x16x32_bf16 v[34:37], v[176:179], v[192:195], v[34:37]
	v_mfma_f32_16x16x32_bf16 v[38:41], v[164:167], v[188:191], v[38:41]
	v_mfma_f32_16x16x32_bf16 v[38:41], v[168:171], v[192:195], v[38:41]
	v_mfma_f32_16x16x32_bf16 v[22:25], v[164:167], v[196:199], v[22:25]
	v_mfma_f32_16x16x32_bf16 v[22:25], v[168:171], v[200:203], v[22:25]
	v_mfma_f32_16x16x32_bf16 v[18:21], v[172:175], v[196:199], v[18:21]
	v_mfma_f32_16x16x32_bf16 v[18:21], v[176:179], v[200:203], v[18:21]
	v_mfma_f32_16x16x32_bf16 v[2:5], v[172:175], v[204:207], v[2:5]
	v_mfma_f32_16x16x32_bf16 v[2:5], v[176:179], v[208:211], v[2:5]
	s_setprio 2
	s_barrier
	v_mfma_f32_16x16x32_bf16 v[6:9], v[164:167], v[204:207], v[6:9]
	v_mfma_f32_16x16x32_bf16 v[6:9], v[168:171], v[208:211], v[6:9]
	s_setprio 0
	ds_read_b128 v[148:151], v146
	ds_read_b128 v[152:155], v146 offset:1024
	ds_read_b128 v[156:159], v146 offset:2048
	ds_read_b128 v[160:163], v146 offset:3072
	ds_read_b128 v[164:167], v147
	ds_read_b128 v[168:171], v147 offset:1024
	ds_read_b128 v[172:175], v147 offset:2048
	ds_read_b128 v[176:179], v147 offset:3072
	ds_read_b128 v[180:183], v145 offset:32768
	ds_read_b128 v[184:187], v145 offset:33792
	ds_read_b128 v[188:191], v145 offset:34816
	ds_read_b128 v[192:195], v145 offset:35840
	ds_read_b128 v[196:199], v145 offset:36864
	ds_read_b128 v[200:203], v145 offset:37888
	ds_read_b128 v[204:207], v145 offset:38912
	ds_read_b128 v[208:211], v145 offset:39936
	s_mov_b32 s78, m0
	s_mov_b32 m0, s31
	s_nop 0
	global_load_lds_dwordx4 v138, s[22:23]
	s_mov_b32 m0, s78
	s_nop 0
	s_mov_b32 s78, m0
	s_mov_b32 m0, s41
	s_nop 0
	global_load_lds_dwordx4 v140, s[22:23]
	s_mov_b32 m0, s78
	s_add_u32 s22, s22, 0x80000
	s_addc_u32 s23, s23, 0
	s_mov_b32 s78, m0
	s_mov_b32 m0, s42
	s_nop 0
	global_load_lds_dwordx4 v138, s[22:23]
	s_mov_b32 m0, s78
	s_nop 0
	s_mov_b32 s78, m0
	s_mov_b32 m0, s43
	s_nop 0
	global_load_lds_dwordx4 v140, s[22:23]
	s_mov_b32 m0, s78
	s_waitcnt vmcnt(8)
	s_waitcnt lgkmcnt(0)
	s_barrier
	s_setprio 1
	s_waitcnt lgkmcnt(7)
	v_mfma_f32_16x16x32_bf16 v[126:129], v[148:151], v[180:183], v[126:129]
	v_mfma_f32_16x16x32_bf16 v[126:129], v[152:155], v[184:187], v[126:129]
	s_waitcnt lgkmcnt(5)
	v_mfma_f32_16x16x32_bf16 v[122:125], v[156:159], v[180:183], v[122:125]
	v_mfma_f32_16x16x32_bf16 v[122:125], v[160:163], v[184:187], v[122:125]
	s_waitcnt lgkmcnt(3)
	v_mfma_f32_16x16x32_bf16 v[106:109], v[156:159], v[188:191], v[106:109]
	v_mfma_f32_16x16x32_bf16 v[106:109], v[160:163], v[192:195], v[106:109]
	s_waitcnt lgkmcnt(1)
	v_mfma_f32_16x16x32_bf16 v[110:113], v[148:151], v[188:191], v[110:113]
	v_mfma_f32_16x16x32_bf16 v[110:113], v[152:155], v[192:195], v[110:113]
	v_mfma_f32_16x16x32_bf16 v[94:97], v[148:151], v[196:199], v[94:97]
	v_mfma_f32_16x16x32_bf16 v[94:97], v[152:155], v[200:203], v[94:97]
	v_mfma_f32_16x16x32_bf16 v[90:93], v[156:159], v[196:199], v[90:93]
	v_mfma_f32_16x16x32_bf16 v[90:93], v[160:163], v[200:203], v[90:93]
	v_mfma_f32_16x16x32_bf16 v[74:77], v[156:159], v[204:207], v[74:77]
	v_mfma_f32_16x16x32_bf16 v[74:77], v[160:163], v[208:211], v[74:77]
	s_waitcnt lgkmcnt(0)
	v_mfma_f32_16x16x32_bf16 v[78:81], v[148:151], v[204:207], v[78:81]
	v_mfma_f32_16x16x32_bf16 v[78:81], v[152:155], v[208:211], v[78:81]
	v_mfma_f32_16x16x32_bf16 v[118:121], v[164:167], v[180:183], v[118:121]
	v_mfma_f32_16x16x32_bf16 v[118:121], v[168:171], v[184:187], v[118:121]
	v_mfma_f32_16x16x32_bf16 v[114:117], v[172:175], v[180:183], v[114:117]
	v_mfma_f32_16x16x32_bf16 v[114:117], v[176:179], v[184:187], v[114:117]
	v_mfma_f32_16x16x32_bf16 v[98:101], v[172:175], v[188:191], v[98:101]
	v_mfma_f32_16x16x32_bf16 v[98:101], v[176:179], v[192:195], v[98:101]
	v_mfma_f32_16x16x32_bf16 v[102:105], v[164:167], v[188:191], v[102:105]
	v_mfma_f32_16x16x32_bf16 v[102:105], v[168:171], v[192:195], v[102:105]
	v_mfma_f32_16x16x32_bf16 v[86:89], v[164:167], v[196:199], v[86:89]
	v_mfma_f32_16x16x32_bf16 v[86:89], v[168:171], v[200:203], v[86:89]
	v_mfma_f32_16x16x32_bf16 v[82:85], v[172:175], v[196:199], v[82:85]
	v_mfma_f32_16x16x32_bf16 v[82:85], v[176:179], v[200:203], v[82:85]
	v_mfma_f32_16x16x32_bf16 v[66:69], v[172:175], v[204:207], v[66:69]
	v_mfma_f32_16x16x32_bf16 v[66:69], v[176:179], v[208:211], v[66:69]
	s_setprio 2
	s_barrier
	v_mfma_f32_16x16x32_bf16 v[70:73], v[164:167], v[204:207], v[70:73]
	v_mfma_f32_16x16x32_bf16 v[70:73], v[168:171], v[208:211], v[70:73]
	s_setprio 0
	ds_read_b128 v[180:183], v145 offset:49152
	ds_read_b128 v[184:187], v145 offset:50176
	ds_read_b128 v[188:191], v145 offset:51200
	ds_read_b128 v[192:195], v145 offset:52224
	ds_read_b128 v[196:199], v145 offset:53248
	ds_read_b128 v[200:203], v145 offset:54272
	ds_read_b128 v[204:207], v145 offset:55296
	ds_read_b128 v[208:211], v145 offset:56320
	s_add_u32 s22, s20, 0x80
	s_addc_u32 s23, s21, 0
	s_mov_b32 s78, m0
	s_mov_b32 m0, s46
	s_nop 0
	global_load_lds_dwordx4 v139, s[22:23]
	s_mov_b32 m0, s78
	s_add_u32 s20, s20, 0x80080
	s_mov_b32 s78, m0
	s_mov_b32 m0, s47
	s_nop 0
	global_load_lds_dwordx4 v141, s[22:23]
	s_mov_b32 m0, s78
	s_addc_u32 s21, s21, 0
	s_mov_b32 s22, m0
	s_mov_b32 m0, s48
	s_nop 0
	global_load_lds_dwordx4 v139, s[20:21]
	s_mov_b32 m0, s22
	s_nop 0
	s_mov_b32 s22, m0
	s_mov_b32 m0, s49
	s_nop 0
	global_load_lds_dwordx4 v141, s[20:21]
	s_mov_b32 m0, s22
	s_waitcnt vmcnt(4)
	s_waitcnt lgkmcnt(0)
	s_barrier
	s_setprio 1
	s_waitcnt lgkmcnt(7)
	v_mfma_f32_16x16x32_bf16 v[62:65], v[148:151], v[180:183], v[62:65]
	v_mfma_f32_16x16x32_bf16 v[62:65], v[152:155], v[184:187], v[62:65]
	s_waitcnt lgkmcnt(5)
	v_mfma_f32_16x16x32_bf16 v[58:61], v[156:159], v[180:183], v[58:61]
	v_mfma_f32_16x16x32_bf16 v[58:61], v[160:163], v[184:187], v[58:61]
	s_waitcnt lgkmcnt(3)
	v_mfma_f32_16x16x32_bf16 v[42:45], v[156:159], v[188:191], v[42:45]
	v_mfma_f32_16x16x32_bf16 v[42:45], v[160:163], v[192:195], v[42:45]
	s_waitcnt lgkmcnt(1)
	v_mfma_f32_16x16x32_bf16 v[46:49], v[148:151], v[188:191], v[46:49]
	v_mfma_f32_16x16x32_bf16 v[46:49], v[152:155], v[192:195], v[46:49]
	v_mfma_f32_16x16x32_bf16 v[30:33], v[148:151], v[196:199], v[30:33]
	v_mfma_f32_16x16x32_bf16 v[30:33], v[152:155], v[200:203], v[30:33]
	v_mfma_f32_16x16x32_bf16 v[26:29], v[156:159], v[196:199], v[26:29]
	v_mfma_f32_16x16x32_bf16 v[26:29], v[160:163], v[200:203], v[26:29]
	v_mfma_f32_16x16x32_bf16 v[10:13], v[156:159], v[204:207], v[10:13]
	v_mfma_f32_16x16x32_bf16 v[10:13], v[160:163], v[208:211], v[10:13]
	s_waitcnt lgkmcnt(0)
	v_mfma_f32_16x16x32_bf16 v[14:17], v[148:151], v[204:207], v[14:17]
	v_mfma_f32_16x16x32_bf16 v[14:17], v[152:155], v[208:211], v[14:17]
	v_mfma_f32_16x16x32_bf16 v[54:57], v[164:167], v[180:183], v[54:57]
	v_mfma_f32_16x16x32_bf16 v[54:57], v[168:171], v[184:187], v[54:57]
	v_mfma_f32_16x16x32_bf16 v[50:53], v[172:175], v[180:183], v[50:53]
	v_mfma_f32_16x16x32_bf16 v[50:53], v[176:179], v[184:187], v[50:53]
	v_mfma_f32_16x16x32_bf16 v[34:37], v[172:175], v[188:191], v[34:37]
	v_mfma_f32_16x16x32_bf16 v[34:37], v[176:179], v[192:195], v[34:37]
	v_mfma_f32_16x16x32_bf16 v[38:41], v[164:167], v[188:191], v[38:41]
	v_mfma_f32_16x16x32_bf16 v[38:41], v[168:171], v[192:195], v[38:41]
	v_mfma_f32_16x16x32_bf16 v[22:25], v[164:167], v[196:199], v[22:25]
	v_mfma_f32_16x16x32_bf16 v[22:25], v[168:171], v[200:203], v[22:25]
	v_mfma_f32_16x16x32_bf16 v[18:21], v[172:175], v[196:199], v[18:21]
	v_mfma_f32_16x16x32_bf16 v[18:21], v[176:179], v[200:203], v[18:21]
	v_mfma_f32_16x16x32_bf16 v[2:5], v[172:175], v[204:207], v[2:5]
	v_mfma_f32_16x16x32_bf16 v[2:5], v[176:179], v[208:211], v[2:5]
	s_setprio 2
	s_barrier
	v_mfma_f32_16x16x32_bf16 v[6:9], v[164:167], v[204:207], v[6:9]
	v_mfma_f32_16x16x32_bf16 v[6:9], v[168:171], v[208:211], v[6:9]
	s_setprio 0
	s_add_i32 s77, s77, 2
	s_add_u32 s73, s73, 0x100
	s_addc_u32 s74, s74, 0
	s_add_u32 s18, s18, 0x100
	s_addc_u32 s19, s19, 0
	s_add_u32 s75, s75, 0x100
	s_addc_u32 s76, s76, 0
	s_cmp_gt_u32 s77, 29
	s_cbranch_scc0 .LBB0_1224
	s_and_b64 vcc, exec, s[6:7]
	s_cbranch_vccz .LBB0_1227
	s_barrier

.LBB0_1356:
	s_ashr_i32 s13, s12, 31
	s_lshl_b64 s[14:15], s[12:13], 15
	s_add_u32 s14, s28, s14
	s_addc_u32 s15, s29, s15
	s_and_b64 s[16:17], s[2:3], exec
	s_cselect_b32 s13, s15, s23
	s_cselect_b32 s67, s14, s22
	s_ashr_i32 s11, s10, 31
	s_lshl_b64 s[16:17], s[10:11], 15
	s_add_u32 s16, s30, s16
	s_addc_u32 s17, s31, s17
	s_and_b64 s[24:25], s[2:3], exec
	s_cselect_b32 s11, s17, s21
	s_cselect_b32 s73, s16, s20
	s_add_u32 s74, s20, 0x80000
	s_addc_u32 s75, s21, 0
	s_add_u32 s20, s22, 0x204000
	s_addc_u32 s21, s23, 0
	s_add_u32 s76, s22, 0x400000
	s_addc_u32 s77, s23, 0
	s_mov_b32 s78, -2
	s_waitcnt vmcnt(25)
	s_waitcnt vmcnt(24)
	s_waitcnt vmcnt(15)
	s_waitcnt vmcnt(14)
	s_waitcnt vmcnt(13)
	s_waitcnt vmcnt(12)
	s_waitcnt vmcnt(11)
	s_waitcnt vmcnt(10)
	s_waitcnt vmcnt(9)
	s_waitcnt vmcnt(8)
	s_waitcnt vmcnt(7)
	s_waitcnt vmcnt(6)
	s_waitcnt vmcnt(5)
	s_waitcnt vmcnt(4)
	s_waitcnt vmcnt(3)
	s_waitcnt vmcnt(2)
	s_waitcnt vmcnt(1)
	s_waitcnt vmcnt(0)
	ds_read_b128 v[130:133], v181
	ds_read_b128 v[134:137], v181 offset:1024
	ds_read_b128 v[138:141], v181 offset:2048
	ds_read_b128 v[142:145], v181 offset:3072
	ds_read_b128 v[150:153], v182
	ds_read_b128 v[154:157], v182 offset:1024
	ds_read_b128 v[158:161], v182 offset:2048
	ds_read_b128 v[162:165], v182 offset:3072
	s_cmpk_eq_i32 s78, 0x52
	s_cselect_b32 s23, s11, s75
	s_cselect_b32 s22, s73, s74
	s_cselect_b32 s25, s13, s77
	s_cselect_b32 s24, s67, s76
	ds_read_b128 v[166:169], v183
	ds_read_b128 v[170:173], v183 offset:1024
	ds_read_b128 v[186:189], v183 offset:2048
	ds_read_b128 v[190:193], v183 offset:3072
	ds_read_b128 v[194:197], v183 offset:4096
	ds_read_b128 v[198:201], v183 offset:5120
	ds_read_b128 v[202:205], v183 offset:6144
	ds_read_b128 v[206:209], v183 offset:7168
	s_add_u32 s80, s20, 0xffffc000
	s_addc_u32 s81, s21, -1
	s_mov_b32 s79, m0
	s_mov_b32 m0, s58
	s_nop 0
	global_load_lds_dwordx4 v1, s[80:81]
	s_mov_b32 m0, s79
	s_nop 0
	s_mov_b32 s79, m0
	s_mov_b32 m0, s64
	s_nop 0
	global_load_lds_dwordx4 v177, s[80:81]
	s_mov_b32 m0, s79
	s_nop 0
	s_mov_b32 s79, m0
	s_mov_b32 m0, s59
	s_nop 0
	global_load_lds_dwordx4 v1, s[20:21]
	s_mov_b32 m0, s79
	s_nop 0
	s_mov_b32 s79, m0
	s_mov_b32 m0, s65
	s_nop 0
	global_load_lds_dwordx4 v177, s[20:21]
	s_mov_b32 m0, s79
	s_waitcnt vmcnt(8)
	s_waitcnt lgkmcnt(0)
	s_barrier
	s_setprio 1
	s_waitcnt lgkmcnt(7)
	v_mfma_f32_16x16x32_bf16 v[126:129], v[130:133], v[166:169], 0
	v_mfma_f32_16x16x32_bf16 v[126:129], v[134:137], v[170:173], v[126:129]
	s_waitcnt lgkmcnt(5)
	v_mfma_f32_16x16x32_bf16 v[122:125], v[138:141], v[166:169], 0
	v_mfma_f32_16x16x32_bf16 v[122:125], v[142:145], v[170:173], v[122:125]
	s_waitcnt lgkmcnt(3)
	v_mfma_f32_16x16x32_bf16 v[110:113], v[138:141], v[186:189], 0
	v_mfma_f32_16x16x32_bf16 v[110:113], v[142:145], v[190:193], v[110:113]
	s_waitcnt lgkmcnt(1)
	v_mfma_f32_16x16x32_bf16 v[118:121], v[130:133], v[186:189], 0
	v_mfma_f32_16x16x32_bf16 v[118:121], v[134:137], v[190:193], v[118:121]
	v_mfma_f32_16x16x32_bf16 v[94:97], v[130:133], v[194:197], 0
	v_mfma_f32_16x16x32_bf16 v[94:97], v[134:137], v[198:201], v[94:97]
	v_mfma_f32_16x16x32_bf16 v[90:93], v[138:141], v[194:197], 0
	v_mfma_f32_16x16x32_bf16 v[90:93], v[142:145], v[198:201], v[90:93]
	v_mfma_f32_16x16x32_bf16 v[78:81], v[138:141], v[202:205], 0
	v_mfma_f32_16x16x32_bf16 v[78:81], v[142:145], v[206:209], v[78:81]
	s_waitcnt lgkmcnt(0)
	v_mfma_f32_16x16x32_bf16 v[86:89], v[130:133], v[202:205], 0
	v_mfma_f32_16x16x32_bf16 v[86:89], v[134:137], v[206:209], v[86:89]
	v_mfma_f32_16x16x32_bf16 v[114:117], v[150:153], v[166:169], 0
	v_mfma_f32_16x16x32_bf16 v[114:117], v[154:157], v[170:173], v[114:117]
	v_mfma_f32_16x16x32_bf16 v[106:109], v[158:161], v[166:169], 0
	v_mfma_f32_16x16x32_bf16 v[106:109], v[162:165], v[170:173], v[106:109]
	v_mfma_f32_16x16x32_bf16 v[98:101], v[158:161], v[186:189], 0
	v_mfma_f32_16x16x32_bf16 v[98:101], v[162:165], v[190:193], v[98:101]
	v_mfma_f32_16x16x32_bf16 v[102:105], v[150:153], v[186:189], 0
	v_mfma_f32_16x16x32_bf16 v[102:105], v[154:157], v[190:193], v[102:105]
	v_mfma_f32_16x16x32_bf16 v[82:85], v[150:153], v[194:197], 0
	v_mfma_f32_16x16x32_bf16 v[82:85], v[154:157], v[198:201], v[82:85]
	v_mfma_f32_16x16x32_bf16 v[74:77], v[158:161], v[194:197], 0
	v_mfma_f32_16x16x32_bf16 v[74:77], v[162:165], v[198:201], v[74:77]
	v_mfma_f32_16x16x32_bf16 v[66:69], v[158:161], v[202:205], 0
	v_mfma_f32_16x16x32_bf16 v[66:69], v[162:165], v[206:209], v[66:69]
	s_setprio 2
	s_barrier
	v_mfma_f32_16x16x32_bf16 v[70:73], v[150:153], v[202:205], 0
	v_mfma_f32_16x16x32_bf16 v[70:73], v[154:157], v[206:209], v[70:73]
	s_setprio 0
	ds_read_b128 v[166:169], v183 offset:16384
	ds_read_b128 v[170:173], v183 offset:17408
	ds_read_b128 v[186:189], v183 offset:18432
	ds_read_b128 v[190:193], v183 offset:19456
	ds_read_b128 v[194:197], v183 offset:20480
	ds_read_b128 v[198:201], v183 offset:21504
	ds_read_b128 v[202:205], v183 offset:22528
	ds_read_b128 v[206:209], v183 offset:23552
	s_mov_b32 s79, m0
	s_mov_b32 m0, s35
	s_nop 0
	global_load_lds_dwordx4 v176, s[22:23]
	s_mov_b32 m0, s79
	s_add_u32 s80, s22, 0x4000
	s_mov_b32 s79, m0
	s_mov_b32 m0, s36
	s_nop 0
	global_load_lds_dwordx4 v178, s[22:23]
	s_mov_b32 m0, s79
	s_addc_u32 s81, s23, 0
	s_mov_b32 s79, m0
	s_mov_b32 m0, s37
	s_nop 0
	global_load_lds_dwordx4 v176, s[80:81]
	s_mov_b32 m0, s79
	s_nop 0
	s_mov_b32 s79, m0
	s_mov_b32 m0, s40
	s_nop 0
	global_load_lds_dwordx4 v178, s[80:81]
	s_mov_b32 m0, s79
	s_waitcnt vmcnt(4)
	s_waitcnt lgkmcnt(0)
	s_barrier
	s_setprio 1
	s_waitcnt lgkmcnt(7)
	v_mfma_f32_16x16x32_bf16 v[62:65], v[130:133], v[166:169], 0
	v_mfma_f32_16x16x32_bf16 v[62:65], v[134:137], v[170:173], v[62:65]
	s_waitcnt lgkmcnt(5)
	v_mfma_f32_16x16x32_bf16 v[58:61], v[138:141], v[166:169], 0
	v_mfma_f32_16x16x32_bf16 v[58:61], v[142:145], v[170:173], v[58:61]
	s_waitcnt lgkmcnt(3)
	v_mfma_f32_16x16x32_bf16 v[42:45], v[138:141], v[186:189], 0
	v_mfma_f32_16x16x32_bf16 v[42:45], v[142:145], v[190:193], v[42:45]
	s_waitcnt lgkmcnt(1)
	v_mfma_f32_16x16x32_bf16 v[46:49], v[130:133], v[186:189], 0
	v_mfma_f32_16x16x32_bf16 v[46:49], v[134:137], v[190:193], v[46:49]
	v_mfma_f32_16x16x32_bf16 v[30:33], v[130:133], v[194:197], 0
	v_mfma_f32_16x16x32_bf16 v[30:33], v[134:137], v[198:201], v[30:33]
	v_mfma_f32_16x16x32_bf16 v[26:29], v[138:141], v[194:197], 0
	v_mfma_f32_16x16x32_bf16 v[26:29], v[142:145], v[198:201], v[26:29]
	v_mfma_f32_16x16x32_bf16 v[10:13], v[138:141], v[202:205], 0
	v_mfma_f32_16x16x32_bf16 v[10:13], v[142:145], v[206:209], v[10:13]
	s_waitcnt lgkmcnt(0)
	v_mfma_f32_16x16x32_bf16 v[14:17], v[130:133], v[202:205], 0
	v_mfma_f32_16x16x32_bf16 v[14:17], v[134:137], v[206:209], v[14:17]
	v_mfma_f32_16x16x32_bf16 v[54:57], v[150:153], v[166:169], 0
	v_mfma_f32_16x16x32_bf16 v[54:57], v[154:157], v[170:173], v[54:57]
	v_mfma_f32_16x16x32_bf16 v[50:53], v[158:161], v[166:169], 0
	v_mfma_f32_16x16x32_bf16 v[50:53], v[162:165], v[170:173], v[50:53]
	v_mfma_f32_16x16x32_bf16 v[34:37], v[158:161], v[186:189], 0
	v_mfma_f32_16x16x32_bf16 v[34:37], v[162:165], v[190:193], v[34:37]
	v_mfma_f32_16x16x32_bf16 v[38:41], v[150:153], v[186:189], 0
	v_mfma_f32_16x16x32_bf16 v[38:41], v[154:157], v[190:193], v[38:41]
	v_mfma_f32_16x16x32_bf16 v[22:25], v[150:153], v[194:197], 0
	v_mfma_f32_16x16x32_bf16 v[22:25], v[154:157], v[198:201], v[22:25]
	v_mfma_f32_16x16x32_bf16 v[18:21], v[158:161], v[194:197], 0
	v_mfma_f32_16x16x32_bf16 v[18:21], v[162:165], v[198:201], v[18:21]
	v_mfma_f32_16x16x32_bf16 v[2:5], v[158:161], v[202:205], 0
	v_mfma_f32_16x16x32_bf16 v[2:5], v[162:165], v[206:209], v[2:5]
	s_setprio 2
	s_barrier
	v_mfma_f32_16x16x32_bf16 v[6:9], v[150:153], v[202:205], 0
	v_mfma_f32_16x16x32_bf16 v[6:9], v[154:157], v[206:209], v[6:9]
	s_setprio 0
	ds_read_b128 v[130:133], v184
	ds_read_b128 v[134:137], v184 offset:1024
	ds_read_b128 v[138:141], v184 offset:2048
	ds_read_b128 v[142:145], v184 offset:3072
	ds_read_b128 v[150:153], v185
	ds_read_b128 v[154:157], v185 offset:1024
	ds_read_b128 v[158:161], v185 offset:2048
	ds_read_b128 v[162:165], v185 offset:3072
	ds_read_b128 v[166:169], v183 offset:32768
	ds_read_b128 v[170:173], v183 offset:33792
	ds_read_b128 v[186:189], v183 offset:34816
	ds_read_b128 v[190:193], v183 offset:35840
	ds_read_b128 v[194:197], v183 offset:36864
	ds_read_b128 v[198:201], v183 offset:37888
	ds_read_b128 v[202:205], v183 offset:38912
	ds_read_b128 v[206:209], v183 offset:39936
	s_mov_b32 s79, m0
	s_mov_b32 m0, s34
	s_nop 0
	global_load_lds_dwordx4 v1, s[24:25]
	s_mov_b32 m0, s79
	s_nop 0
	s_mov_b32 s79, m0
	s_mov_b32 m0, s41
	s_nop 0
	global_load_lds_dwordx4 v177, s[24:25]
	s_mov_b32 m0, s79
	s_add_u32 s24, s24, 0x4000
	s_addc_u32 s25, s25, 0
	s_mov_b32 s79, m0
	s_mov_b32 m0, s42
	s_nop 0
	global_load_lds_dwordx4 v1, s[24:25]
	s_mov_b32 m0, s79
	s_nop 0
	s_mov_b32 s79, m0
	s_mov_b32 m0, s43
	s_nop 0
	global_load_lds_dwordx4 v177, s[24:25]
	s_mov_b32 m0, s79
	s_waitcnt vmcnt(8)
	s_waitcnt lgkmcnt(0)
	s_barrier
	s_setprio 1
	s_waitcnt lgkmcnt(7)
	v_mfma_f32_16x16x32_bf16 v[126:129], v[130:133], v[166:169], v[126:129]
	v_mfma_f32_16x16x32_bf16 v[126:129], v[134:137], v[170:173], v[126:129]
	s_waitcnt lgkmcnt(5)
	v_mfma_f32_16x16x32_bf16 v[122:125], v[138:141], v[166:169], v[122:125]
	v_mfma_f32_16x16x32_bf16 v[122:125], v[142:145], v[170:173], v[122:125]
	s_waitcnt lgkmcnt(3)
	v_mfma_f32_16x16x32_bf16 v[110:113], v[138:141], v[186:189], v[110:113]
	v_mfma_f32_16x16x32_bf16 v[110:113], v[142:145], v[190:193], v[110:113]
	s_waitcnt lgkmcnt(1)
	v_mfma_f32_16x16x32_bf16 v[118:121], v[130:133], v[186:189], v[118:121]
	v_mfma_f32_16x16x32_bf16 v[118:121], v[134:137], v[190:193], v[118:121]
	v_mfma_f32_16x16x32_bf16 v[94:97], v[130:133], v[194:197], v[94:97]
	v_mfma_f32_16x16x32_bf16 v[94:97], v[134:137], v[198:201], v[94:97]
	v_mfma_f32_16x16x32_bf16 v[90:93], v[138:141], v[194:197], v[90:93]
	v_mfma_f32_16x16x32_bf16 v[90:93], v[142:145], v[198:201], v[90:93]
	v_mfma_f32_16x16x32_bf16 v[78:81], v[138:141], v[202:205], v[78:81]
	v_mfma_f32_16x16x32_bf16 v[78:81], v[142:145], v[206:209], v[78:81]
	s_waitcnt lgkmcnt(0)
	v_mfma_f32_16x16x32_bf16 v[86:89], v[130:133], v[202:205], v[86:89]
	v_mfma_f32_16x16x32_bf16 v[86:89], v[134:137], v[206:209], v[86:89]
	v_mfma_f32_16x16x32_bf16 v[114:117], v[150:153], v[166:169], v[114:117]
	v_mfma_f32_16x16x32_bf16 v[114:117], v[154:157], v[170:173], v[114:117]
	v_mfma_f32_16x16x32_bf16 v[106:109], v[158:161], v[166:169], v[106:109]
	v_mfma_f32_16x16x32_bf16 v[106:109], v[162:165], v[170:173], v[106:109]
	v_mfma_f32_16x16x32_bf16 v[98:101], v[158:161], v[186:189], v[98:101]
	v_mfma_f32_16x16x32_bf16 v[98:101], v[162:165], v[190:193], v[98:101]
	v_mfma_f32_16x16x32_bf16 v[102:105], v[150:153], v[186:189], v[102:105]
	v_mfma_f32_16x16x32_bf16 v[102:105], v[154:157], v[190:193], v[102:105]
	v_mfma_f32_16x16x32_bf16 v[82:85], v[150:153], v[194:197], v[82:85]
	v_mfma_f32_16x16x32_bf16 v[82:85], v[154:157], v[198:201], v[82:85]
	v_mfma_f32_16x16x32_bf16 v[74:77], v[158:161], v[194:197], v[74:77]
	v_mfma_f32_16x16x32_bf16 v[74:77], v[162:165], v[198:201], v[74:77]
	v_mfma_f32_16x16x32_bf16 v[66:69], v[158:161], v[202:205], v[66:69]
	v_mfma_f32_16x16x32_bf16 v[66:69], v[162:165], v[206:209], v[66:69]
	s_setprio 2
	s_barrier
	v_mfma_f32_16x16x32_bf16 v[70:73], v[150:153], v[202:205], v[70:73]
	v_mfma_f32_16x16x32_bf16 v[70:73], v[154:157], v[206:209], v[70:73]
	s_setprio 0
	ds_read_b128 v[166:169], v183 offset:49152
	ds_read_b128 v[170:173], v183 offset:50176
	ds_read_b128 v[186:189], v183 offset:51200
	ds_read_b128 v[190:193], v183 offset:52224
	ds_read_b128 v[194:197], v183 offset:53248
	ds_read_b128 v[198:201], v183 offset:54272
	ds_read_b128 v[202:205], v183 offset:55296
	ds_read_b128 v[206:209], v183 offset:56320
	s_add_u32 s24, s22, 0x40000
	s_addc_u32 s25, s23, 0
	s_mov_b32 s79, m0
	s_mov_b32 m0, s46
	s_nop 0
	global_load_lds_dwordx4 v176, s[24:25]
	s_mov_b32 m0, s79
	s_add_u32 s22, s22, 0x44000
	s_mov_b32 s79, m0
	s_mov_b32 m0, s47
	s_nop 0
	global_load_lds_dwordx4 v178, s[24:25]
	s_mov_b32 m0, s79
	s_addc_u32 s23, s23, 0
	s_mov_b32 s24, m0
	s_mov_b32 m0, s48
	s_nop 0
	global_load_lds_dwordx4 v176, s[22:23]
	s_mov_b32 m0, s24
	s_nop 0
	s_mov_b32 s24, m0
	s_mov_b32 m0, s49
	s_nop 0
	global_load_lds_dwordx4 v178, s[22:23]
	s_mov_b32 m0, s24
	s_waitcnt vmcnt(4)
	s_waitcnt lgkmcnt(0)
	s_barrier
	s_setprio 1
	s_waitcnt lgkmcnt(7)
	v_mfma_f32_16x16x32_bf16 v[62:65], v[130:133], v[166:169], v[62:65]
	v_mfma_f32_16x16x32_bf16 v[62:65], v[134:137], v[170:173], v[62:65]
	s_waitcnt lgkmcnt(5)
	v_mfma_f32_16x16x32_bf16 v[58:61], v[138:141], v[166:169], v[58:61]
	v_mfma_f32_16x16x32_bf16 v[58:61], v[142:145], v[170:173], v[58:61]
	s_waitcnt lgkmcnt(3)
	v_mfma_f32_16x16x32_bf16 v[42:45], v[138:141], v[186:189], v[42:45]
	v_mfma_f32_16x16x32_bf16 v[42:45], v[142:145], v[190:193], v[42:45]
	s_waitcnt lgkmcnt(1)
	v_mfma_f32_16x16x32_bf16 v[46:49], v[130:133], v[186:189], v[46:49]
	v_mfma_f32_16x16x32_bf16 v[46:49], v[134:137], v[190:193], v[46:49]
	v_mfma_f32_16x16x32_bf16 v[30:33], v[130:133], v[194:197], v[30:33]
	v_mfma_f32_16x16x32_bf16 v[30:33], v[134:137], v[198:201], v[30:33]
	v_mfma_f32_16x16x32_bf16 v[26:29], v[138:141], v[194:197], v[26:29]
	v_mfma_f32_16x16x32_bf16 v[26:29], v[142:145], v[198:201], v[26:29]
	v_mfma_f32_16x16x32_bf16 v[10:13], v[138:141], v[202:205], v[10:13]
	v_mfma_f32_16x16x32_bf16 v[10:13], v[142:145], v[206:209], v[10:13]
	s_waitcnt lgkmcnt(0)
	v_mfma_f32_16x16x32_bf16 v[14:17], v[130:133], v[202:205], v[14:17]
	v_mfma_f32_16x16x32_bf16 v[14:17], v[134:137], v[206:209], v[14:17]
	v_mfma_f32_16x16x32_bf16 v[54:57], v[150:153], v[166:169], v[54:57]
	v_mfma_f32_16x16x32_bf16 v[54:57], v[154:157], v[170:173], v[54:57]
	v_mfma_f32_16x16x32_bf16 v[50:53], v[158:161], v[166:169], v[50:53]
	v_mfma_f32_16x16x32_bf16 v[50:53], v[162:165], v[170:173], v[50:53]
	v_mfma_f32_16x16x32_bf16 v[34:37], v[158:161], v[186:189], v[34:37]
	v_mfma_f32_16x16x32_bf16 v[34:37], v[162:165], v[190:193], v[34:37]
	v_mfma_f32_16x16x32_bf16 v[38:41], v[150:153], v[186:189], v[38:41]
	v_mfma_f32_16x16x32_bf16 v[38:41], v[154:157], v[190:193], v[38:41]
	v_mfma_f32_16x16x32_bf16 v[22:25], v[150:153], v[194:197], v[22:25]
	v_mfma_f32_16x16x32_bf16 v[22:25], v[154:157], v[198:201], v[22:25]
	v_mfma_f32_16x16x32_bf16 v[18:21], v[158:161], v[194:197], v[18:21]
	v_mfma_f32_16x16x32_bf16 v[18:21], v[162:165], v[198:201], v[18:21]
	v_mfma_f32_16x16x32_bf16 v[2:5], v[158:161], v[202:205], v[2:5]
	v_mfma_f32_16x16x32_bf16 v[2:5], v[162:165], v[206:209], v[2:5]
	s_setprio 2
	s_barrier
	v_mfma_f32_16x16x32_bf16 v[6:9], v[150:153], v[202:205], v[6:9]
	v_mfma_f32_16x16x32_bf16 v[6:9], v[154:157], v[206:209], v[6:9]
	s_setprio 0
	s_add_i32 s78, s78, 2
	s_add_u32 s74, s74, 0x80000
	s_addc_u32 s75, s75, 0
	s_add_u32 s20, s20, 0x400000
	s_addc_u32 s21, s21, 0
	s_add_u32 s76, s76, 0x400000
	s_addc_u32 s77, s77, 0
	s_cmpk_gt_u32 s78, 0x53
	.p2align 6
.LBB0_1357:
	ds_read_b128 v[130:133], v181
	ds_read_b128 v[134:137], v181 offset:1024
	ds_read_b128 v[138:141], v181 offset:2048
	ds_read_b128 v[142:145], v181 offset:3072
	ds_read_b128 v[150:153], v182
	ds_read_b128 v[154:157], v182 offset:1024
	ds_read_b128 v[158:161], v182 offset:2048
	ds_read_b128 v[162:165], v182 offset:3072
	s_cmpk_eq_i32 s78, 0x52
	s_cselect_b32 s23, s11, s75
	s_cselect_b32 s22, s73, s74
	s_cselect_b32 s25, s13, s77
	s_cselect_b32 s24, s67, s76
	ds_read_b128 v[166:169], v183
	ds_read_b128 v[170:173], v183 offset:1024
	ds_read_b128 v[186:189], v183 offset:2048
	ds_read_b128 v[190:193], v183 offset:3072
	ds_read_b128 v[194:197], v183 offset:4096
	ds_read_b128 v[198:201], v183 offset:5120
	ds_read_b128 v[202:205], v183 offset:6144
	ds_read_b128 v[206:209], v183 offset:7168
	s_add_u32 s80, s20, 0xffffc000
	s_addc_u32 s81, s21, -1
	s_mov_b32 s79, m0
	s_mov_b32 m0, s58
	s_nop 0
	global_load_lds_dwordx4 v1, s[80:81]
	s_mov_b32 m0, s79
	s_nop 0
	s_mov_b32 s79, m0
	s_mov_b32 m0, s64
	s_nop 0
	global_load_lds_dwordx4 v177, s[80:81]
	s_mov_b32 m0, s79
	s_nop 0
	s_mov_b32 s79, m0
	s_mov_b32 m0, s59
	s_nop 0
	global_load_lds_dwordx4 v1, s[20:21]
	s_mov_b32 m0, s79
	s_nop 0
	s_mov_b32 s79, m0
	s_mov_b32 m0, s65
	s_nop 0
	global_load_lds_dwordx4 v177, s[20:21]
	s_mov_b32 m0, s79
	s_waitcnt vmcnt(8)
	s_waitcnt lgkmcnt(0)
	s_barrier
	s_setprio 1
	s_waitcnt lgkmcnt(7)
	v_mfma_f32_16x16x32_bf16 v[126:129], v[130:133], v[166:169], v[126:129]
	v_mfma_f32_16x16x32_bf16 v[126:129], v[134:137], v[170:173], v[126:129]
	s_waitcnt lgkmcnt(5)
	v_mfma_f32_16x16x32_bf16 v[122:125], v[138:141], v[166:169], v[122:125]
	v_mfma_f32_16x16x32_bf16 v[122:125], v[142:145], v[170:173], v[122:125]
	s_waitcnt lgkmcnt(3)
	v_mfma_f32_16x16x32_bf16 v[110:113], v[138:141], v[186:189], v[110:113]
	v_mfma_f32_16x16x32_bf16 v[110:113], v[142:145], v[190:193], v[110:113]
	s_waitcnt lgkmcnt(1)
	v_mfma_f32_16x16x32_bf16 v[118:121], v[130:133], v[186:189], v[118:121]
	v_mfma_f32_16x16x32_bf16 v[118:121], v[134:137], v[190:193], v[118:121]
	v_mfma_f32_16x16x32_bf16 v[94:97], v[130:133], v[194:197], v[94:97]
	v_mfma_f32_16x16x32_bf16 v[94:97], v[134:137], v[198:201], v[94:97]
	v_mfma_f32_16x16x32_bf16 v[90:93], v[138:141], v[194:197], v[90:93]
	v_mfma_f32_16x16x32_bf16 v[90:93], v[142:145], v[198:201], v[90:93]
	v_mfma_f32_16x16x32_bf16 v[78:81], v[138:141], v[202:205], v[78:81]
	v_mfma_f32_16x16x32_bf16 v[78:81], v[142:145], v[206:209], v[78:81]
	s_waitcnt lgkmcnt(0)
	v_mfma_f32_16x16x32_bf16 v[86:89], v[130:133], v[202:205], v[86:89]
	v_mfma_f32_16x16x32_bf16 v[86:89], v[134:137], v[206:209], v[86:89]
	v_mfma_f32_16x16x32_bf16 v[114:117], v[150:153], v[166:169], v[114:117]
	v_mfma_f32_16x16x32_bf16 v[114:117], v[154:157], v[170:173], v[114:117]
	v_mfma_f32_16x16x32_bf16 v[106:109], v[158:161], v[166:169], v[106:109]
	v_mfma_f32_16x16x32_bf16 v[106:109], v[162:165], v[170:173], v[106:109]
	v_mfma_f32_16x16x32_bf16 v[98:101], v[158:161], v[186:189], v[98:101]
	v_mfma_f32_16x16x32_bf16 v[98:101], v[162:165], v[190:193], v[98:101]
	v_mfma_f32_16x16x32_bf16 v[102:105], v[150:153], v[186:189], v[102:105]
	v_mfma_f32_16x16x32_bf16 v[102:105], v[154:157], v[190:193], v[102:105]
	v_mfma_f32_16x16x32_bf16 v[82:85], v[150:153], v[194:197], v[82:85]
	v_mfma_f32_16x16x32_bf16 v[82:85], v[154:157], v[198:201], v[82:85]
	v_mfma_f32_16x16x32_bf16 v[74:77], v[158:161], v[194:197], v[74:77]
	v_mfma_f32_16x16x32_bf16 v[74:77], v[162:165], v[198:201], v[74:77]
	v_mfma_f32_16x16x32_bf16 v[66:69], v[158:161], v[202:205], v[66:69]
	v_mfma_f32_16x16x32_bf16 v[66:69], v[162:165], v[206:209], v[66:69]
	s_setprio 2
	s_barrier
	v_mfma_f32_16x16x32_bf16 v[70:73], v[150:153], v[202:205], v[70:73]
	v_mfma_f32_16x16x32_bf16 v[70:73], v[154:157], v[206:209], v[70:73]
	s_setprio 0
	ds_read_b128 v[166:169], v183 offset:16384
	ds_read_b128 v[170:173], v183 offset:17408
	ds_read_b128 v[186:189], v183 offset:18432
	ds_read_b128 v[190:193], v183 offset:19456
	ds_read_b128 v[194:197], v183 offset:20480
	ds_read_b128 v[198:201], v183 offset:21504
	ds_read_b128 v[202:205], v183 offset:22528
	ds_read_b128 v[206:209], v183 offset:23552
	s_mov_b32 s79, m0
	s_mov_b32 m0, s35
	s_nop 0
	global_load_lds_dwordx4 v176, s[22:23]
	s_mov_b32 m0, s79
	s_add_u32 s80, s22, 0x4000
	s_mov_b32 s79, m0
	s_mov_b32 m0, s36
	s_nop 0
	global_load_lds_dwordx4 v178, s[22:23]
	s_mov_b32 m0, s79
	s_addc_u32 s81, s23, 0
	s_mov_b32 s79, m0
	s_mov_b32 m0, s37
	s_nop 0
	global_load_lds_dwordx4 v176, s[80:81]
	s_mov_b32 m0, s79
	s_nop 0
	s_mov_b32 s79, m0
	s_mov_b32 m0, s40
	s_nop 0
	global_load_lds_dwordx4 v178, s[80:81]
	s_mov_b32 m0, s79
	s_waitcnt vmcnt(4)
	s_waitcnt lgkmcnt(0)
	s_barrier
	s_setprio 1
	s_waitcnt lgkmcnt(7)
	v_mfma_f32_16x16x32_bf16 v[62:65], v[130:133], v[166:169], v[62:65]
	v_mfma_f32_16x16x32_bf16 v[62:65], v[134:137], v[170:173], v[62:65]
	s_waitcnt lgkmcnt(5)
	v_mfma_f32_16x16x32_bf16 v[58:61], v[138:141], v[166:169], v[58:61]
	v_mfma_f32_16x16x32_bf16 v[58:61], v[142:145], v[170:173], v[58:61]
	s_waitcnt lgkmcnt(3)
	v_mfma_f32_16x16x32_bf16 v[42:45], v[138:141], v[186:189], v[42:45]
	v_mfma_f32_16x16x32_bf16 v[42:45], v[142:145], v[190:193], v[42:45]
	s_waitcnt lgkmcnt(1)
	v_mfma_f32_16x16x32_bf16 v[46:49], v[130:133], v[186:189], v[46:49]
	v_mfma_f32_16x16x32_bf16 v[46:49], v[134:137], v[190:193], v[46:49]
	v_mfma_f32_16x16x32_bf16 v[30:33], v[130:133], v[194:197], v[30:33]
	v_mfma_f32_16x16x32_bf16 v[30:33], v[134:137], v[198:201], v[30:33]
	v_mfma_f32_16x16x32_bf16 v[26:29], v[138:141], v[194:197], v[26:29]
	v_mfma_f32_16x16x32_bf16 v[26:29], v[142:145], v[198:201], v[26:29]
	v_mfma_f32_16x16x32_bf16 v[10:13], v[138:141], v[202:205], v[10:13]
	v_mfma_f32_16x16x32_bf16 v[10:13], v[142:145], v[206:209], v[10:13]
	s_waitcnt lgkmcnt(0)
	v_mfma_f32_16x16x32_bf16 v[14:17], v[130:133], v[202:205], v[14:17]
	v_mfma_f32_16x16x32_bf16 v[14:17], v[134:137], v[206:209], v[14:17]
	v_mfma_f32_16x16x32_bf16 v[54:57], v[150:153], v[166:169], v[54:57]
	v_mfma_f32_16x16x32_bf16 v[54:57], v[154:157], v[170:173], v[54:57]
	v_mfma_f32_16x16x32_bf16 v[50:53], v[158:161], v[166:169], v[50:53]
	v_mfma_f32_16x16x32_bf16 v[50:53], v[162:165], v[170:173], v[50:53]
	v_mfma_f32_16x16x32_bf16 v[34:37], v[158:161], v[186:189], v[34:37]
	v_mfma_f32_16x16x32_bf16 v[34:37], v[162:165], v[190:193], v[34:37]
	v_mfma_f32_16x16x32_bf16 v[38:41], v[150:153], v[186:189], v[38:41]
	v_mfma_f32_16x16x32_bf16 v[38:41], v[154:157], v[190:193], v[38:41]
	v_mfma_f32_16x16x32_bf16 v[22:25], v[150:153], v[194:197], v[22:25]
	v_mfma_f32_16x16x32_bf16 v[22:25], v[154:157], v[198:201], v[22:25]
	v_mfma_f32_16x16x32_bf16 v[18:21], v[158:161], v[194:197], v[18:21]
	v_mfma_f32_16x16x32_bf16 v[18:21], v[162:165], v[198:201], v[18:21]
	v_mfma_f32_16x16x32_bf16 v[2:5], v[158:161], v[202:205], v[2:5]
	v_mfma_f32_16x16x32_bf16 v[2:5], v[162:165], v[206:209], v[2:5]
	s_setprio 2
	s_barrier
	v_mfma_f32_16x16x32_bf16 v[6:9], v[150:153], v[202:205], v[6:9]
	v_mfma_f32_16x16x32_bf16 v[6:9], v[154:157], v[206:209], v[6:9]
	s_setprio 0
	ds_read_b128 v[130:133], v184
	ds_read_b128 v[134:137], v184 offset:1024
	ds_read_b128 v[138:141], v184 offset:2048
	ds_read_b128 v[142:145], v184 offset:3072
	ds_read_b128 v[150:153], v185
	ds_read_b128 v[154:157], v185 offset:1024
	ds_read_b128 v[158:161], v185 offset:2048
	ds_read_b128 v[162:165], v185 offset:3072
	ds_read_b128 v[166:169], v183 offset:32768
	ds_read_b128 v[170:173], v183 offset:33792
	ds_read_b128 v[186:189], v183 offset:34816
	ds_read_b128 v[190:193], v183 offset:35840
	ds_read_b128 v[194:197], v183 offset:36864
	ds_read_b128 v[198:201], v183 offset:37888
	ds_read_b128 v[202:205], v183 offset:38912
	ds_read_b128 v[206:209], v183 offset:39936
	s_mov_b32 s79, m0
	s_mov_b32 m0, s34
	s_nop 0
	global_load_lds_dwordx4 v1, s[24:25]
	s_mov_b32 m0, s79
	s_nop 0
	s_mov_b32 s79, m0
	s_mov_b32 m0, s41
	s_nop 0
	global_load_lds_dwordx4 v177, s[24:25]
	s_mov_b32 m0, s79
	s_add_u32 s24, s24, 0x4000
	s_addc_u32 s25, s25, 0
	s_mov_b32 s79, m0
	s_mov_b32 m0, s42
	s_nop 0
	global_load_lds_dwordx4 v1, s[24:25]
	s_mov_b32 m0, s79
	s_nop 0
	s_mov_b32 s79, m0
	s_mov_b32 m0, s43
	s_nop 0
	global_load_lds_dwordx4 v177, s[24:25]
	s_mov_b32 m0, s79
	s_waitcnt vmcnt(8)
	s_waitcnt lgkmcnt(0)
	s_barrier
	s_setprio 1
	s_waitcnt lgkmcnt(7)
	v_mfma_f32_16x16x32_bf16 v[126:129], v[130:133], v[166:169], v[126:129]
	v_mfma_f32_16x16x32_bf16 v[126:129], v[134:137], v[170:173], v[126:129]
	s_waitcnt lgkmcnt(5)
	v_mfma_f32_16x16x32_bf16 v[122:125], v[138:141], v[166:169], v[122:125]
	v_mfma_f32_16x16x32_bf16 v[122:125], v[142:145], v[170:173], v[122:125]
	s_waitcnt lgkmcnt(3)
	v_mfma_f32_16x16x32_bf16 v[110:113], v[138:141], v[186:189], v[110:113]
	v_mfma_f32_16x16x32_bf16 v[110:113], v[142:145], v[190:193], v[110:113]
	s_waitcnt lgkmcnt(1)
	v_mfma_f32_16x16x32_bf16 v[118:121], v[130:133], v[186:189], v[118:121]
	v_mfma_f32_16x16x32_bf16 v[118:121], v[134:137], v[190:193], v[118:121]
	v_mfma_f32_16x16x32_bf16 v[94:97], v[130:133], v[194:197], v[94:97]
	v_mfma_f32_16x16x32_bf16 v[94:97], v[134:137], v[198:201], v[94:97]
	v_mfma_f32_16x16x32_bf16 v[90:93], v[138:141], v[194:197], v[90:93]
	v_mfma_f32_16x16x32_bf16 v[90:93], v[142:145], v[198:201], v[90:93]
	v_mfma_f32_16x16x32_bf16 v[78:81], v[138:141], v[202:205], v[78:81]
	v_mfma_f32_16x16x32_bf16 v[78:81], v[142:145], v[206:209], v[78:81]
	s_waitcnt lgkmcnt(0)
	v_mfma_f32_16x16x32_bf16 v[86:89], v[130:133], v[202:205], v[86:89]
	v_mfma_f32_16x16x32_bf16 v[86:89], v[134:137], v[206:209], v[86:89]
	v_mfma_f32_16x16x32_bf16 v[114:117], v[150:153], v[166:169], v[114:117]
	v_mfma_f32_16x16x32_bf16 v[114:117], v[154:157], v[170:173], v[114:117]
	v_mfma_f32_16x16x32_bf16 v[106:109], v[158:161], v[166:169], v[106:109]
	v_mfma_f32_16x16x32_bf16 v[106:109], v[162:165], v[170:173], v[106:109]
	v_mfma_f32_16x16x32_bf16 v[98:101], v[158:161], v[186:189], v[98:101]
	v_mfma_f32_16x16x32_bf16 v[98:101], v[162:165], v[190:193], v[98:101]
	v_mfma_f32_16x16x32_bf16 v[102:105], v[150:153], v[186:189], v[102:105]
	v_mfma_f32_16x16x32_bf16 v[102:105], v[154:157], v[190:193], v[102:105]
	v_mfma_f32_16x16x32_bf16 v[82:85], v[150:153], v[194:197], v[82:85]
	v_mfma_f32_16x16x32_bf16 v[82:85], v[154:157], v[198:201], v[82:85]
	v_mfma_f32_16x16x32_bf16 v[74:77], v[158:161], v[194:197], v[74:77]
	v_mfma_f32_16x16x32_bf16 v[74:77], v[162:165], v[198:201], v[74:77]
	v_mfma_f32_16x16x32_bf16 v[66:69], v[158:161], v[202:205], v[66:69]
	v_mfma_f32_16x16x32_bf16 v[66:69], v[162:165], v[206:209], v[66:69]
	s_setprio 2
	s_barrier
	v_mfma_f32_16x16x32_bf16 v[70:73], v[150:153], v[202:205], v[70:73]
	v_mfma_f32_16x16x32_bf16 v[70:73], v[154:157], v[206:209], v[70:73]
	s_setprio 0
	ds_read_b128 v[166:169], v183 offset:49152
	ds_read_b128 v[170:173], v183 offset:50176
	ds_read_b128 v[186:189], v183 offset:51200
	ds_read_b128 v[190:193], v183 offset:52224
	ds_read_b128 v[194:197], v183 offset:53248
	ds_read_b128 v[198:201], v183 offset:54272
	ds_read_b128 v[202:205], v183 offset:55296
	ds_read_b128 v[206:209], v183 offset:56320
	s_add_u32 s24, s22, 0x40000
	s_addc_u32 s25, s23, 0
	s_mov_b32 s79, m0
	s_mov_b32 m0, s46
	s_nop 0
	global_load_lds_dwordx4 v176, s[24:25]
	s_mov_b32 m0, s79
	s_add_u32 s22, s22, 0x44000
	s_mov_b32 s79, m0
	s_mov_b32 m0, s47
	s_nop 0
	global_load_lds_dwordx4 v178, s[24:25]
	s_mov_b32 m0, s79
	s_addc_u32 s23, s23, 0
	s_mov_b32 s24, m0
	s_mov_b32 m0, s48
	s_nop 0
	global_load_lds_dwordx4 v176, s[22:23]
	s_mov_b32 m0, s24
	s_nop 0
	s_mov_b32 s24, m0
	s_mov_b32 m0, s49
	s_nop 0
	global_load_lds_dwordx4 v178, s[22:23]
	s_mov_b32 m0, s24
	s_waitcnt vmcnt(4)
	s_waitcnt lgkmcnt(0)
	s_barrier
	s_setprio 1
	s_waitcnt lgkmcnt(7)
	v_mfma_f32_16x16x32_bf16 v[62:65], v[130:133], v[166:169], v[62:65]
	v_mfma_f32_16x16x32_bf16 v[62:65], v[134:137], v[170:173], v[62:65]
	s_waitcnt lgkmcnt(5)
	v_mfma_f32_16x16x32_bf16 v[58:61], v[138:141], v[166:169], v[58:61]
	v_mfma_f32_16x16x32_bf16 v[58:61], v[142:145], v[170:173], v[58:61]
	s_waitcnt lgkmcnt(3)
	v_mfma_f32_16x16x32_bf16 v[42:45], v[138:141], v[186:189], v[42:45]
	v_mfma_f32_16x16x32_bf16 v[42:45], v[142:145], v[190:193], v[42:45]
	s_waitcnt lgkmcnt(1)
	v_mfma_f32_16x16x32_bf16 v[46:49], v[130:133], v[186:189], v[46:49]
	v_mfma_f32_16x16x32_bf16 v[46:49], v[134:137], v[190:193], v[46:49]
	v_mfma_f32_16x16x32_bf16 v[30:33], v[130:133], v[194:197], v[30:33]
	v_mfma_f32_16x16x32_bf16 v[30:33], v[134:137], v[198:201], v[30:33]
	v_mfma_f32_16x16x32_bf16 v[26:29], v[138:141], v[194:197], v[26:29]
	v_mfma_f32_16x16x32_bf16 v[26:29], v[142:145], v[198:201], v[26:29]
	v_mfma_f32_16x16x32_bf16 v[10:13], v[138:141], v[202:205], v[10:13]
	v_mfma_f32_16x16x32_bf16 v[10:13], v[142:145], v[206:209], v[10:13]
	s_waitcnt lgkmcnt(0)
	v_mfma_f32_16x16x32_bf16 v[14:17], v[130:133], v[202:205], v[14:17]
	v_mfma_f32_16x16x32_bf16 v[14:17], v[134:137], v[206:209], v[14:17]
	v_mfma_f32_16x16x32_bf16 v[54:57], v[150:153], v[166:169], v[54:57]
	v_mfma_f32_16x16x32_bf16 v[54:57], v[154:157], v[170:173], v[54:57]
	v_mfma_f32_16x16x32_bf16 v[50:53], v[158:161], v[166:169], v[50:53]
	v_mfma_f32_16x16x32_bf16 v[50:53], v[162:165], v[170:173], v[50:53]
	v_mfma_f32_16x16x32_bf16 v[34:37], v[158:161], v[186:189], v[34:37]
	v_mfma_f32_16x16x32_bf16 v[34:37], v[162:165], v[190:193], v[34:37]
	v_mfma_f32_16x16x32_bf16 v[38:41], v[150:153], v[186:189], v[38:41]
	v_mfma_f32_16x16x32_bf16 v[38:41], v[154:157], v[190:193], v[38:41]
	v_mfma_f32_16x16x32_bf16 v[22:25], v[150:153], v[194:197], v[22:25]
	v_mfma_f32_16x16x32_bf16 v[22:25], v[154:157], v[198:201], v[22:25]
	v_mfma_f32_16x16x32_bf16 v[18:21], v[158:161], v[194:197], v[18:21]
	v_mfma_f32_16x16x32_bf16 v[18:21], v[162:165], v[198:201], v[18:21]
	v_mfma_f32_16x16x32_bf16 v[2:5], v[158:161], v[202:205], v[2:5]
	v_mfma_f32_16x16x32_bf16 v[2:5], v[162:165], v[206:209], v[2:5]
	s_setprio 2
	s_barrier
	v_mfma_f32_16x16x32_bf16 v[6:9], v[150:153], v[202:205], v[6:9]
	v_mfma_f32_16x16x32_bf16 v[6:9], v[154:157], v[206:209], v[6:9]
	s_setprio 0
	s_add_i32 s78, s78, 2
	s_add_u32 s74, s74, 0x80000
	s_addc_u32 s75, s75, 0
	s_add_u32 s20, s20, 0x400000
	s_addc_u32 s21, s21, 0
	s_add_u32 s76, s76, 0x400000
	s_addc_u32 s77, s77, 0
	s_cmpk_gt_u32 s78, 0x53
	s_cbranch_scc0 .LBB0_1357
	s_and_b64 vcc, exec, s[8:9]
	s_cbranch_vccz .LBB0_1360
	s_barrier

.LBB0_1537:
	s_ashr_i32 s23, s22, 31
	s_lshl_b64 s[24:25], s[22:23], 20
	s_add_u32 s24, s41, s24
	s_addc_u32 s25, s42, s25
	s_and_b64 s[26:27], s[4:5], exec
	s_cselect_b32 s7, s25, s35
	s_cselect_b32 s23, s24, s34
	s_ashr_i32 s21, s20, 31
	s_lshl_b64 s[26:27], s[20:21], 20
	s_add_u32 s26, s43, s26
	s_addc_u32 s27, s46, s27
	s_and_b64 s[36:37], s[4:5], exec
	s_cselect_b32 s21, s27, s31
	s_cselect_b32 s29, s26, s30
	s_add_u32 s79, s30, 0x100
	s_addc_u32 s80, s31, 0
	s_add_u32 s30, s34, 0x80080
	s_addc_u32 s31, s35, 0
	s_add_u32 s81, s34, 0x100
	s_addc_u32 s82, s35, 0
	s_mov_b32 s83, -2
	s_waitcnt vmcnt(25)
	s_waitcnt vmcnt(24)
	s_waitcnt vmcnt(4)
	s_waitcnt vmcnt(14)
	s_waitcnt vmcnt(13)
	s_waitcnt vmcnt(12)
	s_waitcnt vmcnt(2)
	s_waitcnt vmcnt(10)
	s_waitcnt vmcnt(9)
	s_waitcnt vmcnt(8)
	s_waitcnt vmcnt(7)
	s_waitcnt vmcnt(6)
	s_waitcnt vmcnt(5)
	s_waitcnt vmcnt(4)
	s_waitcnt vmcnt(3)
	s_waitcnt vmcnt(2)
	s_waitcnt vmcnt(1)
	s_waitcnt vmcnt(0)
	ds_read_b128 v[46:49], v182
	ds_read_b128 v[54:57], v182 offset:1024
	ds_read_b128 v[58:61], v182 offset:2048
	ds_read_b128 v[62:65], v182 offset:3072
	ds_read_b128 v[146:149], v183
	ds_read_b128 v[150:153], v183 offset:1024
	ds_read_b128 v[154:157], v183 offset:2048
	ds_read_b128 v[158:161], v183 offset:3072
	s_cmp_eq_u32 s83, 28
	s_cselect_b32 s35, s21, s80
	s_cselect_b32 s34, s29, s79
	s_cselect_b32 s37, s7, s82
	s_cselect_b32 s36, s23, s81
	ds_read_b128 v[170:173], v184
	ds_read_b128 v[188:191], v184 offset:1024
	ds_read_b128 v[192:195], v184 offset:2048
	ds_read_b128 v[196:199], v184 offset:3072
	ds_read_b128 v[200:203], v184 offset:4096
	ds_read_b128 v[204:207], v184 offset:5120
	ds_read_b128 v[208:211], v184 offset:6144
	ds_read_b128 v[212:215], v184 offset:7168
	s_add_u32 s86, s30, 0xfff80000
	s_addc_u32 s87, s31, -1
	s_mov_b32 s92, m0
	s_mov_b32 m0, s73
	s_nop 0
	global_load_lds_dwordx4 v176, s[86:87]
	s_mov_b32 m0, s92
	s_nop 0
	s_mov_b32 s92, m0
	s_mov_b32 m0, s75
	s_nop 0
	global_load_lds_dwordx4 v178, s[86:87]
	s_mov_b32 m0, s92
	s_mov_b32 s86, m0
	s_mov_b32 m0, s74
	s_nop 0
	global_load_lds_dwordx4 v176, s[30:31]
	s_mov_b32 m0, s86
	s_nop 0
	s_mov_b32 s86, m0
	s_mov_b32 m0, s76
	s_nop 0
	global_load_lds_dwordx4 v178, s[30:31]
	s_mov_b32 m0, s86
	s_waitcnt vmcnt(8)
	s_waitcnt lgkmcnt(0)
	s_barrier
	s_setprio 1
	s_waitcnt lgkmcnt(7)
	v_mfma_f32_16x16x32_bf16 v[142:145], v[46:49], v[170:173], 0
	v_mfma_f32_16x16x32_bf16 v[142:145], v[54:57], v[188:191], v[142:145]
	s_waitcnt lgkmcnt(5)
	v_mfma_f32_16x16x32_bf16 v[138:141], v[58:61], v[170:173], 0
	v_mfma_f32_16x16x32_bf16 v[138:141], v[62:65], v[188:191], v[138:141]
	s_waitcnt lgkmcnt(3)
	v_mfma_f32_16x16x32_bf16 v[126:129], v[46:49], v[192:195], 0
	v_mfma_f32_16x16x32_bf16 v[126:129], v[54:57], v[196:199], v[126:129]
	s_waitcnt lgkmcnt(1)
	v_mfma_f32_16x16x32_bf16 v[122:125], v[58:61], v[192:195], 0
	v_mfma_f32_16x16x32_bf16 v[122:125], v[62:65], v[196:199], v[122:125]
	v_mfma_f32_16x16x32_bf16 v[110:113], v[46:49], v[200:203], 0
	v_mfma_f32_16x16x32_bf16 v[110:113], v[54:57], v[204:207], v[110:113]
	v_mfma_f32_16x16x32_bf16 v[106:109], v[58:61], v[200:203], 0
	v_mfma_f32_16x16x32_bf16 v[106:109], v[62:65], v[204:207], v[106:109]
	v_mfma_f32_16x16x32_bf16 v[94:97], v[46:49], v[208:211], 0
	v_mfma_f32_16x16x32_bf16 v[94:97], v[54:57], v[212:215], v[94:97]
	s_waitcnt lgkmcnt(0)
	v_mfma_f32_16x16x32_bf16 v[90:93], v[58:61], v[208:211], 0
	v_mfma_f32_16x16x32_bf16 v[90:93], v[62:65], v[212:215], v[90:93]
	v_mfma_f32_16x16x32_bf16 v[134:137], v[146:149], v[170:173], 0
	v_mfma_f32_16x16x32_bf16 v[134:137], v[150:153], v[188:191], v[134:137]
	v_mfma_f32_16x16x32_bf16 v[130:133], v[154:157], v[170:173], 0
	v_mfma_f32_16x16x32_bf16 v[130:133], v[158:161], v[188:191], v[130:133]
	v_mfma_f32_16x16x32_bf16 v[118:121], v[146:149], v[192:195], 0
	v_mfma_f32_16x16x32_bf16 v[118:121], v[150:153], v[196:199], v[118:121]
	v_mfma_f32_16x16x32_bf16 v[114:117], v[154:157], v[192:195], 0
	v_mfma_f32_16x16x32_bf16 v[114:117], v[158:161], v[196:199], v[114:117]
	v_mfma_f32_16x16x32_bf16 v[102:105], v[146:149], v[200:203], 0
	v_mfma_f32_16x16x32_bf16 v[102:105], v[150:153], v[204:207], v[102:105]
	v_mfma_f32_16x16x32_bf16 v[98:101], v[154:157], v[200:203], 0
	v_mfma_f32_16x16x32_bf16 v[98:101], v[158:161], v[204:207], v[98:101]
	v_mfma_f32_16x16x32_bf16 v[86:89], v[146:149], v[208:211], 0
	v_mfma_f32_16x16x32_bf16 v[86:89], v[150:153], v[212:215], v[86:89]
	s_setprio 2
	s_barrier
	v_mfma_f32_16x16x32_bf16 v[82:85], v[154:157], v[208:211], 0
	v_mfma_f32_16x16x32_bf16 v[82:85], v[158:161], v[212:215], v[82:85]
	s_setprio 0
	ds_read_b128 v[170:173], v184 offset:16384
	ds_read_b128 v[188:191], v184 offset:17408
	ds_read_b128 v[192:195], v184 offset:18432
	ds_read_b128 v[196:199], v184 offset:19456
	ds_read_b128 v[200:203], v184 offset:20480
	ds_read_b128 v[204:207], v184 offset:21504
	ds_read_b128 v[208:211], v184 offset:22528
	ds_read_b128 v[212:215], v184 offset:23552
	s_mov_b32 s86, m0
	s_mov_b32 m0, s49
	s_nop 0
	global_load_lds_dwordx4 v177, s[34:35]
	s_mov_b32 m0, s86
	s_nop 0
	s_mov_b32 s86, m0
	s_mov_b32 m0, s56
	s_nop 0
	global_load_lds_dwordx4 v179, s[34:35]
	s_mov_b32 m0, s86
	s_add_u32 s86, s34, 0x80000
	s_addc_u32 s87, s35, 0
	s_mov_b32 s92, m0
	s_mov_b32 m0, s57
	s_nop 0
	global_load_lds_dwordx4 v177, s[86:87]
	s_mov_b32 m0, s92
	s_nop 0
	s_mov_b32 s92, m0
	s_mov_b32 m0, s58
	s_nop 0
	global_load_lds_dwordx4 v179, s[86:87]
	s_mov_b32 m0, s92
	s_waitcnt vmcnt(4)
	s_waitcnt lgkmcnt(0)
	s_barrier
	s_setprio 1
	s_waitcnt lgkmcnt(7)
	v_mfma_f32_16x16x32_bf16 v[78:81], v[46:49], v[170:173], 0
	v_mfma_f32_16x16x32_bf16 v[78:81], v[54:57], v[188:191], v[78:81]
	s_waitcnt lgkmcnt(5)
	v_mfma_f32_16x16x32_bf16 v[74:77], v[58:61], v[170:173], 0
	v_mfma_f32_16x16x32_bf16 v[74:77], v[62:65], v[188:191], v[74:77]
	s_waitcnt lgkmcnt(3)
	v_mfma_f32_16x16x32_bf16 v[50:53], v[46:49], v[192:195], 0
	v_mfma_f32_16x16x32_bf16 v[50:53], v[54:57], v[196:199], v[50:53]
	s_waitcnt lgkmcnt(1)
	v_mfma_f32_16x16x32_bf16 v[42:45], v[58:61], v[192:195], 0
	v_mfma_f32_16x16x32_bf16 v[42:45], v[62:65], v[196:199], v[42:45]
	v_mfma_f32_16x16x32_bf16 v[30:33], v[46:49], v[200:203], 0
	v_mfma_f32_16x16x32_bf16 v[30:33], v[54:57], v[204:207], v[30:33]
	v_mfma_f32_16x16x32_bf16 v[26:29], v[58:61], v[200:203], 0
	v_mfma_f32_16x16x32_bf16 v[26:29], v[62:65], v[204:207], v[26:29]
	v_mfma_f32_16x16x32_bf16 v[14:17], v[46:49], v[208:211], 0
	v_mfma_f32_16x16x32_bf16 v[14:17], v[54:57], v[212:215], v[14:17]
	s_waitcnt lgkmcnt(0)
	v_mfma_f32_16x16x32_bf16 v[10:13], v[58:61], v[208:211], 0
	v_mfma_f32_16x16x32_bf16 v[10:13], v[62:65], v[212:215], v[10:13]
	v_mfma_f32_16x16x32_bf16 v[38:41], v[146:149], v[192:195], 0
	v_mfma_f32_16x16x32_bf16 v[38:41], v[150:153], v[196:199], v[38:41]
	v_mfma_f32_16x16x32_bf16 v[34:37], v[154:157], v[192:195], 0
	v_mfma_f32_16x16x32_bf16 v[34:37], v[158:161], v[196:199], v[34:37]
	v_mfma_f32_16x16x32_bf16 v[22:25], v[146:149], v[200:203], 0
	v_mfma_f32_16x16x32_bf16 v[22:25], v[150:153], v[204:207], v[22:25]
	v_mfma_f32_16x16x32_bf16 v[18:21], v[154:157], v[200:203], 0
	v_mfma_f32_16x16x32_bf16 v[18:21], v[158:161], v[204:207], v[18:21]
	v_mfma_f32_16x16x32_bf16 v[6:9], v[146:149], v[208:211], 0
	v_mfma_f32_16x16x32_bf16 v[6:9], v[150:153], v[212:215], v[6:9]
	v_mfma_f32_16x16x32_bf16 v[2:5], v[154:157], v[208:211], 0
	v_mfma_f32_16x16x32_bf16 v[2:5], v[158:161], v[212:215], v[2:5]
	v_mfma_f32_16x16x32_bf16 v[46:49], v[146:149], v[170:173], 0
	v_mfma_f32_16x16x32_bf16 v[46:49], v[150:153], v[188:191], v[46:49]
	s_setprio 2
	s_barrier
	v_mfma_f32_16x16x32_bf16 v[54:57], v[154:157], v[170:173], 0
	v_mfma_f32_16x16x32_bf16 v[54:57], v[158:161], v[188:191], v[54:57]
	s_setprio 0
	ds_read_b128 v[58:61], v185
	ds_read_b128 v[62:65], v185 offset:1024
	ds_read_b128 v[66:69], v185 offset:2048
	ds_read_b128 v[70:73], v185 offset:3072
	ds_read_b128 v[146:149], v186
	ds_read_b128 v[150:153], v186 offset:1024
	ds_read_b128 v[154:157], v186 offset:2048
	ds_read_b128 v[158:161], v186 offset:3072
	ds_read_b128 v[170:173], v184 offset:32768
	ds_read_b128 v[188:191], v184 offset:33792
	ds_read_b128 v[192:195], v184 offset:34816
	ds_read_b128 v[196:199], v184 offset:35840
	ds_read_b128 v[200:203], v184 offset:36864
	ds_read_b128 v[204:207], v184 offset:37888
	ds_read_b128 v[208:211], v184 offset:38912
	ds_read_b128 v[212:215], v184 offset:39936
	s_mov_b32 s86, m0
	s_mov_b32 m0, s48
	s_nop 0
	global_load_lds_dwordx4 v176, s[36:37]
	s_mov_b32 m0, s86
	s_nop 0
	s_mov_b32 s86, m0
	s_mov_b32 m0, s59
	s_nop 0
	global_load_lds_dwordx4 v178, s[36:37]
	s_mov_b32 m0, s86
	s_add_u32 s36, s36, 0x80000
	s_addc_u32 s37, s37, 0
	s_mov_b32 s86, m0
	s_mov_b32 m0, s62
	s_nop 0
	global_load_lds_dwordx4 v176, s[36:37]
	s_mov_b32 m0, s86
	s_nop 0
	s_mov_b32 s86, m0
	s_mov_b32 m0, s63
	s_nop 0
	global_load_lds_dwordx4 v178, s[36:37]
	s_mov_b32 m0, s86
	s_waitcnt vmcnt(8)
	s_waitcnt lgkmcnt(0)
	s_barrier
	s_setprio 1
	s_waitcnt lgkmcnt(7)
	v_mfma_f32_16x16x32_bf16 v[142:145], v[58:61], v[170:173], v[142:145]
	v_mfma_f32_16x16x32_bf16 v[142:145], v[62:65], v[188:191], v[142:145]
	s_waitcnt lgkmcnt(5)
	v_mfma_f32_16x16x32_bf16 v[138:141], v[66:69], v[170:173], v[138:141]
	v_mfma_f32_16x16x32_bf16 v[138:141], v[70:73], v[188:191], v[138:141]
	s_waitcnt lgkmcnt(3)
	v_mfma_f32_16x16x32_bf16 v[126:129], v[58:61], v[192:195], v[126:129]
	v_mfma_f32_16x16x32_bf16 v[126:129], v[62:65], v[196:199], v[126:129]
	s_waitcnt lgkmcnt(1)
	v_mfma_f32_16x16x32_bf16 v[122:125], v[66:69], v[192:195], v[122:125]
	v_mfma_f32_16x16x32_bf16 v[122:125], v[70:73], v[196:199], v[122:125]
	v_mfma_f32_16x16x32_bf16 v[110:113], v[58:61], v[200:203], v[110:113]
	v_mfma_f32_16x16x32_bf16 v[110:113], v[62:65], v[204:207], v[110:113]
	v_mfma_f32_16x16x32_bf16 v[106:109], v[66:69], v[200:203], v[106:109]
	v_mfma_f32_16x16x32_bf16 v[106:109], v[70:73], v[204:207], v[106:109]
	v_mfma_f32_16x16x32_bf16 v[94:97], v[58:61], v[208:211], v[94:97]
	v_mfma_f32_16x16x32_bf16 v[94:97], v[62:65], v[212:215], v[94:97]
	s_waitcnt lgkmcnt(0)
	v_mfma_f32_16x16x32_bf16 v[90:93], v[66:69], v[208:211], v[90:93]
	v_mfma_f32_16x16x32_bf16 v[90:93], v[70:73], v[212:215], v[90:93]
	v_mfma_f32_16x16x32_bf16 v[134:137], v[146:149], v[170:173], v[134:137]
	v_mfma_f32_16x16x32_bf16 v[134:137], v[150:153], v[188:191], v[134:137]
	v_mfma_f32_16x16x32_bf16 v[130:133], v[154:157], v[170:173], v[130:133]
	v_mfma_f32_16x16x32_bf16 v[130:133], v[158:161], v[188:191], v[130:133]
	v_mfma_f32_16x16x32_bf16 v[118:121], v[146:149], v[192:195], v[118:121]
	v_mfma_f32_16x16x32_bf16 v[118:121], v[150:153], v[196:199], v[118:121]
	v_mfma_f32_16x16x32_bf16 v[114:117], v[154:157], v[192:195], v[114:117]
	v_mfma_f32_16x16x32_bf16 v[114:117], v[158:161], v[196:199], v[114:117]
	v_mfma_f32_16x16x32_bf16 v[102:105], v[146:149], v[200:203], v[102:105]
	v_mfma_f32_16x16x32_bf16 v[102:105], v[150:153], v[204:207], v[102:105]
	v_mfma_f32_16x16x32_bf16 v[98:101], v[154:157], v[200:203], v[98:101]
	v_mfma_f32_16x16x32_bf16 v[98:101], v[158:161], v[204:207], v[98:101]
	v_mfma_f32_16x16x32_bf16 v[86:89], v[146:149], v[208:211], v[86:89]
	v_mfma_f32_16x16x32_bf16 v[86:89], v[150:153], v[212:215], v[86:89]
	s_setprio 2
	s_barrier
	v_mfma_f32_16x16x32_bf16 v[82:85], v[154:157], v[208:211], v[82:85]
	v_mfma_f32_16x16x32_bf16 v[82:85], v[158:161], v[212:215], v[82:85]
	s_setprio 0
	ds_read_b128 v[170:173], v184 offset:49152
	ds_read_b128 v[188:191], v184 offset:50176
	ds_read_b128 v[192:195], v184 offset:51200
	ds_read_b128 v[196:199], v184 offset:52224
	ds_read_b128 v[200:203], v184 offset:53248
	ds_read_b128 v[204:207], v184 offset:54272
	ds_read_b128 v[208:211], v184 offset:55296
	ds_read_b128 v[212:215], v184 offset:56320
	s_add_u32 s36, s34, 0x80
	s_addc_u32 s37, s35, 0
	s_mov_b32 s86, m0
	s_mov_b32 m0, s64
	s_nop 0
	global_load_lds_dwordx4 v177, s[36:37]
	s_mov_b32 m0, s86
	s_add_u32 s34, s34, 0x80080
	s_mov_b32 s86, m0
	s_mov_b32 m0, s65
	s_nop 0
	global_load_lds_dwordx4 v179, s[36:37]
	s_mov_b32 m0, s86
	s_addc_u32 s35, s35, 0
	s_mov_b32 s36, m0
	s_mov_b32 m0, s66
	s_nop 0
	global_load_lds_dwordx4 v177, s[34:35]
	s_mov_b32 m0, s36
	s_nop 0
	s_mov_b32 s36, m0
	s_mov_b32 m0, s67
	s_nop 0
	global_load_lds_dwordx4 v179, s[34:35]
	s_mov_b32 m0, s36
	s_waitcnt vmcnt(4)
	s_waitcnt lgkmcnt(0)
	s_barrier
	s_setprio 1
	s_waitcnt lgkmcnt(7)
	v_mfma_f32_16x16x32_bf16 v[78:81], v[58:61], v[170:173], v[78:81]
	v_mfma_f32_16x16x32_bf16 v[78:81], v[62:65], v[188:191], v[78:81]
	s_waitcnt lgkmcnt(5)
	v_mfma_f32_16x16x32_bf16 v[74:77], v[66:69], v[170:173], v[74:77]
	v_mfma_f32_16x16x32_bf16 v[74:77], v[70:73], v[188:191], v[74:77]
	s_waitcnt lgkmcnt(3)
	v_mfma_f32_16x16x32_bf16 v[50:53], v[58:61], v[192:195], v[50:53]
	v_mfma_f32_16x16x32_bf16 v[50:53], v[62:65], v[196:199], v[50:53]
	s_waitcnt lgkmcnt(1)
	v_mfma_f32_16x16x32_bf16 v[42:45], v[66:69], v[192:195], v[42:45]
	v_mfma_f32_16x16x32_bf16 v[42:45], v[70:73], v[196:199], v[42:45]
	v_mfma_f32_16x16x32_bf16 v[30:33], v[58:61], v[200:203], v[30:33]
	v_mfma_f32_16x16x32_bf16 v[30:33], v[62:65], v[204:207], v[30:33]
	v_mfma_f32_16x16x32_bf16 v[26:29], v[66:69], v[200:203], v[26:29]
	v_mfma_f32_16x16x32_bf16 v[26:29], v[70:73], v[204:207], v[26:29]
	v_mfma_f32_16x16x32_bf16 v[14:17], v[58:61], v[208:211], v[14:17]
	v_mfma_f32_16x16x32_bf16 v[14:17], v[62:65], v[212:215], v[14:17]
	s_waitcnt lgkmcnt(0)
	v_mfma_f32_16x16x32_bf16 v[10:13], v[66:69], v[208:211], v[10:13]
	v_mfma_f32_16x16x32_bf16 v[10:13], v[70:73], v[212:215], v[10:13]
	v_mfma_f32_16x16x32_bf16 v[46:49], v[146:149], v[170:173], v[46:49]
	v_mfma_f32_16x16x32_bf16 v[70:73], v[150:153], v[188:191], v[46:49]
	v_mfma_f32_16x16x32_bf16 v[46:49], v[154:157], v[170:173], v[54:57]
	v_mfma_f32_16x16x32_bf16 v[66:69], v[158:161], v[188:191], v[46:49]
	v_mfma_f32_16x16x32_bf16 v[38:41], v[146:149], v[192:195], v[38:41]
	v_mfma_f32_16x16x32_bf16 v[38:41], v[150:153], v[196:199], v[38:41]
	v_mfma_f32_16x16x32_bf16 v[34:37], v[154:157], v[192:195], v[34:37]
	v_mfma_f32_16x16x32_bf16 v[34:37], v[158:161], v[196:199], v[34:37]
	v_mfma_f32_16x16x32_bf16 v[22:25], v[146:149], v[200:203], v[22:25]
	v_mfma_f32_16x16x32_bf16 v[22:25], v[150:153], v[204:207], v[22:25]
	v_mfma_f32_16x16x32_bf16 v[18:21], v[154:157], v[200:203], v[18:21]
	v_mfma_f32_16x16x32_bf16 v[18:21], v[158:161], v[204:207], v[18:21]
	v_mfma_f32_16x16x32_bf16 v[6:9], v[146:149], v[208:211], v[6:9]
	v_mfma_f32_16x16x32_bf16 v[6:9], v[150:153], v[212:215], v[6:9]
	s_setprio 2
	s_barrier
	v_mfma_f32_16x16x32_bf16 v[2:5], v[154:157], v[208:211], v[2:5]
	v_mfma_f32_16x16x32_bf16 v[2:5], v[158:161], v[212:215], v[2:5]
	s_setprio 0
	s_add_i32 s83, s83, 2
	s_add_u32 s79, s79, 0x100
	s_addc_u32 s80, s80, 0
	s_add_u32 s30, s30, 0x100
	s_addc_u32 s31, s31, 0
	s_add_u32 s81, s81, 0x100
	s_addc_u32 s82, s82, 0
	s_cmp_gt_u32 s83, 29
	.p2align 6
.LBB0_1538:
	ds_read_b128 v[46:49], v182
	ds_read_b128 v[54:57], v182 offset:1024
	ds_read_b128 v[58:61], v182 offset:2048
	ds_read_b128 v[62:65], v182 offset:3072
	ds_read_b128 v[146:149], v183
	ds_read_b128 v[150:153], v183 offset:1024
	ds_read_b128 v[154:157], v183 offset:2048
	ds_read_b128 v[158:161], v183 offset:3072
	s_cmp_eq_u32 s83, 28
	s_cselect_b32 s35, s21, s80
	s_cselect_b32 s34, s29, s79
	s_cselect_b32 s37, s7, s82
	s_cselect_b32 s36, s23, s81
	ds_read_b128 v[170:173], v184
	ds_read_b128 v[188:191], v184 offset:1024
	ds_read_b128 v[192:195], v184 offset:2048
	ds_read_b128 v[196:199], v184 offset:3072
	ds_read_b128 v[200:203], v184 offset:4096
	ds_read_b128 v[204:207], v184 offset:5120
	ds_read_b128 v[208:211], v184 offset:6144
	ds_read_b128 v[212:215], v184 offset:7168
	s_add_u32 s86, s30, 0xfff80000
	s_addc_u32 s87, s31, -1
	s_mov_b32 s92, m0
	s_mov_b32 m0, s73
	s_nop 0
	global_load_lds_dwordx4 v176, s[86:87]
	s_mov_b32 m0, s92
	s_nop 0
	s_mov_b32 s92, m0
	s_mov_b32 m0, s75
	s_nop 0
	global_load_lds_dwordx4 v178, s[86:87]
	s_mov_b32 m0, s92
	s_mov_b32 s86, m0
	s_mov_b32 m0, s74
	s_nop 0
	global_load_lds_dwordx4 v176, s[30:31]
	s_mov_b32 m0, s86
	s_nop 0
	s_mov_b32 s86, m0
	s_mov_b32 m0, s76
	s_nop 0
	global_load_lds_dwordx4 v178, s[30:31]
	s_mov_b32 m0, s86
	s_waitcnt vmcnt(8)
	s_waitcnt lgkmcnt(0)
	s_barrier
	s_setprio 1
	s_waitcnt lgkmcnt(7)
	v_mfma_f32_16x16x32_bf16 v[142:145], v[46:49], v[170:173], v[142:145]
	v_mfma_f32_16x16x32_bf16 v[142:145], v[54:57], v[188:191], v[142:145]
	s_waitcnt lgkmcnt(5)
	v_mfma_f32_16x16x32_bf16 v[138:141], v[58:61], v[170:173], v[138:141]
	v_mfma_f32_16x16x32_bf16 v[138:141], v[62:65], v[188:191], v[138:141]
	s_waitcnt lgkmcnt(3)
	v_mfma_f32_16x16x32_bf16 v[126:129], v[46:49], v[192:195], v[126:129]
	v_mfma_f32_16x16x32_bf16 v[126:129], v[54:57], v[196:199], v[126:129]
	s_waitcnt lgkmcnt(1)
	v_mfma_f32_16x16x32_bf16 v[122:125], v[58:61], v[192:195], v[122:125]
	v_mfma_f32_16x16x32_bf16 v[122:125], v[62:65], v[196:199], v[122:125]
	v_mfma_f32_16x16x32_bf16 v[110:113], v[46:49], v[200:203], v[110:113]
	v_mfma_f32_16x16x32_bf16 v[110:113], v[54:57], v[204:207], v[110:113]
	v_mfma_f32_16x16x32_bf16 v[106:109], v[58:61], v[200:203], v[106:109]
	v_mfma_f32_16x16x32_bf16 v[106:109], v[62:65], v[204:207], v[106:109]
	v_mfma_f32_16x16x32_bf16 v[94:97], v[46:49], v[208:211], v[94:97]
	v_mfma_f32_16x16x32_bf16 v[94:97], v[54:57], v[212:215], v[94:97]
	s_waitcnt lgkmcnt(0)
	v_mfma_f32_16x16x32_bf16 v[90:93], v[58:61], v[208:211], v[90:93]
	v_mfma_f32_16x16x32_bf16 v[90:93], v[62:65], v[212:215], v[90:93]
	v_mfma_f32_16x16x32_bf16 v[134:137], v[146:149], v[170:173], v[134:137]
	v_mfma_f32_16x16x32_bf16 v[134:137], v[150:153], v[188:191], v[134:137]
	v_mfma_f32_16x16x32_bf16 v[130:133], v[154:157], v[170:173], v[130:133]
	v_mfma_f32_16x16x32_bf16 v[130:133], v[158:161], v[188:191], v[130:133]
	v_mfma_f32_16x16x32_bf16 v[118:121], v[146:149], v[192:195], v[118:121]
	v_mfma_f32_16x16x32_bf16 v[118:121], v[150:153], v[196:199], v[118:121]
	v_mfma_f32_16x16x32_bf16 v[114:117], v[154:157], v[192:195], v[114:117]
	v_mfma_f32_16x16x32_bf16 v[114:117], v[158:161], v[196:199], v[114:117]
	v_mfma_f32_16x16x32_bf16 v[102:105], v[146:149], v[200:203], v[102:105]
	v_mfma_f32_16x16x32_bf16 v[102:105], v[150:153], v[204:207], v[102:105]
	v_mfma_f32_16x16x32_bf16 v[98:101], v[154:157], v[200:203], v[98:101]
	v_mfma_f32_16x16x32_bf16 v[98:101], v[158:161], v[204:207], v[98:101]
	v_mfma_f32_16x16x32_bf16 v[86:89], v[146:149], v[208:211], v[86:89]
	v_mfma_f32_16x16x32_bf16 v[86:89], v[150:153], v[212:215], v[86:89]
	s_setprio 2
	s_barrier
	v_mfma_f32_16x16x32_bf16 v[82:85], v[154:157], v[208:211], v[82:85]
	v_mfma_f32_16x16x32_bf16 v[82:85], v[158:161], v[212:215], v[82:85]
	s_setprio 0
	ds_read_b128 v[170:173], v184 offset:16384
	ds_read_b128 v[188:191], v184 offset:17408
	ds_read_b128 v[192:195], v184 offset:18432
	ds_read_b128 v[196:199], v184 offset:19456
	ds_read_b128 v[200:203], v184 offset:20480
	ds_read_b128 v[204:207], v184 offset:21504
	ds_read_b128 v[208:211], v184 offset:22528
	ds_read_b128 v[212:215], v184 offset:23552
	s_mov_b32 s86, m0
	s_mov_b32 m0, s49
	s_nop 0
	global_load_lds_dwordx4 v177, s[34:35]
	s_mov_b32 m0, s86
	s_nop 0
	s_mov_b32 s86, m0
	s_mov_b32 m0, s56
	s_nop 0
	global_load_lds_dwordx4 v179, s[34:35]
	s_mov_b32 m0, s86
	s_add_u32 s86, s34, 0x80000
	s_addc_u32 s87, s35, 0
	s_mov_b32 s92, m0
	s_mov_b32 m0, s57
	s_nop 0
	global_load_lds_dwordx4 v177, s[86:87]
	s_mov_b32 m0, s92
	s_nop 0
	s_mov_b32 s92, m0
	s_mov_b32 m0, s58
	s_nop 0
	global_load_lds_dwordx4 v179, s[86:87]
	s_mov_b32 m0, s92
	s_waitcnt vmcnt(4)
	s_waitcnt lgkmcnt(0)
	s_barrier
	s_setprio 1
	s_waitcnt lgkmcnt(7)
	v_mfma_f32_16x16x32_bf16 v[78:81], v[46:49], v[170:173], v[78:81]
	v_mfma_f32_16x16x32_bf16 v[78:81], v[54:57], v[188:191], v[78:81]
	s_waitcnt lgkmcnt(5)
	v_mfma_f32_16x16x32_bf16 v[74:77], v[58:61], v[170:173], v[74:77]
	v_mfma_f32_16x16x32_bf16 v[74:77], v[62:65], v[188:191], v[74:77]
	s_waitcnt lgkmcnt(3)
	v_mfma_f32_16x16x32_bf16 v[50:53], v[46:49], v[192:195], v[50:53]
	v_mfma_f32_16x16x32_bf16 v[50:53], v[54:57], v[196:199], v[50:53]
	s_waitcnt lgkmcnt(1)
	v_mfma_f32_16x16x32_bf16 v[42:45], v[58:61], v[192:195], v[42:45]
	v_mfma_f32_16x16x32_bf16 v[42:45], v[62:65], v[196:199], v[42:45]
	v_mfma_f32_16x16x32_bf16 v[30:33], v[46:49], v[200:203], v[30:33]
	v_mfma_f32_16x16x32_bf16 v[30:33], v[54:57], v[204:207], v[30:33]
	v_mfma_f32_16x16x32_bf16 v[26:29], v[58:61], v[200:203], v[26:29]
	v_mfma_f32_16x16x32_bf16 v[26:29], v[62:65], v[204:207], v[26:29]
	v_mfma_f32_16x16x32_bf16 v[14:17], v[46:49], v[208:211], v[14:17]
	v_mfma_f32_16x16x32_bf16 v[14:17], v[54:57], v[212:215], v[14:17]
	s_waitcnt lgkmcnt(0)
	v_mfma_f32_16x16x32_bf16 v[10:13], v[58:61], v[208:211], v[10:13]
	v_mfma_f32_16x16x32_bf16 v[10:13], v[62:65], v[212:215], v[10:13]
	v_mfma_f32_16x16x32_bf16 v[38:41], v[146:149], v[192:195], v[38:41]
	v_mfma_f32_16x16x32_bf16 v[38:41], v[150:153], v[196:199], v[38:41]
	v_mfma_f32_16x16x32_bf16 v[34:37], v[154:157], v[192:195], v[34:37]
	v_mfma_f32_16x16x32_bf16 v[34:37], v[158:161], v[196:199], v[34:37]
	v_mfma_f32_16x16x32_bf16 v[22:25], v[146:149], v[200:203], v[22:25]
	v_mfma_f32_16x16x32_bf16 v[22:25], v[150:153], v[204:207], v[22:25]
	v_mfma_f32_16x16x32_bf16 v[18:21], v[154:157], v[200:203], v[18:21]
	v_mfma_f32_16x16x32_bf16 v[18:21], v[158:161], v[204:207], v[18:21]
	v_mfma_f32_16x16x32_bf16 v[6:9], v[146:149], v[208:211], v[6:9]
	v_mfma_f32_16x16x32_bf16 v[6:9], v[150:153], v[212:215], v[6:9]
	v_mfma_f32_16x16x32_bf16 v[2:5], v[154:157], v[208:211], v[2:5]
	v_mfma_f32_16x16x32_bf16 v[2:5], v[158:161], v[212:215], v[2:5]
	v_mfma_f32_16x16x32_bf16 v[46:49], v[146:149], v[170:173], v[70:73]
	v_mfma_f32_16x16x32_bf16 v[46:49], v[150:153], v[188:191], v[46:49]
	s_setprio 2
	s_barrier
	v_mfma_f32_16x16x32_bf16 v[54:57], v[154:157], v[170:173], v[66:69]
	v_mfma_f32_16x16x32_bf16 v[54:57], v[158:161], v[188:191], v[54:57]
	s_setprio 0
	ds_read_b128 v[58:61], v185
	ds_read_b128 v[62:65], v185 offset:1024
	ds_read_b128 v[66:69], v185 offset:2048
	ds_read_b128 v[70:73], v185 offset:3072
	ds_read_b128 v[146:149], v186
	ds_read_b128 v[150:153], v186 offset:1024
	ds_read_b128 v[154:157], v186 offset:2048
	ds_read_b128 v[158:161], v186 offset:3072
	ds_read_b128 v[170:173], v184 offset:32768
	ds_read_b128 v[188:191], v184 offset:33792
	ds_read_b128 v[192:195], v184 offset:34816
	ds_read_b128 v[196:199], v184 offset:35840
	ds_read_b128 v[200:203], v184 offset:36864
	ds_read_b128 v[204:207], v184 offset:37888
	ds_read_b128 v[208:211], v184 offset:38912
	ds_read_b128 v[212:215], v184 offset:39936
	s_mov_b32 s86, m0
	s_mov_b32 m0, s48
	s_nop 0
	global_load_lds_dwordx4 v176, s[36:37]
	s_mov_b32 m0, s86
	s_nop 0
	s_mov_b32 s86, m0
	s_mov_b32 m0, s59
	s_nop 0
	global_load_lds_dwordx4 v178, s[36:37]
	s_mov_b32 m0, s86
	s_add_u32 s36, s36, 0x80000
	s_addc_u32 s37, s37, 0
	s_mov_b32 s86, m0
	s_mov_b32 m0, s62
	s_nop 0
	global_load_lds_dwordx4 v176, s[36:37]
	s_mov_b32 m0, s86
	s_nop 0
	s_mov_b32 s86, m0
	s_mov_b32 m0, s63
	s_nop 0
	global_load_lds_dwordx4 v178, s[36:37]
	s_mov_b32 m0, s86
	s_waitcnt vmcnt(8)
	s_waitcnt lgkmcnt(0)
	s_barrier
	s_setprio 1
	s_waitcnt lgkmcnt(7)
	v_mfma_f32_16x16x32_bf16 v[142:145], v[58:61], v[170:173], v[142:145]
	v_mfma_f32_16x16x32_bf16 v[142:145], v[62:65], v[188:191], v[142:145]
	s_waitcnt lgkmcnt(5)
	v_mfma_f32_16x16x32_bf16 v[138:141], v[66:69], v[170:173], v[138:141]
	v_mfma_f32_16x16x32_bf16 v[138:141], v[70:73], v[188:191], v[138:141]
	s_waitcnt lgkmcnt(3)
	v_mfma_f32_16x16x32_bf16 v[126:129], v[58:61], v[192:195], v[126:129]
	v_mfma_f32_16x16x32_bf16 v[126:129], v[62:65], v[196:199], v[126:129]
	s_waitcnt lgkmcnt(1)
	v_mfma_f32_16x16x32_bf16 v[122:125], v[66:69], v[192:195], v[122:125]
	v_mfma_f32_16x16x32_bf16 v[122:125], v[70:73], v[196:199], v[122:125]
	v_mfma_f32_16x16x32_bf16 v[110:113], v[58:61], v[200:203], v[110:113]
	v_mfma_f32_16x16x32_bf16 v[110:113], v[62:65], v[204:207], v[110:113]
	v_mfma_f32_16x16x32_bf16 v[106:109], v[66:69], v[200:203], v[106:109]
	v_mfma_f32_16x16x32_bf16 v[106:109], v[70:73], v[204:207], v[106:109]
	v_mfma_f32_16x16x32_bf16 v[94:97], v[58:61], v[208:211], v[94:97]
	v_mfma_f32_16x16x32_bf16 v[94:97], v[62:65], v[212:215], v[94:97]
	s_waitcnt lgkmcnt(0)
	v_mfma_f32_16x16x32_bf16 v[90:93], v[66:69], v[208:211], v[90:93]
	v_mfma_f32_16x16x32_bf16 v[90:93], v[70:73], v[212:215], v[90:93]
	v_mfma_f32_16x16x32_bf16 v[134:137], v[146:149], v[170:173], v[134:137]
	v_mfma_f32_16x16x32_bf16 v[134:137], v[150:153], v[188:191], v[134:137]
	v_mfma_f32_16x16x32_bf16 v[130:133], v[154:157], v[170:173], v[130:133]
	v_mfma_f32_16x16x32_bf16 v[130:133], v[158:161], v[188:191], v[130:133]
	v_mfma_f32_16x16x32_bf16 v[118:121], v[146:149], v[192:195], v[118:121]
	v_mfma_f32_16x16x32_bf16 v[118:121], v[150:153], v[196:199], v[118:121]
	v_mfma_f32_16x16x32_bf16 v[114:117], v[154:157], v[192:195], v[114:117]
	v_mfma_f32_16x16x32_bf16 v[114:117], v[158:161], v[196:199], v[114:117]
	v_mfma_f32_16x16x32_bf16 v[102:105], v[146:149], v[200:203], v[102:105]
	v_mfma_f32_16x16x32_bf16 v[102:105], v[150:153], v[204:207], v[102:105]
	v_mfma_f32_16x16x32_bf16 v[98:101], v[154:157], v[200:203], v[98:101]
	v_mfma_f32_16x16x32_bf16 v[98:101], v[158:161], v[204:207], v[98:101]
	v_mfma_f32_16x16x32_bf16 v[86:89], v[146:149], v[208:211], v[86:89]
	v_mfma_f32_16x16x32_bf16 v[86:89], v[150:153], v[212:215], v[86:89]
	s_setprio 2
	s_barrier
	v_mfma_f32_16x16x32_bf16 v[82:85], v[154:157], v[208:211], v[82:85]
	v_mfma_f32_16x16x32_bf16 v[82:85], v[158:161], v[212:215], v[82:85]
	s_setprio 0
	ds_read_b128 v[170:173], v184 offset:49152
	ds_read_b128 v[188:191], v184 offset:50176
	ds_read_b128 v[192:195], v184 offset:51200
	ds_read_b128 v[196:199], v184 offset:52224
	ds_read_b128 v[200:203], v184 offset:53248
	ds_read_b128 v[204:207], v184 offset:54272
	ds_read_b128 v[208:211], v184 offset:55296
	ds_read_b128 v[212:215], v184 offset:56320
	s_add_u32 s36, s34, 0x80
	s_addc_u32 s37, s35, 0
	s_mov_b32 s86, m0
	s_mov_b32 m0, s64
	s_nop 0
	global_load_lds_dwordx4 v177, s[36:37]
	s_mov_b32 m0, s86
	s_add_u32 s34, s34, 0x80080
	s_mov_b32 s86, m0
	s_mov_b32 m0, s65
	s_nop 0
	global_load_lds_dwordx4 v179, s[36:37]
	s_mov_b32 m0, s86
	s_addc_u32 s35, s35, 0
	s_mov_b32 s36, m0
	s_mov_b32 m0, s66
	s_nop 0
	global_load_lds_dwordx4 v177, s[34:35]
	s_mov_b32 m0, s36
	s_nop 0
	s_mov_b32 s36, m0
	s_mov_b32 m0, s67
	s_nop 0
	global_load_lds_dwordx4 v179, s[34:35]
	s_mov_b32 m0, s36
	s_waitcnt vmcnt(4)
	s_waitcnt lgkmcnt(0)
	s_barrier
	s_setprio 1
	s_waitcnt lgkmcnt(7)
	v_mfma_f32_16x16x32_bf16 v[78:81], v[58:61], v[170:173], v[78:81]
	v_mfma_f32_16x16x32_bf16 v[78:81], v[62:65], v[188:191], v[78:81]
	s_waitcnt lgkmcnt(5)
	v_mfma_f32_16x16x32_bf16 v[74:77], v[66:69], v[170:173], v[74:77]
	v_mfma_f32_16x16x32_bf16 v[74:77], v[70:73], v[188:191], v[74:77]
	s_waitcnt lgkmcnt(3)
	v_mfma_f32_16x16x32_bf16 v[50:53], v[58:61], v[192:195], v[50:53]
	v_mfma_f32_16x16x32_bf16 v[50:53], v[62:65], v[196:199], v[50:53]
	s_waitcnt lgkmcnt(1)
	v_mfma_f32_16x16x32_bf16 v[42:45], v[66:69], v[192:195], v[42:45]
	v_mfma_f32_16x16x32_bf16 v[42:45], v[70:73], v[196:199], v[42:45]
	v_mfma_f32_16x16x32_bf16 v[30:33], v[58:61], v[200:203], v[30:33]
	v_mfma_f32_16x16x32_bf16 v[30:33], v[62:65], v[204:207], v[30:33]
	v_mfma_f32_16x16x32_bf16 v[26:29], v[66:69], v[200:203], v[26:29]
	v_mfma_f32_16x16x32_bf16 v[26:29], v[70:73], v[204:207], v[26:29]
	v_mfma_f32_16x16x32_bf16 v[14:17], v[58:61], v[208:211], v[14:17]
	v_mfma_f32_16x16x32_bf16 v[14:17], v[62:65], v[212:215], v[14:17]
	s_waitcnt lgkmcnt(0)
	v_mfma_f32_16x16x32_bf16 v[10:13], v[66:69], v[208:211], v[10:13]
	v_mfma_f32_16x16x32_bf16 v[10:13], v[70:73], v[212:215], v[10:13]
	v_mfma_f32_16x16x32_bf16 v[46:49], v[146:149], v[170:173], v[46:49]
	v_mfma_f32_16x16x32_bf16 v[70:73], v[150:153], v[188:191], v[46:49]
	v_mfma_f32_16x16x32_bf16 v[46:49], v[154:157], v[170:173], v[54:57]
	v_mfma_f32_16x16x32_bf16 v[66:69], v[158:161], v[188:191], v[46:49]
	v_mfma_f32_16x16x32_bf16 v[38:41], v[146:149], v[192:195], v[38:41]
	v_mfma_f32_16x16x32_bf16 v[38:41], v[150:153], v[196:199], v[38:41]
	v_mfma_f32_16x16x32_bf16 v[34:37], v[154:157], v[192:195], v[34:37]
	v_mfma_f32_16x16x32_bf16 v[34:37], v[158:161], v[196:199], v[34:37]
	v_mfma_f32_16x16x32_bf16 v[22:25], v[146:149], v[200:203], v[22:25]
	v_mfma_f32_16x16x32_bf16 v[22:25], v[150:153], v[204:207], v[22:25]
	v_mfma_f32_16x16x32_bf16 v[18:21], v[154:157], v[200:203], v[18:21]
	v_mfma_f32_16x16x32_bf16 v[18:21], v[158:161], v[204:207], v[18:21]
	v_mfma_f32_16x16x32_bf16 v[6:9], v[146:149], v[208:211], v[6:9]
	v_mfma_f32_16x16x32_bf16 v[6:9], v[150:153], v[212:215], v[6:9]
	s_setprio 2
	s_barrier
	v_mfma_f32_16x16x32_bf16 v[2:5], v[154:157], v[208:211], v[2:5]
	v_mfma_f32_16x16x32_bf16 v[2:5], v[158:161], v[212:215], v[2:5]
	s_setprio 0
	s_add_i32 s83, s83, 2
	s_add_u32 s79, s79, 0x100
	s_addc_u32 s80, s80, 0
	s_add_u32 s30, s30, 0x100
	s_addc_u32 s31, s31, 0
	s_add_u32 s81, s81, 0x100
	s_addc_u32 s82, s82, 0
	s_cmp_gt_u32 s83, 29
	s_cbranch_scc0 .LBB0_1538
	s_and_b64 vcc, exec, s[16:17]
	s_cbranch_vccz .LBB0_1541
	s_barrier

.LBB0_1784:
	s_ashr_i32 s11, s10, 31
	s_lshl_b64 s[12:13], s[10:11], 20
	s_add_u32 s12, s26, s12
	s_addc_u32 s13, s27, s13
	s_and_b64 s[14:15], s[2:3], exec
	s_cselect_b32 s11, s13, s21
	s_cselect_b32 s64, s12, s20
	s_ashr_i32 s9, s8, 31
	s_lshl_b64 s[14:15], s[8:9], 20
	s_add_u32 s14, s28, s14
	s_addc_u32 s15, s29, s15
	s_and_b64 s[22:23], s[2:3], exec
	s_cselect_b32 s9, s15, s19
	s_cselect_b32 s65, s14, s18
	s_add_u32 s66, s18, 0x100
	s_addc_u32 s67, s19, 0
	s_add_u32 s18, s20, 0x80080
	s_addc_u32 s19, s21, 0
	s_add_u32 s70, s20, 0x100
	s_addc_u32 s71, s21, 0
	s_mov_b32 s73, -2
	ds_read_b128 v[148:151], v143
	ds_read_b128 v[152:155], v143 offset:1024
	ds_read_b128 v[156:159], v143 offset:2048
	ds_read_b128 v[160:163], v143 offset:3072
	ds_read_b128 v[164:167], v144
	ds_read_b128 v[168:171], v144 offset:1024
	ds_read_b128 v[172:175], v144 offset:2048
	ds_read_b128 v[176:179], v144 offset:3072
	s_cmp_eq_u32 s73, 28
	s_cselect_b32 s21, s9, s67
	s_cselect_b32 s20, s65, s66
	s_cselect_b32 s23, s11, s71
	s_cselect_b32 s22, s64, s70
	ds_read_b128 v[180:183], v145
	ds_read_b128 v[184:187], v145 offset:1024
	ds_read_b128 v[188:191], v145 offset:2048
	ds_read_b128 v[192:195], v145 offset:3072
	ds_read_b128 v[196:199], v145 offset:4096
	ds_read_b128 v[200:203], v145 offset:5120
	ds_read_b128 v[204:207], v145 offset:6144
	ds_read_b128 v[208:211], v145 offset:7168
	s_add_u32 s74, s18, 0xfff80000
	s_addc_u32 s75, s19, -1
	s_mov_b32 s76, m0
	s_mov_b32 m0, s56
	s_nop 0
	global_load_lds_dwordx4 v138, s[74:75]
	s_mov_b32 m0, s76
	s_nop 0
	s_mov_b32 s76, m0
	s_mov_b32 m0, s59
	s_nop 0
	global_load_lds_dwordx4 v140, s[74:75]
	s_mov_b32 m0, s76
	s_mov_b32 s74, m0
	s_mov_b32 m0, s57
	s_nop 0
	global_load_lds_dwordx4 v138, s[18:19]
	s_mov_b32 m0, s74
	s_nop 0
	s_mov_b32 s74, m0
	s_mov_b32 m0, s62
	s_nop 0
	global_load_lds_dwordx4 v140, s[18:19]
	s_mov_b32 m0, s74
	s_waitcnt vmcnt(8)
	s_waitcnt lgkmcnt(0)
	s_barrier
	s_setprio 1
	s_waitcnt lgkmcnt(7)
	v_mfma_f32_16x16x32_bf16 v[126:129], v[148:151], v[180:183], 0
	v_mfma_f32_16x16x32_bf16 v[126:129], v[152:155], v[184:187], v[126:129]
	s_waitcnt lgkmcnt(5)
	v_mfma_f32_16x16x32_bf16 v[122:125], v[156:159], v[180:183], 0
	v_mfma_f32_16x16x32_bf16 v[122:125], v[160:163], v[184:187], v[122:125]
	s_waitcnt lgkmcnt(3)
	v_mfma_f32_16x16x32_bf16 v[106:109], v[156:159], v[188:191], 0
	v_mfma_f32_16x16x32_bf16 v[106:109], v[160:163], v[192:195], v[106:109]
	s_waitcnt lgkmcnt(1)
	v_mfma_f32_16x16x32_bf16 v[110:113], v[148:151], v[188:191], 0
	v_mfma_f32_16x16x32_bf16 v[110:113], v[152:155], v[192:195], v[110:113]
	v_mfma_f32_16x16x32_bf16 v[94:97], v[148:151], v[196:199], 0
	v_mfma_f32_16x16x32_bf16 v[94:97], v[152:155], v[200:203], v[94:97]
	v_mfma_f32_16x16x32_bf16 v[90:93], v[156:159], v[196:199], 0
	v_mfma_f32_16x16x32_bf16 v[90:93], v[160:163], v[200:203], v[90:93]
	v_mfma_f32_16x16x32_bf16 v[74:77], v[156:159], v[204:207], 0
	v_mfma_f32_16x16x32_bf16 v[74:77], v[160:163], v[208:211], v[74:77]
	s_waitcnt lgkmcnt(0)
	v_mfma_f32_16x16x32_bf16 v[78:81], v[148:151], v[204:207], 0
	v_mfma_f32_16x16x32_bf16 v[78:81], v[152:155], v[208:211], v[78:81]
	v_mfma_f32_16x16x32_bf16 v[118:121], v[164:167], v[180:183], 0
	v_mfma_f32_16x16x32_bf16 v[118:121], v[168:171], v[184:187], v[118:121]
	v_mfma_f32_16x16x32_bf16 v[114:117], v[172:175], v[180:183], 0
	v_mfma_f32_16x16x32_bf16 v[114:117], v[176:179], v[184:187], v[114:117]
	v_mfma_f32_16x16x32_bf16 v[98:101], v[172:175], v[188:191], 0
	v_mfma_f32_16x16x32_bf16 v[98:101], v[176:179], v[192:195], v[98:101]
	v_mfma_f32_16x16x32_bf16 v[102:105], v[164:167], v[188:191], 0
	v_mfma_f32_16x16x32_bf16 v[102:105], v[168:171], v[192:195], v[102:105]
	v_mfma_f32_16x16x32_bf16 v[86:89], v[164:167], v[196:199], 0
	v_mfma_f32_16x16x32_bf16 v[86:89], v[168:171], v[200:203], v[86:89]
	v_mfma_f32_16x16x32_bf16 v[82:85], v[172:175], v[196:199], 0
	v_mfma_f32_16x16x32_bf16 v[82:85], v[176:179], v[200:203], v[82:85]
	v_mfma_f32_16x16x32_bf16 v[66:69], v[172:175], v[204:207], 0
	v_mfma_f32_16x16x32_bf16 v[66:69], v[176:179], v[208:211], v[66:69]
	s_setprio 2
	s_barrier
	v_mfma_f32_16x16x32_bf16 v[70:73], v[164:167], v[204:207], 0
	v_mfma_f32_16x16x32_bf16 v[70:73], v[168:171], v[208:211], v[70:73]
	s_setprio 0
	ds_read_b128 v[180:183], v145 offset:16384
	ds_read_b128 v[184:187], v145 offset:17408
	ds_read_b128 v[188:191], v145 offset:18432
	ds_read_b128 v[192:195], v145 offset:19456
	ds_read_b128 v[196:199], v145 offset:20480
	ds_read_b128 v[200:203], v145 offset:21504
	ds_read_b128 v[204:207], v145 offset:22528
	ds_read_b128 v[208:211], v145 offset:23552
	s_mov_b32 s74, m0
	s_mov_b32 m0, s35
	s_nop 0
	global_load_lds_dwordx4 v139, s[20:21]
	s_mov_b32 m0, s74
	s_nop 0
	s_mov_b32 s74, m0
	s_mov_b32 m0, s36
	s_nop 0
	global_load_lds_dwordx4 v141, s[20:21]
	s_mov_b32 m0, s74
	s_add_u32 s74, s20, 0x80000
	s_addc_u32 s75, s21, 0
	s_mov_b32 s76, m0
	s_mov_b32 m0, s37
	s_nop 0
	global_load_lds_dwordx4 v139, s[74:75]
	s_mov_b32 m0, s76
	s_nop 0
	s_mov_b32 s76, m0
	s_mov_b32 m0, s40
	s_nop 0
	global_load_lds_dwordx4 v141, s[74:75]
	s_mov_b32 m0, s76
	s_waitcnt vmcnt(4)
	s_waitcnt lgkmcnt(0)
	s_barrier
	s_setprio 1
	s_waitcnt lgkmcnt(7)
	v_mfma_f32_16x16x32_bf16 v[62:65], v[148:151], v[180:183], 0
	v_mfma_f32_16x16x32_bf16 v[62:65], v[152:155], v[184:187], v[62:65]
	s_waitcnt lgkmcnt(5)
	v_mfma_f32_16x16x32_bf16 v[58:61], v[156:159], v[180:183], 0
	v_mfma_f32_16x16x32_bf16 v[58:61], v[160:163], v[184:187], v[58:61]
	s_waitcnt lgkmcnt(3)
	v_mfma_f32_16x16x32_bf16 v[42:45], v[156:159], v[188:191], 0
	v_mfma_f32_16x16x32_bf16 v[42:45], v[160:163], v[192:195], v[42:45]
	s_waitcnt lgkmcnt(1)
	v_mfma_f32_16x16x32_bf16 v[46:49], v[148:151], v[188:191], 0
	v_mfma_f32_16x16x32_bf16 v[46:49], v[152:155], v[192:195], v[46:49]
	v_mfma_f32_16x16x32_bf16 v[30:33], v[148:151], v[196:199], 0
	v_mfma_f32_16x16x32_bf16 v[30:33], v[152:155], v[200:203], v[30:33]
	v_mfma_f32_16x16x32_bf16 v[26:29], v[156:159], v[196:199], 0
	v_mfma_f32_16x16x32_bf16 v[26:29], v[160:163], v[200:203], v[26:29]
	v_mfma_f32_16x16x32_bf16 v[10:13], v[156:159], v[204:207], 0
	v_mfma_f32_16x16x32_bf16 v[10:13], v[160:163], v[208:211], v[10:13]
	s_waitcnt lgkmcnt(0)
	v_mfma_f32_16x16x32_bf16 v[14:17], v[148:151], v[204:207], 0
	v_mfma_f32_16x16x32_bf16 v[14:17], v[152:155], v[208:211], v[14:17]
	v_mfma_f32_16x16x32_bf16 v[54:57], v[164:167], v[180:183], 0
	v_mfma_f32_16x16x32_bf16 v[54:57], v[168:171], v[184:187], v[54:57]
	v_mfma_f32_16x16x32_bf16 v[50:53], v[172:175], v[180:183], 0
	v_mfma_f32_16x16x32_bf16 v[50:53], v[176:179], v[184:187], v[50:53]
	v_mfma_f32_16x16x32_bf16 v[34:37], v[172:175], v[188:191], 0
	v_mfma_f32_16x16x32_bf16 v[34:37], v[176:179], v[192:195], v[34:37]
	v_mfma_f32_16x16x32_bf16 v[38:41], v[164:167], v[188:191], 0
	v_mfma_f32_16x16x32_bf16 v[38:41], v[168:171], v[192:195], v[38:41]
	v_mfma_f32_16x16x32_bf16 v[22:25], v[164:167], v[196:199], 0
	v_mfma_f32_16x16x32_bf16 v[22:25], v[168:171], v[200:203], v[22:25]
	v_mfma_f32_16x16x32_bf16 v[18:21], v[172:175], v[196:199], 0
	v_mfma_f32_16x16x32_bf16 v[18:21], v[176:179], v[200:203], v[18:21]
	v_mfma_f32_16x16x32_bf16 v[2:5], v[172:175], v[204:207], 0
	v_mfma_f32_16x16x32_bf16 v[2:5], v[176:179], v[208:211], v[2:5]
	s_setprio 2
	s_barrier
	v_mfma_f32_16x16x32_bf16 v[6:9], v[164:167], v[204:207], 0
	v_mfma_f32_16x16x32_bf16 v[6:9], v[168:171], v[208:211], v[6:9]
	s_setprio 0
	ds_read_b128 v[148:151], v146
	ds_read_b128 v[152:155], v146 offset:1024
	ds_read_b128 v[156:159], v146 offset:2048
	ds_read_b128 v[160:163], v146 offset:3072
	ds_read_b128 v[164:167], v147
	ds_read_b128 v[168:171], v147 offset:1024
	ds_read_b128 v[172:175], v147 offset:2048
	ds_read_b128 v[176:179], v147 offset:3072
	ds_read_b128 v[180:183], v145 offset:32768
	ds_read_b128 v[184:187], v145 offset:33792
	ds_read_b128 v[188:191], v145 offset:34816
	ds_read_b128 v[192:195], v145 offset:35840
	ds_read_b128 v[196:199], v145 offset:36864
	ds_read_b128 v[200:203], v145 offset:37888
	ds_read_b128 v[204:207], v145 offset:38912
	ds_read_b128 v[208:211], v145 offset:39936
	s_mov_b32 s74, m0
	s_mov_b32 m0, s31
	s_nop 0
	global_load_lds_dwordx4 v138, s[22:23]
	s_mov_b32 m0, s74
	s_nop 0
	s_mov_b32 s74, m0
	s_mov_b32 m0, s41
	s_nop 0
	global_load_lds_dwordx4 v140, s[22:23]
	s_mov_b32 m0, s74
	s_add_u32 s22, s22, 0x80000
	s_addc_u32 s23, s23, 0
	s_mov_b32 s74, m0
	s_mov_b32 m0, s42
	s_nop 0
	global_load_lds_dwordx4 v138, s[22:23]
	s_mov_b32 m0, s74
	s_nop 0
	s_mov_b32 s74, m0
	s_mov_b32 m0, s43
	s_nop 0
	global_load_lds_dwordx4 v140, s[22:23]
	s_mov_b32 m0, s74
	s_waitcnt vmcnt(8)
	s_waitcnt lgkmcnt(0)
	s_barrier
	s_setprio 1
	s_waitcnt lgkmcnt(7)
	v_mfma_f32_16x16x32_bf16 v[126:129], v[148:151], v[180:183], v[126:129]
	v_mfma_f32_16x16x32_bf16 v[126:129], v[152:155], v[184:187], v[126:129]
	s_waitcnt lgkmcnt(5)
	v_mfma_f32_16x16x32_bf16 v[122:125], v[156:159], v[180:183], v[122:125]
	v_mfma_f32_16x16x32_bf16 v[122:125], v[160:163], v[184:187], v[122:125]
	s_waitcnt lgkmcnt(3)
	v_mfma_f32_16x16x32_bf16 v[106:109], v[156:159], v[188:191], v[106:109]
	v_mfma_f32_16x16x32_bf16 v[106:109], v[160:163], v[192:195], v[106:109]
	s_waitcnt lgkmcnt(1)
	v_mfma_f32_16x16x32_bf16 v[110:113], v[148:151], v[188:191], v[110:113]
	v_mfma_f32_16x16x32_bf16 v[110:113], v[152:155], v[192:195], v[110:113]
	v_mfma_f32_16x16x32_bf16 v[94:97], v[148:151], v[196:199], v[94:97]
	v_mfma_f32_16x16x32_bf16 v[94:97], v[152:155], v[200:203], v[94:97]
	v_mfma_f32_16x16x32_bf16 v[90:93], v[156:159], v[196:199], v[90:93]
	v_mfma_f32_16x16x32_bf16 v[90:93], v[160:163], v[200:203], v[90:93]
	v_mfma_f32_16x16x32_bf16 v[74:77], v[156:159], v[204:207], v[74:77]
	v_mfma_f32_16x16x32_bf16 v[74:77], v[160:163], v[208:211], v[74:77]
	s_waitcnt lgkmcnt(0)
	v_mfma_f32_16x16x32_bf16 v[78:81], v[148:151], v[204:207], v[78:81]
	v_mfma_f32_16x16x32_bf16 v[78:81], v[152:155], v[208:211], v[78:81]
	v_mfma_f32_16x16x32_bf16 v[118:121], v[164:167], v[180:183], v[118:121]
	v_mfma_f32_16x16x32_bf16 v[118:121], v[168:171], v[184:187], v[118:121]
	v_mfma_f32_16x16x32_bf16 v[114:117], v[172:175], v[180:183], v[114:117]
	v_mfma_f32_16x16x32_bf16 v[114:117], v[176:179], v[184:187], v[114:117]
	v_mfma_f32_16x16x32_bf16 v[98:101], v[172:175], v[188:191], v[98:101]
	v_mfma_f32_16x16x32_bf16 v[98:101], v[176:179], v[192:195], v[98:101]
	v_mfma_f32_16x16x32_bf16 v[102:105], v[164:167], v[188:191], v[102:105]
	v_mfma_f32_16x16x32_bf16 v[102:105], v[168:171], v[192:195], v[102:105]
	v_mfma_f32_16x16x32_bf16 v[86:89], v[164:167], v[196:199], v[86:89]
	v_mfma_f32_16x16x32_bf16 v[86:89], v[168:171], v[200:203], v[86:89]
	v_mfma_f32_16x16x32_bf16 v[82:85], v[172:175], v[196:199], v[82:85]
	v_mfma_f32_16x16x32_bf16 v[82:85], v[176:179], v[200:203], v[82:85]
	v_mfma_f32_16x16x32_bf16 v[66:69], v[172:175], v[204:207], v[66:69]
	v_mfma_f32_16x16x32_bf16 v[66:69], v[176:179], v[208:211], v[66:69]
	s_setprio 2
	s_barrier
	v_mfma_f32_16x16x32_bf16 v[70:73], v[164:167], v[204:207], v[70:73]
	v_mfma_f32_16x16x32_bf16 v[70:73], v[168:171], v[208:211], v[70:73]
	s_setprio 0
	ds_read_b128 v[180:183], v145 offset:49152
	ds_read_b128 v[184:187], v145 offset:50176
	ds_read_b128 v[188:191], v145 offset:51200
	ds_read_b128 v[192:195], v145 offset:52224
	ds_read_b128 v[196:199], v145 offset:53248
	ds_read_b128 v[200:203], v145 offset:54272
	ds_read_b128 v[204:207], v145 offset:55296
	ds_read_b128 v[208:211], v145 offset:56320
	s_add_u32 s22, s20, 0x80
	s_addc_u32 s23, s21, 0
	s_mov_b32 s74, m0
	s_mov_b32 m0, s46
	s_nop 0
	global_load_lds_dwordx4 v139, s[22:23]
	s_mov_b32 m0, s74
	s_add_u32 s20, s20, 0x80080
	s_mov_b32 s74, m0
	s_mov_b32 m0, s47
	s_nop 0
	global_load_lds_dwordx4 v141, s[22:23]
	s_mov_b32 m0, s74
	s_addc_u32 s21, s21, 0
	s_mov_b32 s22, m0
	s_mov_b32 m0, s48
	s_nop 0
	global_load_lds_dwordx4 v139, s[20:21]
	s_mov_b32 m0, s22
	s_nop 0
	s_mov_b32 s22, m0
	s_mov_b32 m0, s49
	s_nop 0
	global_load_lds_dwordx4 v141, s[20:21]
	s_mov_b32 m0, s22
	s_waitcnt vmcnt(4)
	s_waitcnt lgkmcnt(0)
	s_barrier
	s_setprio 1
	s_waitcnt lgkmcnt(7)
	v_mfma_f32_16x16x32_bf16 v[62:65], v[148:151], v[180:183], v[62:65]
	v_mfma_f32_16x16x32_bf16 v[62:65], v[152:155], v[184:187], v[62:65]
	s_waitcnt lgkmcnt(5)
	v_mfma_f32_16x16x32_bf16 v[58:61], v[156:159], v[180:183], v[58:61]
	v_mfma_f32_16x16x32_bf16 v[58:61], v[160:163], v[184:187], v[58:61]
	s_waitcnt lgkmcnt(3)
	v_mfma_f32_16x16x32_bf16 v[42:45], v[156:159], v[188:191], v[42:45]
	v_mfma_f32_16x16x32_bf16 v[42:45], v[160:163], v[192:195], v[42:45]
	s_waitcnt lgkmcnt(1)
	v_mfma_f32_16x16x32_bf16 v[46:49], v[148:151], v[188:191], v[46:49]
	v_mfma_f32_16x16x32_bf16 v[46:49], v[152:155], v[192:195], v[46:49]
	v_mfma_f32_16x16x32_bf16 v[30:33], v[148:151], v[196:199], v[30:33]
	v_mfma_f32_16x16x32_bf16 v[30:33], v[152:155], v[200:203], v[30:33]
	v_mfma_f32_16x16x32_bf16 v[26:29], v[156:159], v[196:199], v[26:29]
	v_mfma_f32_16x16x32_bf16 v[26:29], v[160:163], v[200:203], v[26:29]
	v_mfma_f32_16x16x32_bf16 v[10:13], v[156:159], v[204:207], v[10:13]
	v_mfma_f32_16x16x32_bf16 v[10:13], v[160:163], v[208:211], v[10:13]
	s_waitcnt lgkmcnt(0)
	v_mfma_f32_16x16x32_bf16 v[14:17], v[148:151], v[204:207], v[14:17]
	v_mfma_f32_16x16x32_bf16 v[14:17], v[152:155], v[208:211], v[14:17]
	v_mfma_f32_16x16x32_bf16 v[54:57], v[164:167], v[180:183], v[54:57]
	v_mfma_f32_16x16x32_bf16 v[54:57], v[168:171], v[184:187], v[54:57]
	v_mfma_f32_16x16x32_bf16 v[50:53], v[172:175], v[180:183], v[50:53]
	v_mfma_f32_16x16x32_bf16 v[50:53], v[176:179], v[184:187], v[50:53]
	v_mfma_f32_16x16x32_bf16 v[34:37], v[172:175], v[188:191], v[34:37]
	v_mfma_f32_16x16x32_bf16 v[34:37], v[176:179], v[192:195], v[34:37]
	v_mfma_f32_16x16x32_bf16 v[38:41], v[164:167], v[188:191], v[38:41]
	v_mfma_f32_16x16x32_bf16 v[38:41], v[168:171], v[192:195], v[38:41]
	v_mfma_f32_16x16x32_bf16 v[22:25], v[164:167], v[196:199], v[22:25]
	v_mfma_f32_16x16x32_bf16 v[22:25], v[168:171], v[200:203], v[22:25]
	v_mfma_f32_16x16x32_bf16 v[18:21], v[172:175], v[196:199], v[18:21]
	v_mfma_f32_16x16x32_bf16 v[18:21], v[176:179], v[200:203], v[18:21]
	v_mfma_f32_16x16x32_bf16 v[2:5], v[172:175], v[204:207], v[2:5]
	v_mfma_f32_16x16x32_bf16 v[2:5], v[176:179], v[208:211], v[2:5]
	s_setprio 2
	s_barrier
	v_mfma_f32_16x16x32_bf16 v[6:9], v[164:167], v[204:207], v[6:9]
	v_mfma_f32_16x16x32_bf16 v[6:9], v[168:171], v[208:211], v[6:9]
	s_setprio 0
	s_add_i32 s73, s73, 2
	s_add_u32 s66, s66, 0x100
	s_addc_u32 s67, s67, 0
	s_add_u32 s18, s18, 0x100
	s_addc_u32 s19, s19, 0
	s_add_u32 s70, s70, 0x100
	s_addc_u32 s71, s71, 0
	s_cmp_gt_u32 s73, 29
	.p2align 6
.LBB0_1785:
	ds_read_b128 v[148:151], v143
	ds_read_b128 v[152:155], v143 offset:1024
	ds_read_b128 v[156:159], v143 offset:2048
	ds_read_b128 v[160:163], v143 offset:3072
	ds_read_b128 v[164:167], v144
	ds_read_b128 v[168:171], v144 offset:1024
	ds_read_b128 v[172:175], v144 offset:2048
	ds_read_b128 v[176:179], v144 offset:3072
	s_cmp_eq_u32 s73, 28
	s_cselect_b32 s21, s9, s67
	s_cselect_b32 s20, s65, s66
	s_cselect_b32 s23, s11, s71
	s_cselect_b32 s22, s64, s70
	ds_read_b128 v[180:183], v145
	ds_read_b128 v[184:187], v145 offset:1024
	ds_read_b128 v[188:191], v145 offset:2048
	ds_read_b128 v[192:195], v145 offset:3072
	ds_read_b128 v[196:199], v145 offset:4096
	ds_read_b128 v[200:203], v145 offset:5120
	ds_read_b128 v[204:207], v145 offset:6144
	ds_read_b128 v[208:211], v145 offset:7168
	s_add_u32 s74, s18, 0xfff80000
	s_addc_u32 s75, s19, -1
	s_mov_b32 s76, m0
	s_mov_b32 m0, s56
	s_nop 0
	global_load_lds_dwordx4 v138, s[74:75]
	s_mov_b32 m0, s76
	s_nop 0
	s_mov_b32 s76, m0
	s_mov_b32 m0, s59
	s_nop 0
	global_load_lds_dwordx4 v140, s[74:75]
	s_mov_b32 m0, s76
	s_mov_b32 s74, m0
	s_mov_b32 m0, s57
	s_nop 0
	global_load_lds_dwordx4 v138, s[18:19]
	s_mov_b32 m0, s74
	s_nop 0
	s_mov_b32 s74, m0
	s_mov_b32 m0, s62
	s_nop 0
	global_load_lds_dwordx4 v140, s[18:19]
	s_mov_b32 m0, s74
	s_waitcnt vmcnt(8)
	s_waitcnt lgkmcnt(0)
	s_barrier
	s_setprio 1
	s_waitcnt lgkmcnt(7)
	v_mfma_f32_16x16x32_bf16 v[126:129], v[148:151], v[180:183], v[126:129]
	v_mfma_f32_16x16x32_bf16 v[126:129], v[152:155], v[184:187], v[126:129]
	s_waitcnt lgkmcnt(5)
	v_mfma_f32_16x16x32_bf16 v[122:125], v[156:159], v[180:183], v[122:125]
	v_mfma_f32_16x16x32_bf16 v[122:125], v[160:163], v[184:187], v[122:125]
	s_waitcnt lgkmcnt(3)
	v_mfma_f32_16x16x32_bf16 v[106:109], v[156:159], v[188:191], v[106:109]
	v_mfma_f32_16x16x32_bf16 v[106:109], v[160:163], v[192:195], v[106:109]
	s_waitcnt lgkmcnt(1)
	v_mfma_f32_16x16x32_bf16 v[110:113], v[148:151], v[188:191], v[110:113]
	v_mfma_f32_16x16x32_bf16 v[110:113], v[152:155], v[192:195], v[110:113]
	v_mfma_f32_16x16x32_bf16 v[94:97], v[148:151], v[196:199], v[94:97]
	v_mfma_f32_16x16x32_bf16 v[94:97], v[152:155], v[200:203], v[94:97]
	v_mfma_f32_16x16x32_bf16 v[90:93], v[156:159], v[196:199], v[90:93]
	v_mfma_f32_16x16x32_bf16 v[90:93], v[160:163], v[200:203], v[90:93]
	v_mfma_f32_16x16x32_bf16 v[74:77], v[156:159], v[204:207], v[74:77]
	v_mfma_f32_16x16x32_bf16 v[74:77], v[160:163], v[208:211], v[74:77]
	s_waitcnt lgkmcnt(0)
	v_mfma_f32_16x16x32_bf16 v[78:81], v[148:151], v[204:207], v[78:81]
	v_mfma_f32_16x16x32_bf16 v[78:81], v[152:155], v[208:211], v[78:81]
	v_mfma_f32_16x16x32_bf16 v[118:121], v[164:167], v[180:183], v[118:121]
	v_mfma_f32_16x16x32_bf16 v[118:121], v[168:171], v[184:187], v[118:121]
	v_mfma_f32_16x16x32_bf16 v[114:117], v[172:175], v[180:183], v[114:117]
	v_mfma_f32_16x16x32_bf16 v[114:117], v[176:179], v[184:187], v[114:117]
	v_mfma_f32_16x16x32_bf16 v[98:101], v[172:175], v[188:191], v[98:101]
	v_mfma_f32_16x16x32_bf16 v[98:101], v[176:179], v[192:195], v[98:101]
	v_mfma_f32_16x16x32_bf16 v[102:105], v[164:167], v[188:191], v[102:105]
	v_mfma_f32_16x16x32_bf16 v[102:105], v[168:171], v[192:195], v[102:105]
	v_mfma_f32_16x16x32_bf16 v[86:89], v[164:167], v[196:199], v[86:89]
	v_mfma_f32_16x16x32_bf16 v[86:89], v[168:171], v[200:203], v[86:89]
	v_mfma_f32_16x16x32_bf16 v[82:85], v[172:175], v[196:199], v[82:85]
	v_mfma_f32_16x16x32_bf16 v[82:85], v[176:179], v[200:203], v[82:85]
	v_mfma_f32_16x16x32_bf16 v[66:69], v[172:175], v[204:207], v[66:69]
	v_mfma_f32_16x16x32_bf16 v[66:69], v[176:179], v[208:211], v[66:69]
	s_setprio 2
	s_barrier
	v_mfma_f32_16x16x32_bf16 v[70:73], v[164:167], v[204:207], v[70:73]
	v_mfma_f32_16x16x32_bf16 v[70:73], v[168:171], v[208:211], v[70:73]
	s_setprio 0
	ds_read_b128 v[180:183], v145 offset:16384
	ds_read_b128 v[184:187], v145 offset:17408
	ds_read_b128 v[188:191], v145 offset:18432
	ds_read_b128 v[192:195], v145 offset:19456
	ds_read_b128 v[196:199], v145 offset:20480
	ds_read_b128 v[200:203], v145 offset:21504
	ds_read_b128 v[204:207], v145 offset:22528
	ds_read_b128 v[208:211], v145 offset:23552
	s_mov_b32 s74, m0
	s_mov_b32 m0, s35
	s_nop 0
	global_load_lds_dwordx4 v139, s[20:21]
	s_mov_b32 m0, s74
	s_nop 0
	s_mov_b32 s74, m0
	s_mov_b32 m0, s36
	s_nop 0
	global_load_lds_dwordx4 v141, s[20:21]
	s_mov_b32 m0, s74
	s_add_u32 s74, s20, 0x80000
	s_addc_u32 s75, s21, 0
	s_mov_b32 s76, m0
	s_mov_b32 m0, s37
	s_nop 0
	global_load_lds_dwordx4 v139, s[74:75]
	s_mov_b32 m0, s76
	s_nop 0
	s_mov_b32 s76, m0
	s_mov_b32 m0, s40
	s_nop 0
	global_load_lds_dwordx4 v141, s[74:75]
	s_mov_b32 m0, s76
	s_waitcnt vmcnt(4)
	s_waitcnt lgkmcnt(0)
	s_barrier
	s_setprio 1
	s_waitcnt lgkmcnt(7)
	v_mfma_f32_16x16x32_bf16 v[62:65], v[148:151], v[180:183], v[62:65]
	v_mfma_f32_16x16x32_bf16 v[62:65], v[152:155], v[184:187], v[62:65]
	s_waitcnt lgkmcnt(5)
	v_mfma_f32_16x16x32_bf16 v[58:61], v[156:159], v[180:183], v[58:61]
	v_mfma_f32_16x16x32_bf16 v[58:61], v[160:163], v[184:187], v[58:61]
	s_waitcnt lgkmcnt(3)
	v_mfma_f32_16x16x32_bf16 v[42:45], v[156:159], v[188:191], v[42:45]
	v_mfma_f32_16x16x32_bf16 v[42:45], v[160:163], v[192:195], v[42:45]
	s_waitcnt lgkmcnt(1)
	v_mfma_f32_16x16x32_bf16 v[46:49], v[148:151], v[188:191], v[46:49]
	v_mfma_f32_16x16x32_bf16 v[46:49], v[152:155], v[192:195], v[46:49]
	v_mfma_f32_16x16x32_bf16 v[30:33], v[148:151], v[196:199], v[30:33]
	v_mfma_f32_16x16x32_bf16 v[30:33], v[152:155], v[200:203], v[30:33]
	v_mfma_f32_16x16x32_bf16 v[26:29], v[156:159], v[196:199], v[26:29]
	v_mfma_f32_16x16x32_bf16 v[26:29], v[160:163], v[200:203], v[26:29]
	v_mfma_f32_16x16x32_bf16 v[10:13], v[156:159], v[204:207], v[10:13]
	v_mfma_f32_16x16x32_bf16 v[10:13], v[160:163], v[208:211], v[10:13]
	s_waitcnt lgkmcnt(0)
	v_mfma_f32_16x16x32_bf16 v[14:17], v[148:151], v[204:207], v[14:17]
	v_mfma_f32_16x16x32_bf16 v[14:17], v[152:155], v[208:211], v[14:17]
	v_mfma_f32_16x16x32_bf16 v[54:57], v[164:167], v[180:183], v[54:57]
	v_mfma_f32_16x16x32_bf16 v[54:57], v[168:171], v[184:187], v[54:57]
	v_mfma_f32_16x16x32_bf16 v[50:53], v[172:175], v[180:183], v[50:53]
	v_mfma_f32_16x16x32_bf16 v[50:53], v[176:179], v[184:187], v[50:53]
	v_mfma_f32_16x16x32_bf16 v[34:37], v[172:175], v[188:191], v[34:37]
	v_mfma_f32_16x16x32_bf16 v[34:37], v[176:179], v[192:195], v[34:37]
	v_mfma_f32_16x16x32_bf16 v[38:41], v[164:167], v[188:191], v[38:41]
	v_mfma_f32_16x16x32_bf16 v[38:41], v[168:171], v[192:195], v[38:41]
	v_mfma_f32_16x16x32_bf16 v[22:25], v[164:167], v[196:199], v[22:25]
	v_mfma_f32_16x16x32_bf16 v[22:25], v[168:171], v[200:203], v[22:25]
	v_mfma_f32_16x16x32_bf16 v[18:21], v[172:175], v[196:199], v[18:21]
	v_mfma_f32_16x16x32_bf16 v[18:21], v[176:179], v[200:203], v[18:21]
	v_mfma_f32_16x16x32_bf16 v[2:5], v[172:175], v[204:207], v[2:5]
	v_mfma_f32_16x16x32_bf16 v[2:5], v[176:179], v[208:211], v[2:5]
	s_setprio 2
	s_barrier
	v_mfma_f32_16x16x32_bf16 v[6:9], v[164:167], v[204:207], v[6:9]
	v_mfma_f32_16x16x32_bf16 v[6:9], v[168:171], v[208:211], v[6:9]
	s_setprio 0
	ds_read_b128 v[148:151], v146
	ds_read_b128 v[152:155], v146 offset:1024
	ds_read_b128 v[156:159], v146 offset:2048
	ds_read_b128 v[160:163], v146 offset:3072
	ds_read_b128 v[164:167], v147
	ds_read_b128 v[168:171], v147 offset:1024
	ds_read_b128 v[172:175], v147 offset:2048
	ds_read_b128 v[176:179], v147 offset:3072
	ds_read_b128 v[180:183], v145 offset:32768
	ds_read_b128 v[184:187], v145 offset:33792
	ds_read_b128 v[188:191], v145 offset:34816
	ds_read_b128 v[192:195], v145 offset:35840
	ds_read_b128 v[196:199], v145 offset:36864
	ds_read_b128 v[200:203], v145 offset:37888
	ds_read_b128 v[204:207], v145 offset:38912
	ds_read_b128 v[208:211], v145 offset:39936
	s_mov_b32 s74, m0
	s_mov_b32 m0, s31
	s_nop 0
	global_load_lds_dwordx4 v138, s[22:23]
	s_mov_b32 m0, s74
	s_nop 0
	s_mov_b32 s74, m0
	s_mov_b32 m0, s41
	s_nop 0
	global_load_lds_dwordx4 v140, s[22:23]
	s_mov_b32 m0, s74
	s_add_u32 s22, s22, 0x80000
	s_addc_u32 s23, s23, 0
	s_mov_b32 s74, m0
	s_mov_b32 m0, s42
	s_nop 0
	global_load_lds_dwordx4 v138, s[22:23]
	s_mov_b32 m0, s74
	s_nop 0
	s_mov_b32 s74, m0
	s_mov_b32 m0, s43
	s_nop 0
	global_load_lds_dwordx4 v140, s[22:23]
	s_mov_b32 m0, s74
	s_waitcnt vmcnt(8)
	s_waitcnt lgkmcnt(0)
	s_barrier
	s_setprio 1
	s_waitcnt lgkmcnt(7)
	v_mfma_f32_16x16x32_bf16 v[126:129], v[148:151], v[180:183], v[126:129]
	v_mfma_f32_16x16x32_bf16 v[126:129], v[152:155], v[184:187], v[126:129]
	s_waitcnt lgkmcnt(5)
	v_mfma_f32_16x16x32_bf16 v[122:125], v[156:159], v[180:183], v[122:125]
	v_mfma_f32_16x16x32_bf16 v[122:125], v[160:163], v[184:187], v[122:125]
	s_waitcnt lgkmcnt(3)
	v_mfma_f32_16x16x32_bf16 v[106:109], v[156:159], v[188:191], v[106:109]
	v_mfma_f32_16x16x32_bf16 v[106:109], v[160:163], v[192:195], v[106:109]
	s_waitcnt lgkmcnt(1)
	v_mfma_f32_16x16x32_bf16 v[110:113], v[148:151], v[188:191], v[110:113]
	v_mfma_f32_16x16x32_bf16 v[110:113], v[152:155], v[192:195], v[110:113]
	v_mfma_f32_16x16x32_bf16 v[94:97], v[148:151], v[196:199], v[94:97]
	v_mfma_f32_16x16x32_bf16 v[94:97], v[152:155], v[200:203], v[94:97]
	v_mfma_f32_16x16x32_bf16 v[90:93], v[156:159], v[196:199], v[90:93]
	v_mfma_f32_16x16x32_bf16 v[90:93], v[160:163], v[200:203], v[90:93]
	v_mfma_f32_16x16x32_bf16 v[74:77], v[156:159], v[204:207], v[74:77]
	v_mfma_f32_16x16x32_bf16 v[74:77], v[160:163], v[208:211], v[74:77]
	s_waitcnt lgkmcnt(0)
	v_mfma_f32_16x16x32_bf16 v[78:81], v[148:151], v[204:207], v[78:81]
	v_mfma_f32_16x16x32_bf16 v[78:81], v[152:155], v[208:211], v[78:81]
	v_mfma_f32_16x16x32_bf16 v[118:121], v[164:167], v[180:183], v[118:121]
	v_mfma_f32_16x16x32_bf16 v[118:121], v[168:171], v[184:187], v[118:121]
	v_mfma_f32_16x16x32_bf16 v[114:117], v[172:175], v[180:183], v[114:117]
	v_mfma_f32_16x16x32_bf16 v[114:117], v[176:179], v[184:187], v[114:117]
	v_mfma_f32_16x16x32_bf16 v[98:101], v[172:175], v[188:191], v[98:101]
	v_mfma_f32_16x16x32_bf16 v[98:101], v[176:179], v[192:195], v[98:101]
	v_mfma_f32_16x16x32_bf16 v[102:105], v[164:167], v[188:191], v[102:105]
	v_mfma_f32_16x16x32_bf16 v[102:105], v[168:171], v[192:195], v[102:105]
	v_mfma_f32_16x16x32_bf16 v[86:89], v[164:167], v[196:199], v[86:89]
	v_mfma_f32_16x16x32_bf16 v[86:89], v[168:171], v[200:203], v[86:89]
	v_mfma_f32_16x16x32_bf16 v[82:85], v[172:175], v[196:199], v[82:85]
	v_mfma_f32_16x16x32_bf16 v[82:85], v[176:179], v[200:203], v[82:85]
	v_mfma_f32_16x16x32_bf16 v[66:69], v[172:175], v[204:207], v[66:69]
	v_mfma_f32_16x16x32_bf16 v[66:69], v[176:179], v[208:211], v[66:69]
	s_setprio 2
	s_barrier
	v_mfma_f32_16x16x32_bf16 v[70:73], v[164:167], v[204:207], v[70:73]
	v_mfma_f32_16x16x32_bf16 v[70:73], v[168:171], v[208:211], v[70:73]
	s_setprio 0
	ds_read_b128 v[180:183], v145 offset:49152
	ds_read_b128 v[184:187], v145 offset:50176
	ds_read_b128 v[188:191], v145 offset:51200
	ds_read_b128 v[192:195], v145 offset:52224
	ds_read_b128 v[196:199], v145 offset:53248
	ds_read_b128 v[200:203], v145 offset:54272
	ds_read_b128 v[204:207], v145 offset:55296
	ds_read_b128 v[208:211], v145 offset:56320
	s_add_u32 s22, s20, 0x80
	s_addc_u32 s23, s21, 0
	s_mov_b32 s74, m0
	s_mov_b32 m0, s46
	s_nop 0
	global_load_lds_dwordx4 v139, s[22:23]
	s_mov_b32 m0, s74
	s_add_u32 s20, s20, 0x80080
	s_mov_b32 s74, m0
	s_mov_b32 m0, s47
	s_nop 0
	global_load_lds_dwordx4 v141, s[22:23]
	s_mov_b32 m0, s74
	s_addc_u32 s21, s21, 0
	s_mov_b32 s22, m0
	s_mov_b32 m0, s48
	s_nop 0
	global_load_lds_dwordx4 v139, s[20:21]
	s_mov_b32 m0, s22
	s_nop 0
	s_mov_b32 s22, m0
	s_mov_b32 m0, s49
	s_nop 0
	global_load_lds_dwordx4 v141, s[20:21]
	s_mov_b32 m0, s22
	s_waitcnt vmcnt(4)
	s_waitcnt lgkmcnt(0)
	s_barrier
	s_setprio 1
	s_waitcnt lgkmcnt(7)
	v_mfma_f32_16x16x32_bf16 v[62:65], v[148:151], v[180:183], v[62:65]
	v_mfma_f32_16x16x32_bf16 v[62:65], v[152:155], v[184:187], v[62:65]
	s_waitcnt lgkmcnt(5)
	v_mfma_f32_16x16x32_bf16 v[58:61], v[156:159], v[180:183], v[58:61]
	v_mfma_f32_16x16x32_bf16 v[58:61], v[160:163], v[184:187], v[58:61]
	s_waitcnt lgkmcnt(3)
	v_mfma_f32_16x16x32_bf16 v[42:45], v[156:159], v[188:191], v[42:45]
	v_mfma_f32_16x16x32_bf16 v[42:45], v[160:163], v[192:195], v[42:45]
	s_waitcnt lgkmcnt(1)
	v_mfma_f32_16x16x32_bf16 v[46:49], v[148:151], v[188:191], v[46:49]
	v_mfma_f32_16x16x32_bf16 v[46:49], v[152:155], v[192:195], v[46:49]
	v_mfma_f32_16x16x32_bf16 v[30:33], v[148:151], v[196:199], v[30:33]
	v_mfma_f32_16x16x32_bf16 v[30:33], v[152:155], v[200:203], v[30:33]
	v_mfma_f32_16x16x32_bf16 v[26:29], v[156:159], v[196:199], v[26:29]
	v_mfma_f32_16x16x32_bf16 v[26:29], v[160:163], v[200:203], v[26:29]
	v_mfma_f32_16x16x32_bf16 v[10:13], v[156:159], v[204:207], v[10:13]
	v_mfma_f32_16x16x32_bf16 v[10:13], v[160:163], v[208:211], v[10:13]
	s_waitcnt lgkmcnt(0)
	v_mfma_f32_16x16x32_bf16 v[14:17], v[148:151], v[204:207], v[14:17]
	v_mfma_f32_16x16x32_bf16 v[14:17], v[152:155], v[208:211], v[14:17]
	v_mfma_f32_16x16x32_bf16 v[54:57], v[164:167], v[180:183], v[54:57]
	v_mfma_f32_16x16x32_bf16 v[54:57], v[168:171], v[184:187], v[54:57]
	v_mfma_f32_16x16x32_bf16 v[50:53], v[172:175], v[180:183], v[50:53]
	v_mfma_f32_16x16x32_bf16 v[50:53], v[176:179], v[184:187], v[50:53]
	v_mfma_f32_16x16x32_bf16 v[34:37], v[172:175], v[188:191], v[34:37]
	v_mfma_f32_16x16x32_bf16 v[34:37], v[176:179], v[192:195], v[34:37]
	v_mfma_f32_16x16x32_bf16 v[38:41], v[164:167], v[188:191], v[38:41]
	v_mfma_f32_16x16x32_bf16 v[38:41], v[168:171], v[192:195], v[38:41]
	v_mfma_f32_16x16x32_bf16 v[22:25], v[164:167], v[196:199], v[22:25]
	v_mfma_f32_16x16x32_bf16 v[22:25], v[168:171], v[200:203], v[22:25]
	v_mfma_f32_16x16x32_bf16 v[18:21], v[172:175], v[196:199], v[18:21]
	v_mfma_f32_16x16x32_bf16 v[18:21], v[176:179], v[200:203], v[18:21]
	v_mfma_f32_16x16x32_bf16 v[2:5], v[172:175], v[204:207], v[2:5]
	v_mfma_f32_16x16x32_bf16 v[2:5], v[176:179], v[208:211], v[2:5]
	s_setprio 2
	s_barrier
	v_mfma_f32_16x16x32_bf16 v[6:9], v[164:167], v[204:207], v[6:9]
	v_mfma_f32_16x16x32_bf16 v[6:9], v[168:171], v[208:211], v[6:9]
	s_setprio 0
	s_add_i32 s73, s73, 2
	s_add_u32 s66, s66, 0x100
	s_addc_u32 s67, s67, 0
	s_add_u32 s18, s18, 0x100
	s_addc_u32 s19, s19, 0
	s_add_u32 s70, s70, 0x100
	s_addc_u32 s71, s71, 0
	s_cmp_gt_u32 s73, 29
	s_cbranch_scc0 .LBB0_1785
	s_and_b64 vcc, exec, s[6:7]
	s_cbranch_vccz .LBB0_1788
	s_barrier

.LBB0_1951:
	s_ashr_i32 s13, s12, 31
	s_lshl_b64 s[14:15], s[12:13], 15
	s_add_u32 s14, s28, s14
	s_addc_u32 s15, s29, s15
	s_and_b64 s[16:17], s[2:3], exec
	s_cselect_b32 s13, s15, s23
	s_cselect_b32 s65, s14, s22
	s_ashr_i32 s11, s10, 31
	s_lshl_b64 s[16:17], s[10:11], 15
	s_add_u32 s16, s30, s16
	s_addc_u32 s17, s31, s17
	s_and_b64 s[24:25], s[2:3], exec
	s_cselect_b32 s11, s17, s21
	s_cselect_b32 s66, s16, s20
	s_add_u32 s67, s20, 0x80000
	s_addc_u32 s70, s21, 0
	s_add_u32 s20, s22, 0x204000
	s_addc_u32 s21, s23, 0
	s_add_u32 s71, s22, 0x400000
	s_addc_u32 s73, s23, 0
	s_mov_b32 s74, -2
	s_waitcnt vmcnt(25)
	s_waitcnt vmcnt(24)
	s_waitcnt vmcnt(4)
	s_waitcnt vmcnt(2)
	s_waitcnt vmcnt(1)
	s_waitcnt vmcnt(0)
	ds_read_b128 v[130:133], v181
	ds_read_b128 v[134:137], v181 offset:1024
	ds_read_b128 v[138:141], v181 offset:2048
	ds_read_b128 v[142:145], v181 offset:3072
	ds_read_b128 v[150:153], v182
	ds_read_b128 v[154:157], v182 offset:1024
	ds_read_b128 v[158:161], v182 offset:2048
	ds_read_b128 v[162:165], v182 offset:3072
	s_cmpk_eq_i32 s74, 0x52
	s_cselect_b32 s23, s11, s70
	s_cselect_b32 s22, s66, s67
	s_cselect_b32 s25, s13, s73
	s_cselect_b32 s24, s65, s71
	ds_read_b128 v[166:169], v183
	ds_read_b128 v[170:173], v183 offset:1024
	ds_read_b128 v[186:189], v183 offset:2048
	ds_read_b128 v[190:193], v183 offset:3072
	ds_read_b128 v[194:197], v183 offset:4096
	ds_read_b128 v[198:201], v183 offset:5120
	ds_read_b128 v[202:205], v183 offset:6144
	ds_read_b128 v[206:209], v183 offset:7168
	s_add_u32 s76, s20, 0xffffc000
	s_addc_u32 s77, s21, -1
	s_mov_b32 s75, m0
	s_mov_b32 m0, s58
	s_nop 0
	global_load_lds_dwordx4 v1, s[76:77]
	s_mov_b32 m0, s75
	s_nop 0
	s_mov_b32 s75, m0
	s_mov_b32 m0, s62
	s_nop 0
	global_load_lds_dwordx4 v177, s[76:77]
	s_mov_b32 m0, s75
	s_nop 0
	s_mov_b32 s75, m0
	s_mov_b32 m0, s59
	s_nop 0
	global_load_lds_dwordx4 v1, s[20:21]
	s_mov_b32 m0, s75
	s_nop 0
	s_mov_b32 s75, m0
	s_mov_b32 m0, s63
	s_nop 0
	global_load_lds_dwordx4 v177, s[20:21]
	s_mov_b32 m0, s75
	s_waitcnt vmcnt(8)
	s_waitcnt lgkmcnt(0)
	s_barrier
	s_setprio 1
	s_waitcnt lgkmcnt(7)
	v_mfma_f32_16x16x32_bf16 v[126:129], v[130:133], v[166:169], 0
	v_mfma_f32_16x16x32_bf16 v[126:129], v[134:137], v[170:173], v[126:129]
	s_waitcnt lgkmcnt(5)
	v_mfma_f32_16x16x32_bf16 v[122:125], v[138:141], v[166:169], 0
	v_mfma_f32_16x16x32_bf16 v[122:125], v[142:145], v[170:173], v[122:125]
	s_waitcnt lgkmcnt(3)
	v_mfma_f32_16x16x32_bf16 v[110:113], v[138:141], v[186:189], 0
	v_mfma_f32_16x16x32_bf16 v[110:113], v[142:145], v[190:193], v[110:113]
	s_waitcnt lgkmcnt(1)
	v_mfma_f32_16x16x32_bf16 v[118:121], v[130:133], v[186:189], 0
	v_mfma_f32_16x16x32_bf16 v[118:121], v[134:137], v[190:193], v[118:121]
	v_mfma_f32_16x16x32_bf16 v[94:97], v[130:133], v[194:197], 0
	v_mfma_f32_16x16x32_bf16 v[94:97], v[134:137], v[198:201], v[94:97]
	v_mfma_f32_16x16x32_bf16 v[90:93], v[138:141], v[194:197], 0
	v_mfma_f32_16x16x32_bf16 v[90:93], v[142:145], v[198:201], v[90:93]
	v_mfma_f32_16x16x32_bf16 v[78:81], v[138:141], v[202:205], 0
	v_mfma_f32_16x16x32_bf16 v[78:81], v[142:145], v[206:209], v[78:81]
	s_waitcnt lgkmcnt(0)
	v_mfma_f32_16x16x32_bf16 v[86:89], v[130:133], v[202:205], 0
	v_mfma_f32_16x16x32_bf16 v[86:89], v[134:137], v[206:209], v[86:89]
	v_mfma_f32_16x16x32_bf16 v[114:117], v[150:153], v[166:169], 0
	v_mfma_f32_16x16x32_bf16 v[114:117], v[154:157], v[170:173], v[114:117]
	v_mfma_f32_16x16x32_bf16 v[106:109], v[158:161], v[166:169], 0
	v_mfma_f32_16x16x32_bf16 v[106:109], v[162:165], v[170:173], v[106:109]
	v_mfma_f32_16x16x32_bf16 v[98:101], v[158:161], v[186:189], 0
	v_mfma_f32_16x16x32_bf16 v[98:101], v[162:165], v[190:193], v[98:101]
	v_mfma_f32_16x16x32_bf16 v[102:105], v[150:153], v[186:189], 0
	v_mfma_f32_16x16x32_bf16 v[102:105], v[154:157], v[190:193], v[102:105]
	v_mfma_f32_16x16x32_bf16 v[82:85], v[150:153], v[194:197], 0
	v_mfma_f32_16x16x32_bf16 v[82:85], v[154:157], v[198:201], v[82:85]
	v_mfma_f32_16x16x32_bf16 v[74:77], v[158:161], v[194:197], 0
	v_mfma_f32_16x16x32_bf16 v[74:77], v[162:165], v[198:201], v[74:77]
	v_mfma_f32_16x16x32_bf16 v[66:69], v[158:161], v[202:205], 0
	v_mfma_f32_16x16x32_bf16 v[66:69], v[162:165], v[206:209], v[66:69]
	s_setprio 2
	s_barrier
	v_mfma_f32_16x16x32_bf16 v[70:73], v[150:153], v[202:205], 0
	v_mfma_f32_16x16x32_bf16 v[70:73], v[154:157], v[206:209], v[70:73]
	s_setprio 0
	ds_read_b128 v[166:169], v183 offset:16384
	ds_read_b128 v[170:173], v183 offset:17408
	ds_read_b128 v[186:189], v183 offset:18432
	ds_read_b128 v[190:193], v183 offset:19456
	ds_read_b128 v[194:197], v183 offset:20480
	ds_read_b128 v[198:201], v183 offset:21504
	ds_read_b128 v[202:205], v183 offset:22528
	ds_read_b128 v[206:209], v183 offset:23552
	s_mov_b32 s75, m0
	s_mov_b32 m0, s35
	s_nop 0
	global_load_lds_dwordx4 v176, s[22:23]
	s_mov_b32 m0, s75
	s_add_u32 s76, s22, 0x4000
	s_mov_b32 s75, m0
	s_mov_b32 m0, s36
	s_nop 0
	global_load_lds_dwordx4 v178, s[22:23]
	s_mov_b32 m0, s75
	s_addc_u32 s77, s23, 0
	s_mov_b32 s75, m0
	s_mov_b32 m0, s37
	s_nop 0
	global_load_lds_dwordx4 v176, s[76:77]
	s_mov_b32 m0, s75
	s_nop 0
	s_mov_b32 s75, m0
	s_mov_b32 m0, s40
	s_nop 0
	global_load_lds_dwordx4 v178, s[76:77]
	s_mov_b32 m0, s75
	s_waitcnt vmcnt(4)
	s_waitcnt lgkmcnt(0)
	s_barrier
	s_setprio 1
	s_waitcnt lgkmcnt(7)
	v_mfma_f32_16x16x32_bf16 v[62:65], v[130:133], v[166:169], 0
	v_mfma_f32_16x16x32_bf16 v[62:65], v[134:137], v[170:173], v[62:65]
	s_waitcnt lgkmcnt(5)
	v_mfma_f32_16x16x32_bf16 v[58:61], v[138:141], v[166:169], 0
	v_mfma_f32_16x16x32_bf16 v[58:61], v[142:145], v[170:173], v[58:61]
	s_waitcnt lgkmcnt(3)
	v_mfma_f32_16x16x32_bf16 v[42:45], v[138:141], v[186:189], 0
	v_mfma_f32_16x16x32_bf16 v[42:45], v[142:145], v[190:193], v[42:45]
	s_waitcnt lgkmcnt(1)
	v_mfma_f32_16x16x32_bf16 v[46:49], v[130:133], v[186:189], 0
	v_mfma_f32_16x16x32_bf16 v[46:49], v[134:137], v[190:193], v[46:49]
	v_mfma_f32_16x16x32_bf16 v[30:33], v[130:133], v[194:197], 0
	v_mfma_f32_16x16x32_bf16 v[30:33], v[134:137], v[198:201], v[30:33]
	v_mfma_f32_16x16x32_bf16 v[26:29], v[138:141], v[194:197], 0
	v_mfma_f32_16x16x32_bf16 v[26:29], v[142:145], v[198:201], v[26:29]
	v_mfma_f32_16x16x32_bf16 v[10:13], v[138:141], v[202:205], 0
	v_mfma_f32_16x16x32_bf16 v[10:13], v[142:145], v[206:209], v[10:13]
	s_waitcnt lgkmcnt(0)
	v_mfma_f32_16x16x32_bf16 v[14:17], v[130:133], v[202:205], 0
	v_mfma_f32_16x16x32_bf16 v[14:17], v[134:137], v[206:209], v[14:17]
	v_mfma_f32_16x16x32_bf16 v[54:57], v[150:153], v[166:169], 0
	v_mfma_f32_16x16x32_bf16 v[54:57], v[154:157], v[170:173], v[54:57]
	v_mfma_f32_16x16x32_bf16 v[50:53], v[158:161], v[166:169], 0
	v_mfma_f32_16x16x32_bf16 v[50:53], v[162:165], v[170:173], v[50:53]
	v_mfma_f32_16x16x32_bf16 v[34:37], v[158:161], v[186:189], 0
	v_mfma_f32_16x16x32_bf16 v[34:37], v[162:165], v[190:193], v[34:37]
	v_mfma_f32_16x16x32_bf16 v[38:41], v[150:153], v[186:189], 0
	v_mfma_f32_16x16x32_bf16 v[38:41], v[154:157], v[190:193], v[38:41]
	v_mfma_f32_16x16x32_bf16 v[22:25], v[150:153], v[194:197], 0
	v_mfma_f32_16x16x32_bf16 v[22:25], v[154:157], v[198:201], v[22:25]
	v_mfma_f32_16x16x32_bf16 v[18:21], v[158:161], v[194:197], 0
	v_mfma_f32_16x16x32_bf16 v[18:21], v[162:165], v[198:201], v[18:21]
	v_mfma_f32_16x16x32_bf16 v[2:5], v[158:161], v[202:205], 0
	v_mfma_f32_16x16x32_bf16 v[2:5], v[162:165], v[206:209], v[2:5]
	s_setprio 2
	s_barrier
	v_mfma_f32_16x16x32_bf16 v[6:9], v[150:153], v[202:205], 0
	v_mfma_f32_16x16x32_bf16 v[6:9], v[154:157], v[206:209], v[6:9]
	s_setprio 0
	ds_read_b128 v[130:133], v184
	ds_read_b128 v[134:137], v184 offset:1024
	ds_read_b128 v[138:141], v184 offset:2048
	ds_read_b128 v[142:145], v184 offset:3072
	ds_read_b128 v[150:153], v185
	ds_read_b128 v[154:157], v185 offset:1024
	ds_read_b128 v[158:161], v185 offset:2048
	ds_read_b128 v[162:165], v185 offset:3072
	ds_read_b128 v[166:169], v183 offset:32768
	ds_read_b128 v[170:173], v183 offset:33792
	ds_read_b128 v[186:189], v183 offset:34816
	ds_read_b128 v[190:193], v183 offset:35840
	ds_read_b128 v[194:197], v183 offset:36864
	ds_read_b128 v[198:201], v183 offset:37888
	ds_read_b128 v[202:205], v183 offset:38912
	ds_read_b128 v[206:209], v183 offset:39936
	s_mov_b32 s75, m0
	s_mov_b32 m0, s34
	s_nop 0
	global_load_lds_dwordx4 v1, s[24:25]
	s_mov_b32 m0, s75
	s_nop 0
	s_mov_b32 s75, m0
	s_mov_b32 m0, s41
	s_nop 0
	global_load_lds_dwordx4 v177, s[24:25]
	s_mov_b32 m0, s75
	s_add_u32 s24, s24, 0x4000
	s_addc_u32 s25, s25, 0
	s_mov_b32 s75, m0
	s_mov_b32 m0, s42
	s_nop 0
	global_load_lds_dwordx4 v1, s[24:25]
	s_mov_b32 m0, s75
	s_nop 0
	s_mov_b32 s75, m0
	s_mov_b32 m0, s43
	s_nop 0
	global_load_lds_dwordx4 v177, s[24:25]
	s_mov_b32 m0, s75
	s_waitcnt vmcnt(8)
	s_waitcnt lgkmcnt(0)
	s_barrier
	s_setprio 1
	s_waitcnt lgkmcnt(7)
	v_mfma_f32_16x16x32_bf16 v[126:129], v[130:133], v[166:169], v[126:129]
	v_mfma_f32_16x16x32_bf16 v[126:129], v[134:137], v[170:173], v[126:129]
	s_waitcnt lgkmcnt(5)
	v_mfma_f32_16x16x32_bf16 v[122:125], v[138:141], v[166:169], v[122:125]
	v_mfma_f32_16x16x32_bf16 v[122:125], v[142:145], v[170:173], v[122:125]
	s_waitcnt lgkmcnt(3)
	v_mfma_f32_16x16x32_bf16 v[110:113], v[138:141], v[186:189], v[110:113]
	v_mfma_f32_16x16x32_bf16 v[110:113], v[142:145], v[190:193], v[110:113]
	s_waitcnt lgkmcnt(1)
	v_mfma_f32_16x16x32_bf16 v[118:121], v[130:133], v[186:189], v[118:121]
	v_mfma_f32_16x16x32_bf16 v[118:121], v[134:137], v[190:193], v[118:121]
	v_mfma_f32_16x16x32_bf16 v[94:97], v[130:133], v[194:197], v[94:97]
	v_mfma_f32_16x16x32_bf16 v[94:97], v[134:137], v[198:201], v[94:97]
	v_mfma_f32_16x16x32_bf16 v[90:93], v[138:141], v[194:197], v[90:93]
	v_mfma_f32_16x16x32_bf16 v[90:93], v[142:145], v[198:201], v[90:93]
	v_mfma_f32_16x16x32_bf16 v[78:81], v[138:141], v[202:205], v[78:81]
	v_mfma_f32_16x16x32_bf16 v[78:81], v[142:145], v[206:209], v[78:81]
	s_waitcnt lgkmcnt(0)
	v_mfma_f32_16x16x32_bf16 v[86:89], v[130:133], v[202:205], v[86:89]
	v_mfma_f32_16x16x32_bf16 v[86:89], v[134:137], v[206:209], v[86:89]
	v_mfma_f32_16x16x32_bf16 v[114:117], v[150:153], v[166:169], v[114:117]
	v_mfma_f32_16x16x32_bf16 v[114:117], v[154:157], v[170:173], v[114:117]
	v_mfma_f32_16x16x32_bf16 v[106:109], v[158:161], v[166:169], v[106:109]
	v_mfma_f32_16x16x32_bf16 v[106:109], v[162:165], v[170:173], v[106:109]
	v_mfma_f32_16x16x32_bf16 v[98:101], v[158:161], v[186:189], v[98:101]
	v_mfma_f32_16x16x32_bf16 v[98:101], v[162:165], v[190:193], v[98:101]
	v_mfma_f32_16x16x32_bf16 v[102:105], v[150:153], v[186:189], v[102:105]
	v_mfma_f32_16x16x32_bf16 v[102:105], v[154:157], v[190:193], v[102:105]
	v_mfma_f32_16x16x32_bf16 v[82:85], v[150:153], v[194:197], v[82:85]
	v_mfma_f32_16x16x32_bf16 v[82:85], v[154:157], v[198:201], v[82:85]
	v_mfma_f32_16x16x32_bf16 v[74:77], v[158:161], v[194:197], v[74:77]
	v_mfma_f32_16x16x32_bf16 v[74:77], v[162:165], v[198:201], v[74:77]
	v_mfma_f32_16x16x32_bf16 v[66:69], v[158:161], v[202:205], v[66:69]
	v_mfma_f32_16x16x32_bf16 v[66:69], v[162:165], v[206:209], v[66:69]
	s_setprio 2
	s_barrier
	v_mfma_f32_16x16x32_bf16 v[70:73], v[150:153], v[202:205], v[70:73]
	v_mfma_f32_16x16x32_bf16 v[70:73], v[154:157], v[206:209], v[70:73]
	s_setprio 0
	ds_read_b128 v[166:169], v183 offset:49152
	ds_read_b128 v[170:173], v183 offset:50176
	ds_read_b128 v[186:189], v183 offset:51200
	ds_read_b128 v[190:193], v183 offset:52224
	ds_read_b128 v[194:197], v183 offset:53248
	ds_read_b128 v[198:201], v183 offset:54272
	ds_read_b128 v[202:205], v183 offset:55296
	ds_read_b128 v[206:209], v183 offset:56320
	s_add_u32 s24, s22, 0x40000
	s_addc_u32 s25, s23, 0
	s_mov_b32 s75, m0
	s_mov_b32 m0, s46
	s_nop 0
	global_load_lds_dwordx4 v176, s[24:25]
	s_mov_b32 m0, s75
	s_add_u32 s22, s22, 0x44000
	s_mov_b32 s75, m0
	s_mov_b32 m0, s47
	s_nop 0
	global_load_lds_dwordx4 v178, s[24:25]
	s_mov_b32 m0, s75
	s_addc_u32 s23, s23, 0
	s_mov_b32 s24, m0
	s_mov_b32 m0, s48
	s_nop 0
	global_load_lds_dwordx4 v176, s[22:23]
	s_mov_b32 m0, s24
	s_nop 0
	s_mov_b32 s24, m0
	s_mov_b32 m0, s49
	s_nop 0
	global_load_lds_dwordx4 v178, s[22:23]
	s_mov_b32 m0, s24
	s_waitcnt vmcnt(4)
	s_waitcnt lgkmcnt(0)
	s_barrier
	s_setprio 1
	s_waitcnt lgkmcnt(7)
	v_mfma_f32_16x16x32_bf16 v[62:65], v[130:133], v[166:169], v[62:65]
	v_mfma_f32_16x16x32_bf16 v[62:65], v[134:137], v[170:173], v[62:65]
	s_waitcnt lgkmcnt(5)
	v_mfma_f32_16x16x32_bf16 v[58:61], v[138:141], v[166:169], v[58:61]
	v_mfma_f32_16x16x32_bf16 v[58:61], v[142:145], v[170:173], v[58:61]
	s_waitcnt lgkmcnt(3)
	v_mfma_f32_16x16x32_bf16 v[42:45], v[138:141], v[186:189], v[42:45]
	v_mfma_f32_16x16x32_bf16 v[42:45], v[142:145], v[190:193], v[42:45]
	s_waitcnt lgkmcnt(1)
	v_mfma_f32_16x16x32_bf16 v[46:49], v[130:133], v[186:189], v[46:49]
	v_mfma_f32_16x16x32_bf16 v[46:49], v[134:137], v[190:193], v[46:49]
	v_mfma_f32_16x16x32_bf16 v[30:33], v[130:133], v[194:197], v[30:33]
	v_mfma_f32_16x16x32_bf16 v[30:33], v[134:137], v[198:201], v[30:33]
	v_mfma_f32_16x16x32_bf16 v[26:29], v[138:141], v[194:197], v[26:29]
	v_mfma_f32_16x16x32_bf16 v[26:29], v[142:145], v[198:201], v[26:29]
	v_mfma_f32_16x16x32_bf16 v[10:13], v[138:141], v[202:205], v[10:13]
	v_mfma_f32_16x16x32_bf16 v[10:13], v[142:145], v[206:209], v[10:13]
	s_waitcnt lgkmcnt(0)
	v_mfma_f32_16x16x32_bf16 v[14:17], v[130:133], v[202:205], v[14:17]
	v_mfma_f32_16x16x32_bf16 v[14:17], v[134:137], v[206:209], v[14:17]
	v_mfma_f32_16x16x32_bf16 v[54:57], v[150:153], v[166:169], v[54:57]
	v_mfma_f32_16x16x32_bf16 v[54:57], v[154:157], v[170:173], v[54:57]
	v_mfma_f32_16x16x32_bf16 v[50:53], v[158:161], v[166:169], v[50:53]
	v_mfma_f32_16x16x32_bf16 v[50:53], v[162:165], v[170:173], v[50:53]
	v_mfma_f32_16x16x32_bf16 v[34:37], v[158:161], v[186:189], v[34:37]
	v_mfma_f32_16x16x32_bf16 v[34:37], v[162:165], v[190:193], v[34:37]
	v_mfma_f32_16x16x32_bf16 v[38:41], v[150:153], v[186:189], v[38:41]
	v_mfma_f32_16x16x32_bf16 v[38:41], v[154:157], v[190:193], v[38:41]
	v_mfma_f32_16x16x32_bf16 v[22:25], v[150:153], v[194:197], v[22:25]
	v_mfma_f32_16x16x32_bf16 v[22:25], v[154:157], v[198:201], v[22:25]
	v_mfma_f32_16x16x32_bf16 v[18:21], v[158:161], v[194:197], v[18:21]
	v_mfma_f32_16x16x32_bf16 v[18:21], v[162:165], v[198:201], v[18:21]
	v_mfma_f32_16x16x32_bf16 v[2:5], v[158:161], v[202:205], v[2:5]
	v_mfma_f32_16x16x32_bf16 v[2:5], v[162:165], v[206:209], v[2:5]
	s_setprio 2
	s_barrier
	v_mfma_f32_16x16x32_bf16 v[6:9], v[150:153], v[202:205], v[6:9]
	v_mfma_f32_16x16x32_bf16 v[6:9], v[154:157], v[206:209], v[6:9]
	s_setprio 0
	s_add_i32 s74, s74, 2
	s_add_u32 s67, s67, 0x80000
	s_addc_u32 s70, s70, 0
	s_add_u32 s20, s20, 0x400000
	s_addc_u32 s21, s21, 0
	s_add_u32 s71, s71, 0x400000
	s_addc_u32 s73, s73, 0
	s_cmpk_gt_u32 s74, 0x53
	.p2align 6
.LBB0_1952:
	ds_read_b128 v[130:133], v181
	ds_read_b128 v[134:137], v181 offset:1024
	ds_read_b128 v[138:141], v181 offset:2048
	ds_read_b128 v[142:145], v181 offset:3072
	ds_read_b128 v[150:153], v182
	ds_read_b128 v[154:157], v182 offset:1024
	ds_read_b128 v[158:161], v182 offset:2048
	ds_read_b128 v[162:165], v182 offset:3072
	s_cmpk_eq_i32 s74, 0x52
	s_cselect_b32 s23, s11, s70
	s_cselect_b32 s22, s66, s67
	s_cselect_b32 s25, s13, s73
	s_cselect_b32 s24, s65, s71
	ds_read_b128 v[166:169], v183
	ds_read_b128 v[170:173], v183 offset:1024
	ds_read_b128 v[186:189], v183 offset:2048
	ds_read_b128 v[190:193], v183 offset:3072
	ds_read_b128 v[194:197], v183 offset:4096
	ds_read_b128 v[198:201], v183 offset:5120
	ds_read_b128 v[202:205], v183 offset:6144
	ds_read_b128 v[206:209], v183 offset:7168
	s_add_u32 s76, s20, 0xffffc000
	s_addc_u32 s77, s21, -1
	s_mov_b32 s75, m0
	s_mov_b32 m0, s58
	s_nop 0
	global_load_lds_dwordx4 v1, s[76:77]
	s_mov_b32 m0, s75
	s_nop 0
	s_mov_b32 s75, m0
	s_mov_b32 m0, s62
	s_nop 0
	global_load_lds_dwordx4 v177, s[76:77]
	s_mov_b32 m0, s75
	s_nop 0
	s_mov_b32 s75, m0
	s_mov_b32 m0, s59
	s_nop 0
	global_load_lds_dwordx4 v1, s[20:21]
	s_mov_b32 m0, s75
	s_nop 0
	s_mov_b32 s75, m0
	s_mov_b32 m0, s63
	s_nop 0
	global_load_lds_dwordx4 v177, s[20:21]
	s_mov_b32 m0, s75
	s_waitcnt vmcnt(8)
	s_waitcnt lgkmcnt(0)
	s_barrier
	s_setprio 1
	s_waitcnt lgkmcnt(7)
	v_mfma_f32_16x16x32_bf16 v[126:129], v[130:133], v[166:169], v[126:129]
	v_mfma_f32_16x16x32_bf16 v[126:129], v[134:137], v[170:173], v[126:129]
	s_waitcnt lgkmcnt(5)
	v_mfma_f32_16x16x32_bf16 v[122:125], v[138:141], v[166:169], v[122:125]
	v_mfma_f32_16x16x32_bf16 v[122:125], v[142:145], v[170:173], v[122:125]
	s_waitcnt lgkmcnt(3)
	v_mfma_f32_16x16x32_bf16 v[110:113], v[138:141], v[186:189], v[110:113]
	v_mfma_f32_16x16x32_bf16 v[110:113], v[142:145], v[190:193], v[110:113]
	s_waitcnt lgkmcnt(1)
	v_mfma_f32_16x16x32_bf16 v[118:121], v[130:133], v[186:189], v[118:121]
	v_mfma_f32_16x16x32_bf16 v[118:121], v[134:137], v[190:193], v[118:121]
	v_mfma_f32_16x16x32_bf16 v[94:97], v[130:133], v[194:197], v[94:97]
	v_mfma_f32_16x16x32_bf16 v[94:97], v[134:137], v[198:201], v[94:97]
	v_mfma_f32_16x16x32_bf16 v[90:93], v[138:141], v[194:197], v[90:93]
	v_mfma_f32_16x16x32_bf16 v[90:93], v[142:145], v[198:201], v[90:93]
	v_mfma_f32_16x16x32_bf16 v[78:81], v[138:141], v[202:205], v[78:81]
	v_mfma_f32_16x16x32_bf16 v[78:81], v[142:145], v[206:209], v[78:81]
	s_waitcnt lgkmcnt(0)
	v_mfma_f32_16x16x32_bf16 v[86:89], v[130:133], v[202:205], v[86:89]
	v_mfma_f32_16x16x32_bf16 v[86:89], v[134:137], v[206:209], v[86:89]
	v_mfma_f32_16x16x32_bf16 v[114:117], v[150:153], v[166:169], v[114:117]
	v_mfma_f32_16x16x32_bf16 v[114:117], v[154:157], v[170:173], v[114:117]
	v_mfma_f32_16x16x32_bf16 v[106:109], v[158:161], v[166:169], v[106:109]
	v_mfma_f32_16x16x32_bf16 v[106:109], v[162:165], v[170:173], v[106:109]
	v_mfma_f32_16x16x32_bf16 v[98:101], v[158:161], v[186:189], v[98:101]
	v_mfma_f32_16x16x32_bf16 v[98:101], v[162:165], v[190:193], v[98:101]
	v_mfma_f32_16x16x32_bf16 v[102:105], v[150:153], v[186:189], v[102:105]
	v_mfma_f32_16x16x32_bf16 v[102:105], v[154:157], v[190:193], v[102:105]
	v_mfma_f32_16x16x32_bf16 v[82:85], v[150:153], v[194:197], v[82:85]
	v_mfma_f32_16x16x32_bf16 v[82:85], v[154:157], v[198:201], v[82:85]
	v_mfma_f32_16x16x32_bf16 v[74:77], v[158:161], v[194:197], v[74:77]
	v_mfma_f32_16x16x32_bf16 v[74:77], v[162:165], v[198:201], v[74:77]
	v_mfma_f32_16x16x32_bf16 v[66:69], v[158:161], v[202:205], v[66:69]
	v_mfma_f32_16x16x32_bf16 v[66:69], v[162:165], v[206:209], v[66:69]
	s_setprio 2
	s_barrier
	v_mfma_f32_16x16x32_bf16 v[70:73], v[150:153], v[202:205], v[70:73]
	v_mfma_f32_16x16x32_bf16 v[70:73], v[154:157], v[206:209], v[70:73]
	s_setprio 0
	ds_read_b128 v[166:169], v183 offset:16384
	ds_read_b128 v[170:173], v183 offset:17408
	ds_read_b128 v[186:189], v183 offset:18432
	ds_read_b128 v[190:193], v183 offset:19456
	ds_read_b128 v[194:197], v183 offset:20480
	ds_read_b128 v[198:201], v183 offset:21504
	ds_read_b128 v[202:205], v183 offset:22528
	ds_read_b128 v[206:209], v183 offset:23552
	s_mov_b32 s75, m0
	s_mov_b32 m0, s35
	s_nop 0
	global_load_lds_dwordx4 v176, s[22:23]
	s_mov_b32 m0, s75
	s_add_u32 s76, s22, 0x4000
	s_mov_b32 s75, m0
	s_mov_b32 m0, s36
	s_nop 0
	global_load_lds_dwordx4 v178, s[22:23]
	s_mov_b32 m0, s75
	s_addc_u32 s77, s23, 0
	s_mov_b32 s75, m0
	s_mov_b32 m0, s37
	s_nop 0
	global_load_lds_dwordx4 v176, s[76:77]
	s_mov_b32 m0, s75
	s_nop 0
	s_mov_b32 s75, m0
	s_mov_b32 m0, s40
	s_nop 0
	global_load_lds_dwordx4 v178, s[76:77]
	s_mov_b32 m0, s75
	s_waitcnt vmcnt(4)
	s_waitcnt lgkmcnt(0)
	s_barrier
	s_setprio 1
	s_waitcnt lgkmcnt(7)
	v_mfma_f32_16x16x32_bf16 v[62:65], v[130:133], v[166:169], v[62:65]
	v_mfma_f32_16x16x32_bf16 v[62:65], v[134:137], v[170:173], v[62:65]
	s_waitcnt lgkmcnt(5)
	v_mfma_f32_16x16x32_bf16 v[58:61], v[138:141], v[166:169], v[58:61]
	v_mfma_f32_16x16x32_bf16 v[58:61], v[142:145], v[170:173], v[58:61]
	s_waitcnt lgkmcnt(3)
	v_mfma_f32_16x16x32_bf16 v[42:45], v[138:141], v[186:189], v[42:45]
	v_mfma_f32_16x16x32_bf16 v[42:45], v[142:145], v[190:193], v[42:45]
	s_waitcnt lgkmcnt(1)
	v_mfma_f32_16x16x32_bf16 v[46:49], v[130:133], v[186:189], v[46:49]
	v_mfma_f32_16x16x32_bf16 v[46:49], v[134:137], v[190:193], v[46:49]
	v_mfma_f32_16x16x32_bf16 v[30:33], v[130:133], v[194:197], v[30:33]
	v_mfma_f32_16x16x32_bf16 v[30:33], v[134:137], v[198:201], v[30:33]
	v_mfma_f32_16x16x32_bf16 v[26:29], v[138:141], v[194:197], v[26:29]
	v_mfma_f32_16x16x32_bf16 v[26:29], v[142:145], v[198:201], v[26:29]
	v_mfma_f32_16x16x32_bf16 v[10:13], v[138:141], v[202:205], v[10:13]
	v_mfma_f32_16x16x32_bf16 v[10:13], v[142:145], v[206:209], v[10:13]
	s_waitcnt lgkmcnt(0)
	v_mfma_f32_16x16x32_bf16 v[14:17], v[130:133], v[202:205], v[14:17]
	v_mfma_f32_16x16x32_bf16 v[14:17], v[134:137], v[206:209], v[14:17]
	v_mfma_f32_16x16x32_bf16 v[54:57], v[150:153], v[166:169], v[54:57]
	v_mfma_f32_16x16x32_bf16 v[54:57], v[154:157], v[170:173], v[54:57]
	v_mfma_f32_16x16x32_bf16 v[50:53], v[158:161], v[166:169], v[50:53]
	v_mfma_f32_16x16x32_bf16 v[50:53], v[162:165], v[170:173], v[50:53]
	v_mfma_f32_16x16x32_bf16 v[34:37], v[158:161], v[186:189], v[34:37]
	v_mfma_f32_16x16x32_bf16 v[34:37], v[162:165], v[190:193], v[34:37]
	v_mfma_f32_16x16x32_bf16 v[38:41], v[150:153], v[186:189], v[38:41]
	v_mfma_f32_16x16x32_bf16 v[38:41], v[154:157], v[190:193], v[38:41]
	v_mfma_f32_16x16x32_bf16 v[22:25], v[150:153], v[194:197], v[22:25]
	v_mfma_f32_16x16x32_bf16 v[22:25], v[154:157], v[198:201], v[22:25]
	v_mfma_f32_16x16x32_bf16 v[18:21], v[158:161], v[194:197], v[18:21]
	v_mfma_f32_16x16x32_bf16 v[18:21], v[162:165], v[198:201], v[18:21]
	v_mfma_f32_16x16x32_bf16 v[2:5], v[158:161], v[202:205], v[2:5]
	v_mfma_f32_16x16x32_bf16 v[2:5], v[162:165], v[206:209], v[2:5]
	s_setprio 2
	s_barrier
	v_mfma_f32_16x16x32_bf16 v[6:9], v[150:153], v[202:205], v[6:9]
	v_mfma_f32_16x16x32_bf16 v[6:9], v[154:157], v[206:209], v[6:9]
	s_setprio 0
	ds_read_b128 v[130:133], v184
	ds_read_b128 v[134:137], v184 offset:1024
	ds_read_b128 v[138:141], v184 offset:2048
	ds_read_b128 v[142:145], v184 offset:3072
	ds_read_b128 v[150:153], v185
	ds_read_b128 v[154:157], v185 offset:1024
	ds_read_b128 v[158:161], v185 offset:2048
	ds_read_b128 v[162:165], v185 offset:3072
	ds_read_b128 v[166:169], v183 offset:32768
	ds_read_b128 v[170:173], v183 offset:33792
	ds_read_b128 v[186:189], v183 offset:34816
	ds_read_b128 v[190:193], v183 offset:35840
	ds_read_b128 v[194:197], v183 offset:36864
	ds_read_b128 v[198:201], v183 offset:37888
	ds_read_b128 v[202:205], v183 offset:38912
	ds_read_b128 v[206:209], v183 offset:39936
	s_mov_b32 s75, m0
	s_mov_b32 m0, s34
	s_nop 0
	global_load_lds_dwordx4 v1, s[24:25]
	s_mov_b32 m0, s75
	s_nop 0
	s_mov_b32 s75, m0
	s_mov_b32 m0, s41
	s_nop 0
	global_load_lds_dwordx4 v177, s[24:25]
	s_mov_b32 m0, s75
	s_add_u32 s24, s24, 0x4000
	s_addc_u32 s25, s25, 0
	s_mov_b32 s75, m0
	s_mov_b32 m0, s42
	s_nop 0
	global_load_lds_dwordx4 v1, s[24:25]
	s_mov_b32 m0, s75
	s_nop 0
	s_mov_b32 s75, m0
	s_mov_b32 m0, s43
	s_nop 0
	global_load_lds_dwordx4 v177, s[24:25]
	s_mov_b32 m0, s75
	s_waitcnt vmcnt(8)
	s_waitcnt lgkmcnt(0)
	s_barrier
	s_setprio 1
	s_waitcnt lgkmcnt(7)
	v_mfma_f32_16x16x32_bf16 v[126:129], v[130:133], v[166:169], v[126:129]
	v_mfma_f32_16x16x32_bf16 v[126:129], v[134:137], v[170:173], v[126:129]
	s_waitcnt lgkmcnt(5)
	v_mfma_f32_16x16x32_bf16 v[122:125], v[138:141], v[166:169], v[122:125]
	v_mfma_f32_16x16x32_bf16 v[122:125], v[142:145], v[170:173], v[122:125]
	s_waitcnt lgkmcnt(3)
	v_mfma_f32_16x16x32_bf16 v[110:113], v[138:141], v[186:189], v[110:113]
	v_mfma_f32_16x16x32_bf16 v[110:113], v[142:145], v[190:193], v[110:113]
	s_waitcnt lgkmcnt(1)
	v_mfma_f32_16x16x32_bf16 v[118:121], v[130:133], v[186:189], v[118:121]
	v_mfma_f32_16x16x32_bf16 v[118:121], v[134:137], v[190:193], v[118:121]
	v_mfma_f32_16x16x32_bf16 v[94:97], v[130:133], v[194:197], v[94:97]
	v_mfma_f32_16x16x32_bf16 v[94:97], v[134:137], v[198:201], v[94:97]
	v_mfma_f32_16x16x32_bf16 v[90:93], v[138:141], v[194:197], v[90:93]
	v_mfma_f32_16x16x32_bf16 v[90:93], v[142:145], v[198:201], v[90:93]
	v_mfma_f32_16x16x32_bf16 v[78:81], v[138:141], v[202:205], v[78:81]
	v_mfma_f32_16x16x32_bf16 v[78:81], v[142:145], v[206:209], v[78:81]
	s_waitcnt lgkmcnt(0)
	v_mfma_f32_16x16x32_bf16 v[86:89], v[130:133], v[202:205], v[86:89]
	v_mfma_f32_16x16x32_bf16 v[86:89], v[134:137], v[206:209], v[86:89]
	v_mfma_f32_16x16x32_bf16 v[114:117], v[150:153], v[166:169], v[114:117]
	v_mfma_f32_16x16x32_bf16 v[114:117], v[154:157], v[170:173], v[114:117]
	v_mfma_f32_16x16x32_bf16 v[106:109], v[158:161], v[166:169], v[106:109]
	v_mfma_f32_16x16x32_bf16 v[106:109], v[162:165], v[170:173], v[106:109]
	v_mfma_f32_16x16x32_bf16 v[98:101], v[158:161], v[186:189], v[98:101]
	v_mfma_f32_16x16x32_bf16 v[98:101], v[162:165], v[190:193], v[98:101]
	v_mfma_f32_16x16x32_bf16 v[102:105], v[150:153], v[186:189], v[102:105]
	v_mfma_f32_16x16x32_bf16 v[102:105], v[154:157], v[190:193], v[102:105]
	v_mfma_f32_16x16x32_bf16 v[82:85], v[150:153], v[194:197], v[82:85]
	v_mfma_f32_16x16x32_bf16 v[82:85], v[154:157], v[198:201], v[82:85]
	v_mfma_f32_16x16x32_bf16 v[74:77], v[158:161], v[194:197], v[74:77]
	v_mfma_f32_16x16x32_bf16 v[74:77], v[162:165], v[198:201], v[74:77]
	v_mfma_f32_16x16x32_bf16 v[66:69], v[158:161], v[202:205], v[66:69]
	v_mfma_f32_16x16x32_bf16 v[66:69], v[162:165], v[206:209], v[66:69]
	s_setprio 2
	s_barrier
	v_mfma_f32_16x16x32_bf16 v[70:73], v[150:153], v[202:205], v[70:73]
	v_mfma_f32_16x16x32_bf16 v[70:73], v[154:157], v[206:209], v[70:73]
	s_setprio 0
	ds_read_b128 v[166:169], v183 offset:49152
	ds_read_b128 v[170:173], v183 offset:50176
	ds_read_b128 v[186:189], v183 offset:51200
	ds_read_b128 v[190:193], v183 offset:52224
	ds_read_b128 v[194:197], v183 offset:53248
	ds_read_b128 v[198:201], v183 offset:54272
	ds_read_b128 v[202:205], v183 offset:55296
	ds_read_b128 v[206:209], v183 offset:56320
	s_add_u32 s24, s22, 0x40000
	s_addc_u32 s25, s23, 0
	s_mov_b32 s75, m0
	s_mov_b32 m0, s46
	s_nop 0
	global_load_lds_dwordx4 v176, s[24:25]
	s_mov_b32 m0, s75
	s_add_u32 s22, s22, 0x44000
	s_mov_b32 s75, m0
	s_mov_b32 m0, s47
	s_nop 0
	global_load_lds_dwordx4 v178, s[24:25]
	s_mov_b32 m0, s75
	s_addc_u32 s23, s23, 0
	s_mov_b32 s24, m0
	s_mov_b32 m0, s48
	s_nop 0
	global_load_lds_dwordx4 v176, s[22:23]
	s_mov_b32 m0, s24
	s_nop 0
	s_mov_b32 s24, m0
	s_mov_b32 m0, s49
	s_nop 0
	global_load_lds_dwordx4 v178, s[22:23]
	s_mov_b32 m0, s24
	s_waitcnt vmcnt(4)
	s_waitcnt lgkmcnt(0)
	s_barrier
	s_setprio 1
	s_waitcnt lgkmcnt(7)
	v_mfma_f32_16x16x32_bf16 v[62:65], v[130:133], v[166:169], v[62:65]
	v_mfma_f32_16x16x32_bf16 v[62:65], v[134:137], v[170:173], v[62:65]
	s_waitcnt lgkmcnt(5)
	v_mfma_f32_16x16x32_bf16 v[58:61], v[138:141], v[166:169], v[58:61]
	v_mfma_f32_16x16x32_bf16 v[58:61], v[142:145], v[170:173], v[58:61]
	s_waitcnt lgkmcnt(3)
	v_mfma_f32_16x16x32_bf16 v[42:45], v[138:141], v[186:189], v[42:45]
	v_mfma_f32_16x16x32_bf16 v[42:45], v[142:145], v[190:193], v[42:45]
	s_waitcnt lgkmcnt(1)
	v_mfma_f32_16x16x32_bf16 v[46:49], v[130:133], v[186:189], v[46:49]
	v_mfma_f32_16x16x32_bf16 v[46:49], v[134:137], v[190:193], v[46:49]
	v_mfma_f32_16x16x32_bf16 v[30:33], v[130:133], v[194:197], v[30:33]
	v_mfma_f32_16x16x32_bf16 v[30:33], v[134:137], v[198:201], v[30:33]
	v_mfma_f32_16x16x32_bf16 v[26:29], v[138:141], v[194:197], v[26:29]
	v_mfma_f32_16x16x32_bf16 v[26:29], v[142:145], v[198:201], v[26:29]
	v_mfma_f32_16x16x32_bf16 v[10:13], v[138:141], v[202:205], v[10:13]
	v_mfma_f32_16x16x32_bf16 v[10:13], v[142:145], v[206:209], v[10:13]
	s_waitcnt lgkmcnt(0)
	v_mfma_f32_16x16x32_bf16 v[14:17], v[130:133], v[202:205], v[14:17]
	v_mfma_f32_16x16x32_bf16 v[14:17], v[134:137], v[206:209], v[14:17]
	v_mfma_f32_16x16x32_bf16 v[54:57], v[150:153], v[166:169], v[54:57]
	v_mfma_f32_16x16x32_bf16 v[54:57], v[154:157], v[170:173], v[54:57]
	v_mfma_f32_16x16x32_bf16 v[50:53], v[158:161], v[166:169], v[50:53]
	v_mfma_f32_16x16x32_bf16 v[50:53], v[162:165], v[170:173], v[50:53]
	v_mfma_f32_16x16x32_bf16 v[34:37], v[158:161], v[186:189], v[34:37]
	v_mfma_f32_16x16x32_bf16 v[34:37], v[162:165], v[190:193], v[34:37]
	v_mfma_f32_16x16x32_bf16 v[38:41], v[150:153], v[186:189], v[38:41]
	v_mfma_f32_16x16x32_bf16 v[38:41], v[154:157], v[190:193], v[38:41]
	v_mfma_f32_16x16x32_bf16 v[22:25], v[150:153], v[194:197], v[22:25]
	v_mfma_f32_16x16x32_bf16 v[22:25], v[154:157], v[198:201], v[22:25]
	v_mfma_f32_16x16x32_bf16 v[18:21], v[158:161], v[194:197], v[18:21]
	v_mfma_f32_16x16x32_bf16 v[18:21], v[162:165], v[198:201], v[18:21]
	v_mfma_f32_16x16x32_bf16 v[2:5], v[158:161], v[202:205], v[2:5]
	v_mfma_f32_16x16x32_bf16 v[2:5], v[162:165], v[206:209], v[2:5]
	s_setprio 2
	s_barrier
	v_mfma_f32_16x16x32_bf16 v[6:9], v[150:153], v[202:205], v[6:9]
	v_mfma_f32_16x16x32_bf16 v[6:9], v[154:157], v[206:209], v[6:9]
	s_setprio 0
	s_add_i32 s74, s74, 2
	s_add_u32 s67, s67, 0x80000
	s_addc_u32 s70, s70, 0
	s_add_u32 s20, s20, 0x400000
	s_addc_u32 s21, s21, 0
	s_add_u32 s71, s71, 0x400000
	s_addc_u32 s73, s73, 0
	s_cmpk_gt_u32 s74, 0x53
	s_cbranch_scc0 .LBB0_1952
	s_and_b64 vcc, exec, s[8:9]
	s_cbranch_vccz .LBB0_1955
	s_barrier

.LBB0_2145:
	s_ashr_i32 s25, s24, 31
	s_lshl_b64 s[26:27], s[24:25], 20
	s_add_u32 s26, s33, s26
	s_addc_u32 s27, s42, s27
	s_and_b64 s[28:29], s[2:3], exec
	s_cselect_b32 s5, s27, s37
	s_cselect_b32 s25, s26, s36
	s_ashr_i32 s23, s22, 31
	s_lshl_b64 s[28:29], s[22:23], 20
	s_add_u32 s28, s43, s28
	s_addc_u32 s29, s46, s29
	s_and_b64 s[40:41], s[2:3], exec
	s_cselect_b32 s23, s29, s35
	s_cselect_b32 s31, s28, s34
	s_add_u32 s77, s34, 0x100
	s_addc_u32 s78, s35, 0
	s_add_u32 s34, s36, 0x80080
	s_addc_u32 s35, s37, 0
	s_add_u32 s79, s36, 0x100
	s_addc_u32 s80, s37, 0
	s_mov_b32 s81, -2
	s_waitcnt vmcnt(25)
	s_waitcnt vmcnt(24)
	s_waitcnt vmcnt(4)
	s_waitcnt vmcnt(2)
	s_waitcnt vmcnt(1)
	s_waitcnt vmcnt(0)
	ds_read_b128 v[42:45], v181
	ds_read_b128 v[46:49], v181 offset:1024
	ds_read_b128 v[58:61], v181 offset:2048
	ds_read_b128 v[62:65], v181 offset:3072
	ds_read_b128 v[146:149], v182
	ds_read_b128 v[150:153], v182 offset:1024
	ds_read_b128 v[154:157], v182 offset:2048
	ds_read_b128 v[158:161], v182 offset:3072
	s_cmp_eq_u32 s81, 28
	s_cselect_b32 s37, s23, s78
	s_cselect_b32 s36, s31, s77
	s_cselect_b32 s41, s5, s80
	s_cselect_b32 s40, s25, s79
	ds_read_b128 v[170:173], v183
	ds_read_b128 v[188:191], v183 offset:1024
	ds_read_b128 v[192:195], v183 offset:2048
	ds_read_b128 v[196:199], v183 offset:3072
	ds_read_b128 v[200:203], v183 offset:4096
	ds_read_b128 v[204:207], v183 offset:5120
	ds_read_b128 v[208:211], v183 offset:6144
	ds_read_b128 v[212:215], v183 offset:7168
	s_add_u32 s82, s34, 0xfff80000
	s_addc_u32 s83, s35, -1
	s_mov_b32 s86, m0
	s_mov_b32 m0, s70
	s_nop 0
	global_load_lds_dwordx4 v1, s[82:83]
	s_mov_b32 m0, s86
	s_nop 0
	s_mov_b32 s86, m0
	s_mov_b32 m0, s73
	s_nop 0
	global_load_lds_dwordx4 v177, s[82:83]
	s_mov_b32 m0, s86
	s_mov_b32 s82, m0
	s_mov_b32 m0, s71
	s_nop 0
	global_load_lds_dwordx4 v1, s[34:35]
	s_mov_b32 m0, s82
	s_nop 0
	s_mov_b32 s82, m0
	s_mov_b32 m0, s74
	s_nop 0
	global_load_lds_dwordx4 v177, s[34:35]
	s_mov_b32 m0, s82
	s_waitcnt vmcnt(8)
	s_waitcnt lgkmcnt(0)
	s_barrier
	s_setprio 1
	s_waitcnt lgkmcnt(7)
	v_mfma_f32_16x16x32_bf16 v[142:145], v[42:45], v[170:173], 0
	v_mfma_f32_16x16x32_bf16 v[142:145], v[46:49], v[188:191], v[142:145]
	s_waitcnt lgkmcnt(5)
	v_mfma_f32_16x16x32_bf16 v[138:141], v[58:61], v[170:173], 0
	v_mfma_f32_16x16x32_bf16 v[138:141], v[62:65], v[188:191], v[138:141]
	s_waitcnt lgkmcnt(3)
	v_mfma_f32_16x16x32_bf16 v[126:129], v[42:45], v[192:195], 0
	v_mfma_f32_16x16x32_bf16 v[126:129], v[46:49], v[196:199], v[126:129]
	s_waitcnt lgkmcnt(1)
	v_mfma_f32_16x16x32_bf16 v[122:125], v[58:61], v[192:195], 0
	v_mfma_f32_16x16x32_bf16 v[122:125], v[62:65], v[196:199], v[122:125]
	v_mfma_f32_16x16x32_bf16 v[110:113], v[42:45], v[200:203], 0
	v_mfma_f32_16x16x32_bf16 v[110:113], v[46:49], v[204:207], v[110:113]
	v_mfma_f32_16x16x32_bf16 v[106:109], v[58:61], v[200:203], 0
	v_mfma_f32_16x16x32_bf16 v[106:109], v[62:65], v[204:207], v[106:109]
	v_mfma_f32_16x16x32_bf16 v[94:97], v[42:45], v[208:211], 0
	v_mfma_f32_16x16x32_bf16 v[94:97], v[46:49], v[212:215], v[94:97]
	s_waitcnt lgkmcnt(0)
	v_mfma_f32_16x16x32_bf16 v[90:93], v[58:61], v[208:211], 0
	v_mfma_f32_16x16x32_bf16 v[90:93], v[62:65], v[212:215], v[90:93]
	v_mfma_f32_16x16x32_bf16 v[134:137], v[146:149], v[170:173], 0
	v_mfma_f32_16x16x32_bf16 v[134:137], v[150:153], v[188:191], v[134:137]
	v_mfma_f32_16x16x32_bf16 v[130:133], v[154:157], v[170:173], 0
	v_mfma_f32_16x16x32_bf16 v[130:133], v[158:161], v[188:191], v[130:133]
	v_mfma_f32_16x16x32_bf16 v[118:121], v[146:149], v[192:195], 0
	v_mfma_f32_16x16x32_bf16 v[118:121], v[150:153], v[196:199], v[118:121]
	v_mfma_f32_16x16x32_bf16 v[114:117], v[154:157], v[192:195], 0
	v_mfma_f32_16x16x32_bf16 v[114:117], v[158:161], v[196:199], v[114:117]
	v_mfma_f32_16x16x32_bf16 v[102:105], v[146:149], v[200:203], 0
	v_mfma_f32_16x16x32_bf16 v[102:105], v[150:153], v[204:207], v[102:105]
	v_mfma_f32_16x16x32_bf16 v[98:101], v[154:157], v[200:203], 0
	v_mfma_f32_16x16x32_bf16 v[98:101], v[158:161], v[204:207], v[98:101]
	v_mfma_f32_16x16x32_bf16 v[86:89], v[146:149], v[208:211], 0
	v_mfma_f32_16x16x32_bf16 v[86:89], v[150:153], v[212:215], v[86:89]
	s_setprio 2
	s_barrier
	v_mfma_f32_16x16x32_bf16 v[82:85], v[154:157], v[208:211], 0
	v_mfma_f32_16x16x32_bf16 v[82:85], v[158:161], v[212:215], v[82:85]
	s_setprio 0
	ds_read_b128 v[170:173], v183 offset:16384
	ds_read_b128 v[188:191], v183 offset:17408
	ds_read_b128 v[192:195], v183 offset:18432
	ds_read_b128 v[196:199], v183 offset:19456
	ds_read_b128 v[200:203], v183 offset:20480
	ds_read_b128 v[204:207], v183 offset:21504
	ds_read_b128 v[208:211], v183 offset:22528
	ds_read_b128 v[212:215], v183 offset:23552
	s_mov_b32 s82, m0
	s_mov_b32 m0, s49
	s_nop 0
	global_load_lds_dwordx4 v176, s[36:37]
	s_mov_b32 m0, s82
	s_nop 0
	s_mov_b32 s82, m0
	s_mov_b32 m0, s56
	s_nop 0
	global_load_lds_dwordx4 v178, s[36:37]
	s_mov_b32 m0, s82
	s_add_u32 s82, s36, 0x80000
	s_addc_u32 s83, s37, 0
	s_mov_b32 s86, m0
	s_mov_b32 m0, s57
	s_nop 0
	global_load_lds_dwordx4 v176, s[82:83]
	s_mov_b32 m0, s86
	s_nop 0
	s_mov_b32 s86, m0
	s_mov_b32 m0, s58
	s_nop 0
	global_load_lds_dwordx4 v178, s[82:83]
	s_mov_b32 m0, s86
	s_waitcnt vmcnt(4)
	s_waitcnt lgkmcnt(0)
	s_barrier
	s_setprio 1
	s_waitcnt lgkmcnt(7)
	v_mfma_f32_16x16x32_bf16 v[78:81], v[42:45], v[170:173], 0
	v_mfma_f32_16x16x32_bf16 v[78:81], v[46:49], v[188:191], v[78:81]
	s_waitcnt lgkmcnt(5)
	v_mfma_f32_16x16x32_bf16 v[74:77], v[58:61], v[170:173], 0
	v_mfma_f32_16x16x32_bf16 v[74:77], v[62:65], v[188:191], v[74:77]
	s_waitcnt lgkmcnt(3)
	v_mfma_f32_16x16x32_bf16 v[54:57], v[42:45], v[192:195], 0
	v_mfma_f32_16x16x32_bf16 v[54:57], v[46:49], v[196:199], v[54:57]
	s_waitcnt lgkmcnt(1)
	v_mfma_f32_16x16x32_bf16 v[50:53], v[58:61], v[192:195], 0
	v_mfma_f32_16x16x32_bf16 v[50:53], v[62:65], v[196:199], v[50:53]
	v_mfma_f32_16x16x32_bf16 v[30:33], v[42:45], v[200:203], 0
	v_mfma_f32_16x16x32_bf16 v[30:33], v[46:49], v[204:207], v[30:33]
	v_mfma_f32_16x16x32_bf16 v[26:29], v[58:61], v[200:203], 0
	v_mfma_f32_16x16x32_bf16 v[26:29], v[62:65], v[204:207], v[26:29]
	v_mfma_f32_16x16x32_bf16 v[14:17], v[42:45], v[208:211], 0
	v_mfma_f32_16x16x32_bf16 v[14:17], v[46:49], v[212:215], v[14:17]
	s_waitcnt lgkmcnt(0)
	v_mfma_f32_16x16x32_bf16 v[10:13], v[58:61], v[208:211], 0
	v_mfma_f32_16x16x32_bf16 v[10:13], v[62:65], v[212:215], v[10:13]
	v_mfma_f32_16x16x32_bf16 v[38:41], v[146:149], v[192:195], 0
	v_mfma_f32_16x16x32_bf16 v[38:41], v[150:153], v[196:199], v[38:41]
	v_mfma_f32_16x16x32_bf16 v[34:37], v[154:157], v[192:195], 0
	v_mfma_f32_16x16x32_bf16 v[34:37], v[158:161], v[196:199], v[34:37]
	v_mfma_f32_16x16x32_bf16 v[22:25], v[146:149], v[200:203], 0
	v_mfma_f32_16x16x32_bf16 v[22:25], v[150:153], v[204:207], v[22:25]
	v_mfma_f32_16x16x32_bf16 v[18:21], v[154:157], v[200:203], 0
	v_mfma_f32_16x16x32_bf16 v[18:21], v[158:161], v[204:207], v[18:21]
	v_mfma_f32_16x16x32_bf16 v[6:9], v[146:149], v[208:211], 0
	v_mfma_f32_16x16x32_bf16 v[6:9], v[150:153], v[212:215], v[6:9]
	v_mfma_f32_16x16x32_bf16 v[2:5], v[154:157], v[208:211], 0
	v_mfma_f32_16x16x32_bf16 v[2:5], v[158:161], v[212:215], v[2:5]
	v_mfma_f32_16x16x32_bf16 v[42:45], v[146:149], v[170:173], 0
	v_mfma_f32_16x16x32_bf16 v[42:45], v[150:153], v[188:191], v[42:45]
	s_setprio 2
	s_barrier
	v_mfma_f32_16x16x32_bf16 v[46:49], v[154:157], v[170:173], 0
	v_mfma_f32_16x16x32_bf16 v[46:49], v[158:161], v[188:191], v[46:49]
	s_setprio 0
	ds_read_b128 v[58:61], v184
	ds_read_b128 v[62:65], v184 offset:1024
	ds_read_b128 v[66:69], v184 offset:2048
	ds_read_b128 v[70:73], v184 offset:3072
	ds_read_b128 v[146:149], v185
	ds_read_b128 v[150:153], v185 offset:1024
	ds_read_b128 v[154:157], v185 offset:2048
	ds_read_b128 v[158:161], v185 offset:3072
	ds_read_b128 v[170:173], v183 offset:32768
	ds_read_b128 v[188:191], v183 offset:33792
	ds_read_b128 v[192:195], v183 offset:34816
	ds_read_b128 v[196:199], v183 offset:35840
	ds_read_b128 v[200:203], v183 offset:36864
	ds_read_b128 v[204:207], v183 offset:37888
	ds_read_b128 v[208:211], v183 offset:38912
	ds_read_b128 v[212:215], v183 offset:39936
	s_mov_b32 s82, m0
	s_mov_b32 m0, s48
	s_nop 0
	global_load_lds_dwordx4 v1, s[40:41]
	s_mov_b32 m0, s82
	s_nop 0
	s_mov_b32 s82, m0
	s_mov_b32 m0, s59
	s_nop 0
	global_load_lds_dwordx4 v177, s[40:41]
	s_mov_b32 m0, s82
	s_add_u32 s40, s40, 0x80000
	s_addc_u32 s41, s41, 0
	s_mov_b32 s82, m0
	s_mov_b32 m0, s62
	s_nop 0
	global_load_lds_dwordx4 v1, s[40:41]
	s_mov_b32 m0, s82
	s_nop 0
	s_mov_b32 s82, m0
	s_mov_b32 m0, s63
	s_nop 0
	global_load_lds_dwordx4 v177, s[40:41]
	s_mov_b32 m0, s82
	s_waitcnt vmcnt(8)
	s_waitcnt lgkmcnt(0)
	s_barrier
	s_setprio 1
	s_waitcnt lgkmcnt(7)
	v_mfma_f32_16x16x32_bf16 v[142:145], v[58:61], v[170:173], v[142:145]
	v_mfma_f32_16x16x32_bf16 v[142:145], v[62:65], v[188:191], v[142:145]
	s_waitcnt lgkmcnt(5)
	v_mfma_f32_16x16x32_bf16 v[138:141], v[66:69], v[170:173], v[138:141]
	v_mfma_f32_16x16x32_bf16 v[138:141], v[70:73], v[188:191], v[138:141]
	s_waitcnt lgkmcnt(3)
	v_mfma_f32_16x16x32_bf16 v[126:129], v[58:61], v[192:195], v[126:129]
	v_mfma_f32_16x16x32_bf16 v[126:129], v[62:65], v[196:199], v[126:129]
	s_waitcnt lgkmcnt(1)
	v_mfma_f32_16x16x32_bf16 v[122:125], v[66:69], v[192:195], v[122:125]
	v_mfma_f32_16x16x32_bf16 v[122:125], v[70:73], v[196:199], v[122:125]
	v_mfma_f32_16x16x32_bf16 v[110:113], v[58:61], v[200:203], v[110:113]
	v_mfma_f32_16x16x32_bf16 v[110:113], v[62:65], v[204:207], v[110:113]
	v_mfma_f32_16x16x32_bf16 v[106:109], v[66:69], v[200:203], v[106:109]
	v_mfma_f32_16x16x32_bf16 v[106:109], v[70:73], v[204:207], v[106:109]
	v_mfma_f32_16x16x32_bf16 v[94:97], v[58:61], v[208:211], v[94:97]
	v_mfma_f32_16x16x32_bf16 v[94:97], v[62:65], v[212:215], v[94:97]
	s_waitcnt lgkmcnt(0)
	v_mfma_f32_16x16x32_bf16 v[90:93], v[66:69], v[208:211], v[90:93]
	v_mfma_f32_16x16x32_bf16 v[90:93], v[70:73], v[212:215], v[90:93]
	v_mfma_f32_16x16x32_bf16 v[134:137], v[146:149], v[170:173], v[134:137]
	v_mfma_f32_16x16x32_bf16 v[134:137], v[150:153], v[188:191], v[134:137]
	v_mfma_f32_16x16x32_bf16 v[130:133], v[154:157], v[170:173], v[130:133]
	v_mfma_f32_16x16x32_bf16 v[130:133], v[158:161], v[188:191], v[130:133]
	v_mfma_f32_16x16x32_bf16 v[118:121], v[146:149], v[192:195], v[118:121]
	v_mfma_f32_16x16x32_bf16 v[118:121], v[150:153], v[196:199], v[118:121]
	v_mfma_f32_16x16x32_bf16 v[114:117], v[154:157], v[192:195], v[114:117]
	v_mfma_f32_16x16x32_bf16 v[114:117], v[158:161], v[196:199], v[114:117]
	v_mfma_f32_16x16x32_bf16 v[102:105], v[146:149], v[200:203], v[102:105]
	v_mfma_f32_16x16x32_bf16 v[102:105], v[150:153], v[204:207], v[102:105]
	v_mfma_f32_16x16x32_bf16 v[98:101], v[154:157], v[200:203], v[98:101]
	v_mfma_f32_16x16x32_bf16 v[98:101], v[158:161], v[204:207], v[98:101]
	v_mfma_f32_16x16x32_bf16 v[86:89], v[146:149], v[208:211], v[86:89]
	v_mfma_f32_16x16x32_bf16 v[86:89], v[150:153], v[212:215], v[86:89]
	s_setprio 2
	s_barrier
	v_mfma_f32_16x16x32_bf16 v[82:85], v[154:157], v[208:211], v[82:85]
	v_mfma_f32_16x16x32_bf16 v[82:85], v[158:161], v[212:215], v[82:85]
	s_setprio 0
	ds_read_b128 v[170:173], v183 offset:49152
	ds_read_b128 v[188:191], v183 offset:50176
	ds_read_b128 v[192:195], v183 offset:51200
	ds_read_b128 v[196:199], v183 offset:52224
	ds_read_b128 v[200:203], v183 offset:53248
	ds_read_b128 v[204:207], v183 offset:54272
	ds_read_b128 v[208:211], v183 offset:55296
	ds_read_b128 v[212:215], v183 offset:56320
	s_add_u32 s40, s36, 0x80
	s_addc_u32 s41, s37, 0
	s_mov_b32 s82, m0
	s_mov_b32 m0, s64
	s_nop 0
	global_load_lds_dwordx4 v176, s[40:41]
	s_mov_b32 m0, s82
	s_add_u32 s36, s36, 0x80080
	s_mov_b32 s82, m0
	s_mov_b32 m0, s65
	s_nop 0
	global_load_lds_dwordx4 v178, s[40:41]
	s_mov_b32 m0, s82
	s_addc_u32 s37, s37, 0
	s_mov_b32 s40, m0
	s_mov_b32 m0, s66
	s_nop 0
	global_load_lds_dwordx4 v176, s[36:37]
	s_mov_b32 m0, s40
	s_nop 0
	s_mov_b32 s40, m0
	s_mov_b32 m0, s67
	s_nop 0
	global_load_lds_dwordx4 v178, s[36:37]
	s_mov_b32 m0, s40
	s_waitcnt vmcnt(4)
	s_waitcnt lgkmcnt(0)
	s_barrier
	s_setprio 1
	s_waitcnt lgkmcnt(7)
	v_mfma_f32_16x16x32_bf16 v[78:81], v[58:61], v[170:173], v[78:81]
	v_mfma_f32_16x16x32_bf16 v[78:81], v[62:65], v[188:191], v[78:81]
	s_waitcnt lgkmcnt(5)
	v_mfma_f32_16x16x32_bf16 v[74:77], v[66:69], v[170:173], v[74:77]
	v_mfma_f32_16x16x32_bf16 v[74:77], v[70:73], v[188:191], v[74:77]
	s_waitcnt lgkmcnt(3)
	v_mfma_f32_16x16x32_bf16 v[54:57], v[58:61], v[192:195], v[54:57]
	v_mfma_f32_16x16x32_bf16 v[54:57], v[62:65], v[196:199], v[54:57]
	s_waitcnt lgkmcnt(1)
	v_mfma_f32_16x16x32_bf16 v[50:53], v[66:69], v[192:195], v[50:53]
	v_mfma_f32_16x16x32_bf16 v[50:53], v[70:73], v[196:199], v[50:53]
	v_mfma_f32_16x16x32_bf16 v[30:33], v[58:61], v[200:203], v[30:33]
	v_mfma_f32_16x16x32_bf16 v[30:33], v[62:65], v[204:207], v[30:33]
	v_mfma_f32_16x16x32_bf16 v[26:29], v[66:69], v[200:203], v[26:29]
	v_mfma_f32_16x16x32_bf16 v[26:29], v[70:73], v[204:207], v[26:29]
	v_mfma_f32_16x16x32_bf16 v[14:17], v[58:61], v[208:211], v[14:17]
	v_mfma_f32_16x16x32_bf16 v[14:17], v[62:65], v[212:215], v[14:17]
	s_waitcnt lgkmcnt(0)
	v_mfma_f32_16x16x32_bf16 v[10:13], v[66:69], v[208:211], v[10:13]
	v_mfma_f32_16x16x32_bf16 v[10:13], v[70:73], v[212:215], v[10:13]
	v_mfma_f32_16x16x32_bf16 v[42:45], v[146:149], v[170:173], v[42:45]
	v_mfma_f32_16x16x32_bf16 v[70:73], v[150:153], v[188:191], v[42:45]
	v_mfma_f32_16x16x32_bf16 v[42:45], v[154:157], v[170:173], v[46:49]
	v_mfma_f32_16x16x32_bf16 v[66:69], v[158:161], v[188:191], v[42:45]
	v_mfma_f32_16x16x32_bf16 v[38:41], v[146:149], v[192:195], v[38:41]
	v_mfma_f32_16x16x32_bf16 v[38:41], v[150:153], v[196:199], v[38:41]
	v_mfma_f32_16x16x32_bf16 v[34:37], v[154:157], v[192:195], v[34:37]
	v_mfma_f32_16x16x32_bf16 v[34:37], v[158:161], v[196:199], v[34:37]
	v_mfma_f32_16x16x32_bf16 v[22:25], v[146:149], v[200:203], v[22:25]
	v_mfma_f32_16x16x32_bf16 v[22:25], v[150:153], v[204:207], v[22:25]
	v_mfma_f32_16x16x32_bf16 v[18:21], v[154:157], v[200:203], v[18:21]
	v_mfma_f32_16x16x32_bf16 v[18:21], v[158:161], v[204:207], v[18:21]
	v_mfma_f32_16x16x32_bf16 v[6:9], v[146:149], v[208:211], v[6:9]
	v_mfma_f32_16x16x32_bf16 v[6:9], v[150:153], v[212:215], v[6:9]
	s_setprio 2
	s_barrier
	v_mfma_f32_16x16x32_bf16 v[2:5], v[154:157], v[208:211], v[2:5]
	v_mfma_f32_16x16x32_bf16 v[2:5], v[158:161], v[212:215], v[2:5]
	s_setprio 0
	s_add_i32 s81, s81, 2
	s_add_u32 s77, s77, 0x100
	s_addc_u32 s78, s78, 0
	s_add_u32 s34, s34, 0x100
	s_addc_u32 s35, s35, 0
	s_add_u32 s79, s79, 0x100
	s_addc_u32 s80, s80, 0
	s_cmp_gt_u32 s81, 29
	.p2align 6
.LBB0_2146:
	ds_read_b128 v[42:45], v181
	ds_read_b128 v[46:49], v181 offset:1024
	ds_read_b128 v[58:61], v181 offset:2048
	ds_read_b128 v[62:65], v181 offset:3072
	ds_read_b128 v[146:149], v182
	ds_read_b128 v[150:153], v182 offset:1024
	ds_read_b128 v[154:157], v182 offset:2048
	ds_read_b128 v[158:161], v182 offset:3072
	s_cmp_eq_u32 s81, 28
	s_cselect_b32 s37, s23, s78
	s_cselect_b32 s36, s31, s77
	s_cselect_b32 s41, s5, s80
	s_cselect_b32 s40, s25, s79
	ds_read_b128 v[170:173], v183
	ds_read_b128 v[188:191], v183 offset:1024
	ds_read_b128 v[192:195], v183 offset:2048
	ds_read_b128 v[196:199], v183 offset:3072
	ds_read_b128 v[200:203], v183 offset:4096
	ds_read_b128 v[204:207], v183 offset:5120
	ds_read_b128 v[208:211], v183 offset:6144
	ds_read_b128 v[212:215], v183 offset:7168
	s_add_u32 s82, s34, 0xfff80000
	s_addc_u32 s83, s35, -1
	s_mov_b32 s86, m0
	s_mov_b32 m0, s70
	s_nop 0
	global_load_lds_dwordx4 v1, s[82:83]
	s_mov_b32 m0, s86
	s_nop 0
	s_mov_b32 s86, m0
	s_mov_b32 m0, s73
	s_nop 0
	global_load_lds_dwordx4 v177, s[82:83]
	s_mov_b32 m0, s86
	s_mov_b32 s82, m0
	s_mov_b32 m0, s71
	s_nop 0
	global_load_lds_dwordx4 v1, s[34:35]
	s_mov_b32 m0, s82
	s_nop 0
	s_mov_b32 s82, m0
	s_mov_b32 m0, s74
	s_nop 0
	global_load_lds_dwordx4 v177, s[34:35]
	s_mov_b32 m0, s82
	s_waitcnt vmcnt(8)
	s_waitcnt lgkmcnt(0)
	s_barrier
	s_setprio 1
	s_waitcnt lgkmcnt(7)
	v_mfma_f32_16x16x32_bf16 v[142:145], v[42:45], v[170:173], v[142:145]
	v_mfma_f32_16x16x32_bf16 v[142:145], v[46:49], v[188:191], v[142:145]
	s_waitcnt lgkmcnt(5)
	v_mfma_f32_16x16x32_bf16 v[138:141], v[58:61], v[170:173], v[138:141]
	v_mfma_f32_16x16x32_bf16 v[138:141], v[62:65], v[188:191], v[138:141]
	s_waitcnt lgkmcnt(3)
	v_mfma_f32_16x16x32_bf16 v[126:129], v[42:45], v[192:195], v[126:129]
	v_mfma_f32_16x16x32_bf16 v[126:129], v[46:49], v[196:199], v[126:129]
	s_waitcnt lgkmcnt(1)
	v_mfma_f32_16x16x32_bf16 v[122:125], v[58:61], v[192:195], v[122:125]
	v_mfma_f32_16x16x32_bf16 v[122:125], v[62:65], v[196:199], v[122:125]
	v_mfma_f32_16x16x32_bf16 v[110:113], v[42:45], v[200:203], v[110:113]
	v_mfma_f32_16x16x32_bf16 v[110:113], v[46:49], v[204:207], v[110:113]
	v_mfma_f32_16x16x32_bf16 v[106:109], v[58:61], v[200:203], v[106:109]
	v_mfma_f32_16x16x32_bf16 v[106:109], v[62:65], v[204:207], v[106:109]
	v_mfma_f32_16x16x32_bf16 v[94:97], v[42:45], v[208:211], v[94:97]
	v_mfma_f32_16x16x32_bf16 v[94:97], v[46:49], v[212:215], v[94:97]
	s_waitcnt lgkmcnt(0)
	v_mfma_f32_16x16x32_bf16 v[90:93], v[58:61], v[208:211], v[90:93]
	v_mfma_f32_16x16x32_bf16 v[90:93], v[62:65], v[212:215], v[90:93]
	v_mfma_f32_16x16x32_bf16 v[134:137], v[146:149], v[170:173], v[134:137]
	v_mfma_f32_16x16x32_bf16 v[134:137], v[150:153], v[188:191], v[134:137]
	v_mfma_f32_16x16x32_bf16 v[130:133], v[154:157], v[170:173], v[130:133]
	v_mfma_f32_16x16x32_bf16 v[130:133], v[158:161], v[188:191], v[130:133]
	v_mfma_f32_16x16x32_bf16 v[118:121], v[146:149], v[192:195], v[118:121]
	v_mfma_f32_16x16x32_bf16 v[118:121], v[150:153], v[196:199], v[118:121]
	v_mfma_f32_16x16x32_bf16 v[114:117], v[154:157], v[192:195], v[114:117]
	v_mfma_f32_16x16x32_bf16 v[114:117], v[158:161], v[196:199], v[114:117]
	v_mfma_f32_16x16x32_bf16 v[102:105], v[146:149], v[200:203], v[102:105]
	v_mfma_f32_16x16x32_bf16 v[102:105], v[150:153], v[204:207], v[102:105]
	v_mfma_f32_16x16x32_bf16 v[98:101], v[154:157], v[200:203], v[98:101]
	v_mfma_f32_16x16x32_bf16 v[98:101], v[158:161], v[204:207], v[98:101]
	v_mfma_f32_16x16x32_bf16 v[86:89], v[146:149], v[208:211], v[86:89]
	v_mfma_f32_16x16x32_bf16 v[86:89], v[150:153], v[212:215], v[86:89]
	s_setprio 2
	s_barrier
	v_mfma_f32_16x16x32_bf16 v[82:85], v[154:157], v[208:211], v[82:85]
	v_mfma_f32_16x16x32_bf16 v[82:85], v[158:161], v[212:215], v[82:85]
	s_setprio 0
	ds_read_b128 v[170:173], v183 offset:16384
	ds_read_b128 v[188:191], v183 offset:17408
	ds_read_b128 v[192:195], v183 offset:18432
	ds_read_b128 v[196:199], v183 offset:19456
	ds_read_b128 v[200:203], v183 offset:20480
	ds_read_b128 v[204:207], v183 offset:21504
	ds_read_b128 v[208:211], v183 offset:22528
	ds_read_b128 v[212:215], v183 offset:23552
	s_mov_b32 s82, m0
	s_mov_b32 m0, s49
	s_nop 0
	global_load_lds_dwordx4 v176, s[36:37]
	s_mov_b32 m0, s82
	s_nop 0
	s_mov_b32 s82, m0
	s_mov_b32 m0, s56
	s_nop 0
	global_load_lds_dwordx4 v178, s[36:37]
	s_mov_b32 m0, s82
	s_add_u32 s82, s36, 0x80000
	s_addc_u32 s83, s37, 0
	s_mov_b32 s86, m0
	s_mov_b32 m0, s57
	s_nop 0
	global_load_lds_dwordx4 v176, s[82:83]
	s_mov_b32 m0, s86
	s_nop 0
	s_mov_b32 s86, m0
	s_mov_b32 m0, s58
	s_nop 0
	global_load_lds_dwordx4 v178, s[82:83]
	s_mov_b32 m0, s86
	s_waitcnt vmcnt(4)
	s_waitcnt lgkmcnt(0)
	s_barrier
	s_setprio 1
	s_waitcnt lgkmcnt(7)
	v_mfma_f32_16x16x32_bf16 v[78:81], v[42:45], v[170:173], v[78:81]
	v_mfma_f32_16x16x32_bf16 v[78:81], v[46:49], v[188:191], v[78:81]
	s_waitcnt lgkmcnt(5)
	v_mfma_f32_16x16x32_bf16 v[74:77], v[58:61], v[170:173], v[74:77]
	v_mfma_f32_16x16x32_bf16 v[74:77], v[62:65], v[188:191], v[74:77]
	s_waitcnt lgkmcnt(3)
	v_mfma_f32_16x16x32_bf16 v[54:57], v[42:45], v[192:195], v[54:57]
	v_mfma_f32_16x16x32_bf16 v[54:57], v[46:49], v[196:199], v[54:57]
	s_waitcnt lgkmcnt(1)
	v_mfma_f32_16x16x32_bf16 v[50:53], v[58:61], v[192:195], v[50:53]
	v_mfma_f32_16x16x32_bf16 v[50:53], v[62:65], v[196:199], v[50:53]
	v_mfma_f32_16x16x32_bf16 v[30:33], v[42:45], v[200:203], v[30:33]
	v_mfma_f32_16x16x32_bf16 v[30:33], v[46:49], v[204:207], v[30:33]
	v_mfma_f32_16x16x32_bf16 v[26:29], v[58:61], v[200:203], v[26:29]
	v_mfma_f32_16x16x32_bf16 v[26:29], v[62:65], v[204:207], v[26:29]
	v_mfma_f32_16x16x32_bf16 v[14:17], v[42:45], v[208:211], v[14:17]
	v_mfma_f32_16x16x32_bf16 v[14:17], v[46:49], v[212:215], v[14:17]
	s_waitcnt lgkmcnt(0)
	v_mfma_f32_16x16x32_bf16 v[10:13], v[58:61], v[208:211], v[10:13]
	v_mfma_f32_16x16x32_bf16 v[10:13], v[62:65], v[212:215], v[10:13]
	v_mfma_f32_16x16x32_bf16 v[38:41], v[146:149], v[192:195], v[38:41]
	v_mfma_f32_16x16x32_bf16 v[38:41], v[150:153], v[196:199], v[38:41]
	v_mfma_f32_16x16x32_bf16 v[34:37], v[154:157], v[192:195], v[34:37]
	v_mfma_f32_16x16x32_bf16 v[34:37], v[158:161], v[196:199], v[34:37]
	v_mfma_f32_16x16x32_bf16 v[22:25], v[146:149], v[200:203], v[22:25]
	v_mfma_f32_16x16x32_bf16 v[22:25], v[150:153], v[204:207], v[22:25]
	v_mfma_f32_16x16x32_bf16 v[18:21], v[154:157], v[200:203], v[18:21]
	v_mfma_f32_16x16x32_bf16 v[18:21], v[158:161], v[204:207], v[18:21]
	v_mfma_f32_16x16x32_bf16 v[6:9], v[146:149], v[208:211], v[6:9]
	v_mfma_f32_16x16x32_bf16 v[6:9], v[150:153], v[212:215], v[6:9]
	v_mfma_f32_16x16x32_bf16 v[2:5], v[154:157], v[208:211], v[2:5]
	v_mfma_f32_16x16x32_bf16 v[2:5], v[158:161], v[212:215], v[2:5]
	v_mfma_f32_16x16x32_bf16 v[42:45], v[146:149], v[170:173], v[70:73]
	v_mfma_f32_16x16x32_bf16 v[42:45], v[150:153], v[188:191], v[42:45]
	s_setprio 2
	s_barrier
	v_mfma_f32_16x16x32_bf16 v[46:49], v[154:157], v[170:173], v[66:69]
	v_mfma_f32_16x16x32_bf16 v[46:49], v[158:161], v[188:191], v[46:49]
	s_setprio 0
	ds_read_b128 v[58:61], v184
	ds_read_b128 v[62:65], v184 offset:1024
	ds_read_b128 v[66:69], v184 offset:2048
	ds_read_b128 v[70:73], v184 offset:3072
	ds_read_b128 v[146:149], v185
	ds_read_b128 v[150:153], v185 offset:1024
	ds_read_b128 v[154:157], v185 offset:2048
	ds_read_b128 v[158:161], v185 offset:3072
	ds_read_b128 v[170:173], v183 offset:32768
	ds_read_b128 v[188:191], v183 offset:33792
	ds_read_b128 v[192:195], v183 offset:34816
	ds_read_b128 v[196:199], v183 offset:35840
	ds_read_b128 v[200:203], v183 offset:36864
	ds_read_b128 v[204:207], v183 offset:37888
	ds_read_b128 v[208:211], v183 offset:38912
	ds_read_b128 v[212:215], v183 offset:39936
	s_mov_b32 s82, m0
	s_mov_b32 m0, s48
	s_nop 0
	global_load_lds_dwordx4 v1, s[40:41]
	s_mov_b32 m0, s82
	s_nop 0
	s_mov_b32 s82, m0
	s_mov_b32 m0, s59
	s_nop 0
	global_load_lds_dwordx4 v177, s[40:41]
	s_mov_b32 m0, s82
	s_add_u32 s40, s40, 0x80000
	s_addc_u32 s41, s41, 0
	s_mov_b32 s82, m0
	s_mov_b32 m0, s62
	s_nop 0
	global_load_lds_dwordx4 v1, s[40:41]
	s_mov_b32 m0, s82
	s_nop 0
	s_mov_b32 s82, m0
	s_mov_b32 m0, s63
	s_nop 0
	global_load_lds_dwordx4 v177, s[40:41]
	s_mov_b32 m0, s82
	s_waitcnt vmcnt(8)
	s_waitcnt lgkmcnt(0)
	s_barrier
	s_setprio 1
	s_waitcnt lgkmcnt(7)
	v_mfma_f32_16x16x32_bf16 v[142:145], v[58:61], v[170:173], v[142:145]
	v_mfma_f32_16x16x32_bf16 v[142:145], v[62:65], v[188:191], v[142:145]
	s_waitcnt lgkmcnt(5)
	v_mfma_f32_16x16x32_bf16 v[138:141], v[66:69], v[170:173], v[138:141]
	v_mfma_f32_16x16x32_bf16 v[138:141], v[70:73], v[188:191], v[138:141]
	s_waitcnt lgkmcnt(3)
	v_mfma_f32_16x16x32_bf16 v[126:129], v[58:61], v[192:195], v[126:129]
	v_mfma_f32_16x16x32_bf16 v[126:129], v[62:65], v[196:199], v[126:129]
	s_waitcnt lgkmcnt(1)
	v_mfma_f32_16x16x32_bf16 v[122:125], v[66:69], v[192:195], v[122:125]
	v_mfma_f32_16x16x32_bf16 v[122:125], v[70:73], v[196:199], v[122:125]
	v_mfma_f32_16x16x32_bf16 v[110:113], v[58:61], v[200:203], v[110:113]
	v_mfma_f32_16x16x32_bf16 v[110:113], v[62:65], v[204:207], v[110:113]
	v_mfma_f32_16x16x32_bf16 v[106:109], v[66:69], v[200:203], v[106:109]
	v_mfma_f32_16x16x32_bf16 v[106:109], v[70:73], v[204:207], v[106:109]
	v_mfma_f32_16x16x32_bf16 v[94:97], v[58:61], v[208:211], v[94:97]
	v_mfma_f32_16x16x32_bf16 v[94:97], v[62:65], v[212:215], v[94:97]
	s_waitcnt lgkmcnt(0)
	v_mfma_f32_16x16x32_bf16 v[90:93], v[66:69], v[208:211], v[90:93]
	v_mfma_f32_16x16x32_bf16 v[90:93], v[70:73], v[212:215], v[90:93]
	v_mfma_f32_16x16x32_bf16 v[134:137], v[146:149], v[170:173], v[134:137]
	v_mfma_f32_16x16x32_bf16 v[134:137], v[150:153], v[188:191], v[134:137]
	v_mfma_f32_16x16x32_bf16 v[130:133], v[154:157], v[170:173], v[130:133]
	v_mfma_f32_16x16x32_bf16 v[130:133], v[158:161], v[188:191], v[130:133]
	v_mfma_f32_16x16x32_bf16 v[118:121], v[146:149], v[192:195], v[118:121]
	v_mfma_f32_16x16x32_bf16 v[118:121], v[150:153], v[196:199], v[118:121]
	v_mfma_f32_16x16x32_bf16 v[114:117], v[154:157], v[192:195], v[114:117]
	v_mfma_f32_16x16x32_bf16 v[114:117], v[158:161], v[196:199], v[114:117]
	v_mfma_f32_16x16x32_bf16 v[102:105], v[146:149], v[200:203], v[102:105]
	v_mfma_f32_16x16x32_bf16 v[102:105], v[150:153], v[204:207], v[102:105]
	v_mfma_f32_16x16x32_bf16 v[98:101], v[154:157], v[200:203], v[98:101]
	v_mfma_f32_16x16x32_bf16 v[98:101], v[158:161], v[204:207], v[98:101]
	v_mfma_f32_16x16x32_bf16 v[86:89], v[146:149], v[208:211], v[86:89]
	v_mfma_f32_16x16x32_bf16 v[86:89], v[150:153], v[212:215], v[86:89]
	s_setprio 2
	s_barrier
	v_mfma_f32_16x16x32_bf16 v[82:85], v[154:157], v[208:211], v[82:85]
	v_mfma_f32_16x16x32_bf16 v[82:85], v[158:161], v[212:215], v[82:85]
	s_setprio 0
	ds_read_b128 v[170:173], v183 offset:49152
	ds_read_b128 v[188:191], v183 offset:50176
	ds_read_b128 v[192:195], v183 offset:51200
	ds_read_b128 v[196:199], v183 offset:52224
	ds_read_b128 v[200:203], v183 offset:53248
	ds_read_b128 v[204:207], v183 offset:54272
	ds_read_b128 v[208:211], v183 offset:55296
	ds_read_b128 v[212:215], v183 offset:56320
	s_add_u32 s40, s36, 0x80
	s_addc_u32 s41, s37, 0
	s_mov_b32 s82, m0
	s_mov_b32 m0, s64
	s_nop 0
	global_load_lds_dwordx4 v176, s[40:41]
	s_mov_b32 m0, s82
	s_add_u32 s36, s36, 0x80080
	s_mov_b32 s82, m0
	s_mov_b32 m0, s65
	s_nop 0
	global_load_lds_dwordx4 v178, s[40:41]
	s_mov_b32 m0, s82
	s_addc_u32 s37, s37, 0
	s_mov_b32 s40, m0
	s_mov_b32 m0, s66
	s_nop 0
	global_load_lds_dwordx4 v176, s[36:37]
	s_mov_b32 m0, s40
	s_nop 0
	s_mov_b32 s40, m0
	s_mov_b32 m0, s67
	s_nop 0
	global_load_lds_dwordx4 v178, s[36:37]
	s_mov_b32 m0, s40
	s_waitcnt vmcnt(4)
	s_waitcnt lgkmcnt(0)
	s_barrier
	s_setprio 1
	s_waitcnt lgkmcnt(7)
	v_mfma_f32_16x16x32_bf16 v[78:81], v[58:61], v[170:173], v[78:81]
	v_mfma_f32_16x16x32_bf16 v[78:81], v[62:65], v[188:191], v[78:81]
	s_waitcnt lgkmcnt(5)
	v_mfma_f32_16x16x32_bf16 v[74:77], v[66:69], v[170:173], v[74:77]
	v_mfma_f32_16x16x32_bf16 v[74:77], v[70:73], v[188:191], v[74:77]
	s_waitcnt lgkmcnt(3)
	v_mfma_f32_16x16x32_bf16 v[54:57], v[58:61], v[192:195], v[54:57]
	v_mfma_f32_16x16x32_bf16 v[54:57], v[62:65], v[196:199], v[54:57]
	s_waitcnt lgkmcnt(1)
	v_mfma_f32_16x16x32_bf16 v[50:53], v[66:69], v[192:195], v[50:53]
	v_mfma_f32_16x16x32_bf16 v[50:53], v[70:73], v[196:199], v[50:53]
	v_mfma_f32_16x16x32_bf16 v[30:33], v[58:61], v[200:203], v[30:33]
	v_mfma_f32_16x16x32_bf16 v[30:33], v[62:65], v[204:207], v[30:33]
	v_mfma_f32_16x16x32_bf16 v[26:29], v[66:69], v[200:203], v[26:29]
	v_mfma_f32_16x16x32_bf16 v[26:29], v[70:73], v[204:207], v[26:29]
	v_mfma_f32_16x16x32_bf16 v[14:17], v[58:61], v[208:211], v[14:17]
	v_mfma_f32_16x16x32_bf16 v[14:17], v[62:65], v[212:215], v[14:17]
	s_waitcnt lgkmcnt(0)
	v_mfma_f32_16x16x32_bf16 v[10:13], v[66:69], v[208:211], v[10:13]
	v_mfma_f32_16x16x32_bf16 v[10:13], v[70:73], v[212:215], v[10:13]
	v_mfma_f32_16x16x32_bf16 v[42:45], v[146:149], v[170:173], v[42:45]
	v_mfma_f32_16x16x32_bf16 v[70:73], v[150:153], v[188:191], v[42:45]
	v_mfma_f32_16x16x32_bf16 v[42:45], v[154:157], v[170:173], v[46:49]
	v_mfma_f32_16x16x32_bf16 v[66:69], v[158:161], v[188:191], v[42:45]
	v_mfma_f32_16x16x32_bf16 v[38:41], v[146:149], v[192:195], v[38:41]
	v_mfma_f32_16x16x32_bf16 v[38:41], v[150:153], v[196:199], v[38:41]
	v_mfma_f32_16x16x32_bf16 v[34:37], v[154:157], v[192:195], v[34:37]
	v_mfma_f32_16x16x32_bf16 v[34:37], v[158:161], v[196:199], v[34:37]
	v_mfma_f32_16x16x32_bf16 v[22:25], v[146:149], v[200:203], v[22:25]
	v_mfma_f32_16x16x32_bf16 v[22:25], v[150:153], v[204:207], v[22:25]
	v_mfma_f32_16x16x32_bf16 v[18:21], v[154:157], v[200:203], v[18:21]
	v_mfma_f32_16x16x32_bf16 v[18:21], v[158:161], v[204:207], v[18:21]
	v_mfma_f32_16x16x32_bf16 v[6:9], v[146:149], v[208:211], v[6:9]
	v_mfma_f32_16x16x32_bf16 v[6:9], v[150:153], v[212:215], v[6:9]
	s_setprio 2
	s_barrier
	v_mfma_f32_16x16x32_bf16 v[2:5], v[154:157], v[208:211], v[2:5]
	v_mfma_f32_16x16x32_bf16 v[2:5], v[158:161], v[212:215], v[2:5]
	s_setprio 0
	s_add_i32 s81, s81, 2
	s_add_u32 s77, s77, 0x100
	s_addc_u32 s78, s78, 0
	s_add_u32 s34, s34, 0x100
	s_addc_u32 s35, s35, 0
	s_add_u32 s79, s79, 0x100
	s_addc_u32 s80, s80, 0
	s_cmp_gt_u32 s81, 29
	s_cbranch_scc0 .LBB0_2146
	s_and_b64 vcc, exec, s[14:15]
	s_cbranch_vccz .LBB0_2149
	s_barrier

.LBB0_2409:
	s_ashr_i32 s17, s16, 31
	s_lshl_b64 s[18:19], s[16:17], 20
	s_add_u32 s18, s33, s18
	s_addc_u32 s19, s34, s19
	s_and_b64 s[20:21], s[2:3], exec
	s_cselect_b32 s17, s19, s27
	s_cselect_b32 s71, s18, s26
	s_ashr_i32 s15, s14, 31
	s_lshl_b64 s[20:21], s[14:15], 20
	s_add_u32 s20, s35, s20
	s_addc_u32 s21, s36, s21
	s_and_b64 s[28:29], s[2:3], exec
	s_cselect_b32 s15, s21, s25
	s_cselect_b32 s73, s20, s24
	s_add_u32 s74, s24, 0x100
	s_addc_u32 s75, s25, 0
	s_add_u32 s24, s26, 0x80080
	s_addc_u32 s25, s27, 0
	s_add_u32 s76, s26, 0x100
	s_addc_u32 s77, s27, 0
	s_mov_b32 s78, -2
	s_waitcnt vmcnt(25)
	s_waitcnt vmcnt(24)
	s_waitcnt vmcnt(4)
	s_waitcnt vmcnt(2)
	s_waitcnt vmcnt(1)
	s_waitcnt vmcnt(0)
	ds_read_b128 v[130:133], v181
	ds_read_b128 v[134:137], v181 offset:1024
	ds_read_b128 v[138:141], v181 offset:2048
	ds_read_b128 v[142:145], v181 offset:3072
	ds_read_b128 v[146:149], v182
	ds_read_b128 v[150:153], v182 offset:1024
	ds_read_b128 v[154:157], v182 offset:2048
	ds_read_b128 v[158:161], v182 offset:3072
	s_cmp_eq_u32 s78, 28
	s_cselect_b32 s27, s15, s75
	s_cselect_b32 s26, s73, s74
	s_cselect_b32 s29, s17, s77
	s_cselect_b32 s28, s71, s76
	ds_read_b128 v[166:169], v183
	ds_read_b128 v[170:173], v183 offset:1024
	ds_read_b128 v[186:189], v183 offset:2048
	ds_read_b128 v[190:193], v183 offset:3072
	ds_read_b128 v[194:197], v183 offset:4096
	ds_read_b128 v[198:201], v183 offset:5120
	ds_read_b128 v[202:205], v183 offset:6144
	ds_read_b128 v[206:209], v183 offset:7168
	s_add_u32 s80, s24, 0xfff80000
	s_addc_u32 s81, s25, -1
	s_mov_b32 s79, m0
	s_mov_b32 m0, s64
	s_nop 0
	global_load_lds_dwordx4 v1, s[80:81]
	s_mov_b32 m0, s79
	s_nop 0
	s_mov_b32 s79, m0
	s_mov_b32 m0, s66
	s_nop 0
	global_load_lds_dwordx4 v177, s[80:81]
	s_mov_b32 m0, s79
	s_nop 0
	s_mov_b32 s79, m0
	s_mov_b32 m0, s65
	s_nop 0
	global_load_lds_dwordx4 v1, s[24:25]
	s_mov_b32 m0, s79
	s_nop 0
	s_mov_b32 s79, m0
	s_mov_b32 m0, s67
	s_nop 0
	global_load_lds_dwordx4 v177, s[24:25]
	s_mov_b32 m0, s79
	s_waitcnt vmcnt(8)
	s_waitcnt lgkmcnt(0)
	s_barrier
	s_setprio 1
	s_waitcnt lgkmcnt(7)
	v_mfma_f32_16x16x32_bf16 v[126:129], v[130:133], v[166:169], 0
	v_mfma_f32_16x16x32_bf16 v[126:129], v[134:137], v[170:173], v[126:129]
	s_waitcnt lgkmcnt(5)
	v_mfma_f32_16x16x32_bf16 v[122:125], v[138:141], v[166:169], 0
	v_mfma_f32_16x16x32_bf16 v[122:125], v[142:145], v[170:173], v[122:125]
	s_waitcnt lgkmcnt(3)
	v_mfma_f32_16x16x32_bf16 v[114:117], v[138:141], v[186:189], 0
	v_mfma_f32_16x16x32_bf16 v[114:117], v[142:145], v[190:193], v[114:117]
	s_waitcnt lgkmcnt(1)
	v_mfma_f32_16x16x32_bf16 v[118:121], v[130:133], v[186:189], 0
	v_mfma_f32_16x16x32_bf16 v[118:121], v[134:137], v[190:193], v[118:121]
	v_mfma_f32_16x16x32_bf16 v[94:97], v[130:133], v[194:197], 0
	v_mfma_f32_16x16x32_bf16 v[94:97], v[134:137], v[198:201], v[94:97]
	v_mfma_f32_16x16x32_bf16 v[90:93], v[138:141], v[194:197], 0
	v_mfma_f32_16x16x32_bf16 v[90:93], v[142:145], v[198:201], v[90:93]
	v_mfma_f32_16x16x32_bf16 v[78:81], v[138:141], v[202:205], 0
	v_mfma_f32_16x16x32_bf16 v[78:81], v[142:145], v[206:209], v[78:81]
	s_waitcnt lgkmcnt(0)
	v_mfma_f32_16x16x32_bf16 v[86:89], v[130:133], v[202:205], 0
	v_mfma_f32_16x16x32_bf16 v[86:89], v[134:137], v[206:209], v[86:89]
	v_mfma_f32_16x16x32_bf16 v[110:113], v[146:149], v[166:169], 0
	v_mfma_f32_16x16x32_bf16 v[110:113], v[150:153], v[170:173], v[110:113]
	v_mfma_f32_16x16x32_bf16 v[106:109], v[154:157], v[166:169], 0
	v_mfma_f32_16x16x32_bf16 v[106:109], v[158:161], v[170:173], v[106:109]
	v_mfma_f32_16x16x32_bf16 v[98:101], v[154:157], v[186:189], 0
	v_mfma_f32_16x16x32_bf16 v[98:101], v[158:161], v[190:193], v[98:101]
	v_mfma_f32_16x16x32_bf16 v[102:105], v[146:149], v[186:189], 0
	v_mfma_f32_16x16x32_bf16 v[102:105], v[150:153], v[190:193], v[102:105]
	v_mfma_f32_16x16x32_bf16 v[82:85], v[146:149], v[194:197], 0
	v_mfma_f32_16x16x32_bf16 v[82:85], v[150:153], v[198:201], v[82:85]
	v_mfma_f32_16x16x32_bf16 v[74:77], v[154:157], v[194:197], 0
	v_mfma_f32_16x16x32_bf16 v[74:77], v[158:161], v[198:201], v[74:77]
	v_mfma_f32_16x16x32_bf16 v[66:69], v[154:157], v[202:205], 0
	v_mfma_f32_16x16x32_bf16 v[66:69], v[158:161], v[206:209], v[66:69]
	s_setprio 2
	s_barrier
	v_mfma_f32_16x16x32_bf16 v[70:73], v[146:149], v[202:205], 0
	v_mfma_f32_16x16x32_bf16 v[70:73], v[150:153], v[206:209], v[70:73]
	s_setprio 0
	ds_read_b128 v[166:169], v183 offset:16384
	ds_read_b128 v[170:173], v183 offset:17408
	ds_read_b128 v[186:189], v183 offset:18432
	ds_read_b128 v[190:193], v183 offset:19456
	ds_read_b128 v[194:197], v183 offset:20480
	ds_read_b128 v[198:201], v183 offset:21504
	ds_read_b128 v[202:205], v183 offset:22528
	ds_read_b128 v[206:209], v183 offset:23552
	s_mov_b32 s79, m0
	s_mov_b32 m0, s41
	s_nop 0
	global_load_lds_dwordx4 v176, s[26:27]
	s_mov_b32 m0, s79
	s_add_u32 s80, s26, 0x80000
	s_mov_b32 s79, m0
	s_mov_b32 m0, s42
	s_nop 0
	global_load_lds_dwordx4 v178, s[26:27]
	s_mov_b32 m0, s79
	s_addc_u32 s81, s27, 0
	s_mov_b32 s79, m0
	s_mov_b32 m0, s43
	s_nop 0
	global_load_lds_dwordx4 v176, s[80:81]
	s_mov_b32 m0, s79
	s_nop 0
	s_mov_b32 s79, m0
	s_mov_b32 m0, s46
	s_nop 0
	global_load_lds_dwordx4 v178, s[80:81]
	s_mov_b32 m0, s79
	s_waitcnt vmcnt(4)
	s_waitcnt lgkmcnt(0)
	s_barrier
	s_setprio 1
	s_waitcnt lgkmcnt(7)
	v_mfma_f32_16x16x32_bf16 v[62:65], v[130:133], v[166:169], 0
	v_mfma_f32_16x16x32_bf16 v[62:65], v[134:137], v[170:173], v[62:65]
	s_waitcnt lgkmcnt(5)
	v_mfma_f32_16x16x32_bf16 v[58:61], v[138:141], v[166:169], 0
	v_mfma_f32_16x16x32_bf16 v[58:61], v[142:145], v[170:173], v[58:61]
	s_waitcnt lgkmcnt(3)
	v_mfma_f32_16x16x32_bf16 v[42:45], v[138:141], v[186:189], 0
	v_mfma_f32_16x16x32_bf16 v[42:45], v[142:145], v[190:193], v[42:45]
	s_waitcnt lgkmcnt(1)
	v_mfma_f32_16x16x32_bf16 v[46:49], v[130:133], v[186:189], 0
	v_mfma_f32_16x16x32_bf16 v[46:49], v[134:137], v[190:193], v[46:49]
	v_mfma_f32_16x16x32_bf16 v[30:33], v[130:133], v[194:197], 0
	v_mfma_f32_16x16x32_bf16 v[30:33], v[134:137], v[198:201], v[30:33]
	v_mfma_f32_16x16x32_bf16 v[26:29], v[138:141], v[194:197], 0
	v_mfma_f32_16x16x32_bf16 v[26:29], v[142:145], v[198:201], v[26:29]
	v_mfma_f32_16x16x32_bf16 v[10:13], v[138:141], v[202:205], 0
	v_mfma_f32_16x16x32_bf16 v[10:13], v[142:145], v[206:209], v[10:13]
	s_waitcnt lgkmcnt(0)
	v_mfma_f32_16x16x32_bf16 v[14:17], v[130:133], v[202:205], 0
	v_mfma_f32_16x16x32_bf16 v[14:17], v[134:137], v[206:209], v[14:17]
	v_mfma_f32_16x16x32_bf16 v[54:57], v[146:149], v[166:169], 0
	v_mfma_f32_16x16x32_bf16 v[54:57], v[150:153], v[170:173], v[54:57]
	v_mfma_f32_16x16x32_bf16 v[50:53], v[154:157], v[166:169], 0
	v_mfma_f32_16x16x32_bf16 v[50:53], v[158:161], v[170:173], v[50:53]
	v_mfma_f32_16x16x32_bf16 v[34:37], v[154:157], v[186:189], 0
	v_mfma_f32_16x16x32_bf16 v[34:37], v[158:161], v[190:193], v[34:37]
	v_mfma_f32_16x16x32_bf16 v[38:41], v[146:149], v[186:189], 0
	v_mfma_f32_16x16x32_bf16 v[38:41], v[150:153], v[190:193], v[38:41]
	v_mfma_f32_16x16x32_bf16 v[22:25], v[146:149], v[194:197], 0
	v_mfma_f32_16x16x32_bf16 v[22:25], v[150:153], v[198:201], v[22:25]
	v_mfma_f32_16x16x32_bf16 v[18:21], v[154:157], v[194:197], 0
	v_mfma_f32_16x16x32_bf16 v[18:21], v[158:161], v[198:201], v[18:21]
	v_mfma_f32_16x16x32_bf16 v[2:5], v[154:157], v[202:205], 0
	v_mfma_f32_16x16x32_bf16 v[2:5], v[158:161], v[206:209], v[2:5]
	s_setprio 2
	s_barrier
	v_mfma_f32_16x16x32_bf16 v[6:9], v[146:149], v[202:205], 0
	v_mfma_f32_16x16x32_bf16 v[6:9], v[150:153], v[206:209], v[6:9]
	s_setprio 0
	ds_read_b128 v[130:133], v184
	ds_read_b128 v[134:137], v184 offset:1024
	ds_read_b128 v[138:141], v184 offset:2048
	ds_read_b128 v[142:145], v184 offset:3072
	ds_read_b128 v[146:149], v185
	ds_read_b128 v[150:153], v185 offset:1024
	ds_read_b128 v[154:157], v185 offset:2048
	ds_read_b128 v[158:161], v185 offset:3072
	ds_read_b128 v[166:169], v183 offset:32768
	ds_read_b128 v[170:173], v183 offset:33792
	ds_read_b128 v[186:189], v183 offset:34816
	ds_read_b128 v[190:193], v183 offset:35840
	ds_read_b128 v[194:197], v183 offset:36864
	ds_read_b128 v[198:201], v183 offset:37888
	ds_read_b128 v[202:205], v183 offset:38912
	ds_read_b128 v[206:209], v183 offset:39936
	s_mov_b32 s79, m0
	s_mov_b32 m0, s40
	s_nop 0
	global_load_lds_dwordx4 v1, s[28:29]
	s_mov_b32 m0, s79
	s_nop 0
	s_mov_b32 s79, m0
	s_mov_b32 m0, s47
	s_nop 0
	global_load_lds_dwordx4 v177, s[28:29]
	s_mov_b32 m0, s79
	s_add_u32 s28, s28, 0x80000
	s_addc_u32 s29, s29, 0
	s_mov_b32 s79, m0
	s_mov_b32 m0, s48
	s_nop 0
	global_load_lds_dwordx4 v1, s[28:29]
	s_mov_b32 m0, s79
	s_nop 0
	s_mov_b32 s79, m0
	s_mov_b32 m0, s49
	s_nop 0
	global_load_lds_dwordx4 v177, s[28:29]
	s_mov_b32 m0, s79
	s_waitcnt vmcnt(8)
	s_waitcnt lgkmcnt(0)
	s_barrier
	s_setprio 1
	s_waitcnt lgkmcnt(7)
	v_mfma_f32_16x16x32_bf16 v[126:129], v[130:133], v[166:169], v[126:129]
	v_mfma_f32_16x16x32_bf16 v[126:129], v[134:137], v[170:173], v[126:129]
	s_waitcnt lgkmcnt(5)
	v_mfma_f32_16x16x32_bf16 v[122:125], v[138:141], v[166:169], v[122:125]
	v_mfma_f32_16x16x32_bf16 v[122:125], v[142:145], v[170:173], v[122:125]
	s_waitcnt lgkmcnt(3)
	v_mfma_f32_16x16x32_bf16 v[114:117], v[138:141], v[186:189], v[114:117]
	v_mfma_f32_16x16x32_bf16 v[114:117], v[142:145], v[190:193], v[114:117]
	s_waitcnt lgkmcnt(1)
	v_mfma_f32_16x16x32_bf16 v[118:121], v[130:133], v[186:189], v[118:121]
	v_mfma_f32_16x16x32_bf16 v[118:121], v[134:137], v[190:193], v[118:121]
	v_mfma_f32_16x16x32_bf16 v[94:97], v[130:133], v[194:197], v[94:97]
	v_mfma_f32_16x16x32_bf16 v[94:97], v[134:137], v[198:201], v[94:97]
	v_mfma_f32_16x16x32_bf16 v[90:93], v[138:141], v[194:197], v[90:93]
	v_mfma_f32_16x16x32_bf16 v[90:93], v[142:145], v[198:201], v[90:93]
	v_mfma_f32_16x16x32_bf16 v[78:81], v[138:141], v[202:205], v[78:81]
	v_mfma_f32_16x16x32_bf16 v[78:81], v[142:145], v[206:209], v[78:81]
	s_waitcnt lgkmcnt(0)
	v_mfma_f32_16x16x32_bf16 v[86:89], v[130:133], v[202:205], v[86:89]
	v_mfma_f32_16x16x32_bf16 v[86:89], v[134:137], v[206:209], v[86:89]
	v_mfma_f32_16x16x32_bf16 v[110:113], v[146:149], v[166:169], v[110:113]
	v_mfma_f32_16x16x32_bf16 v[110:113], v[150:153], v[170:173], v[110:113]
	v_mfma_f32_16x16x32_bf16 v[106:109], v[154:157], v[166:169], v[106:109]
	v_mfma_f32_16x16x32_bf16 v[106:109], v[158:161], v[170:173], v[106:109]
	v_mfma_f32_16x16x32_bf16 v[98:101], v[154:157], v[186:189], v[98:101]
	v_mfma_f32_16x16x32_bf16 v[98:101], v[158:161], v[190:193], v[98:101]
	v_mfma_f32_16x16x32_bf16 v[102:105], v[146:149], v[186:189], v[102:105]
	v_mfma_f32_16x16x32_bf16 v[102:105], v[150:153], v[190:193], v[102:105]
	v_mfma_f32_16x16x32_bf16 v[82:85], v[146:149], v[194:197], v[82:85]
	v_mfma_f32_16x16x32_bf16 v[82:85], v[150:153], v[198:201], v[82:85]
	v_mfma_f32_16x16x32_bf16 v[74:77], v[154:157], v[194:197], v[74:77]
	v_mfma_f32_16x16x32_bf16 v[74:77], v[158:161], v[198:201], v[74:77]
	v_mfma_f32_16x16x32_bf16 v[66:69], v[154:157], v[202:205], v[66:69]
	v_mfma_f32_16x16x32_bf16 v[66:69], v[158:161], v[206:209], v[66:69]
	s_setprio 2
	s_barrier
	v_mfma_f32_16x16x32_bf16 v[70:73], v[146:149], v[202:205], v[70:73]
	v_mfma_f32_16x16x32_bf16 v[70:73], v[150:153], v[206:209], v[70:73]
	s_setprio 0
	ds_read_b128 v[166:169], v183 offset:49152
	ds_read_b128 v[170:173], v183 offset:50176
	ds_read_b128 v[186:189], v183 offset:51200
	ds_read_b128 v[190:193], v183 offset:52224
	ds_read_b128 v[194:197], v183 offset:53248
	ds_read_b128 v[198:201], v183 offset:54272
	ds_read_b128 v[202:205], v183 offset:55296
	ds_read_b128 v[206:209], v183 offset:56320
	s_add_u32 s28, s26, 0x80
	s_addc_u32 s29, s27, 0
	s_mov_b32 s79, m0
	s_mov_b32 m0, s56
	s_nop 0
	global_load_lds_dwordx4 v176, s[28:29]
	s_mov_b32 m0, s79
	s_add_u32 s26, s26, 0x80080
	s_mov_b32 s79, m0
	s_mov_b32 m0, s57
	s_nop 0
	global_load_lds_dwordx4 v178, s[28:29]
	s_mov_b32 m0, s79
	s_addc_u32 s27, s27, 0
	s_mov_b32 s28, m0
	s_mov_b32 m0, s58
	s_nop 0
	global_load_lds_dwordx4 v176, s[26:27]
	s_mov_b32 m0, s28
	s_nop 0
	s_mov_b32 s28, m0
	s_mov_b32 m0, s59
	s_nop 0
	global_load_lds_dwordx4 v178, s[26:27]
	s_mov_b32 m0, s28
	s_waitcnt vmcnt(4)
	s_waitcnt lgkmcnt(0)
	s_barrier
	s_setprio 1
	s_waitcnt lgkmcnt(7)
	v_mfma_f32_16x16x32_bf16 v[62:65], v[130:133], v[166:169], v[62:65]
	v_mfma_f32_16x16x32_bf16 v[62:65], v[134:137], v[170:173], v[62:65]
	s_waitcnt lgkmcnt(5)
	v_mfma_f32_16x16x32_bf16 v[58:61], v[138:141], v[166:169], v[58:61]
	v_mfma_f32_16x16x32_bf16 v[58:61], v[142:145], v[170:173], v[58:61]
	s_waitcnt lgkmcnt(3)
	v_mfma_f32_16x16x32_bf16 v[42:45], v[138:141], v[186:189], v[42:45]
	v_mfma_f32_16x16x32_bf16 v[42:45], v[142:145], v[190:193], v[42:45]
	s_waitcnt lgkmcnt(1)
	v_mfma_f32_16x16x32_bf16 v[46:49], v[130:133], v[186:189], v[46:49]
	v_mfma_f32_16x16x32_bf16 v[46:49], v[134:137], v[190:193], v[46:49]
	v_mfma_f32_16x16x32_bf16 v[30:33], v[130:133], v[194:197], v[30:33]
	v_mfma_f32_16x16x32_bf16 v[30:33], v[134:137], v[198:201], v[30:33]
	v_mfma_f32_16x16x32_bf16 v[26:29], v[138:141], v[194:197], v[26:29]
	v_mfma_f32_16x16x32_bf16 v[26:29], v[142:145], v[198:201], v[26:29]
	v_mfma_f32_16x16x32_bf16 v[10:13], v[138:141], v[202:205], v[10:13]
	v_mfma_f32_16x16x32_bf16 v[10:13], v[142:145], v[206:209], v[10:13]
	s_waitcnt lgkmcnt(0)
	v_mfma_f32_16x16x32_bf16 v[14:17], v[130:133], v[202:205], v[14:17]
	v_mfma_f32_16x16x32_bf16 v[14:17], v[134:137], v[206:209], v[14:17]
	v_mfma_f32_16x16x32_bf16 v[54:57], v[146:149], v[166:169], v[54:57]
	v_mfma_f32_16x16x32_bf16 v[54:57], v[150:153], v[170:173], v[54:57]
	v_mfma_f32_16x16x32_bf16 v[50:53], v[154:157], v[166:169], v[50:53]
	v_mfma_f32_16x16x32_bf16 v[50:53], v[158:161], v[170:173], v[50:53]
	v_mfma_f32_16x16x32_bf16 v[34:37], v[154:157], v[186:189], v[34:37]
	v_mfma_f32_16x16x32_bf16 v[34:37], v[158:161], v[190:193], v[34:37]
	v_mfma_f32_16x16x32_bf16 v[38:41], v[146:149], v[186:189], v[38:41]
	v_mfma_f32_16x16x32_bf16 v[38:41], v[150:153], v[190:193], v[38:41]
	v_mfma_f32_16x16x32_bf16 v[22:25], v[146:149], v[194:197], v[22:25]
	v_mfma_f32_16x16x32_bf16 v[22:25], v[150:153], v[198:201], v[22:25]
	v_mfma_f32_16x16x32_bf16 v[18:21], v[154:157], v[194:197], v[18:21]
	v_mfma_f32_16x16x32_bf16 v[18:21], v[158:161], v[198:201], v[18:21]
	v_mfma_f32_16x16x32_bf16 v[2:5], v[154:157], v[202:205], v[2:5]
	v_mfma_f32_16x16x32_bf16 v[2:5], v[158:161], v[206:209], v[2:5]
	s_setprio 2
	s_barrier
	v_mfma_f32_16x16x32_bf16 v[6:9], v[146:149], v[202:205], v[6:9]
	v_mfma_f32_16x16x32_bf16 v[6:9], v[150:153], v[206:209], v[6:9]
	s_setprio 0
	s_add_i32 s78, s78, 2
	s_add_u32 s74, s74, 0x100
	s_addc_u32 s75, s75, 0
	s_add_u32 s24, s24, 0x100
	s_addc_u32 s25, s25, 0
	s_add_u32 s76, s76, 0x100
	s_addc_u32 s77, s77, 0
	s_cmp_gt_u32 s78, 29
	.p2align 6
.LBB0_2410:
	ds_read_b128 v[130:133], v181
	ds_read_b128 v[134:137], v181 offset:1024
	ds_read_b128 v[138:141], v181 offset:2048
	ds_read_b128 v[142:145], v181 offset:3072
	ds_read_b128 v[146:149], v182
	ds_read_b128 v[150:153], v182 offset:1024
	ds_read_b128 v[154:157], v182 offset:2048
	ds_read_b128 v[158:161], v182 offset:3072
	s_cmp_eq_u32 s78, 28
	s_cselect_b32 s27, s15, s75
	s_cselect_b32 s26, s73, s74
	s_cselect_b32 s29, s17, s77
	s_cselect_b32 s28, s71, s76
	ds_read_b128 v[166:169], v183
	ds_read_b128 v[170:173], v183 offset:1024
	ds_read_b128 v[186:189], v183 offset:2048
	ds_read_b128 v[190:193], v183 offset:3072
	ds_read_b128 v[194:197], v183 offset:4096
	ds_read_b128 v[198:201], v183 offset:5120
	ds_read_b128 v[202:205], v183 offset:6144
	ds_read_b128 v[206:209], v183 offset:7168
	s_add_u32 s80, s24, 0xfff80000
	s_addc_u32 s81, s25, -1
	s_mov_b32 s79, m0
	s_mov_b32 m0, s64
	s_nop 0
	global_load_lds_dwordx4 v1, s[80:81]
	s_mov_b32 m0, s79
	s_nop 0
	s_mov_b32 s79, m0
	s_mov_b32 m0, s66
	s_nop 0
	global_load_lds_dwordx4 v177, s[80:81]
	s_mov_b32 m0, s79
	s_nop 0
	s_mov_b32 s79, m0
	s_mov_b32 m0, s65
	s_nop 0
	global_load_lds_dwordx4 v1, s[24:25]
	s_mov_b32 m0, s79
	s_nop 0
	s_mov_b32 s79, m0
	s_mov_b32 m0, s67
	s_nop 0
	global_load_lds_dwordx4 v177, s[24:25]
	s_mov_b32 m0, s79
	s_waitcnt vmcnt(8)
	s_waitcnt lgkmcnt(0)
	s_barrier
	s_setprio 1
	s_waitcnt lgkmcnt(7)
	v_mfma_f32_16x16x32_bf16 v[126:129], v[130:133], v[166:169], v[126:129]
	v_mfma_f32_16x16x32_bf16 v[126:129], v[134:137], v[170:173], v[126:129]
	s_waitcnt lgkmcnt(5)
	v_mfma_f32_16x16x32_bf16 v[122:125], v[138:141], v[166:169], v[122:125]
	v_mfma_f32_16x16x32_bf16 v[122:125], v[142:145], v[170:173], v[122:125]
	s_waitcnt lgkmcnt(3)
	v_mfma_f32_16x16x32_bf16 v[114:117], v[138:141], v[186:189], v[114:117]
	v_mfma_f32_16x16x32_bf16 v[114:117], v[142:145], v[190:193], v[114:117]
	s_waitcnt lgkmcnt(1)
	v_mfma_f32_16x16x32_bf16 v[118:121], v[130:133], v[186:189], v[118:121]
	v_mfma_f32_16x16x32_bf16 v[118:121], v[134:137], v[190:193], v[118:121]
	v_mfma_f32_16x16x32_bf16 v[94:97], v[130:133], v[194:197], v[94:97]
	v_mfma_f32_16x16x32_bf16 v[94:97], v[134:137], v[198:201], v[94:97]
	v_mfma_f32_16x16x32_bf16 v[90:93], v[138:141], v[194:197], v[90:93]
	v_mfma_f32_16x16x32_bf16 v[90:93], v[142:145], v[198:201], v[90:93]
	v_mfma_f32_16x16x32_bf16 v[78:81], v[138:141], v[202:205], v[78:81]
	v_mfma_f32_16x16x32_bf16 v[78:81], v[142:145], v[206:209], v[78:81]
	s_waitcnt lgkmcnt(0)
	v_mfma_f32_16x16x32_bf16 v[86:89], v[130:133], v[202:205], v[86:89]
	v_mfma_f32_16x16x32_bf16 v[86:89], v[134:137], v[206:209], v[86:89]
	v_mfma_f32_16x16x32_bf16 v[110:113], v[146:149], v[166:169], v[110:113]
	v_mfma_f32_16x16x32_bf16 v[110:113], v[150:153], v[170:173], v[110:113]
	v_mfma_f32_16x16x32_bf16 v[106:109], v[154:157], v[166:169], v[106:109]
	v_mfma_f32_16x16x32_bf16 v[106:109], v[158:161], v[170:173], v[106:109]
	v_mfma_f32_16x16x32_bf16 v[98:101], v[154:157], v[186:189], v[98:101]
	v_mfma_f32_16x16x32_bf16 v[98:101], v[158:161], v[190:193], v[98:101]
	v_mfma_f32_16x16x32_bf16 v[102:105], v[146:149], v[186:189], v[102:105]
	v_mfma_f32_16x16x32_bf16 v[102:105], v[150:153], v[190:193], v[102:105]
	v_mfma_f32_16x16x32_bf16 v[82:85], v[146:149], v[194:197], v[82:85]
	v_mfma_f32_16x16x32_bf16 v[82:85], v[150:153], v[198:201], v[82:85]
	v_mfma_f32_16x16x32_bf16 v[74:77], v[154:157], v[194:197], v[74:77]
	v_mfma_f32_16x16x32_bf16 v[74:77], v[158:161], v[198:201], v[74:77]
	v_mfma_f32_16x16x32_bf16 v[66:69], v[154:157], v[202:205], v[66:69]
	v_mfma_f32_16x16x32_bf16 v[66:69], v[158:161], v[206:209], v[66:69]
	s_setprio 2
	s_barrier
	v_mfma_f32_16x16x32_bf16 v[70:73], v[146:149], v[202:205], v[70:73]
	v_mfma_f32_16x16x32_bf16 v[70:73], v[150:153], v[206:209], v[70:73]
	s_setprio 0
	ds_read_b128 v[166:169], v183 offset:16384
	ds_read_b128 v[170:173], v183 offset:17408
	ds_read_b128 v[186:189], v183 offset:18432
	ds_read_b128 v[190:193], v183 offset:19456
	ds_read_b128 v[194:197], v183 offset:20480
	ds_read_b128 v[198:201], v183 offset:21504
	ds_read_b128 v[202:205], v183 offset:22528
	ds_read_b128 v[206:209], v183 offset:23552
	s_mov_b32 s79, m0
	s_mov_b32 m0, s41
	s_nop 0
	global_load_lds_dwordx4 v176, s[26:27]
	s_mov_b32 m0, s79
	s_add_u32 s80, s26, 0x80000
	s_mov_b32 s79, m0
	s_mov_b32 m0, s42
	s_nop 0
	global_load_lds_dwordx4 v178, s[26:27]
	s_mov_b32 m0, s79
	s_addc_u32 s81, s27, 0
	s_mov_b32 s79, m0
	s_mov_b32 m0, s43
	s_nop 0
	global_load_lds_dwordx4 v176, s[80:81]
	s_mov_b32 m0, s79
	s_nop 0
	s_mov_b32 s79, m0
	s_mov_b32 m0, s46
	s_nop 0
	global_load_lds_dwordx4 v178, s[80:81]
	s_mov_b32 m0, s79
	s_waitcnt vmcnt(4)
	s_waitcnt lgkmcnt(0)
	s_barrier
	s_setprio 1
	s_waitcnt lgkmcnt(7)
	v_mfma_f32_16x16x32_bf16 v[62:65], v[130:133], v[166:169], v[62:65]
	v_mfma_f32_16x16x32_bf16 v[62:65], v[134:137], v[170:173], v[62:65]
	s_waitcnt lgkmcnt(5)
	v_mfma_f32_16x16x32_bf16 v[58:61], v[138:141], v[166:169], v[58:61]
	v_mfma_f32_16x16x32_bf16 v[58:61], v[142:145], v[170:173], v[58:61]
	s_waitcnt lgkmcnt(3)
	v_mfma_f32_16x16x32_bf16 v[42:45], v[138:141], v[186:189], v[42:45]
	v_mfma_f32_16x16x32_bf16 v[42:45], v[142:145], v[190:193], v[42:45]
	s_waitcnt lgkmcnt(1)
	v_mfma_f32_16x16x32_bf16 v[46:49], v[130:133], v[186:189], v[46:49]
	v_mfma_f32_16x16x32_bf16 v[46:49], v[134:137], v[190:193], v[46:49]
	v_mfma_f32_16x16x32_bf16 v[30:33], v[130:133], v[194:197], v[30:33]
	v_mfma_f32_16x16x32_bf16 v[30:33], v[134:137], v[198:201], v[30:33]
	v_mfma_f32_16x16x32_bf16 v[26:29], v[138:141], v[194:197], v[26:29]
	v_mfma_f32_16x16x32_bf16 v[26:29], v[142:145], v[198:201], v[26:29]
	v_mfma_f32_16x16x32_bf16 v[10:13], v[138:141], v[202:205], v[10:13]
	v_mfma_f32_16x16x32_bf16 v[10:13], v[142:145], v[206:209], v[10:13]
	s_waitcnt lgkmcnt(0)
	v_mfma_f32_16x16x32_bf16 v[14:17], v[130:133], v[202:205], v[14:17]
	v_mfma_f32_16x16x32_bf16 v[14:17], v[134:137], v[206:209], v[14:17]
	v_mfma_f32_16x16x32_bf16 v[54:57], v[146:149], v[166:169], v[54:57]
	v_mfma_f32_16x16x32_bf16 v[54:57], v[150:153], v[170:173], v[54:57]
	v_mfma_f32_16x16x32_bf16 v[50:53], v[154:157], v[166:169], v[50:53]
	v_mfma_f32_16x16x32_bf16 v[50:53], v[158:161], v[170:173], v[50:53]
	v_mfma_f32_16x16x32_bf16 v[34:37], v[154:157], v[186:189], v[34:37]
	v_mfma_f32_16x16x32_bf16 v[34:37], v[158:161], v[190:193], v[34:37]
	v_mfma_f32_16x16x32_bf16 v[38:41], v[146:149], v[186:189], v[38:41]
	v_mfma_f32_16x16x32_bf16 v[38:41], v[150:153], v[190:193], v[38:41]
	v_mfma_f32_16x16x32_bf16 v[22:25], v[146:149], v[194:197], v[22:25]
	v_mfma_f32_16x16x32_bf16 v[22:25], v[150:153], v[198:201], v[22:25]
	v_mfma_f32_16x16x32_bf16 v[18:21], v[154:157], v[194:197], v[18:21]
	v_mfma_f32_16x16x32_bf16 v[18:21], v[158:161], v[198:201], v[18:21]
	v_mfma_f32_16x16x32_bf16 v[2:5], v[154:157], v[202:205], v[2:5]
	v_mfma_f32_16x16x32_bf16 v[2:5], v[158:161], v[206:209], v[2:5]
	s_setprio 2
	s_barrier
	v_mfma_f32_16x16x32_bf16 v[6:9], v[146:149], v[202:205], v[6:9]
	v_mfma_f32_16x16x32_bf16 v[6:9], v[150:153], v[206:209], v[6:9]
	s_setprio 0
	ds_read_b128 v[130:133], v184
	ds_read_b128 v[134:137], v184 offset:1024
	ds_read_b128 v[138:141], v184 offset:2048
	ds_read_b128 v[142:145], v184 offset:3072
	ds_read_b128 v[146:149], v185
	ds_read_b128 v[150:153], v185 offset:1024
	ds_read_b128 v[154:157], v185 offset:2048
	ds_read_b128 v[158:161], v185 offset:3072
	ds_read_b128 v[166:169], v183 offset:32768
	ds_read_b128 v[170:173], v183 offset:33792
	ds_read_b128 v[186:189], v183 offset:34816
	ds_read_b128 v[190:193], v183 offset:35840
	ds_read_b128 v[194:197], v183 offset:36864
	ds_read_b128 v[198:201], v183 offset:37888
	ds_read_b128 v[202:205], v183 offset:38912
	ds_read_b128 v[206:209], v183 offset:39936
	s_mov_b32 s79, m0
	s_mov_b32 m0, s40
	s_nop 0
	global_load_lds_dwordx4 v1, s[28:29]
	s_mov_b32 m0, s79
	s_nop 0
	s_mov_b32 s79, m0
	s_mov_b32 m0, s47
	s_nop 0
	global_load_lds_dwordx4 v177, s[28:29]
	s_mov_b32 m0, s79
	s_add_u32 s28, s28, 0x80000
	s_addc_u32 s29, s29, 0
	s_mov_b32 s79, m0
	s_mov_b32 m0, s48
	s_nop 0
	global_load_lds_dwordx4 v1, s[28:29]
	s_mov_b32 m0, s79
	s_nop 0
	s_mov_b32 s79, m0
	s_mov_b32 m0, s49
	s_nop 0
	global_load_lds_dwordx4 v177, s[28:29]
	s_mov_b32 m0, s79
	s_waitcnt vmcnt(8)
	s_waitcnt lgkmcnt(0)
	s_barrier
	s_setprio 1
	s_waitcnt lgkmcnt(7)
	v_mfma_f32_16x16x32_bf16 v[126:129], v[130:133], v[166:169], v[126:129]
	v_mfma_f32_16x16x32_bf16 v[126:129], v[134:137], v[170:173], v[126:129]
	s_waitcnt lgkmcnt(5)
	v_mfma_f32_16x16x32_bf16 v[122:125], v[138:141], v[166:169], v[122:125]
	v_mfma_f32_16x16x32_bf16 v[122:125], v[142:145], v[170:173], v[122:125]
	s_waitcnt lgkmcnt(3)
	v_mfma_f32_16x16x32_bf16 v[114:117], v[138:141], v[186:189], v[114:117]
	v_mfma_f32_16x16x32_bf16 v[114:117], v[142:145], v[190:193], v[114:117]
	s_waitcnt lgkmcnt(1)
	v_mfma_f32_16x16x32_bf16 v[118:121], v[130:133], v[186:189], v[118:121]
	v_mfma_f32_16x16x32_bf16 v[118:121], v[134:137], v[190:193], v[118:121]
	v_mfma_f32_16x16x32_bf16 v[94:97], v[130:133], v[194:197], v[94:97]
	v_mfma_f32_16x16x32_bf16 v[94:97], v[134:137], v[198:201], v[94:97]
	v_mfma_f32_16x16x32_bf16 v[90:93], v[138:141], v[194:197], v[90:93]
	v_mfma_f32_16x16x32_bf16 v[90:93], v[142:145], v[198:201], v[90:93]
	v_mfma_f32_16x16x32_bf16 v[78:81], v[138:141], v[202:205], v[78:81]
	v_mfma_f32_16x16x32_bf16 v[78:81], v[142:145], v[206:209], v[78:81]
	s_waitcnt lgkmcnt(0)
	v_mfma_f32_16x16x32_bf16 v[86:89], v[130:133], v[202:205], v[86:89]
	v_mfma_f32_16x16x32_bf16 v[86:89], v[134:137], v[206:209], v[86:89]
	v_mfma_f32_16x16x32_bf16 v[110:113], v[146:149], v[166:169], v[110:113]
	v_mfma_f32_16x16x32_bf16 v[110:113], v[150:153], v[170:173], v[110:113]
	v_mfma_f32_16x16x32_bf16 v[106:109], v[154:157], v[166:169], v[106:109]
	v_mfma_f32_16x16x32_bf16 v[106:109], v[158:161], v[170:173], v[106:109]
	v_mfma_f32_16x16x32_bf16 v[98:101], v[154:157], v[186:189], v[98:101]
	v_mfma_f32_16x16x32_bf16 v[98:101], v[158:161], v[190:193], v[98:101]
	v_mfma_f32_16x16x32_bf16 v[102:105], v[146:149], v[186:189], v[102:105]
	v_mfma_f32_16x16x32_bf16 v[102:105], v[150:153], v[190:193], v[102:105]
	v_mfma_f32_16x16x32_bf16 v[82:85], v[146:149], v[194:197], v[82:85]
	v_mfma_f32_16x16x32_bf16 v[82:85], v[150:153], v[198:201], v[82:85]
	v_mfma_f32_16x16x32_bf16 v[74:77], v[154:157], v[194:197], v[74:77]
	v_mfma_f32_16x16x32_bf16 v[74:77], v[158:161], v[198:201], v[74:77]
	v_mfma_f32_16x16x32_bf16 v[66:69], v[154:157], v[202:205], v[66:69]
	v_mfma_f32_16x16x32_bf16 v[66:69], v[158:161], v[206:209], v[66:69]
	s_setprio 2
	s_barrier
	v_mfma_f32_16x16x32_bf16 v[70:73], v[146:149], v[202:205], v[70:73]
	v_mfma_f32_16x16x32_bf16 v[70:73], v[150:153], v[206:209], v[70:73]
	s_setprio 0
	ds_read_b128 v[166:169], v183 offset:49152
	ds_read_b128 v[170:173], v183 offset:50176
	ds_read_b128 v[186:189], v183 offset:51200
	ds_read_b128 v[190:193], v183 offset:52224
	ds_read_b128 v[194:197], v183 offset:53248
	ds_read_b128 v[198:201], v183 offset:54272
	ds_read_b128 v[202:205], v183 offset:55296
	ds_read_b128 v[206:209], v183 offset:56320
	s_add_u32 s28, s26, 0x80
	s_addc_u32 s29, s27, 0
	s_mov_b32 s79, m0
	s_mov_b32 m0, s56
	s_nop 0
	global_load_lds_dwordx4 v176, s[28:29]
	s_mov_b32 m0, s79
	s_add_u32 s26, s26, 0x80080
	s_mov_b32 s79, m0
	s_mov_b32 m0, s57
	s_nop 0
	global_load_lds_dwordx4 v178, s[28:29]
	s_mov_b32 m0, s79
	s_addc_u32 s27, s27, 0
	s_mov_b32 s28, m0
	s_mov_b32 m0, s58
	s_nop 0
	global_load_lds_dwordx4 v176, s[26:27]
	s_mov_b32 m0, s28
	s_nop 0
	s_mov_b32 s28, m0
	s_mov_b32 m0, s59
	s_nop 0
	global_load_lds_dwordx4 v178, s[26:27]
	s_mov_b32 m0, s28
	s_waitcnt vmcnt(4)
	s_waitcnt lgkmcnt(0)
	s_barrier
	s_setprio 1
	s_waitcnt lgkmcnt(7)
	v_mfma_f32_16x16x32_bf16 v[62:65], v[130:133], v[166:169], v[62:65]
	v_mfma_f32_16x16x32_bf16 v[62:65], v[134:137], v[170:173], v[62:65]
	s_waitcnt lgkmcnt(5)
	v_mfma_f32_16x16x32_bf16 v[58:61], v[138:141], v[166:169], v[58:61]
	v_mfma_f32_16x16x32_bf16 v[58:61], v[142:145], v[170:173], v[58:61]
	s_waitcnt lgkmcnt(3)
	v_mfma_f32_16x16x32_bf16 v[42:45], v[138:141], v[186:189], v[42:45]
	v_mfma_f32_16x16x32_bf16 v[42:45], v[142:145], v[190:193], v[42:45]
	s_waitcnt lgkmcnt(1)
	v_mfma_f32_16x16x32_bf16 v[46:49], v[130:133], v[186:189], v[46:49]
	v_mfma_f32_16x16x32_bf16 v[46:49], v[134:137], v[190:193], v[46:49]
	v_mfma_f32_16x16x32_bf16 v[30:33], v[130:133], v[194:197], v[30:33]
	v_mfma_f32_16x16x32_bf16 v[30:33], v[134:137], v[198:201], v[30:33]
	v_mfma_f32_16x16x32_bf16 v[26:29], v[138:141], v[194:197], v[26:29]
	v_mfma_f32_16x16x32_bf16 v[26:29], v[142:145], v[198:201], v[26:29]
	v_mfma_f32_16x16x32_bf16 v[10:13], v[138:141], v[202:205], v[10:13]
	v_mfma_f32_16x16x32_bf16 v[10:13], v[142:145], v[206:209], v[10:13]
	s_waitcnt lgkmcnt(0)
	v_mfma_f32_16x16x32_bf16 v[14:17], v[130:133], v[202:205], v[14:17]
	v_mfma_f32_16x16x32_bf16 v[14:17], v[134:137], v[206:209], v[14:17]
	v_mfma_f32_16x16x32_bf16 v[54:57], v[146:149], v[166:169], v[54:57]
	v_mfma_f32_16x16x32_bf16 v[54:57], v[150:153], v[170:173], v[54:57]
	v_mfma_f32_16x16x32_bf16 v[50:53], v[154:157], v[166:169], v[50:53]
	v_mfma_f32_16x16x32_bf16 v[50:53], v[158:161], v[170:173], v[50:53]
	v_mfma_f32_16x16x32_bf16 v[34:37], v[154:157], v[186:189], v[34:37]
	v_mfma_f32_16x16x32_bf16 v[34:37], v[158:161], v[190:193], v[34:37]
	v_mfma_f32_16x16x32_bf16 v[38:41], v[146:149], v[186:189], v[38:41]
	v_mfma_f32_16x16x32_bf16 v[38:41], v[150:153], v[190:193], v[38:41]
	v_mfma_f32_16x16x32_bf16 v[22:25], v[146:149], v[194:197], v[22:25]
	v_mfma_f32_16x16x32_bf16 v[22:25], v[150:153], v[198:201], v[22:25]
	v_mfma_f32_16x16x32_bf16 v[18:21], v[154:157], v[194:197], v[18:21]
	v_mfma_f32_16x16x32_bf16 v[18:21], v[158:161], v[198:201], v[18:21]
	v_mfma_f32_16x16x32_bf16 v[2:5], v[154:157], v[202:205], v[2:5]
	v_mfma_f32_16x16x32_bf16 v[2:5], v[158:161], v[206:209], v[2:5]
	s_setprio 2
	s_barrier
	v_mfma_f32_16x16x32_bf16 v[6:9], v[146:149], v[202:205], v[6:9]
	v_mfma_f32_16x16x32_bf16 v[6:9], v[150:153], v[206:209], v[6:9]
	s_setprio 0
	s_add_i32 s78, s78, 2
	s_add_u32 s74, s74, 0x100
	s_addc_u32 s75, s75, 0
	s_add_u32 s24, s24, 0x100
	s_addc_u32 s25, s25, 0
	s_add_u32 s76, s76, 0x100
	s_addc_u32 s77, s77, 0
	s_cmp_gt_u32 s78, 29
	s_cbranch_scc0 .LBB0_2410
	s_and_b64 vcc, exec, s[8:9]
	s_cbranch_vccz .LBB0_2413
	s_barrier

.LBB0_2593:
	s_ashr_i32 s11, s10, 31
	s_lshl_b64 s[12:13], s[10:11], 20
	s_add_u32 s12, s26, s12
	s_addc_u32 s13, s27, s13
	s_and_b64 s[14:15], s[2:3], exec
	s_cselect_b32 s11, s13, s21
	s_cselect_b32 s62, s12, s20
	s_ashr_i32 s9, s8, 31
	s_lshl_b64 s[14:15], s[8:9], 20
	s_add_u32 s14, s28, s14
	s_addc_u32 s15, s29, s15
	s_and_b64 s[22:23], s[2:3], exec
	s_cselect_b32 s9, s15, s19
	s_cselect_b32 s63, s14, s18
	s_add_u32 s64, s18, 0x100
	s_addc_u32 s65, s19, 0
	s_add_u32 s18, s20, 0x80080
	s_addc_u32 s19, s21, 0
	s_add_u32 s66, s20, 0x100
	s_addc_u32 s67, s21, 0
	s_mov_b32 s70, -2
	ds_read_b128 v[148:151], v143
	ds_read_b128 v[152:155], v143 offset:1024
	ds_read_b128 v[156:159], v143 offset:2048
	ds_read_b128 v[160:163], v143 offset:3072
	ds_read_b128 v[164:167], v144
	ds_read_b128 v[168:171], v144 offset:1024
	ds_read_b128 v[172:175], v144 offset:2048
	ds_read_b128 v[176:179], v144 offset:3072
	s_cmp_eq_u32 s70, 28
	s_cselect_b32 s21, s9, s65
	s_cselect_b32 s20, s63, s64
	s_cselect_b32 s23, s11, s67
	s_cselect_b32 s22, s62, s66
	ds_read_b128 v[180:183], v145
	ds_read_b128 v[184:187], v145 offset:1024
	ds_read_b128 v[188:191], v145 offset:2048
	ds_read_b128 v[192:195], v145 offset:3072
	ds_read_b128 v[196:199], v145 offset:4096
	ds_read_b128 v[200:203], v145 offset:5120
	ds_read_b128 v[204:207], v145 offset:6144
	ds_read_b128 v[208:211], v145 offset:7168
	s_add_u32 s74, s18, 0xfff80000
	s_addc_u32 s75, s19, -1
	s_mov_b32 s71, m0
	s_mov_b32 m0, s48
	s_nop 0
	global_load_lds_dwordx4 v138, s[74:75]
	s_mov_b32 m0, s71
	s_nop 0
	s_mov_b32 s71, m0
	s_mov_b32 m0, s57
	s_nop 0
	global_load_lds_dwordx4 v140, s[74:75]
	s_mov_b32 m0, s71
	s_nop 0
	s_mov_b32 s71, m0
	s_mov_b32 m0, s49
	s_nop 0
	global_load_lds_dwordx4 v138, s[18:19]
	s_mov_b32 m0, s71
	s_nop 0
	s_mov_b32 s71, m0
	s_mov_b32 m0, s58
	s_nop 0
	global_load_lds_dwordx4 v140, s[18:19]
	s_mov_b32 m0, s71
	s_waitcnt vmcnt(8)
	s_waitcnt lgkmcnt(0)
	s_barrier
	s_setprio 1
	s_waitcnt lgkmcnt(7)
	v_mfma_f32_16x16x32_bf16 v[126:129], v[148:151], v[180:183], 0
	v_mfma_f32_16x16x32_bf16 v[126:129], v[152:155], v[184:187], v[126:129]
	s_waitcnt lgkmcnt(5)
	v_mfma_f32_16x16x32_bf16 v[122:125], v[156:159], v[180:183], 0
	v_mfma_f32_16x16x32_bf16 v[122:125], v[160:163], v[184:187], v[122:125]
	s_waitcnt lgkmcnt(3)
	v_mfma_f32_16x16x32_bf16 v[106:109], v[156:159], v[188:191], 0
	v_mfma_f32_16x16x32_bf16 v[106:109], v[160:163], v[192:195], v[106:109]
	s_waitcnt lgkmcnt(1)
	v_mfma_f32_16x16x32_bf16 v[110:113], v[148:151], v[188:191], 0
	v_mfma_f32_16x16x32_bf16 v[110:113], v[152:155], v[192:195], v[110:113]
	v_mfma_f32_16x16x32_bf16 v[94:97], v[148:151], v[196:199], 0
	v_mfma_f32_16x16x32_bf16 v[94:97], v[152:155], v[200:203], v[94:97]
	v_mfma_f32_16x16x32_bf16 v[90:93], v[156:159], v[196:199], 0
	v_mfma_f32_16x16x32_bf16 v[90:93], v[160:163], v[200:203], v[90:93]
	v_mfma_f32_16x16x32_bf16 v[74:77], v[156:159], v[204:207], 0
	v_mfma_f32_16x16x32_bf16 v[74:77], v[160:163], v[208:211], v[74:77]
	s_waitcnt lgkmcnt(0)
	v_mfma_f32_16x16x32_bf16 v[78:81], v[148:151], v[204:207], 0
	v_mfma_f32_16x16x32_bf16 v[78:81], v[152:155], v[208:211], v[78:81]
	v_mfma_f32_16x16x32_bf16 v[118:121], v[164:167], v[180:183], 0
	v_mfma_f32_16x16x32_bf16 v[118:121], v[168:171], v[184:187], v[118:121]
	v_mfma_f32_16x16x32_bf16 v[114:117], v[172:175], v[180:183], 0
	v_mfma_f32_16x16x32_bf16 v[114:117], v[176:179], v[184:187], v[114:117]
	v_mfma_f32_16x16x32_bf16 v[98:101], v[172:175], v[188:191], 0
	v_mfma_f32_16x16x32_bf16 v[98:101], v[176:179], v[192:195], v[98:101]
	v_mfma_f32_16x16x32_bf16 v[102:105], v[164:167], v[188:191], 0
	v_mfma_f32_16x16x32_bf16 v[102:105], v[168:171], v[192:195], v[102:105]
	v_mfma_f32_16x16x32_bf16 v[86:89], v[164:167], v[196:199], 0
	v_mfma_f32_16x16x32_bf16 v[86:89], v[168:171], v[200:203], v[86:89]
	v_mfma_f32_16x16x32_bf16 v[82:85], v[172:175], v[196:199], 0
	v_mfma_f32_16x16x32_bf16 v[82:85], v[176:179], v[200:203], v[82:85]
	v_mfma_f32_16x16x32_bf16 v[66:69], v[172:175], v[204:207], 0
	v_mfma_f32_16x16x32_bf16 v[66:69], v[176:179], v[208:211], v[66:69]
	s_setprio 2
	s_barrier
	v_mfma_f32_16x16x32_bf16 v[70:73], v[164:167], v[204:207], 0
	v_mfma_f32_16x16x32_bf16 v[70:73], v[168:171], v[208:211], v[70:73]
	s_setprio 0
	ds_read_b128 v[180:183], v145 offset:16384
	ds_read_b128 v[184:187], v145 offset:17408
	ds_read_b128 v[188:191], v145 offset:18432
	ds_read_b128 v[192:195], v145 offset:19456
	ds_read_b128 v[196:199], v145 offset:20480
	ds_read_b128 v[200:203], v145 offset:21504
	ds_read_b128 v[204:207], v145 offset:22528
	ds_read_b128 v[208:211], v145 offset:23552
	s_mov_b32 s71, m0
	s_mov_b32 m0, s35
	s_nop 0
	global_load_lds_dwordx4 v139, s[20:21]
	s_mov_b32 m0, s71
	s_add_u32 s74, s20, 0x80000
	s_mov_b32 s71, m0
	s_mov_b32 m0, s36
	s_nop 0
	global_load_lds_dwordx4 v141, s[20:21]
	s_mov_b32 m0, s71
	s_addc_u32 s75, s21, 0
	s_mov_b32 s71, m0
	s_mov_b32 m0, s37
	s_nop 0
	global_load_lds_dwordx4 v139, s[74:75]
	s_mov_b32 m0, s71
	s_nop 0
	s_mov_b32 s71, m0
	s_mov_b32 m0, s40
	s_nop 0
	global_load_lds_dwordx4 v141, s[74:75]
	s_mov_b32 m0, s71
	s_waitcnt vmcnt(4)
	s_waitcnt lgkmcnt(0)
	s_barrier
	s_setprio 1
	s_waitcnt lgkmcnt(7)
	v_mfma_f32_16x16x32_bf16 v[62:65], v[148:151], v[180:183], 0
	v_mfma_f32_16x16x32_bf16 v[62:65], v[152:155], v[184:187], v[62:65]
	s_waitcnt lgkmcnt(5)
	v_mfma_f32_16x16x32_bf16 v[58:61], v[156:159], v[180:183], 0
	v_mfma_f32_16x16x32_bf16 v[58:61], v[160:163], v[184:187], v[58:61]
	s_waitcnt lgkmcnt(3)
	v_mfma_f32_16x16x32_bf16 v[42:45], v[156:159], v[188:191], 0
	v_mfma_f32_16x16x32_bf16 v[42:45], v[160:163], v[192:195], v[42:45]
	s_waitcnt lgkmcnt(1)
	v_mfma_f32_16x16x32_bf16 v[46:49], v[148:151], v[188:191], 0
	v_mfma_f32_16x16x32_bf16 v[46:49], v[152:155], v[192:195], v[46:49]
	v_mfma_f32_16x16x32_bf16 v[30:33], v[148:151], v[196:199], 0
	v_mfma_f32_16x16x32_bf16 v[30:33], v[152:155], v[200:203], v[30:33]
	v_mfma_f32_16x16x32_bf16 v[26:29], v[156:159], v[196:199], 0
	v_mfma_f32_16x16x32_bf16 v[26:29], v[160:163], v[200:203], v[26:29]
	v_mfma_f32_16x16x32_bf16 v[10:13], v[156:159], v[204:207], 0
	v_mfma_f32_16x16x32_bf16 v[10:13], v[160:163], v[208:211], v[10:13]
	s_waitcnt lgkmcnt(0)
	v_mfma_f32_16x16x32_bf16 v[14:17], v[148:151], v[204:207], 0
	v_mfma_f32_16x16x32_bf16 v[14:17], v[152:155], v[208:211], v[14:17]
	v_mfma_f32_16x16x32_bf16 v[54:57], v[164:167], v[180:183], 0
	v_mfma_f32_16x16x32_bf16 v[54:57], v[168:171], v[184:187], v[54:57]
	v_mfma_f32_16x16x32_bf16 v[50:53], v[172:175], v[180:183], 0
	v_mfma_f32_16x16x32_bf16 v[50:53], v[176:179], v[184:187], v[50:53]
	v_mfma_f32_16x16x32_bf16 v[34:37], v[172:175], v[188:191], 0
	v_mfma_f32_16x16x32_bf16 v[34:37], v[176:179], v[192:195], v[34:37]
	v_mfma_f32_16x16x32_bf16 v[38:41], v[164:167], v[188:191], 0
	v_mfma_f32_16x16x32_bf16 v[38:41], v[168:171], v[192:195], v[38:41]
	v_mfma_f32_16x16x32_bf16 v[22:25], v[164:167], v[196:199], 0
	v_mfma_f32_16x16x32_bf16 v[22:25], v[168:171], v[200:203], v[22:25]
	v_mfma_f32_16x16x32_bf16 v[18:21], v[172:175], v[196:199], 0
	v_mfma_f32_16x16x32_bf16 v[18:21], v[176:179], v[200:203], v[18:21]
	v_mfma_f32_16x16x32_bf16 v[2:5], v[172:175], v[204:207], 0
	v_mfma_f32_16x16x32_bf16 v[2:5], v[176:179], v[208:211], v[2:5]
	s_setprio 2
	s_barrier
	v_mfma_f32_16x16x32_bf16 v[6:9], v[164:167], v[204:207], 0
	v_mfma_f32_16x16x32_bf16 v[6:9], v[168:171], v[208:211], v[6:9]
	s_setprio 0
	ds_read_b128 v[148:151], v146
	ds_read_b128 v[152:155], v146 offset:1024
	ds_read_b128 v[156:159], v146 offset:2048
	ds_read_b128 v[160:163], v146 offset:3072
	ds_read_b128 v[164:167], v147
	ds_read_b128 v[168:171], v147 offset:1024
	ds_read_b128 v[172:175], v147 offset:2048
	ds_read_b128 v[176:179], v147 offset:3072
	ds_read_b128 v[180:183], v145 offset:32768
	ds_read_b128 v[184:187], v145 offset:33792
	ds_read_b128 v[188:191], v145 offset:34816
	ds_read_b128 v[192:195], v145 offset:35840
	ds_read_b128 v[196:199], v145 offset:36864
	ds_read_b128 v[200:203], v145 offset:37888
	ds_read_b128 v[204:207], v145 offset:38912
	ds_read_b128 v[208:211], v145 offset:39936
	s_mov_b32 s71, m0
	s_mov_b32 m0, s31
	s_nop 0
	global_load_lds_dwordx4 v138, s[22:23]
	s_mov_b32 m0, s71
	s_nop 0
	s_mov_b32 s71, m0
	s_mov_b32 m0, s41
	s_nop 0
	global_load_lds_dwordx4 v140, s[22:23]
	s_mov_b32 m0, s71
	s_add_u32 s22, s22, 0x80000
	s_addc_u32 s23, s23, 0
	s_mov_b32 s71, m0
	s_mov_b32 m0, s42
	s_nop 0
	global_load_lds_dwordx4 v138, s[22:23]
	s_mov_b32 m0, s71
	s_nop 0
	s_mov_b32 s71, m0
	s_mov_b32 m0, s43
	s_nop 0
	global_load_lds_dwordx4 v140, s[22:23]
	s_mov_b32 m0, s71
	s_waitcnt vmcnt(8)
	s_waitcnt lgkmcnt(0)
	s_barrier
	s_setprio 1
	s_waitcnt lgkmcnt(7)
	v_mfma_f32_16x16x32_bf16 v[126:129], v[148:151], v[180:183], v[126:129]
	v_mfma_f32_16x16x32_bf16 v[126:129], v[152:155], v[184:187], v[126:129]
	s_waitcnt lgkmcnt(5)
	v_mfma_f32_16x16x32_bf16 v[122:125], v[156:159], v[180:183], v[122:125]
	v_mfma_f32_16x16x32_bf16 v[122:125], v[160:163], v[184:187], v[122:125]
	s_waitcnt lgkmcnt(3)
	v_mfma_f32_16x16x32_bf16 v[106:109], v[156:159], v[188:191], v[106:109]
	v_mfma_f32_16x16x32_bf16 v[106:109], v[160:163], v[192:195], v[106:109]
	s_waitcnt lgkmcnt(1)
	v_mfma_f32_16x16x32_bf16 v[110:113], v[148:151], v[188:191], v[110:113]
	v_mfma_f32_16x16x32_bf16 v[110:113], v[152:155], v[192:195], v[110:113]
	v_mfma_f32_16x16x32_bf16 v[94:97], v[148:151], v[196:199], v[94:97]
	v_mfma_f32_16x16x32_bf16 v[94:97], v[152:155], v[200:203], v[94:97]
	v_mfma_f32_16x16x32_bf16 v[90:93], v[156:159], v[196:199], v[90:93]
	v_mfma_f32_16x16x32_bf16 v[90:93], v[160:163], v[200:203], v[90:93]
	v_mfma_f32_16x16x32_bf16 v[74:77], v[156:159], v[204:207], v[74:77]
	v_mfma_f32_16x16x32_bf16 v[74:77], v[160:163], v[208:211], v[74:77]
	s_waitcnt lgkmcnt(0)
	v_mfma_f32_16x16x32_bf16 v[78:81], v[148:151], v[204:207], v[78:81]
	v_mfma_f32_16x16x32_bf16 v[78:81], v[152:155], v[208:211], v[78:81]
	v_mfma_f32_16x16x32_bf16 v[118:121], v[164:167], v[180:183], v[118:121]
	v_mfma_f32_16x16x32_bf16 v[118:121], v[168:171], v[184:187], v[118:121]
	v_mfma_f32_16x16x32_bf16 v[114:117], v[172:175], v[180:183], v[114:117]
	v_mfma_f32_16x16x32_bf16 v[114:117], v[176:179], v[184:187], v[114:117]
	v_mfma_f32_16x16x32_bf16 v[98:101], v[172:175], v[188:191], v[98:101]
	v_mfma_f32_16x16x32_bf16 v[98:101], v[176:179], v[192:195], v[98:101]
	v_mfma_f32_16x16x32_bf16 v[102:105], v[164:167], v[188:191], v[102:105]
	v_mfma_f32_16x16x32_bf16 v[102:105], v[168:171], v[192:195], v[102:105]
	v_mfma_f32_16x16x32_bf16 v[86:89], v[164:167], v[196:199], v[86:89]
	v_mfma_f32_16x16x32_bf16 v[86:89], v[168:171], v[200:203], v[86:89]
	v_mfma_f32_16x16x32_bf16 v[82:85], v[172:175], v[196:199], v[82:85]
	v_mfma_f32_16x16x32_bf16 v[82:85], v[176:179], v[200:203], v[82:85]
	v_mfma_f32_16x16x32_bf16 v[66:69], v[172:175], v[204:207], v[66:69]
	v_mfma_f32_16x16x32_bf16 v[66:69], v[176:179], v[208:211], v[66:69]
	s_setprio 2
	s_barrier
	v_mfma_f32_16x16x32_bf16 v[70:73], v[164:167], v[204:207], v[70:73]
	v_mfma_f32_16x16x32_bf16 v[70:73], v[168:171], v[208:211], v[70:73]
	s_setprio 0
	ds_read_b128 v[180:183], v145 offset:49152
	ds_read_b128 v[184:187], v145 offset:50176
	ds_read_b128 v[188:191], v145 offset:51200
	ds_read_b128 v[192:195], v145 offset:52224
	ds_read_b128 v[196:199], v145 offset:53248
	ds_read_b128 v[200:203], v145 offset:54272
	ds_read_b128 v[204:207], v145 offset:55296
	ds_read_b128 v[208:211], v145 offset:56320
	s_add_u32 s22, s20, 0x80
	s_addc_u32 s23, s21, 0
	s_mov_b32 s71, m0
	s_mov_b32 m0, s44
	s_nop 0
	global_load_lds_dwordx4 v139, s[22:23]
	s_mov_b32 m0, s71
	s_add_u32 s20, s20, 0x80080
	s_mov_b32 s71, m0
	s_mov_b32 m0, s45
	s_nop 0
	global_load_lds_dwordx4 v141, s[22:23]
	s_mov_b32 m0, s71
	s_addc_u32 s21, s21, 0
	s_mov_b32 s22, m0
	s_mov_b32 m0, s46
	s_nop 0
	global_load_lds_dwordx4 v139, s[20:21]
	s_mov_b32 m0, s22
	s_nop 0
	s_mov_b32 s22, m0
	s_mov_b32 m0, s47
	s_nop 0
	global_load_lds_dwordx4 v141, s[20:21]
	s_mov_b32 m0, s22
	s_waitcnt vmcnt(4)
	s_waitcnt lgkmcnt(0)
	s_barrier
	s_setprio 1
	s_waitcnt lgkmcnt(7)
	v_mfma_f32_16x16x32_bf16 v[62:65], v[148:151], v[180:183], v[62:65]
	v_mfma_f32_16x16x32_bf16 v[62:65], v[152:155], v[184:187], v[62:65]
	s_waitcnt lgkmcnt(5)
	v_mfma_f32_16x16x32_bf16 v[58:61], v[156:159], v[180:183], v[58:61]
	v_mfma_f32_16x16x32_bf16 v[58:61], v[160:163], v[184:187], v[58:61]
	s_waitcnt lgkmcnt(3)
	v_mfma_f32_16x16x32_bf16 v[42:45], v[156:159], v[188:191], v[42:45]
	v_mfma_f32_16x16x32_bf16 v[42:45], v[160:163], v[192:195], v[42:45]
	s_waitcnt lgkmcnt(1)
	v_mfma_f32_16x16x32_bf16 v[46:49], v[148:151], v[188:191], v[46:49]
	v_mfma_f32_16x16x32_bf16 v[46:49], v[152:155], v[192:195], v[46:49]
	v_mfma_f32_16x16x32_bf16 v[30:33], v[148:151], v[196:199], v[30:33]
	v_mfma_f32_16x16x32_bf16 v[30:33], v[152:155], v[200:203], v[30:33]
	v_mfma_f32_16x16x32_bf16 v[26:29], v[156:159], v[196:199], v[26:29]
	v_mfma_f32_16x16x32_bf16 v[26:29], v[160:163], v[200:203], v[26:29]
	v_mfma_f32_16x16x32_bf16 v[10:13], v[156:159], v[204:207], v[10:13]
	v_mfma_f32_16x16x32_bf16 v[10:13], v[160:163], v[208:211], v[10:13]
	s_waitcnt lgkmcnt(0)
	v_mfma_f32_16x16x32_bf16 v[14:17], v[148:151], v[204:207], v[14:17]
	v_mfma_f32_16x16x32_bf16 v[14:17], v[152:155], v[208:211], v[14:17]
	v_mfma_f32_16x16x32_bf16 v[54:57], v[164:167], v[180:183], v[54:57]
	v_mfma_f32_16x16x32_bf16 v[54:57], v[168:171], v[184:187], v[54:57]
	v_mfma_f32_16x16x32_bf16 v[50:53], v[172:175], v[180:183], v[50:53]
	v_mfma_f32_16x16x32_bf16 v[50:53], v[176:179], v[184:187], v[50:53]
	v_mfma_f32_16x16x32_bf16 v[34:37], v[172:175], v[188:191], v[34:37]
	v_mfma_f32_16x16x32_bf16 v[34:37], v[176:179], v[192:195], v[34:37]
	v_mfma_f32_16x16x32_bf16 v[38:41], v[164:167], v[188:191], v[38:41]
	v_mfma_f32_16x16x32_bf16 v[38:41], v[168:171], v[192:195], v[38:41]
	v_mfma_f32_16x16x32_bf16 v[22:25], v[164:167], v[196:199], v[22:25]
	v_mfma_f32_16x16x32_bf16 v[22:25], v[168:171], v[200:203], v[22:25]
	v_mfma_f32_16x16x32_bf16 v[18:21], v[172:175], v[196:199], v[18:21]
	v_mfma_f32_16x16x32_bf16 v[18:21], v[176:179], v[200:203], v[18:21]
	v_mfma_f32_16x16x32_bf16 v[2:5], v[172:175], v[204:207], v[2:5]
	v_mfma_f32_16x16x32_bf16 v[2:5], v[176:179], v[208:211], v[2:5]
	s_setprio 2
	s_barrier
	v_mfma_f32_16x16x32_bf16 v[6:9], v[164:167], v[204:207], v[6:9]
	v_mfma_f32_16x16x32_bf16 v[6:9], v[168:171], v[208:211], v[6:9]
	s_setprio 0
	s_add_i32 s70, s70, 2
	s_add_u32 s64, s64, 0x100
	s_addc_u32 s65, s65, 0
	s_add_u32 s18, s18, 0x100
	s_addc_u32 s19, s19, 0
	s_add_u32 s66, s66, 0x100
	s_addc_u32 s67, s67, 0
	s_cmp_gt_u32 s70, 29
	.p2align 6
.LBB0_2594:
	ds_read_b128 v[148:151], v143
	ds_read_b128 v[152:155], v143 offset:1024
	ds_read_b128 v[156:159], v143 offset:2048
	ds_read_b128 v[160:163], v143 offset:3072
	ds_read_b128 v[164:167], v144
	ds_read_b128 v[168:171], v144 offset:1024
	ds_read_b128 v[172:175], v144 offset:2048
	ds_read_b128 v[176:179], v144 offset:3072
	s_cmp_eq_u32 s70, 28
	s_cselect_b32 s21, s9, s65
	s_cselect_b32 s20, s63, s64
	s_cselect_b32 s23, s11, s67
	s_cselect_b32 s22, s62, s66
	ds_read_b128 v[180:183], v145
	ds_read_b128 v[184:187], v145 offset:1024
	ds_read_b128 v[188:191], v145 offset:2048
	ds_read_b128 v[192:195], v145 offset:3072
	ds_read_b128 v[196:199], v145 offset:4096
	ds_read_b128 v[200:203], v145 offset:5120
	ds_read_b128 v[204:207], v145 offset:6144
	ds_read_b128 v[208:211], v145 offset:7168
	s_add_u32 s74, s18, 0xfff80000
	s_addc_u32 s75, s19, -1
	s_mov_b32 s71, m0
	s_mov_b32 m0, s48
	s_nop 0
	global_load_lds_dwordx4 v138, s[74:75]
	s_mov_b32 m0, s71
	s_nop 0
	s_mov_b32 s71, m0
	s_mov_b32 m0, s57
	s_nop 0
	global_load_lds_dwordx4 v140, s[74:75]
	s_mov_b32 m0, s71
	s_nop 0
	s_mov_b32 s71, m0
	s_mov_b32 m0, s49
	s_nop 0
	global_load_lds_dwordx4 v138, s[18:19]
	s_mov_b32 m0, s71
	s_nop 0
	s_mov_b32 s71, m0
	s_mov_b32 m0, s58
	s_nop 0
	global_load_lds_dwordx4 v140, s[18:19]
	s_mov_b32 m0, s71
	s_waitcnt vmcnt(8)
	s_waitcnt lgkmcnt(0)
	s_barrier
	s_setprio 1
	s_waitcnt lgkmcnt(7)
	v_mfma_f32_16x16x32_bf16 v[126:129], v[148:151], v[180:183], v[126:129]
	v_mfma_f32_16x16x32_bf16 v[126:129], v[152:155], v[184:187], v[126:129]
	s_waitcnt lgkmcnt(5)
	v_mfma_f32_16x16x32_bf16 v[122:125], v[156:159], v[180:183], v[122:125]
	v_mfma_f32_16x16x32_bf16 v[122:125], v[160:163], v[184:187], v[122:125]
	s_waitcnt lgkmcnt(3)
	v_mfma_f32_16x16x32_bf16 v[106:109], v[156:159], v[188:191], v[106:109]
	v_mfma_f32_16x16x32_bf16 v[106:109], v[160:163], v[192:195], v[106:109]
	s_waitcnt lgkmcnt(1)
	v_mfma_f32_16x16x32_bf16 v[110:113], v[148:151], v[188:191], v[110:113]
	v_mfma_f32_16x16x32_bf16 v[110:113], v[152:155], v[192:195], v[110:113]
	v_mfma_f32_16x16x32_bf16 v[94:97], v[148:151], v[196:199], v[94:97]
	v_mfma_f32_16x16x32_bf16 v[94:97], v[152:155], v[200:203], v[94:97]
	v_mfma_f32_16x16x32_bf16 v[90:93], v[156:159], v[196:199], v[90:93]
	v_mfma_f32_16x16x32_bf16 v[90:93], v[160:163], v[200:203], v[90:93]
	v_mfma_f32_16x16x32_bf16 v[74:77], v[156:159], v[204:207], v[74:77]
	v_mfma_f32_16x16x32_bf16 v[74:77], v[160:163], v[208:211], v[74:77]
	s_waitcnt lgkmcnt(0)
	v_mfma_f32_16x16x32_bf16 v[78:81], v[148:151], v[204:207], v[78:81]
	v_mfma_f32_16x16x32_bf16 v[78:81], v[152:155], v[208:211], v[78:81]
	v_mfma_f32_16x16x32_bf16 v[118:121], v[164:167], v[180:183], v[118:121]
	v_mfma_f32_16x16x32_bf16 v[118:121], v[168:171], v[184:187], v[118:121]
	v_mfma_f32_16x16x32_bf16 v[114:117], v[172:175], v[180:183], v[114:117]
	v_mfma_f32_16x16x32_bf16 v[114:117], v[176:179], v[184:187], v[114:117]
	v_mfma_f32_16x16x32_bf16 v[98:101], v[172:175], v[188:191], v[98:101]
	v_mfma_f32_16x16x32_bf16 v[98:101], v[176:179], v[192:195], v[98:101]
	v_mfma_f32_16x16x32_bf16 v[102:105], v[164:167], v[188:191], v[102:105]
	v_mfma_f32_16x16x32_bf16 v[102:105], v[168:171], v[192:195], v[102:105]
	v_mfma_f32_16x16x32_bf16 v[86:89], v[164:167], v[196:199], v[86:89]
	v_mfma_f32_16x16x32_bf16 v[86:89], v[168:171], v[200:203], v[86:89]
	v_mfma_f32_16x16x32_bf16 v[82:85], v[172:175], v[196:199], v[82:85]
	v_mfma_f32_16x16x32_bf16 v[82:85], v[176:179], v[200:203], v[82:85]
	v_mfma_f32_16x16x32_bf16 v[66:69], v[172:175], v[204:207], v[66:69]
	v_mfma_f32_16x16x32_bf16 v[66:69], v[176:179], v[208:211], v[66:69]
	s_setprio 2
	s_barrier
	v_mfma_f32_16x16x32_bf16 v[70:73], v[164:167], v[204:207], v[70:73]
	v_mfma_f32_16x16x32_bf16 v[70:73], v[168:171], v[208:211], v[70:73]
	s_setprio 0
	ds_read_b128 v[180:183], v145 offset:16384
	ds_read_b128 v[184:187], v145 offset:17408
	ds_read_b128 v[188:191], v145 offset:18432
	ds_read_b128 v[192:195], v145 offset:19456
	ds_read_b128 v[196:199], v145 offset:20480
	ds_read_b128 v[200:203], v145 offset:21504
	ds_read_b128 v[204:207], v145 offset:22528
	ds_read_b128 v[208:211], v145 offset:23552
	s_mov_b32 s71, m0
	s_mov_b32 m0, s35
	s_nop 0
	global_load_lds_dwordx4 v139, s[20:21]
	s_mov_b32 m0, s71
	s_add_u32 s74, s20, 0x80000
	s_mov_b32 s71, m0
	s_mov_b32 m0, s36
	s_nop 0
	global_load_lds_dwordx4 v141, s[20:21]
	s_mov_b32 m0, s71
	s_addc_u32 s75, s21, 0
	s_mov_b32 s71, m0
	s_mov_b32 m0, s37
	s_nop 0
	global_load_lds_dwordx4 v139, s[74:75]
	s_mov_b32 m0, s71
	s_nop 0
	s_mov_b32 s71, m0
	s_mov_b32 m0, s40
	s_nop 0
	global_load_lds_dwordx4 v141, s[74:75]
	s_mov_b32 m0, s71
	s_waitcnt vmcnt(4)
	s_waitcnt lgkmcnt(0)
	s_barrier
	s_setprio 1
	s_waitcnt lgkmcnt(7)
	v_mfma_f32_16x16x32_bf16 v[62:65], v[148:151], v[180:183], v[62:65]
	v_mfma_f32_16x16x32_bf16 v[62:65], v[152:155], v[184:187], v[62:65]
	s_waitcnt lgkmcnt(5)
	v_mfma_f32_16x16x32_bf16 v[58:61], v[156:159], v[180:183], v[58:61]
	v_mfma_f32_16x16x32_bf16 v[58:61], v[160:163], v[184:187], v[58:61]
	s_waitcnt lgkmcnt(3)
	v_mfma_f32_16x16x32_bf16 v[42:45], v[156:159], v[188:191], v[42:45]
	v_mfma_f32_16x16x32_bf16 v[42:45], v[160:163], v[192:195], v[42:45]
	s_waitcnt lgkmcnt(1)
	v_mfma_f32_16x16x32_bf16 v[46:49], v[148:151], v[188:191], v[46:49]
	v_mfma_f32_16x16x32_bf16 v[46:49], v[152:155], v[192:195], v[46:49]
	v_mfma_f32_16x16x32_bf16 v[30:33], v[148:151], v[196:199], v[30:33]
	v_mfma_f32_16x16x32_bf16 v[30:33], v[152:155], v[200:203], v[30:33]
	v_mfma_f32_16x16x32_bf16 v[26:29], v[156:159], v[196:199], v[26:29]
	v_mfma_f32_16x16x32_bf16 v[26:29], v[160:163], v[200:203], v[26:29]
	v_mfma_f32_16x16x32_bf16 v[10:13], v[156:159], v[204:207], v[10:13]
	v_mfma_f32_16x16x32_bf16 v[10:13], v[160:163], v[208:211], v[10:13]
	s_waitcnt lgkmcnt(0)
	v_mfma_f32_16x16x32_bf16 v[14:17], v[148:151], v[204:207], v[14:17]
	v_mfma_f32_16x16x32_bf16 v[14:17], v[152:155], v[208:211], v[14:17]
	v_mfma_f32_16x16x32_bf16 v[54:57], v[164:167], v[180:183], v[54:57]
	v_mfma_f32_16x16x32_bf16 v[54:57], v[168:171], v[184:187], v[54:57]
	v_mfma_f32_16x16x32_bf16 v[50:53], v[172:175], v[180:183], v[50:53]
	v_mfma_f32_16x16x32_bf16 v[50:53], v[176:179], v[184:187], v[50:53]
	v_mfma_f32_16x16x32_bf16 v[34:37], v[172:175], v[188:191], v[34:37]
	v_mfma_f32_16x16x32_bf16 v[34:37], v[176:179], v[192:195], v[34:37]
	v_mfma_f32_16x16x32_bf16 v[38:41], v[164:167], v[188:191], v[38:41]
	v_mfma_f32_16x16x32_bf16 v[38:41], v[168:171], v[192:195], v[38:41]
	v_mfma_f32_16x16x32_bf16 v[22:25], v[164:167], v[196:199], v[22:25]
	v_mfma_f32_16x16x32_bf16 v[22:25], v[168:171], v[200:203], v[22:25]
	v_mfma_f32_16x16x32_bf16 v[18:21], v[172:175], v[196:199], v[18:21]
	v_mfma_f32_16x16x32_bf16 v[18:21], v[176:179], v[200:203], v[18:21]
	v_mfma_f32_16x16x32_bf16 v[2:5], v[172:175], v[204:207], v[2:5]
	v_mfma_f32_16x16x32_bf16 v[2:5], v[176:179], v[208:211], v[2:5]
	s_setprio 2
	s_barrier
	v_mfma_f32_16x16x32_bf16 v[6:9], v[164:167], v[204:207], v[6:9]
	v_mfma_f32_16x16x32_bf16 v[6:9], v[168:171], v[208:211], v[6:9]
	s_setprio 0
	ds_read_b128 v[148:151], v146
	ds_read_b128 v[152:155], v146 offset:1024
	ds_read_b128 v[156:159], v146 offset:2048
	ds_read_b128 v[160:163], v146 offset:3072
	ds_read_b128 v[164:167], v147
	ds_read_b128 v[168:171], v147 offset:1024
	ds_read_b128 v[172:175], v147 offset:2048
	ds_read_b128 v[176:179], v147 offset:3072
	ds_read_b128 v[180:183], v145 offset:32768
	ds_read_b128 v[184:187], v145 offset:33792
	ds_read_b128 v[188:191], v145 offset:34816
	ds_read_b128 v[192:195], v145 offset:35840
	ds_read_b128 v[196:199], v145 offset:36864
	ds_read_b128 v[200:203], v145 offset:37888
	ds_read_b128 v[204:207], v145 offset:38912
	ds_read_b128 v[208:211], v145 offset:39936
	s_mov_b32 s71, m0
	s_mov_b32 m0, s31
	s_nop 0
	global_load_lds_dwordx4 v138, s[22:23]
	s_mov_b32 m0, s71
	s_nop 0
	s_mov_b32 s71, m0
	s_mov_b32 m0, s41
	s_nop 0
	global_load_lds_dwordx4 v140, s[22:23]
	s_mov_b32 m0, s71
	s_add_u32 s22, s22, 0x80000
	s_addc_u32 s23, s23, 0
	s_mov_b32 s71, m0
	s_mov_b32 m0, s42
	s_nop 0
	global_load_lds_dwordx4 v138, s[22:23]
	s_mov_b32 m0, s71
	s_nop 0
	s_mov_b32 s71, m0
	s_mov_b32 m0, s43
	s_nop 0
	global_load_lds_dwordx4 v140, s[22:23]
	s_mov_b32 m0, s71
	s_waitcnt vmcnt(8)
	s_waitcnt lgkmcnt(0)
	s_barrier
	s_setprio 1
	s_waitcnt lgkmcnt(7)
	v_mfma_f32_16x16x32_bf16 v[126:129], v[148:151], v[180:183], v[126:129]
	v_mfma_f32_16x16x32_bf16 v[126:129], v[152:155], v[184:187], v[126:129]
	s_waitcnt lgkmcnt(5)
	v_mfma_f32_16x16x32_bf16 v[122:125], v[156:159], v[180:183], v[122:125]
	v_mfma_f32_16x16x32_bf16 v[122:125], v[160:163], v[184:187], v[122:125]
	s_waitcnt lgkmcnt(3)
	v_mfma_f32_16x16x32_bf16 v[106:109], v[156:159], v[188:191], v[106:109]
	v_mfma_f32_16x16x32_bf16 v[106:109], v[160:163], v[192:195], v[106:109]
	s_waitcnt lgkmcnt(1)
	v_mfma_f32_16x16x32_bf16 v[110:113], v[148:151], v[188:191], v[110:113]
	v_mfma_f32_16x16x32_bf16 v[110:113], v[152:155], v[192:195], v[110:113]
	v_mfma_f32_16x16x32_bf16 v[94:97], v[148:151], v[196:199], v[94:97]
	v_mfma_f32_16x16x32_bf16 v[94:97], v[152:155], v[200:203], v[94:97]
	v_mfma_f32_16x16x32_bf16 v[90:93], v[156:159], v[196:199], v[90:93]
	v_mfma_f32_16x16x32_bf16 v[90:93], v[160:163], v[200:203], v[90:93]
	v_mfma_f32_16x16x32_bf16 v[74:77], v[156:159], v[204:207], v[74:77]
	v_mfma_f32_16x16x32_bf16 v[74:77], v[160:163], v[208:211], v[74:77]
	s_waitcnt lgkmcnt(0)
	v_mfma_f32_16x16x32_bf16 v[78:81], v[148:151], v[204:207], v[78:81]
	v_mfma_f32_16x16x32_bf16 v[78:81], v[152:155], v[208:211], v[78:81]
	v_mfma_f32_16x16x32_bf16 v[118:121], v[164:167], v[180:183], v[118:121]
	v_mfma_f32_16x16x32_bf16 v[118:121], v[168:171], v[184:187], v[118:121]
	v_mfma_f32_16x16x32_bf16 v[114:117], v[172:175], v[180:183], v[114:117]
	v_mfma_f32_16x16x32_bf16 v[114:117], v[176:179], v[184:187], v[114:117]
	v_mfma_f32_16x16x32_bf16 v[98:101], v[172:175], v[188:191], v[98:101]
	v_mfma_f32_16x16x32_bf16 v[98:101], v[176:179], v[192:195], v[98:101]
	v_mfma_f32_16x16x32_bf16 v[102:105], v[164:167], v[188:191], v[102:105]
	v_mfma_f32_16x16x32_bf16 v[102:105], v[168:171], v[192:195], v[102:105]
	v_mfma_f32_16x16x32_bf16 v[86:89], v[164:167], v[196:199], v[86:89]
	v_mfma_f32_16x16x32_bf16 v[86:89], v[168:171], v[200:203], v[86:89]
	v_mfma_f32_16x16x32_bf16 v[82:85], v[172:175], v[196:199], v[82:85]
	v_mfma_f32_16x16x32_bf16 v[82:85], v[176:179], v[200:203], v[82:85]
	v_mfma_f32_16x16x32_bf16 v[66:69], v[172:175], v[204:207], v[66:69]
	v_mfma_f32_16x16x32_bf16 v[66:69], v[176:179], v[208:211], v[66:69]
	s_setprio 2
	s_barrier
	v_mfma_f32_16x16x32_bf16 v[70:73], v[164:167], v[204:207], v[70:73]
	v_mfma_f32_16x16x32_bf16 v[70:73], v[168:171], v[208:211], v[70:73]
	s_setprio 0
	ds_read_b128 v[180:183], v145 offset:49152
	ds_read_b128 v[184:187], v145 offset:50176
	ds_read_b128 v[188:191], v145 offset:51200
	ds_read_b128 v[192:195], v145 offset:52224
	ds_read_b128 v[196:199], v145 offset:53248
	ds_read_b128 v[200:203], v145 offset:54272
	ds_read_b128 v[204:207], v145 offset:55296
	ds_read_b128 v[208:211], v145 offset:56320
	s_add_u32 s22, s20, 0x80
	s_addc_u32 s23, s21, 0
	s_mov_b32 s71, m0
	s_mov_b32 m0, s44
	s_nop 0
	global_load_lds_dwordx4 v139, s[22:23]
	s_mov_b32 m0, s71
	s_add_u32 s20, s20, 0x80080
	s_mov_b32 s71, m0
	s_mov_b32 m0, s45
	s_nop 0
	global_load_lds_dwordx4 v141, s[22:23]
	s_mov_b32 m0, s71
	s_addc_u32 s21, s21, 0
	s_mov_b32 s22, m0
	s_mov_b32 m0, s46
	s_nop 0
	global_load_lds_dwordx4 v139, s[20:21]
	s_mov_b32 m0, s22
	s_nop 0
	s_mov_b32 s22, m0
	s_mov_b32 m0, s47
	s_nop 0
	global_load_lds_dwordx4 v141, s[20:21]
	s_mov_b32 m0, s22
	s_waitcnt vmcnt(4)
	s_waitcnt lgkmcnt(0)
	s_barrier
	s_setprio 1
	s_waitcnt lgkmcnt(7)
	v_mfma_f32_16x16x32_bf16 v[62:65], v[148:151], v[180:183], v[62:65]
	v_mfma_f32_16x16x32_bf16 v[62:65], v[152:155], v[184:187], v[62:65]
	s_waitcnt lgkmcnt(5)
	v_mfma_f32_16x16x32_bf16 v[58:61], v[156:159], v[180:183], v[58:61]
	v_mfma_f32_16x16x32_bf16 v[58:61], v[160:163], v[184:187], v[58:61]
	s_waitcnt lgkmcnt(3)
	v_mfma_f32_16x16x32_bf16 v[42:45], v[156:159], v[188:191], v[42:45]
	v_mfma_f32_16x16x32_bf16 v[42:45], v[160:163], v[192:195], v[42:45]
	s_waitcnt lgkmcnt(1)
	v_mfma_f32_16x16x32_bf16 v[46:49], v[148:151], v[188:191], v[46:49]
	v_mfma_f32_16x16x32_bf16 v[46:49], v[152:155], v[192:195], v[46:49]
	v_mfma_f32_16x16x32_bf16 v[30:33], v[148:151], v[196:199], v[30:33]
	v_mfma_f32_16x16x32_bf16 v[30:33], v[152:155], v[200:203], v[30:33]
	v_mfma_f32_16x16x32_bf16 v[26:29], v[156:159], v[196:199], v[26:29]
	v_mfma_f32_16x16x32_bf16 v[26:29], v[160:163], v[200:203], v[26:29]
	v_mfma_f32_16x16x32_bf16 v[10:13], v[156:159], v[204:207], v[10:13]
	v_mfma_f32_16x16x32_bf16 v[10:13], v[160:163], v[208:211], v[10:13]
	s_waitcnt lgkmcnt(0)
	v_mfma_f32_16x16x32_bf16 v[14:17], v[148:151], v[204:207], v[14:17]
	v_mfma_f32_16x16x32_bf16 v[14:17], v[152:155], v[208:211], v[14:17]
	v_mfma_f32_16x16x32_bf16 v[54:57], v[164:167], v[180:183], v[54:57]
	v_mfma_f32_16x16x32_bf16 v[54:57], v[168:171], v[184:187], v[54:57]
	v_mfma_f32_16x16x32_bf16 v[50:53], v[172:175], v[180:183], v[50:53]
	v_mfma_f32_16x16x32_bf16 v[50:53], v[176:179], v[184:187], v[50:53]
	v_mfma_f32_16x16x32_bf16 v[34:37], v[172:175], v[188:191], v[34:37]
	v_mfma_f32_16x16x32_bf16 v[34:37], v[176:179], v[192:195], v[34:37]
	v_mfma_f32_16x16x32_bf16 v[38:41], v[164:167], v[188:191], v[38:41]
	v_mfma_f32_16x16x32_bf16 v[38:41], v[168:171], v[192:195], v[38:41]
	v_mfma_f32_16x16x32_bf16 v[22:25], v[164:167], v[196:199], v[22:25]
	v_mfma_f32_16x16x32_bf16 v[22:25], v[168:171], v[200:203], v[22:25]
	v_mfma_f32_16x16x32_bf16 v[18:21], v[172:175], v[196:199], v[18:21]
	v_mfma_f32_16x16x32_bf16 v[18:21], v[176:179], v[200:203], v[18:21]
	v_mfma_f32_16x16x32_bf16 v[2:5], v[172:175], v[204:207], v[2:5]
	v_mfma_f32_16x16x32_bf16 v[2:5], v[176:179], v[208:211], v[2:5]
	s_setprio 2
	s_barrier
	v_mfma_f32_16x16x32_bf16 v[6:9], v[164:167], v[204:207], v[6:9]
	v_mfma_f32_16x16x32_bf16 v[6:9], v[168:171], v[208:211], v[6:9]
	s_setprio 0
	s_add_i32 s70, s70, 2
	s_add_u32 s64, s64, 0x100
	s_addc_u32 s65, s65, 0
	s_add_u32 s18, s18, 0x100
	s_addc_u32 s19, s19, 0
	s_add_u32 s66, s66, 0x100
	s_addc_u32 s67, s67, 0
	s_cmp_gt_u32 s70, 29
	s_cbranch_scc0 .LBB0_2594
	s_and_b64 vcc, exec, s[6:7]
	s_cbranch_vccz .LBB0_2597
	s_barrier

.LBB0_2791:
	s_ashr_i32 s21, s20, 31
	s_lshl_b64 s[22:23], s[20:21], 15
	s_add_u32 s22, s37, s22
	s_addc_u32 s23, s40, s23
	s_and_b64 s[24:25], s[2:3], exec
	s_cselect_b32 s21, s23, s31
	s_cselect_b32 s63, s22, s30
	s_ashr_i32 s19, s18, 31
	s_lshl_b64 s[24:25], s[18:19], 15
	s_add_u32 s24, s41, s24
	s_addc_u32 s25, s42, s25
	s_and_b64 s[34:35], s[2:3], exec
	s_cselect_b32 s19, s25, s29
	s_cselect_b32 s64, s24, s28
	s_add_u32 s65, s28, 0x80000
	s_addc_u32 s66, s29, 0
	s_add_u32 s28, s30, 0x204000
	s_addc_u32 s29, s31, 0
	s_add_u32 s67, s30, 0x400000
	s_addc_u32 s68, s31, 0
	s_mov_b32 s69, -2
	s_waitcnt vmcnt(25)
	s_waitcnt vmcnt(24)
	s_waitcnt vmcnt(4)
	s_waitcnt vmcnt(2)
	s_waitcnt vmcnt(1)
	s_waitcnt vmcnt(0)
	ds_read_b128 v[130:133], v181
	ds_read_b128 v[134:137], v181 offset:1024
	ds_read_b128 v[138:141], v181 offset:2048
	ds_read_b128 v[142:145], v181 offset:3072
	ds_read_b128 v[150:153], v182
	ds_read_b128 v[154:157], v182 offset:1024
	ds_read_b128 v[158:161], v182 offset:2048
	ds_read_b128 v[162:165], v182 offset:3072
	s_cmpk_eq_i32 s69, 0x52
	s_cselect_b32 s31, s19, s66
	s_cselect_b32 s30, s64, s65
	s_cselect_b32 s35, s21, s68
	s_cselect_b32 s34, s63, s67
	ds_read_b128 v[166:169], v183
	ds_read_b128 v[170:173], v183 offset:1024
	ds_read_b128 v[186:189], v183 offset:2048
	ds_read_b128 v[190:193], v183 offset:3072
	ds_read_b128 v[194:197], v183 offset:4096
	ds_read_b128 v[198:201], v183 offset:5120
	ds_read_b128 v[202:205], v183 offset:6144
	ds_read_b128 v[206:209], v183 offset:7168
	s_add_u32 s70, s28, 0xffffc000
	s_addc_u32 s71, s29, -1
	s_mov_b32 s73, m0
	s_mov_b32 m0, s57
	s_nop 0
	global_load_lds_dwordx4 v1, s[70:71]
	s_mov_b32 m0, s73
	s_nop 0
	s_mov_b32 s73, m0
	s_mov_b32 m0, s59
	s_nop 0
	global_load_lds_dwordx4 v177, s[70:71]
	s_mov_b32 m0, s73
	s_mov_b32 s70, m0
	s_mov_b32 m0, s58
	s_nop 0
	global_load_lds_dwordx4 v1, s[28:29]
	s_mov_b32 m0, s70
	s_nop 0
	s_mov_b32 s70, m0
	s_mov_b32 m0, s60
	s_nop 0
	global_load_lds_dwordx4 v177, s[28:29]
	s_mov_b32 m0, s70
	s_waitcnt vmcnt(8)
	s_waitcnt lgkmcnt(0)
	s_barrier
	s_setprio 1
	s_waitcnt lgkmcnt(7)
	v_mfma_f32_16x16x32_bf16 v[126:129], v[130:133], v[166:169], 0
	v_mfma_f32_16x16x32_bf16 v[126:129], v[134:137], v[170:173], v[126:129]
	s_waitcnt lgkmcnt(5)
	v_mfma_f32_16x16x32_bf16 v[122:125], v[138:141], v[166:169], 0
	v_mfma_f32_16x16x32_bf16 v[122:125], v[142:145], v[170:173], v[122:125]
	s_waitcnt lgkmcnt(3)
	v_mfma_f32_16x16x32_bf16 v[110:113], v[138:141], v[186:189], 0
	v_mfma_f32_16x16x32_bf16 v[110:113], v[142:145], v[190:193], v[110:113]
	s_waitcnt lgkmcnt(1)
	v_mfma_f32_16x16x32_bf16 v[118:121], v[130:133], v[186:189], 0
	v_mfma_f32_16x16x32_bf16 v[118:121], v[134:137], v[190:193], v[118:121]
	v_mfma_f32_16x16x32_bf16 v[94:97], v[130:133], v[194:197], 0
	v_mfma_f32_16x16x32_bf16 v[94:97], v[134:137], v[198:201], v[94:97]
	v_mfma_f32_16x16x32_bf16 v[90:93], v[138:141], v[194:197], 0
	v_mfma_f32_16x16x32_bf16 v[90:93], v[142:145], v[198:201], v[90:93]
	v_mfma_f32_16x16x32_bf16 v[78:81], v[138:141], v[202:205], 0
	v_mfma_f32_16x16x32_bf16 v[78:81], v[142:145], v[206:209], v[78:81]
	s_waitcnt lgkmcnt(0)
	v_mfma_f32_16x16x32_bf16 v[86:89], v[130:133], v[202:205], 0
	v_mfma_f32_16x16x32_bf16 v[86:89], v[134:137], v[206:209], v[86:89]
	v_mfma_f32_16x16x32_bf16 v[114:117], v[150:153], v[166:169], 0
	v_mfma_f32_16x16x32_bf16 v[114:117], v[154:157], v[170:173], v[114:117]
	v_mfma_f32_16x16x32_bf16 v[106:109], v[158:161], v[166:169], 0
	v_mfma_f32_16x16x32_bf16 v[106:109], v[162:165], v[170:173], v[106:109]
	v_mfma_f32_16x16x32_bf16 v[98:101], v[158:161], v[186:189], 0
	v_mfma_f32_16x16x32_bf16 v[98:101], v[162:165], v[190:193], v[98:101]
	v_mfma_f32_16x16x32_bf16 v[102:105], v[150:153], v[186:189], 0
	v_mfma_f32_16x16x32_bf16 v[102:105], v[154:157], v[190:193], v[102:105]
	v_mfma_f32_16x16x32_bf16 v[82:85], v[150:153], v[194:197], 0
	v_mfma_f32_16x16x32_bf16 v[82:85], v[154:157], v[198:201], v[82:85]
	v_mfma_f32_16x16x32_bf16 v[74:77], v[158:161], v[194:197], 0
	v_mfma_f32_16x16x32_bf16 v[74:77], v[162:165], v[198:201], v[74:77]
	v_mfma_f32_16x16x32_bf16 v[66:69], v[158:161], v[202:205], 0
	v_mfma_f32_16x16x32_bf16 v[66:69], v[162:165], v[206:209], v[66:69]
	s_setprio 2
	s_barrier
	v_mfma_f32_16x16x32_bf16 v[70:73], v[150:153], v[202:205], 0
	v_mfma_f32_16x16x32_bf16 v[70:73], v[154:157], v[206:209], v[70:73]
	s_setprio 0
	ds_read_b128 v[166:169], v183 offset:16384
	ds_read_b128 v[170:173], v183 offset:17408
	ds_read_b128 v[186:189], v183 offset:18432
	ds_read_b128 v[190:193], v183 offset:19456
	ds_read_b128 v[194:197], v183 offset:20480
	ds_read_b128 v[198:201], v183 offset:21504
	ds_read_b128 v[202:205], v183 offset:22528
	ds_read_b128 v[206:209], v183 offset:23552
	s_mov_b32 s70, m0
	s_mov_b32 m0, s27
	s_nop 0
	global_load_lds_dwordx4 v176, s[30:31]
	s_mov_b32 m0, s70
	s_nop 0
	s_mov_b32 s70, m0
	s_mov_b32 m0, s45
	s_nop 0
	global_load_lds_dwordx4 v178, s[30:31]
	s_mov_b32 m0, s70
	s_add_u32 s70, s30, 0x4000
	s_addc_u32 s71, s31, 0
	s_mov_b32 s73, m0
	s_mov_b32 m0, s46
	s_nop 0
	global_load_lds_dwordx4 v176, s[70:71]
	s_mov_b32 m0, s73
	s_nop 0
	s_mov_b32 s73, m0
	s_mov_b32 m0, s47
	s_nop 0
	global_load_lds_dwordx4 v178, s[70:71]
	s_mov_b32 m0, s73
	s_waitcnt vmcnt(4)
	s_waitcnt lgkmcnt(0)
	s_barrier
	s_setprio 1
	s_waitcnt lgkmcnt(7)
	v_mfma_f32_16x16x32_bf16 v[62:65], v[130:133], v[166:169], 0
	v_mfma_f32_16x16x32_bf16 v[62:65], v[134:137], v[170:173], v[62:65]
	s_waitcnt lgkmcnt(5)
	v_mfma_f32_16x16x32_bf16 v[58:61], v[138:141], v[166:169], 0
	v_mfma_f32_16x16x32_bf16 v[58:61], v[142:145], v[170:173], v[58:61]
	s_waitcnt lgkmcnt(3)
	v_mfma_f32_16x16x32_bf16 v[42:45], v[138:141], v[186:189], 0
	v_mfma_f32_16x16x32_bf16 v[42:45], v[142:145], v[190:193], v[42:45]
	s_waitcnt lgkmcnt(1)
	v_mfma_f32_16x16x32_bf16 v[46:49], v[130:133], v[186:189], 0
	v_mfma_f32_16x16x32_bf16 v[46:49], v[134:137], v[190:193], v[46:49]
	v_mfma_f32_16x16x32_bf16 v[30:33], v[130:133], v[194:197], 0
	v_mfma_f32_16x16x32_bf16 v[30:33], v[134:137], v[198:201], v[30:33]
	v_mfma_f32_16x16x32_bf16 v[26:29], v[138:141], v[194:197], 0
	v_mfma_f32_16x16x32_bf16 v[26:29], v[142:145], v[198:201], v[26:29]
	v_mfma_f32_16x16x32_bf16 v[10:13], v[138:141], v[202:205], 0
	v_mfma_f32_16x16x32_bf16 v[10:13], v[142:145], v[206:209], v[10:13]
	s_waitcnt lgkmcnt(0)
	v_mfma_f32_16x16x32_bf16 v[14:17], v[130:133], v[202:205], 0
	v_mfma_f32_16x16x32_bf16 v[14:17], v[134:137], v[206:209], v[14:17]
	v_mfma_f32_16x16x32_bf16 v[54:57], v[150:153], v[166:169], 0
	v_mfma_f32_16x16x32_bf16 v[54:57], v[154:157], v[170:173], v[54:57]
	v_mfma_f32_16x16x32_bf16 v[50:53], v[158:161], v[166:169], 0
	v_mfma_f32_16x16x32_bf16 v[50:53], v[162:165], v[170:173], v[50:53]
	v_mfma_f32_16x16x32_bf16 v[34:37], v[158:161], v[186:189], 0
	v_mfma_f32_16x16x32_bf16 v[34:37], v[162:165], v[190:193], v[34:37]
	v_mfma_f32_16x16x32_bf16 v[38:41], v[150:153], v[186:189], 0
	v_mfma_f32_16x16x32_bf16 v[38:41], v[154:157], v[190:193], v[38:41]
	v_mfma_f32_16x16x32_bf16 v[22:25], v[150:153], v[194:197], 0
	v_mfma_f32_16x16x32_bf16 v[22:25], v[154:157], v[198:201], v[22:25]
	v_mfma_f32_16x16x32_bf16 v[18:21], v[158:161], v[194:197], 0
	v_mfma_f32_16x16x32_bf16 v[18:21], v[162:165], v[198:201], v[18:21]
	v_mfma_f32_16x16x32_bf16 v[2:5], v[158:161], v[202:205], 0
	v_mfma_f32_16x16x32_bf16 v[2:5], v[162:165], v[206:209], v[2:5]
	s_setprio 2
	s_barrier
	v_mfma_f32_16x16x32_bf16 v[6:9], v[150:153], v[202:205], 0
	v_mfma_f32_16x16x32_bf16 v[6:9], v[154:157], v[206:209], v[6:9]
	s_setprio 0
	ds_read_b128 v[130:133], v184
	ds_read_b128 v[134:137], v184 offset:1024
	ds_read_b128 v[138:141], v184 offset:2048
	ds_read_b128 v[142:145], v184 offset:3072
	ds_read_b128 v[150:153], v185
	ds_read_b128 v[154:157], v185 offset:1024
	ds_read_b128 v[158:161], v185 offset:2048
	ds_read_b128 v[162:165], v185 offset:3072
	ds_read_b128 v[166:169], v183 offset:32768
	ds_read_b128 v[170:173], v183 offset:33792
	ds_read_b128 v[186:189], v183 offset:34816
	ds_read_b128 v[190:193], v183 offset:35840
	ds_read_b128 v[194:197], v183 offset:36864
	ds_read_b128 v[198:201], v183 offset:37888
	ds_read_b128 v[202:205], v183 offset:38912
	ds_read_b128 v[206:209], v183 offset:39936
	s_mov_b32 s70, m0
	s_mov_b32 m0, s44
	s_nop 0
	global_load_lds_dwordx4 v1, s[34:35]
	s_mov_b32 m0, s70
	s_nop 0
	s_mov_b32 s70, m0
	s_mov_b32 m0, s48
	s_nop 0
	global_load_lds_dwordx4 v177, s[34:35]
	s_mov_b32 m0, s70
	s_add_u32 s34, s34, 0x4000
	s_addc_u32 s35, s35, 0
	s_mov_b32 s70, m0
	s_mov_b32 m0, s49
	s_nop 0
	global_load_lds_dwordx4 v1, s[34:35]
	s_mov_b32 m0, s70
	s_nop 0
	s_mov_b32 s70, m0
	s_mov_b32 m0, s50
	s_nop 0
	global_load_lds_dwordx4 v177, s[34:35]
	s_mov_b32 m0, s70
	s_waitcnt vmcnt(8)
	s_waitcnt lgkmcnt(0)
	s_barrier
	s_setprio 1
	s_waitcnt lgkmcnt(7)
	v_mfma_f32_16x16x32_bf16 v[126:129], v[130:133], v[166:169], v[126:129]
	v_mfma_f32_16x16x32_bf16 v[126:129], v[134:137], v[170:173], v[126:129]
	s_waitcnt lgkmcnt(5)
	v_mfma_f32_16x16x32_bf16 v[122:125], v[138:141], v[166:169], v[122:125]
	v_mfma_f32_16x16x32_bf16 v[122:125], v[142:145], v[170:173], v[122:125]
	s_waitcnt lgkmcnt(3)
	v_mfma_f32_16x16x32_bf16 v[110:113], v[138:141], v[186:189], v[110:113]
	v_mfma_f32_16x16x32_bf16 v[110:113], v[142:145], v[190:193], v[110:113]
	s_waitcnt lgkmcnt(1)
	v_mfma_f32_16x16x32_bf16 v[118:121], v[130:133], v[186:189], v[118:121]
	v_mfma_f32_16x16x32_bf16 v[118:121], v[134:137], v[190:193], v[118:121]
	v_mfma_f32_16x16x32_bf16 v[94:97], v[130:133], v[194:197], v[94:97]
	v_mfma_f32_16x16x32_bf16 v[94:97], v[134:137], v[198:201], v[94:97]
	v_mfma_f32_16x16x32_bf16 v[90:93], v[138:141], v[194:197], v[90:93]
	v_mfma_f32_16x16x32_bf16 v[90:93], v[142:145], v[198:201], v[90:93]
	v_mfma_f32_16x16x32_bf16 v[78:81], v[138:141], v[202:205], v[78:81]
	v_mfma_f32_16x16x32_bf16 v[78:81], v[142:145], v[206:209], v[78:81]
	s_waitcnt lgkmcnt(0)
	v_mfma_f32_16x16x32_bf16 v[86:89], v[130:133], v[202:205], v[86:89]
	v_mfma_f32_16x16x32_bf16 v[86:89], v[134:137], v[206:209], v[86:89]
	v_mfma_f32_16x16x32_bf16 v[114:117], v[150:153], v[166:169], v[114:117]
	v_mfma_f32_16x16x32_bf16 v[114:117], v[154:157], v[170:173], v[114:117]
	v_mfma_f32_16x16x32_bf16 v[106:109], v[158:161], v[166:169], v[106:109]
	v_mfma_f32_16x16x32_bf16 v[106:109], v[162:165], v[170:173], v[106:109]
	v_mfma_f32_16x16x32_bf16 v[98:101], v[158:161], v[186:189], v[98:101]
	v_mfma_f32_16x16x32_bf16 v[98:101], v[162:165], v[190:193], v[98:101]
	v_mfma_f32_16x16x32_bf16 v[102:105], v[150:153], v[186:189], v[102:105]
	v_mfma_f32_16x16x32_bf16 v[102:105], v[154:157], v[190:193], v[102:105]
	v_mfma_f32_16x16x32_bf16 v[82:85], v[150:153], v[194:197], v[82:85]
	v_mfma_f32_16x16x32_bf16 v[82:85], v[154:157], v[198:201], v[82:85]
	v_mfma_f32_16x16x32_bf16 v[74:77], v[158:161], v[194:197], v[74:77]
	v_mfma_f32_16x16x32_bf16 v[74:77], v[162:165], v[198:201], v[74:77]
	v_mfma_f32_16x16x32_bf16 v[66:69], v[158:161], v[202:205], v[66:69]
	v_mfma_f32_16x16x32_bf16 v[66:69], v[162:165], v[206:209], v[66:69]
	s_setprio 2
	s_barrier
	v_mfma_f32_16x16x32_bf16 v[70:73], v[150:153], v[202:205], v[70:73]
	v_mfma_f32_16x16x32_bf16 v[70:73], v[154:157], v[206:209], v[70:73]
	s_setprio 0
	ds_read_b128 v[166:169], v183 offset:49152
	ds_read_b128 v[170:173], v183 offset:50176
	ds_read_b128 v[186:189], v183 offset:51200
	ds_read_b128 v[190:193], v183 offset:52224
	ds_read_b128 v[194:197], v183 offset:53248
	ds_read_b128 v[198:201], v183 offset:54272
	ds_read_b128 v[202:205], v183 offset:55296
	ds_read_b128 v[206:209], v183 offset:56320
	s_add_u32 s34, s30, 0x40000
	s_addc_u32 s35, s31, 0
	s_mov_b32 s70, m0
	s_mov_b32 m0, s51
	s_nop 0
	global_load_lds_dwordx4 v176, s[34:35]
	s_mov_b32 m0, s70
	s_add_u32 s30, s30, 0x44000
	s_mov_b32 s70, m0
	s_mov_b32 m0, s52
	s_nop 0
	global_load_lds_dwordx4 v178, s[34:35]
	s_mov_b32 m0, s70
	s_addc_u32 s31, s31, 0
	s_mov_b32 s34, m0
	s_mov_b32 m0, s53
	s_nop 0
	global_load_lds_dwordx4 v176, s[30:31]
	s_mov_b32 m0, s34
	s_nop 0
	s_mov_b32 s34, m0
	s_mov_b32 m0, s54
	s_nop 0
	global_load_lds_dwordx4 v178, s[30:31]
	s_mov_b32 m0, s34
	s_waitcnt vmcnt(4)
	s_waitcnt lgkmcnt(0)
	s_barrier
	s_setprio 1
	s_waitcnt lgkmcnt(7)
	v_mfma_f32_16x16x32_bf16 v[62:65], v[130:133], v[166:169], v[62:65]
	v_mfma_f32_16x16x32_bf16 v[62:65], v[134:137], v[170:173], v[62:65]
	s_waitcnt lgkmcnt(5)
	v_mfma_f32_16x16x32_bf16 v[58:61], v[138:141], v[166:169], v[58:61]
	v_mfma_f32_16x16x32_bf16 v[58:61], v[142:145], v[170:173], v[58:61]
	s_waitcnt lgkmcnt(3)
	v_mfma_f32_16x16x32_bf16 v[42:45], v[138:141], v[186:189], v[42:45]
	v_mfma_f32_16x16x32_bf16 v[42:45], v[142:145], v[190:193], v[42:45]
	s_waitcnt lgkmcnt(1)
	v_mfma_f32_16x16x32_bf16 v[46:49], v[130:133], v[186:189], v[46:49]
	v_mfma_f32_16x16x32_bf16 v[46:49], v[134:137], v[190:193], v[46:49]
	v_mfma_f32_16x16x32_bf16 v[30:33], v[130:133], v[194:197], v[30:33]
	v_mfma_f32_16x16x32_bf16 v[30:33], v[134:137], v[198:201], v[30:33]
	v_mfma_f32_16x16x32_bf16 v[26:29], v[138:141], v[194:197], v[26:29]
	v_mfma_f32_16x16x32_bf16 v[26:29], v[142:145], v[198:201], v[26:29]
	v_mfma_f32_16x16x32_bf16 v[10:13], v[138:141], v[202:205], v[10:13]
	v_mfma_f32_16x16x32_bf16 v[10:13], v[142:145], v[206:209], v[10:13]
	s_waitcnt lgkmcnt(0)
	v_mfma_f32_16x16x32_bf16 v[14:17], v[130:133], v[202:205], v[14:17]
	v_mfma_f32_16x16x32_bf16 v[14:17], v[134:137], v[206:209], v[14:17]
	v_mfma_f32_16x16x32_bf16 v[54:57], v[150:153], v[166:169], v[54:57]
	v_mfma_f32_16x16x32_bf16 v[54:57], v[154:157], v[170:173], v[54:57]
	v_mfma_f32_16x16x32_bf16 v[50:53], v[158:161], v[166:169], v[50:53]
	v_mfma_f32_16x16x32_bf16 v[50:53], v[162:165], v[170:173], v[50:53]
	v_mfma_f32_16x16x32_bf16 v[34:37], v[158:161], v[186:189], v[34:37]
	v_mfma_f32_16x16x32_bf16 v[34:37], v[162:165], v[190:193], v[34:37]
	v_mfma_f32_16x16x32_bf16 v[38:41], v[150:153], v[186:189], v[38:41]
	v_mfma_f32_16x16x32_bf16 v[38:41], v[154:157], v[190:193], v[38:41]
	v_mfma_f32_16x16x32_bf16 v[22:25], v[150:153], v[194:197], v[22:25]
	v_mfma_f32_16x16x32_bf16 v[22:25], v[154:157], v[198:201], v[22:25]
	v_mfma_f32_16x16x32_bf16 v[18:21], v[158:161], v[194:197], v[18:21]
	v_mfma_f32_16x16x32_bf16 v[18:21], v[162:165], v[198:201], v[18:21]
	v_mfma_f32_16x16x32_bf16 v[2:5], v[158:161], v[202:205], v[2:5]
	v_mfma_f32_16x16x32_bf16 v[2:5], v[162:165], v[206:209], v[2:5]
	s_setprio 2
	s_barrier
	v_mfma_f32_16x16x32_bf16 v[6:9], v[150:153], v[202:205], v[6:9]
	v_mfma_f32_16x16x32_bf16 v[6:9], v[154:157], v[206:209], v[6:9]
	s_setprio 0
	s_add_i32 s69, s69, 2
	s_add_u32 s65, s65, 0x80000
	s_addc_u32 s66, s66, 0
	s_add_u32 s28, s28, 0x400000
	s_addc_u32 s29, s29, 0
	s_add_u32 s67, s67, 0x400000
	s_addc_u32 s68, s68, 0
	s_cmpk_gt_u32 s69, 0x53
	.p2align 6
.LBB0_2792:
	ds_read_b128 v[130:133], v181
	ds_read_b128 v[134:137], v181 offset:1024
	ds_read_b128 v[138:141], v181 offset:2048
	ds_read_b128 v[142:145], v181 offset:3072
	ds_read_b128 v[150:153], v182
	ds_read_b128 v[154:157], v182 offset:1024
	ds_read_b128 v[158:161], v182 offset:2048
	ds_read_b128 v[162:165], v182 offset:3072
	s_cmpk_eq_i32 s69, 0x52
	s_cselect_b32 s31, s19, s66
	s_cselect_b32 s30, s64, s65
	s_cselect_b32 s35, s21, s68
	s_cselect_b32 s34, s63, s67
	ds_read_b128 v[166:169], v183
	ds_read_b128 v[170:173], v183 offset:1024
	ds_read_b128 v[186:189], v183 offset:2048
	ds_read_b128 v[190:193], v183 offset:3072
	ds_read_b128 v[194:197], v183 offset:4096
	ds_read_b128 v[198:201], v183 offset:5120
	ds_read_b128 v[202:205], v183 offset:6144
	ds_read_b128 v[206:209], v183 offset:7168
	s_add_u32 s70, s28, 0xffffc000
	s_addc_u32 s71, s29, -1
	s_mov_b32 s73, m0
	s_mov_b32 m0, s57
	s_nop 0
	global_load_lds_dwordx4 v1, s[70:71]
	s_mov_b32 m0, s73
	s_nop 0
	s_mov_b32 s73, m0
	s_mov_b32 m0, s59
	s_nop 0
	global_load_lds_dwordx4 v177, s[70:71]
	s_mov_b32 m0, s73
	s_mov_b32 s70, m0
	s_mov_b32 m0, s58
	s_nop 0
	global_load_lds_dwordx4 v1, s[28:29]
	s_mov_b32 m0, s70
	s_nop 0
	s_mov_b32 s70, m0
	s_mov_b32 m0, s60
	s_nop 0
	global_load_lds_dwordx4 v177, s[28:29]
	s_mov_b32 m0, s70
	s_waitcnt vmcnt(8)
	s_waitcnt lgkmcnt(0)
	s_barrier
	s_setprio 1
	s_waitcnt lgkmcnt(7)
	v_mfma_f32_16x16x32_bf16 v[126:129], v[130:133], v[166:169], v[126:129]
	v_mfma_f32_16x16x32_bf16 v[126:129], v[134:137], v[170:173], v[126:129]
	s_waitcnt lgkmcnt(5)
	v_mfma_f32_16x16x32_bf16 v[122:125], v[138:141], v[166:169], v[122:125]
	v_mfma_f32_16x16x32_bf16 v[122:125], v[142:145], v[170:173], v[122:125]
	s_waitcnt lgkmcnt(3)
	v_mfma_f32_16x16x32_bf16 v[110:113], v[138:141], v[186:189], v[110:113]
	v_mfma_f32_16x16x32_bf16 v[110:113], v[142:145], v[190:193], v[110:113]
	s_waitcnt lgkmcnt(1)
	v_mfma_f32_16x16x32_bf16 v[118:121], v[130:133], v[186:189], v[118:121]
	v_mfma_f32_16x16x32_bf16 v[118:121], v[134:137], v[190:193], v[118:121]
	v_mfma_f32_16x16x32_bf16 v[94:97], v[130:133], v[194:197], v[94:97]
	v_mfma_f32_16x16x32_bf16 v[94:97], v[134:137], v[198:201], v[94:97]
	v_mfma_f32_16x16x32_bf16 v[90:93], v[138:141], v[194:197], v[90:93]
	v_mfma_f32_16x16x32_bf16 v[90:93], v[142:145], v[198:201], v[90:93]
	v_mfma_f32_16x16x32_bf16 v[78:81], v[138:141], v[202:205], v[78:81]
	v_mfma_f32_16x16x32_bf16 v[78:81], v[142:145], v[206:209], v[78:81]
	s_waitcnt lgkmcnt(0)
	v_mfma_f32_16x16x32_bf16 v[86:89], v[130:133], v[202:205], v[86:89]
	v_mfma_f32_16x16x32_bf16 v[86:89], v[134:137], v[206:209], v[86:89]
	v_mfma_f32_16x16x32_bf16 v[114:117], v[150:153], v[166:169], v[114:117]
	v_mfma_f32_16x16x32_bf16 v[114:117], v[154:157], v[170:173], v[114:117]
	v_mfma_f32_16x16x32_bf16 v[106:109], v[158:161], v[166:169], v[106:109]
	v_mfma_f32_16x16x32_bf16 v[106:109], v[162:165], v[170:173], v[106:109]
	v_mfma_f32_16x16x32_bf16 v[98:101], v[158:161], v[186:189], v[98:101]
	v_mfma_f32_16x16x32_bf16 v[98:101], v[162:165], v[190:193], v[98:101]
	v_mfma_f32_16x16x32_bf16 v[102:105], v[150:153], v[186:189], v[102:105]
	v_mfma_f32_16x16x32_bf16 v[102:105], v[154:157], v[190:193], v[102:105]
	v_mfma_f32_16x16x32_bf16 v[82:85], v[150:153], v[194:197], v[82:85]
	v_mfma_f32_16x16x32_bf16 v[82:85], v[154:157], v[198:201], v[82:85]
	v_mfma_f32_16x16x32_bf16 v[74:77], v[158:161], v[194:197], v[74:77]
	v_mfma_f32_16x16x32_bf16 v[74:77], v[162:165], v[198:201], v[74:77]
	v_mfma_f32_16x16x32_bf16 v[66:69], v[158:161], v[202:205], v[66:69]
	v_mfma_f32_16x16x32_bf16 v[66:69], v[162:165], v[206:209], v[66:69]
	s_setprio 2
	s_barrier
	v_mfma_f32_16x16x32_bf16 v[70:73], v[150:153], v[202:205], v[70:73]
	v_mfma_f32_16x16x32_bf16 v[70:73], v[154:157], v[206:209], v[70:73]
	s_setprio 0
	ds_read_b128 v[166:169], v183 offset:16384
	ds_read_b128 v[170:173], v183 offset:17408
	ds_read_b128 v[186:189], v183 offset:18432
	ds_read_b128 v[190:193], v183 offset:19456
	ds_read_b128 v[194:197], v183 offset:20480
	ds_read_b128 v[198:201], v183 offset:21504
	ds_read_b128 v[202:205], v183 offset:22528
	ds_read_b128 v[206:209], v183 offset:23552
	s_mov_b32 s70, m0
	s_mov_b32 m0, s27
	s_nop 0
	global_load_lds_dwordx4 v176, s[30:31]
	s_mov_b32 m0, s70
	s_nop 0
	s_mov_b32 s70, m0
	s_mov_b32 m0, s45
	s_nop 0
	global_load_lds_dwordx4 v178, s[30:31]
	s_mov_b32 m0, s70
	s_add_u32 s70, s30, 0x4000
	s_addc_u32 s71, s31, 0
	s_mov_b32 s73, m0
	s_mov_b32 m0, s46
	s_nop 0
	global_load_lds_dwordx4 v176, s[70:71]
	s_mov_b32 m0, s73
	s_nop 0
	s_mov_b32 s73, m0
	s_mov_b32 m0, s47
	s_nop 0
	global_load_lds_dwordx4 v178, s[70:71]
	s_mov_b32 m0, s73
	s_waitcnt vmcnt(4)
	s_waitcnt lgkmcnt(0)
	s_barrier
	s_setprio 1
	s_waitcnt lgkmcnt(7)
	v_mfma_f32_16x16x32_bf16 v[62:65], v[130:133], v[166:169], v[62:65]
	v_mfma_f32_16x16x32_bf16 v[62:65], v[134:137], v[170:173], v[62:65]
	s_waitcnt lgkmcnt(5)
	v_mfma_f32_16x16x32_bf16 v[58:61], v[138:141], v[166:169], v[58:61]
	v_mfma_f32_16x16x32_bf16 v[58:61], v[142:145], v[170:173], v[58:61]
	s_waitcnt lgkmcnt(3)
	v_mfma_f32_16x16x32_bf16 v[42:45], v[138:141], v[186:189], v[42:45]
	v_mfma_f32_16x16x32_bf16 v[42:45], v[142:145], v[190:193], v[42:45]
	s_waitcnt lgkmcnt(1)
	v_mfma_f32_16x16x32_bf16 v[46:49], v[130:133], v[186:189], v[46:49]
	v_mfma_f32_16x16x32_bf16 v[46:49], v[134:137], v[190:193], v[46:49]
	v_mfma_f32_16x16x32_bf16 v[30:33], v[130:133], v[194:197], v[30:33]
	v_mfma_f32_16x16x32_bf16 v[30:33], v[134:137], v[198:201], v[30:33]
	v_mfma_f32_16x16x32_bf16 v[26:29], v[138:141], v[194:197], v[26:29]
	v_mfma_f32_16x16x32_bf16 v[26:29], v[142:145], v[198:201], v[26:29]
	v_mfma_f32_16x16x32_bf16 v[10:13], v[138:141], v[202:205], v[10:13]
	v_mfma_f32_16x16x32_bf16 v[10:13], v[142:145], v[206:209], v[10:13]
	s_waitcnt lgkmcnt(0)
	v_mfma_f32_16x16x32_bf16 v[14:17], v[130:133], v[202:205], v[14:17]
	v_mfma_f32_16x16x32_bf16 v[14:17], v[134:137], v[206:209], v[14:17]
	v_mfma_f32_16x16x32_bf16 v[54:57], v[150:153], v[166:169], v[54:57]
	v_mfma_f32_16x16x32_bf16 v[54:57], v[154:157], v[170:173], v[54:57]
	v_mfma_f32_16x16x32_bf16 v[50:53], v[158:161], v[166:169], v[50:53]
	v_mfma_f32_16x16x32_bf16 v[50:53], v[162:165], v[170:173], v[50:53]
	v_mfma_f32_16x16x32_bf16 v[34:37], v[158:161], v[186:189], v[34:37]
	v_mfma_f32_16x16x32_bf16 v[34:37], v[162:165], v[190:193], v[34:37]
	v_mfma_f32_16x16x32_bf16 v[38:41], v[150:153], v[186:189], v[38:41]
	v_mfma_f32_16x16x32_bf16 v[38:41], v[154:157], v[190:193], v[38:41]
	v_mfma_f32_16x16x32_bf16 v[22:25], v[150:153], v[194:197], v[22:25]
	v_mfma_f32_16x16x32_bf16 v[22:25], v[154:157], v[198:201], v[22:25]
	v_mfma_f32_16x16x32_bf16 v[18:21], v[158:161], v[194:197], v[18:21]
	v_mfma_f32_16x16x32_bf16 v[18:21], v[162:165], v[198:201], v[18:21]
	v_mfma_f32_16x16x32_bf16 v[2:5], v[158:161], v[202:205], v[2:5]
	v_mfma_f32_16x16x32_bf16 v[2:5], v[162:165], v[206:209], v[2:5]
	s_setprio 2
	s_barrier
	v_mfma_f32_16x16x32_bf16 v[6:9], v[150:153], v[202:205], v[6:9]
	v_mfma_f32_16x16x32_bf16 v[6:9], v[154:157], v[206:209], v[6:9]
	s_setprio 0
	ds_read_b128 v[130:133], v184
	ds_read_b128 v[134:137], v184 offset:1024
	ds_read_b128 v[138:141], v184 offset:2048
	ds_read_b128 v[142:145], v184 offset:3072
	ds_read_b128 v[150:153], v185
	ds_read_b128 v[154:157], v185 offset:1024
	ds_read_b128 v[158:161], v185 offset:2048
	ds_read_b128 v[162:165], v185 offset:3072
	ds_read_b128 v[166:169], v183 offset:32768
	ds_read_b128 v[170:173], v183 offset:33792
	ds_read_b128 v[186:189], v183 offset:34816
	ds_read_b128 v[190:193], v183 offset:35840
	ds_read_b128 v[194:197], v183 offset:36864
	ds_read_b128 v[198:201], v183 offset:37888
	ds_read_b128 v[202:205], v183 offset:38912
	ds_read_b128 v[206:209], v183 offset:39936
	s_mov_b32 s70, m0
	s_mov_b32 m0, s44
	s_nop 0
	global_load_lds_dwordx4 v1, s[34:35]
	s_mov_b32 m0, s70
	s_nop 0
	s_mov_b32 s70, m0
	s_mov_b32 m0, s48
	s_nop 0
	global_load_lds_dwordx4 v177, s[34:35]
	s_mov_b32 m0, s70
	s_add_u32 s34, s34, 0x4000
	s_addc_u32 s35, s35, 0
	s_mov_b32 s70, m0
	s_mov_b32 m0, s49
	s_nop 0
	global_load_lds_dwordx4 v1, s[34:35]
	s_mov_b32 m0, s70
	s_nop 0
	s_mov_b32 s70, m0
	s_mov_b32 m0, s50
	s_nop 0
	global_load_lds_dwordx4 v177, s[34:35]
	s_mov_b32 m0, s70
	s_waitcnt vmcnt(8)
	s_waitcnt lgkmcnt(0)
	s_barrier
	s_setprio 1
	s_waitcnt lgkmcnt(7)
	v_mfma_f32_16x16x32_bf16 v[126:129], v[130:133], v[166:169], v[126:129]
	v_mfma_f32_16x16x32_bf16 v[126:129], v[134:137], v[170:173], v[126:129]
	s_waitcnt lgkmcnt(5)
	v_mfma_f32_16x16x32_bf16 v[122:125], v[138:141], v[166:169], v[122:125]
	v_mfma_f32_16x16x32_bf16 v[122:125], v[142:145], v[170:173], v[122:125]
	s_waitcnt lgkmcnt(3)
	v_mfma_f32_16x16x32_bf16 v[110:113], v[138:141], v[186:189], v[110:113]
	v_mfma_f32_16x16x32_bf16 v[110:113], v[142:145], v[190:193], v[110:113]
	s_waitcnt lgkmcnt(1)
	v_mfma_f32_16x16x32_bf16 v[118:121], v[130:133], v[186:189], v[118:121]
	v_mfma_f32_16x16x32_bf16 v[118:121], v[134:137], v[190:193], v[118:121]
	v_mfma_f32_16x16x32_bf16 v[94:97], v[130:133], v[194:197], v[94:97]
	v_mfma_f32_16x16x32_bf16 v[94:97], v[134:137], v[198:201], v[94:97]
	v_mfma_f32_16x16x32_bf16 v[90:93], v[138:141], v[194:197], v[90:93]
	v_mfma_f32_16x16x32_bf16 v[90:93], v[142:145], v[198:201], v[90:93]
	v_mfma_f32_16x16x32_bf16 v[78:81], v[138:141], v[202:205], v[78:81]
	v_mfma_f32_16x16x32_bf16 v[78:81], v[142:145], v[206:209], v[78:81]
	s_waitcnt lgkmcnt(0)
	v_mfma_f32_16x16x32_bf16 v[86:89], v[130:133], v[202:205], v[86:89]
	v_mfma_f32_16x16x32_bf16 v[86:89], v[134:137], v[206:209], v[86:89]
	v_mfma_f32_16x16x32_bf16 v[114:117], v[150:153], v[166:169], v[114:117]
	v_mfma_f32_16x16x32_bf16 v[114:117], v[154:157], v[170:173], v[114:117]
	v_mfma_f32_16x16x32_bf16 v[106:109], v[158:161], v[166:169], v[106:109]
	v_mfma_f32_16x16x32_bf16 v[106:109], v[162:165], v[170:173], v[106:109]
	v_mfma_f32_16x16x32_bf16 v[98:101], v[158:161], v[186:189], v[98:101]
	v_mfma_f32_16x16x32_bf16 v[98:101], v[162:165], v[190:193], v[98:101]
	v_mfma_f32_16x16x32_bf16 v[102:105], v[150:153], v[186:189], v[102:105]
	v_mfma_f32_16x16x32_bf16 v[102:105], v[154:157], v[190:193], v[102:105]
	v_mfma_f32_16x16x32_bf16 v[82:85], v[150:153], v[194:197], v[82:85]
	v_mfma_f32_16x16x32_bf16 v[82:85], v[154:157], v[198:201], v[82:85]
	v_mfma_f32_16x16x32_bf16 v[74:77], v[158:161], v[194:197], v[74:77]
	v_mfma_f32_16x16x32_bf16 v[74:77], v[162:165], v[198:201], v[74:77]
	v_mfma_f32_16x16x32_bf16 v[66:69], v[158:161], v[202:205], v[66:69]
	v_mfma_f32_16x16x32_bf16 v[66:69], v[162:165], v[206:209], v[66:69]
	s_setprio 2
	s_barrier
	v_mfma_f32_16x16x32_bf16 v[70:73], v[150:153], v[202:205], v[70:73]
	v_mfma_f32_16x16x32_bf16 v[70:73], v[154:157], v[206:209], v[70:73]
	s_setprio 0
	ds_read_b128 v[166:169], v183 offset:49152
	ds_read_b128 v[170:173], v183 offset:50176
	ds_read_b128 v[186:189], v183 offset:51200
	ds_read_b128 v[190:193], v183 offset:52224
	ds_read_b128 v[194:197], v183 offset:53248
	ds_read_b128 v[198:201], v183 offset:54272
	ds_read_b128 v[202:205], v183 offset:55296
	ds_read_b128 v[206:209], v183 offset:56320
	s_add_u32 s34, s30, 0x40000
	s_addc_u32 s35, s31, 0
	s_mov_b32 s70, m0
	s_mov_b32 m0, s51
	s_nop 0
	global_load_lds_dwordx4 v176, s[34:35]
	s_mov_b32 m0, s70
	s_add_u32 s30, s30, 0x44000
	s_mov_b32 s70, m0
	s_mov_b32 m0, s52
	s_nop 0
	global_load_lds_dwordx4 v178, s[34:35]
	s_mov_b32 m0, s70
	s_addc_u32 s31, s31, 0
	s_mov_b32 s34, m0
	s_mov_b32 m0, s53
	s_nop 0
	global_load_lds_dwordx4 v176, s[30:31]
	s_mov_b32 m0, s34
	s_nop 0
	s_mov_b32 s34, m0
	s_mov_b32 m0, s54
	s_nop 0
	global_load_lds_dwordx4 v178, s[30:31]
	s_mov_b32 m0, s34
	s_waitcnt vmcnt(4)
	s_waitcnt lgkmcnt(0)
	s_barrier
	s_setprio 1
	s_waitcnt lgkmcnt(7)
	v_mfma_f32_16x16x32_bf16 v[62:65], v[130:133], v[166:169], v[62:65]
	v_mfma_f32_16x16x32_bf16 v[62:65], v[134:137], v[170:173], v[62:65]
	s_waitcnt lgkmcnt(5)
	v_mfma_f32_16x16x32_bf16 v[58:61], v[138:141], v[166:169], v[58:61]
	v_mfma_f32_16x16x32_bf16 v[58:61], v[142:145], v[170:173], v[58:61]
	s_waitcnt lgkmcnt(3)
	v_mfma_f32_16x16x32_bf16 v[42:45], v[138:141], v[186:189], v[42:45]
	v_mfma_f32_16x16x32_bf16 v[42:45], v[142:145], v[190:193], v[42:45]
	s_waitcnt lgkmcnt(1)
	v_mfma_f32_16x16x32_bf16 v[46:49], v[130:133], v[186:189], v[46:49]
	v_mfma_f32_16x16x32_bf16 v[46:49], v[134:137], v[190:193], v[46:49]
	v_mfma_f32_16x16x32_bf16 v[30:33], v[130:133], v[194:197], v[30:33]
	v_mfma_f32_16x16x32_bf16 v[30:33], v[134:137], v[198:201], v[30:33]
	v_mfma_f32_16x16x32_bf16 v[26:29], v[138:141], v[194:197], v[26:29]
	v_mfma_f32_16x16x32_bf16 v[26:29], v[142:145], v[198:201], v[26:29]
	v_mfma_f32_16x16x32_bf16 v[10:13], v[138:141], v[202:205], v[10:13]
	v_mfma_f32_16x16x32_bf16 v[10:13], v[142:145], v[206:209], v[10:13]
	s_waitcnt lgkmcnt(0)
	v_mfma_f32_16x16x32_bf16 v[14:17], v[130:133], v[202:205], v[14:17]
	v_mfma_f32_16x16x32_bf16 v[14:17], v[134:137], v[206:209], v[14:17]
	v_mfma_f32_16x16x32_bf16 v[54:57], v[150:153], v[166:169], v[54:57]
	v_mfma_f32_16x16x32_bf16 v[54:57], v[154:157], v[170:173], v[54:57]
	v_mfma_f32_16x16x32_bf16 v[50:53], v[158:161], v[166:169], v[50:53]
	v_mfma_f32_16x16x32_bf16 v[50:53], v[162:165], v[170:173], v[50:53]
	v_mfma_f32_16x16x32_bf16 v[34:37], v[158:161], v[186:189], v[34:37]
	v_mfma_f32_16x16x32_bf16 v[34:37], v[162:165], v[190:193], v[34:37]
	v_mfma_f32_16x16x32_bf16 v[38:41], v[150:153], v[186:189], v[38:41]
	v_mfma_f32_16x16x32_bf16 v[38:41], v[154:157], v[190:193], v[38:41]
	v_mfma_f32_16x16x32_bf16 v[22:25], v[150:153], v[194:197], v[22:25]
	v_mfma_f32_16x16x32_bf16 v[22:25], v[154:157], v[198:201], v[22:25]
	v_mfma_f32_16x16x32_bf16 v[18:21], v[158:161], v[194:197], v[18:21]
	v_mfma_f32_16x16x32_bf16 v[18:21], v[162:165], v[198:201], v[18:21]
	v_mfma_f32_16x16x32_bf16 v[2:5], v[158:161], v[202:205], v[2:5]
	v_mfma_f32_16x16x32_bf16 v[2:5], v[162:165], v[206:209], v[2:5]
	s_setprio 2
	s_barrier
	v_mfma_f32_16x16x32_bf16 v[6:9], v[150:153], v[202:205], v[6:9]
	v_mfma_f32_16x16x32_bf16 v[6:9], v[154:157], v[206:209], v[6:9]
	s_setprio 0
	s_add_i32 s69, s69, 2
	s_add_u32 s65, s65, 0x80000
	s_addc_u32 s66, s66, 0
	s_add_u32 s28, s28, 0x400000
	s_addc_u32 s29, s29, 0
	s_add_u32 s67, s67, 0x400000
	s_addc_u32 s68, s68, 0
	s_cmpk_gt_u32 s69, 0x53
	s_cbranch_scc0 .LBB0_2792
	s_and_b64 vcc, exec, s[8:9]
	s_cbranch_vccz .LBB0_2795
	s_barrier
